# write-through (sc1) 16-byte epilogue stores in the single-unit GEMM phases so the L2 is mostly clean when the grid barrier's write-back runs
# baseline (speedup 1.0000x reference)
; __device__ __forceinline__ unsigned cvt_pk_bf16(float lo, float hi) { unsigned r; asm volatile("v_cvt_pk_bf16_f32 %0, %1, %2" : "=v"(r) : "v"(lo), "v"(hi)); return r; }
;     __device__ __forceinline__ void core(const f32x4 (&acc)[2][2][4][2], const Unit& u, int wr, int wc, int fr, int fq, const float (&rsc)[2][4]) const {
;         const int row0 = u.pm * BM + wr * 64 + fr, col0 = u.pn * BM + wc * 32 + 8 * fq;
; #pragma unroll
;         for (int ai = 0; ai < 2; ++ai)
; #pragma unroll
;         for (int mh = 0; mh < 4; mh += MB) {
;             u32x4 va[MB][2]; u32x2 vb[MB][2];
;             f32x4 xa[MB][2], xb[MB][2];
; #pragma unroll
;             for (int m = 0; m < MB; ++m)
; #pragma unroll
;                 for (int bj = 0; bj < 2; ++bj) { const size_t idx = (size_t)(row0 + ai * HALF + (mh + m) * 16) * D + col0 + bj * HALF;
;                     if (F32IN) { xa[m][bj] = *(const f32x4*)(Xin + idx); xb[m][bj] = *(const f32x4*)(Xin + idx + 4); }
;                     else { va[m][bj] = *(const u32x4*)(Hb + idx); vb[m][bj] = *(const u32x2*)(Hl + idx); } }
; #pragma unroll
;             for (int m = 0; m < MB; ++m) { const int row = row0 + ai * HALF + (mh + m) * 16; float sq = 0.f;
;                 const float rs1 = rsc[ai][mh + m];
; #pragma unroll
;                 for (int bj = 0; bj < 2; ++bj) { const size_t idx = (size_t)row * D + col0 + bj * HALF;
;                     unsigned hw[4]; int lw[2] = {0, 0};
; #pragma unroll
;                     for (int pq = 0; pq < 4; ++pq) {
;                         float h0, h1;
;                         if (F32IN) { h0 = (pq < 2) ? xa[m][bj][2 * pq] : xb[m][bj][2 * pq - 4]; h1 = (pq < 2) ? xa[m][bj][2 * pq + 1] : xb[m][bj][2 * pq - 3]; }
;                         else { const unsigned a = va[m][bj][pq]; const int bw = (int)vb[m][bj][pq >> 1]; const hf32x2 lp = (pq & 1) ? __builtin_amdgcn_cvt_pk_f32_fp8(bw, true) : __builtin_amdgcn_cvt_pk_f32_fp8(bw, false);
;                             h0 = __uint_as_float(a << 16) + lp.x * 0.00390625f; h1 = __uint_as_float(a & 0xffff0000u) + lp.y * 0.00390625f; }
;                         const float o0 = h0 + acc[ai][bj][mh + m][pq >> 1][(2 * pq) & 3] * rs1, o1 = h1 + acc[ai][bj][mh + m][pq >> 1][(2 * pq + 1) & 3] * rs1;
;                         sq += o0 * o0 + o1 * o1;
;                         const unsigned hi = cvt_pk_bf16(o0, o1);
;                         hw[pq] = hi;
.LBB0_994:
	v_lshl_add_u32 v156, s12, 8, v194
	v_lshl_or_b32 v154, s58, 8, v196
	v_ashrrev_i32_e32 v157, 31, v156
	v_ashrrev_i32_e32 v155, 31, v154
	v_lshlrev_b64 v[2:3], 11, v[156:157]
	v_lshl_add_u64 v[132:133], v[2:3], 0, v[154:155]
	v_lshl_add_u64 v[202:203], s[44:45], 0, v[132:133]
	v_lshl_add_u64 v[180:181], v[132:133], 1, s[42:43]
	global_load_dwordx2 v[204:205], v[202:203], off
	global_load_dwordx4 v[184:187], v[180:181], off
	v_or_b32_e32 v162, 16, v156
	s_add_i32 s18, s18, s65
	v_ashrrev_i32_e32 v163, 31, v162
	v_lshl_add_u32 v0, v193, 2, s18
	v_lshlrev_b64 v[134:135], 11, v[162:163]
	v_or_b32_e32 v132, 0x80, v132
	v_add_u32_e32 v0, 0xc00, v0
	v_lshl_add_u64 v[134:135], v[134:135], 0, v[154:155]
	v_lshl_add_u64 v[188:189], v[132:133], 1, s[42:43]
	ds_read2_b32 v[176:177], v0 offset1:16
	ds_read2_b32 v[160:161], v0 offset0:32 offset1:48
	ds_read2_b32 v[158:159], v0 offset0:128 offset1:144
	ds_read2_b32 v[2:3], v0 offset0:160 offset1:176
	v_lshl_add_u64 v[190:191], s[44:45], 0, v[132:133]
	v_lshl_add_u64 v[170:171], v[134:135], 1, s[42:43]
	v_lshl_add_u64 v[172:173], s[44:45], 0, v[134:135]
	global_load_dwordx4 v[198:201], v[188:189], off
	global_load_dwordx2 v[210:211], v[190:191], off
	global_load_dwordx4 v[136:139], v[170:171], off
	global_load_dwordx2 v[174:175], v[172:173], off
	s_waitcnt lgkmcnt(0)
	v_mov_b32_e32 v178, v176
	v_mov_b32_e32 v206, v128
	v_mov_b32_e32 v128, v130
	v_mov_b32_e32 v130, v124
	v_or_b32_e32 v134, 0x80, v134
	v_lshl_add_u64 v[164:165], v[134:135], 1, s[42:43]
	v_lshl_add_u64 v[166:167], s[44:45], 0, v[134:135]
	global_load_dwordx4 v[132:135], v[164:165], off
	global_load_dwordx2 v[168:169], v[166:167], off
	v_mov_b32_e32 v208, v1
	s_waitcnt vmcnt(0)
	v_cvt_pk_f32_fp8_e32 v[212:213], v204
	v_lshlrev_b32_e32 v0, 16, v184
	v_and_b32_e32 v176, 0xffff0000, v184
	v_cvt_pk_f32_fp8_sdwa v[214:215], v204 src0_sel:WORD_1
	v_lshlrev_b32_e32 v182, 16, v185
	v_and_b32_e32 v204, 0xffff0000, v185
	v_cvt_pk_f32_fp8_e32 v[184:185], v205
	v_mov_b32_e32 v207, v212
	v_mov_b32_e32 v212, v129
	v_mov_b32_e32 v129, v214
	v_mov_b32_e32 v214, v131
	v_mov_b32_e32 v131, v184
	v_mov_b32_e32 v184, v125
	v_pk_mul_f32 v[124:125], v[206:207], v[178:179]
	v_pk_mul_f32 v[206:207], v[212:213], v[178:179]
	v_lshlrev_b32_e32 v209, 16, v186
	v_and_b32_e32 v186, 0xffff0000, v186
	v_pk_mul_f32 v[128:129], v[128:129], v[178:179]
	v_pk_mul_f32 v[184:185], v[184:185], v[178:179]
	v_add_f32_e32 v0, v125, v0
	v_add_f32_e32 v125, v207, v176
	v_pk_mul_f32 v[212:213], v[214:215], v[178:179]
	v_add_f32_e32 v129, v129, v182
	v_add_f32_e32 v182, v185, v186
	v_add_f32_e32 v0, v124, v0
	v_add_f32_e32 v124, v206, v125
	v_add_f32_e32 v176, v213, v204
	v_add_f32_e32 v125, v128, v129
	v_add_f32_e32 v182, v184, v182
	v_mul_f32_e32 v184, v124, v124
	v_cvt_pk_bf16_f32 v128, v0, v124
	v_fmac_f32_e32 v184, v0, v0
	v_and_b32_e32 v204, 0xffff0000, v128
	v_lshlrev_b32_e32 v206, 16, v128
	v_sub_f32_e32 v124, v124, v204
	v_sub_f32_e32 v0, v0, v206
	v_mul_f32_e32 v124, 0x43800000, v124
	v_mul_f32_e32 v0, 0x43800000, v0
	v_pk_mul_f32 v[130:131], v[130:131], v[178:179]
	v_add_f32_e32 v176, v212, v176
	v_med3_f32 v124, v124, s68, v235
	v_med3_f32 v0, v0, s68, v235
	v_add_f32_e32 v131, v131, v209
	v_mul_f32_e32 v185, v176, v176
	v_cvt_pk_bf16_f32 v129, v125, v176
	v_cvt_pk_fp8_f32 v208, v0, v124
	v_lshlrev_b32_e32 v207, 16, v129
	v_and_b32_e32 v209, 0xffff0000, v129
	v_fmac_f32_e32 v185, v125, v125
	v_sub_f32_e32 v125, v125, v207
	v_sub_f32_e32 v176, v176, v209
	v_mul_f32_e32 v125, 0x43800000, v125
	v_mul_f32_e32 v176, 0x43800000, v176
	v_med3_f32 v124, v125, s68, v235
	v_med3_f32 v125, v176, s68, v235
	v_add_f32_e32 v131, v130, v131
	v_cvt_pk_bf16_f32 v130, v131, v182
	v_cvt_pk_fp8_f32 v208, v124, v125 op_sel:[0,0,1]
	v_and_b32_e32 v212, 0xffff0000, v130
	v_lshlrev_b32_e32 v125, 16, v130
	v_sub_f32_e32 v124, v182, v212
	v_sub_f32_e32 v125, v131, v125
	v_mul_f32_e32 v124, 0x43800000, v124
	v_mul_f32_e32 v125, 0x43800000, v125
	v_med3_f32 v124, v124, s68, v235
	v_med3_f32 v125, v125, s68, v235
	v_mov_b32_e32 v209, v1
	v_cvt_pk_fp8_f32 v209, v125, v124
	v_cvt_pk_f32_fp8_sdwa v[124:125], v205 src0_sel:WORD_1
	v_mul_f32_e32 v186, v182, v182
	v_fmac_f32_e32 v186, v131, v131
	v_add_f32_e32 v184, v184, v185
	v_add_f32_e32 v0, v184, v186
	v_mov_b32_e32 v184, v126
	v_mov_b32_e32 v185, v124
	v_lshlrev_b32_e32 v131, 16, v187
	v_pk_mul_f32 v[184:185], v[184:185], v[178:179]
	v_and_b32_e32 v176, 0xffff0000, v187
	v_add_f32_e32 v124, v185, v131
	v_add_f32_e32 v126, v184, v124
	v_mov_b32_e32 v124, v127
	v_pk_mul_f32 v[124:125], v[124:125], v[178:179]
	s_nop 0
	v_add_f32_e32 v125, v125, v176
	v_add_f32_e32 v124, v124, v125
	v_cvt_pk_bf16_f32 v131, v126, v124
	v_mul_f32_e32 v125, v124, v124
	v_lshlrev_b32_e32 v127, 16, v131
	v_and_b32_e32 v176, 0xffff0000, v131
	v_sub_f32_e32 v127, v126, v127
	v_sub_f32_e32 v124, v124, v176
	v_mul_f32_e32 v127, 0x43800000, v127
	v_mul_f32_e32 v124, 0x43800000, v124
	v_med3_f32 v127, v127, s68, v235
	v_med3_f32 v124, v124, s68, v235
	v_fmac_f32_e32 v125, v126, v126
	v_cvt_pk_fp8_f32 v209, v127, v124 op_sel:[0,0,1]
	v_add_f32_e32 v0, v0, v125
	v_cvt_pk_f32_fp8_e32 v[124:125], v210
	v_mov_b32_e32 v126, v120
	global_store_dwordx4 v[180:181], v[128:131], off sc1
	global_store_dwordx2 v[202:203], v[208:209], off
	v_mov_b32_e32 v127, v124
	v_lshlrev_b32_e32 v128, 16, v198
	v_pk_mul_f32 v[126:127], v[126:127], v[178:179]
	v_mov_b32_e32 v124, v121
	v_add_f32_e32 v120, v127, v128
	v_and_b32_e32 v129, 0xffff0000, v198
	v_add_f32_e32 v126, v126, v120
	v_pk_mul_f32 v[120:121], v[124:125], v[178:179]
	v_mov_b32_e32 v128, v122
	v_add_f32_e32 v121, v121, v129
; __device__ __forceinline__ unsigned cvt_pk_bf16(float lo, float hi) { unsigned r; asm volatile("v_cvt_pk_bf16_f32 %0, %1, %2" : "=v"(r) : "v"(lo), "v"(hi)); return r; }
;     __device__ __forceinline__ void core(const f32x4 (&acc)[2][2][4][2], const Unit& u, int wr, int wc, int fr, int fq, const float (&rsc)[2][4]) const {
;     ...
;                 for (int bj = 0; bj < 2; ++bj) { const size_t idx = (size_t)row * D + col0 + bj * HALF;
;                     unsigned hw[4]; int lw[2] = {0, 0};
; #pragma unroll
;                     for (int pq = 0; pq < 4; ++pq) {
;                         float h0, h1;
;                         if (F32IN) { h0 = (pq < 2) ? xa[m][bj][2 * pq] : xb[m][bj][2 * pq - 4]; h1 = (pq < 2) ? xa[m][bj][2 * pq + 1] : xb[m][bj][2 * pq - 3]; }
;                         else { const unsigned a = va[m][bj][pq]; const int bw = (int)vb[m][bj][pq >> 1]; const hf32x2 lp = (pq & 1) ? __builtin_amdgcn_cvt_pk_f32_fp8(bw, true) : __builtin_amdgcn_cvt_pk_f32_fp8(bw, false);
;                             h0 = __uint_as_float(a << 16) + lp.x * 0.00390625f; h1 = __uint_as_float(a & 0xffff0000u) + lp.y * 0.00390625f; }
;                         const float o0 = h0 + acc[ai][bj][mh + m][pq >> 1][(2 * pq) & 3] * rs1, o1 = h1 + acc[ai][bj][mh + m][pq >> 1][(2 * pq + 1) & 3] * rs1;
;                         sq += o0 * o0 + o1 * o1;
;                         const unsigned hi = cvt_pk_bf16(o0, o1);
;                         hw[pq] = hi;
;                         const float r0 = __builtin_amdgcn_fmed3f((o0 - __uint_as_float(hi << 16)) * 256.0f, -448.0f, 448.0f), r1 = __builtin_amdgcn_fmed3f((o1 - __uint_as_float(hi & 0xffff0000u)) * 256.0f, -448.0f, 448.0f);
;                         lw[pq >> 1] = (pq & 1) ? __builtin_amdgcn_cvt_pk_fp8_f32(r0, r1, lw[pq >> 1], true) : __builtin_amdgcn_cvt_pk_fp8_f32(r0, r1, lw[pq >> 1], false);
;                     }
;                     *(u32x4*)(Hb + idx) = (u32x4){hw[0], hw[1], hw[2], hw[3]}; *(u32x2*)(Hl + idx) = (u32x2){(unsigned)lw[0], (unsigned)lw[1]}; }
;                 sq += __shfl_xor(sq, 16); sq += __shfl_xor(sq, 32); if (fq == 0) ss[(size_t)row * 32 + u.pn * 4 + wc] = sq; }
	v_add_f32_e32 v121, v120, v121
	v_mul_f32_e32 v120, v121, v121
	v_fmac_f32_e32 v120, v126, v126
	v_add_f32_e32 v0, v0, v120
	v_cvt_pk_bf16_f32 v120, v126, v121
	s_nop 0
	v_and_b32_e32 v124, 0xffff0000, v120
	v_sub_f32_e32 v121, v121, v124
	v_lshlrev_b32_e32 v124, 16, v120
	v_sub_f32_e32 v124, v126, v124
	v_cvt_pk_f32_fp8_sdwa v[126:127], v210 src0_sel:WORD_1
	v_mul_f32_e32 v121, 0x43800000, v121
	v_mul_f32_e32 v124, 0x43800000, v124
	v_med3_f32 v121, v121, s68, v235
	v_med3_f32 v125, v124, s68, v235
	v_mov_b32_e32 v124, v1
	v_mov_b32_e32 v129, v126
	v_cvt_pk_fp8_f32 v124, v125, v121
	v_lshlrev_b32_e32 v121, 16, v199
	v_pk_mul_f32 v[128:129], v[128:129], v[178:179]
	v_mov_b32_e32 v126, v123
	v_and_b32_e32 v125, 0xffff0000, v199
	v_add_f32_e32 v121, v129, v121
	v_pk_mul_f32 v[122:123], v[126:127], v[178:179]
	v_add_f32_e32 v128, v128, v121
	v_add_f32_e32 v121, v123, v125
	v_add_f32_e32 v122, v122, v121
	v_mul_f32_e32 v121, v122, v122
	v_fmac_f32_e32 v121, v128, v128
	v_add_f32_e32 v0, v0, v121
	v_cvt_pk_bf16_f32 v121, v128, v122
	v_mov_b32_e32 v126, v116
	v_lshlrev_b32_e32 v123, 16, v121
	v_and_b32_e32 v125, 0xffff0000, v121
	v_sub_f32_e32 v123, v128, v123
	v_sub_f32_e32 v122, v122, v125
	v_mul_f32_e32 v123, 0x43800000, v123
	v_mul_f32_e32 v122, 0x43800000, v122
	v_med3_f32 v123, v123, s68, v235
	v_med3_f32 v122, v122, s68, v235
	v_cvt_pk_fp8_f32 v124, v123, v122 op_sel:[0,0,1]
	v_cvt_pk_f32_fp8_e32 v[122:123], v211
	v_lshlrev_b32_e32 v125, 16, v200
	v_and_b32_e32 v128, 0xffff0000, v200
	v_mov_b32_e32 v127, v122
	v_pk_mul_f32 v[126:127], v[126:127], v[178:179]
	v_mov_b32_e32 v122, v117
	v_add_f32_e32 v116, v127, v125
	v_add_f32_e32 v125, v126, v116
	v_pk_mul_f32 v[116:117], v[122:123], v[178:179]
	v_mov_b32_e32 v126, v118
	v_add_f32_e32 v117, v117, v128
	v_add_f32_e32 v116, v116, v117
	v_mul_f32_e32 v117, v116, v116
	v_fmac_f32_e32 v117, v125, v125
	v_add_f32_e32 v0, v0, v117
	v_cvt_pk_bf16_f32 v122, v125, v116
	v_lshlrev_b32_e32 v123, 16, v201
	v_and_b32_e32 v117, 0xffff0000, v122
	v_sub_f32_e32 v116, v116, v117
	v_lshlrev_b32_e32 v117, 16, v122
	v_sub_f32_e32 v117, v125, v117
	v_mul_f32_e32 v116, 0x43800000, v116
	v_mul_f32_e32 v117, 0x43800000, v117
	v_med3_f32 v116, v116, s68, v235
	v_med3_f32 v117, v117, s68, v235
	v_mov_b32_e32 v125, v1
	v_cvt_pk_fp8_f32 v125, v117, v116
	v_cvt_pk_f32_fp8_sdwa v[116:117], v211 src0_sel:WORD_1
	v_and_b32_e32 v128, 0xffff0000, v201
	v_mov_b32_e32 v127, v116
	v_pk_mul_f32 v[126:127], v[126:127], v[178:179]
	s_nop 0
	v_add_f32_e32 v116, v127, v123
	v_add_f32_e32 v118, v126, v116
	v_mov_b32_e32 v116, v119
	v_pk_mul_f32 v[116:117], v[116:117], v[178:179]
	v_and_b32_e32 v126, 64, v226
	v_add_f32_e32 v117, v117, v128
	v_add_f32_e32 v116, v116, v117
	v_mul_f32_e32 v117, v116, v116
	v_fmac_f32_e32 v117, v118, v118
	v_add_f32_e32 v117, v0, v117
	v_cvt_pk_bf16_f32 v123, v118, v116
	v_add_u32_e32 v126, 64, v126
	v_lshlrev_b32_e32 v0, 16, v123
	v_sub_f32_e32 v0, v118, v0
	v_mul_f32_e32 v0, 0x43800000, v0
	v_med3_f32 v118, v0, s68, v235
	v_xor_b32_e32 v0, 16, v226
	v_cmp_lt_i32_e32 vcc, v0, v126
	v_and_b32_e32 v119, 0xffff0000, v123
	v_sub_f32_e32 v116, v116, v119
	v_cndmask_b32_e32 v0, v226, v0, vcc
	v_lshlrev_b32_e32 v0, 2, v0
	ds_bpermute_b32 v127, v0, v117
	v_mul_f32_e32 v116, 0x43800000, v116
	v_med3_f32 v116, v116, s68, v235
	v_cvt_pk_fp8_f32 v125, v118, v116 op_sel:[0,0,1]
	global_store_dwordx4 v[188:189], v[120:123], off sc1
	global_store_dwordx2 v[190:191], v[124:125], off
	s_waitcnt lgkmcnt(0)
	v_add_f32_e32 v116, v117, v127
	v_xor_b32_e32 v117, 32, v226
	v_cmp_lt_i32_e32 vcc, v117, v126
	s_nop 1
	v_cndmask_b32_e32 v117, v226, v117, vcc
	v_lshlrev_b32_e32 v176, 2, v117
	ds_bpermute_b32 v117, v176, v116
	s_and_saveexec_b64 s[2:3], s[38:39]
	v_readlane_b32 s74, v255, 12
	v_readlane_b32 s76, v255, 14
	v_readlane_b32 s72, v255, 11
	v_readlane_b32 s75, v255, 13
	v_readlane_b32 s77, v255, 15
	v_readlane_b32 s73, v255, 16
	s_cbranch_execz .LBB0_996
	s_waitcnt lgkmcnt(0)
	v_add_f32_e32 v118, v116, v117
	s_lshl_b32 s20, s58, 2
	v_lshlrev_b64 v[116:117], 7, v[156:157]
	s_ashr_i32 s21, s20, 31
	v_lshl_add_u64 v[116:117], s[46:47], 0, v[116:117]
	v_lshl_add_u64 v[116:117], s[20:21], 2, v[116:117]
	s_lshl_b32 s18, s37, 2
	v_lshl_add_u64 v[116:117], v[116:117], 0, s[18:19]
	global_store_dword v[116:117], v118, off
; __device__ __forceinline__ unsigned cvt_pk_bf16(float lo, float hi) { unsigned r; asm volatile("v_cvt_pk_bf16_f32 %0, %1, %2" : "=v"(r) : "v"(lo), "v"(hi)); return r; }
;     __device__ __forceinline__ void core(const f32x4 (&acc)[2][2][4][2], const Unit& u, int wr, int wc, int fr, int fq, const float (&rsc)[2][4]) const {
;     ...
;                 for (int bj = 0; bj < 2; ++bj) { const size_t idx = (size_t)row * D + col0 + bj * HALF;
;                     unsigned hw[4]; int lw[2] = {0, 0};
; #pragma unroll
;                     for (int pq = 0; pq < 4; ++pq) {
;                         float h0, h1;
;                         if (F32IN) { h0 = (pq < 2) ? xa[m][bj][2 * pq] : xb[m][bj][2 * pq - 4]; h1 = (pq < 2) ? xa[m][bj][2 * pq + 1] : xb[m][bj][2 * pq - 3]; }
;                         else { const unsigned a = va[m][bj][pq]; const int bw = (int)vb[m][bj][pq >> 1]; const hf32x2 lp = (pq & 1) ? __builtin_amdgcn_cvt_pk_f32_fp8(bw, true) : __builtin_amdgcn_cvt_pk_f32_fp8(bw, false);
;                             h0 = __uint_as_float(a << 16) + lp.x * 0.00390625f; h1 = __uint_as_float(a & 0xffff0000u) + lp.y * 0.00390625f; }
;                         const float o0 = h0 + acc[ai][bj][mh + m][pq >> 1][(2 * pq) & 3] * rs1, o1 = h1 + acc[ai][bj][mh + m][pq >> 1][(2 * pq + 1) & 3] * rs1;
;                         sq += o0 * o0 + o1 * o1;
;                         const unsigned hi = cvt_pk_bf16(o0, o1);
;                         hw[pq] = hi;
;                         const float r0 = __builtin_amdgcn_fmed3f((o0 - __uint_as_float(hi << 16)) * 256.0f, -448.0f, 448.0f), r1 = __builtin_amdgcn_fmed3f((o1 - __uint_as_float(hi & 0xffff0000u)) * 256.0f, -448.0f, 448.0f);
;                         lw[pq >> 1] = (pq & 1) ? __builtin_amdgcn_cvt_pk_fp8_f32(r0, r1, lw[pq >> 1], true) : __builtin_amdgcn_cvt_pk_fp8_f32(r0, r1, lw[pq >> 1], false);
;                     }
;                     *(u32x4*)(Hb + idx) = (u32x4){hw[0], hw[1], hw[2], hw[3]}; *(u32x2*)(Hl + idx) = (u32x2){(unsigned)lw[0], (unsigned)lw[1]}; }
;                 sq += __shfl_xor(sq, 16); sq += __shfl_xor(sq, 32); if (fq == 0) ss[(size_t)row * 32 + u.pn * 4 + wc] = sq; }
.LBB0_996:
	s_or_b64 exec, exec, s[2:3]
	s_waitcnt lgkmcnt(0)
	v_cvt_pk_f32_fp8_e32 v[116:117], v174
	v_mov_b32_e32 v118, v112
	v_mov_b32_e32 v178, v177
	v_lshlrev_b32_e32 v120, 16, v136
	v_mov_b32_e32 v119, v116
	v_pk_mul_f32 v[118:119], v[118:119], v[178:179]
	v_mov_b32_e32 v116, v113
	v_add_f32_e32 v112, v119, v120
	v_and_b32_e32 v121, 0xffff0000, v136
	v_add_f32_e32 v118, v118, v112
	v_pk_mul_f32 v[112:113], v[116:117], v[178:179]
	v_mov_b32_e32 v120, v114
	v_add_f32_e32 v113, v113, v121
	v_add_f32_e32 v113, v112, v113
	v_cvt_pk_bf16_f32 v112, v118, v113
	v_mul_f32_e32 v117, v113, v113
	v_and_b32_e32 v116, 0xffff0000, v112
	v_sub_f32_e32 v113, v113, v116
	v_lshlrev_b32_e32 v116, 16, v112
	v_sub_f32_e32 v116, v118, v116
	v_mul_f32_e32 v113, 0x43800000, v113
	v_mul_f32_e32 v116, 0x43800000, v116
	v_fmac_f32_e32 v117, v118, v118
	v_med3_f32 v113, v113, s68, v235
	v_med3_f32 v118, v116, s68, v235
	v_mov_b32_e32 v116, v1
	v_cvt_pk_fp8_f32 v116, v118, v113
	v_cvt_pk_f32_fp8_sdwa v[118:119], v174 src0_sel:WORD_1
	v_lshlrev_b32_e32 v113, 16, v137
	v_and_b32_e32 v122, 0xffff0000, v137
	v_mov_b32_e32 v121, v118
	v_pk_mul_f32 v[120:121], v[120:121], v[178:179]
	v_mov_b32_e32 v118, v115
	v_add_f32_e32 v113, v121, v113
	v_pk_mul_f32 v[114:115], v[118:119], v[178:179]
	v_add_f32_e32 v120, v120, v113
	v_add_f32_e32 v113, v115, v122
	v_add_f32_e32 v114, v114, v113
	v_mul_f32_e32 v113, v114, v114
	v_fmac_f32_e32 v113, v120, v120
	v_add_f32_e32 v117, v117, v113
	v_cvt_pk_bf16_f32 v113, v120, v114
	v_and_b32_e32 v121, 0xffff0000, v138
	v_lshlrev_b32_e32 v115, 16, v113
	v_and_b32_e32 v118, 0xffff0000, v113
	v_sub_f32_e32 v115, v120, v115
	v_sub_f32_e32 v114, v114, v118
	v_mul_f32_e32 v115, 0x43800000, v115
	v_mul_f32_e32 v114, 0x43800000, v114
	v_med3_f32 v115, v115, s68, v235
	v_med3_f32 v114, v114, s68, v235
	v_cvt_pk_fp8_f32 v116, v115, v114 op_sel:[0,0,1]
	v_cvt_pk_f32_fp8_e32 v[114:115], v175
	v_mov_b32_e32 v118, v108
	v_lshlrev_b32_e32 v120, 16, v138
	v_mov_b32_e32 v119, v114
	v_pk_mul_f32 v[118:119], v[118:119], v[178:179]
	v_mov_b32_e32 v114, v109
	v_add_f32_e32 v108, v119, v120
	v_add_f32_e32 v118, v118, v108
	v_pk_mul_f32 v[108:109], v[114:115], v[178:179]
	v_lshlrev_b32_e32 v115, 16, v139
	v_add_f32_e32 v109, v109, v121
	v_add_f32_e32 v108, v108, v109
	v_mul_f32_e32 v109, v108, v108
	v_fmac_f32_e32 v109, v118, v118
	v_add_f32_e32 v120, v117, v109
	v_cvt_pk_bf16_f32 v114, v118, v108
	v_mov_b32_e32 v117, v1
	v_and_b32_e32 v109, 0xffff0000, v114
	v_sub_f32_e32 v108, v108, v109
	v_lshlrev_b32_e32 v109, 16, v114
	v_sub_f32_e32 v109, v118, v109
	v_mul_f32_e32 v108, 0x43800000, v108
	v_mul_f32_e32 v109, 0x43800000, v109
	v_med3_f32 v108, v108, s68, v235
	v_med3_f32 v109, v109, s68, v235
	v_cvt_pk_fp8_f32 v117, v109, v108
	v_cvt_pk_f32_fp8_sdwa v[108:109], v175 src0_sel:WORD_1
	v_mov_b32_e32 v118, v110
	v_and_b32_e32 v121, 0xffff0000, v139
	v_mov_b32_e32 v119, v108
	v_pk_mul_f32 v[118:119], v[118:119], v[178:179]
	s_nop 0
	v_add_f32_e32 v108, v119, v115
	v_add_f32_e32 v110, v118, v108
	v_mov_b32_e32 v108, v111
	v_pk_mul_f32 v[108:109], v[108:109], v[178:179]
	s_nop 0
	v_add_f32_e32 v109, v109, v121
	v_add_f32_e32 v108, v108, v109
	v_cvt_pk_bf16_f32 v115, v110, v108
	v_mul_f32_e32 v109, v108, v108
	v_lshlrev_b32_e32 v111, 16, v115
	v_and_b32_e32 v118, 0xffff0000, v115
	v_sub_f32_e32 v111, v110, v111
	v_sub_f32_e32 v108, v108, v118
	v_mul_f32_e32 v111, 0x43800000, v111
	v_mul_f32_e32 v108, 0x43800000, v108
	v_med3_f32 v111, v111, s68, v235
	v_med3_f32 v108, v108, s68, v235
	v_fmac_f32_e32 v109, v110, v110
	v_cvt_pk_fp8_f32 v117, v111, v108 op_sel:[0,0,1]
	v_add_f32_e32 v118, v120, v109
	v_cvt_pk_f32_fp8_e32 v[108:109], v168
	v_mov_b32_e32 v110, v104
	global_store_dwordx4 v[170:171], v[112:115], off sc1
	global_store_dwordx2 v[172:173], v[116:117], off
	v_mov_b32_e32 v111, v108
	v_lshlrev_b32_e32 v112, 16, v132
	v_pk_mul_f32 v[110:111], v[110:111], v[178:179]
	v_mov_b32_e32 v108, v105
	v_add_f32_e32 v104, v111, v112
	v_and_b32_e32 v113, 0xffff0000, v132
	v_add_f32_e32 v110, v110, v104
	v_pk_mul_f32 v[104:105], v[108:109], v[178:179]
	v_mov_b32_e32 v112, v106
	v_add_f32_e32 v105, v105, v113
	v_add_f32_e32 v105, v104, v105
	v_mul_f32_e32 v104, v105, v105
	v_fmac_f32_e32 v104, v110, v110
	v_add_f32_e32 v109, v118, v104
	v_cvt_pk_bf16_f32 v104, v110, v105
	v_and_b32_e32 v114, 0xffff0000, v133
	v_and_b32_e32 v108, 0xffff0000, v104
	v_sub_f32_e32 v105, v105, v108
	v_lshlrev_b32_e32 v108, 16, v104
	v_sub_f32_e32 v108, v110, v108
	v_mul_f32_e32 v105, 0x43800000, v105
	v_mul_f32_e32 v108, 0x43800000, v108
	v_med3_f32 v105, v105, s68, v235
	v_med3_f32 v110, v108, s68, v235
	v_mov_b32_e32 v108, v1
	v_cvt_pk_fp8_f32 v108, v110, v105
	v_cvt_pk_f32_fp8_sdwa v[110:111], v168 src0_sel:WORD_1
	v_lshlrev_b32_e32 v105, 16, v133
	v_mov_b32_e32 v113, v110
	v_pk_mul_f32 v[112:113], v[112:113], v[178:179]
	v_mov_b32_e32 v110, v107
	v_add_f32_e32 v105, v113, v105
	v_pk_mul_f32 v[106:107], v[110:111], v[178:179]
	v_add_f32_e32 v112, v112, v105
	v_add_f32_e32 v105, v107, v114
	v_add_f32_e32 v106, v106, v105
	v_mul_f32_e32 v105, v106, v106
	v_fmac_f32_e32 v105, v112, v112
	v_add_f32_e32 v109, v109, v105
	v_cvt_pk_bf16_f32 v105, v112, v106
	v_and_b32_e32 v113, 0xffff0000, v134
	v_lshlrev_b32_e32 v107, 16, v105
	v_and_b32_e32 v110, 0xffff0000, v105
	v_sub_f32_e32 v107, v112, v107
	v_sub_f32_e32 v106, v106, v110
	v_mul_f32_e32 v107, 0x43800000, v107
	v_mul_f32_e32 v106, 0x43800000, v106
	v_med3_f32 v107, v107, s68, v235
	v_med3_f32 v106, v106, s68, v235
	v_cvt_pk_fp8_f32 v108, v107, v106 op_sel:[0,0,1]
	v_cvt_pk_f32_fp8_e32 v[106:107], v169
	v_mov_b32_e32 v110, v100
;     __device__ __forceinline__ void core(const f32x4 (&acc)[2][2][4][2], const Unit& u, int wr, int wc, int fr, int fq, const float (&rsc)[2][4]) const {
;     ...
;         for (int ai = 0; ai < 2; ++ai)
; #pragma unroll
;         for (int mh = 0; mh < 4; mh += MB) {
;             u32x4 va[MB][2]; u32x2 vb[MB][2];
;             f32x4 xa[MB][2], xb[MB][2];
; #pragma unroll
;             for (int m = 0; m < MB; ++m)
; #pragma unroll
;                 for (int bj = 0; bj < 2; ++bj) { const size_t idx = (size_t)(row0 + ai * HALF + (mh + m) * 16) * D + col0 + bj * HALF;
;                     if (F32IN) { xa[m][bj] = *(const f32x4*)(Xin + idx); xb[m][bj] = *(const f32x4*)(Xin + idx + 4); }
;                     else { va[m][bj] = *(const u32x4*)(Hb + idx); vb[m][bj] = *(const u32x2*)(Hl + idx); } }
; #pragma unroll
;             for (int m = 0; m < MB; ++m) { const int row = row0 + ai * HALF + (mh + m) * 16; float sq = 0.f;
;                 const float rs1 = rsc[ai][mh + m];
; #pragma unroll
;                 for (int bj = 0; bj < 2; ++bj) { const size_t idx = (size_t)row * D + col0 + bj * HALF;
;                     unsigned hw[4]; int lw[2] = {0, 0};
; #pragma unroll
;                     for (int pq = 0; pq < 4; ++pq) {
;                         float h0, h1;
;                         if (F32IN) { h0 = (pq < 2) ? xa[m][bj][2 * pq] : xb[m][bj][2 * pq - 4]; h1 = (pq < 2) ? xa[m][bj][2 * pq + 1] : xb[m][bj][2 * pq - 3]; }
;                         else { const unsigned a = va[m][bj][pq]; const int bw = (int)vb[m][bj][pq >> 1]; const hf32x2 lp = (pq & 1) ? __builtin_amdgcn_cvt_pk_f32_fp8(bw, true) : __builtin_amdgcn_cvt_pk_f32_fp8(bw, false);
;                             h0 = __uint_as_float(a << 16) + lp.x * 0.00390625f; h1 = __uint_as_float(a & 0xffff0000u) + lp.y * 0.00390625f; }
;                         const float o0 = h0 + acc[ai][bj][mh + m][pq >> 1][(2 * pq) & 3] * rs1, o1 = h1 + acc[ai][bj][mh + m][pq >> 1][(2 * pq + 1) & 3] * rs1;
;                         sq += o0 * o0 + o1 * o1;
;                         const unsigned hi = cvt_pk_bf16(o0, o1);
;                         hw[pq] = hi;
;                         const float r0 = __builtin_amdgcn_fmed3f((o0 - __uint_as_float(hi << 16)) * 256.0f, -448.0f, 448.0f), r1 = __builtin_amdgcn_fmed3f((o1 - __uint_as_float(hi & 0xffff0000u)) * 256.0f, -448.0f, 448.0f);
	v_lshlrev_b32_e32 v112, 16, v134
	v_mov_b32_e32 v111, v106
	v_pk_mul_f32 v[110:111], v[110:111], v[178:179]
	v_mov_b32_e32 v106, v101
	v_add_f32_e32 v100, v111, v112
	v_add_f32_e32 v110, v110, v100
	v_pk_mul_f32 v[100:101], v[106:107], v[178:179]
	v_lshlrev_b32_e32 v112, 16, v135
	v_add_f32_e32 v101, v101, v113
	v_add_f32_e32 v100, v100, v101
	v_mul_f32_e32 v101, v100, v100
	v_fmac_f32_e32 v101, v110, v110
	v_add_f32_e32 v107, v109, v101
	v_cvt_pk_bf16_f32 v106, v110, v100
	v_mov_b32_e32 v109, v1
	v_and_b32_e32 v101, 0xffff0000, v106
	v_sub_f32_e32 v100, v100, v101
	v_lshlrev_b32_e32 v101, 16, v106
	v_sub_f32_e32 v101, v110, v101
	v_mul_f32_e32 v100, 0x43800000, v100
	v_mul_f32_e32 v101, 0x43800000, v101
	v_med3_f32 v100, v100, s68, v235
	v_med3_f32 v101, v101, s68, v235
	v_cvt_pk_fp8_f32 v109, v101, v100
	v_cvt_pk_f32_fp8_sdwa v[100:101], v169 src0_sel:WORD_1
	v_mov_b32_e32 v110, v102
	v_and_b32_e32 v113, 0xffff0000, v135
	v_mov_b32_e32 v111, v100
	v_pk_mul_f32 v[110:111], v[110:111], v[178:179]
	s_nop 0
	v_add_f32_e32 v100, v111, v112
	v_add_f32_e32 v102, v110, v100
	v_mov_b32_e32 v100, v103
	v_pk_mul_f32 v[100:101], v[100:101], v[178:179]
	s_nop 0
	v_add_f32_e32 v101, v101, v113
	v_add_f32_e32 v100, v100, v101
	v_mul_f32_e32 v101, v100, v100
	v_fmac_f32_e32 v101, v102, v102
	v_add_f32_e32 v101, v107, v101
	v_cvt_pk_bf16_f32 v107, v102, v100
	ds_bpermute_b32 v110, v0, v101
	v_lshlrev_b32_e32 v103, 16, v107
	v_sub_f32_e32 v102, v102, v103
	v_and_b32_e32 v103, 0xffff0000, v107
	v_sub_f32_e32 v100, v100, v103
	v_mul_f32_e32 v102, 0x43800000, v102
	v_mul_f32_e32 v100, 0x43800000, v100
	v_med3_f32 v102, v102, s68, v235
	v_med3_f32 v100, v100, s68, v235
	v_cvt_pk_fp8_f32 v109, v102, v100 op_sel:[0,0,1]
	s_waitcnt lgkmcnt(0)
	v_add_f32_e32 v100, v101, v110
	ds_bpermute_b32 v101, v176, v100
	global_store_dwordx4 v[164:165], v[104:107], off sc1
	global_store_dwordx2 v[166:167], v[108:109], off
	s_and_saveexec_b64 s[2:3], s[38:39]
	s_cbranch_execz .LBB0_998
	s_waitcnt lgkmcnt(0)
	v_add_f32_e32 v102, v100, v101
	s_lshl_b32 s20, s58, 2
	v_lshlrev_b64 v[100:101], 7, v[162:163]
	s_ashr_i32 s21, s20, 31
	v_lshl_add_u64 v[100:101], s[46:47], 0, v[100:101]
	v_lshl_add_u64 v[100:101], s[20:21], 2, v[100:101]
	s_lshl_b32 s18, s37, 2
	v_lshl_add_u64 v[100:101], v[100:101], 0, s[18:19]
	global_store_dword v[100:101], v102, off
.LBB0_998:
	s_or_b64 exec, exec, s[2:3]
	v_or_b32_e32 v130, 32, v156
	v_ashrrev_i32_e32 v131, 31, v130
	s_waitcnt lgkmcnt(0)
	v_lshlrev_b64 v[100:101], 11, v[130:131]
	v_lshl_add_u64 v[100:101], v[100:101], 0, v[154:155]
	v_lshl_add_u64 v[138:139], v[100:101], 1, s[42:43]
	v_lshl_add_u64 v[162:163], s[44:45], 0, v[100:101]
	global_load_dwordx4 v[112:115], v[138:139], off
	global_load_dwordx2 v[164:165], v[162:163], off
	v_or_b32_e32 v100, 0x80, v100
	v_lshl_add_u64 v[132:133], v[100:101], 1, s[42:43]
	v_lshl_add_u64 v[134:135], s[44:45], 0, v[100:101]
	global_load_dwordx4 v[108:111], v[132:133], off
	global_load_dwordx2 v[136:137], v[134:135], off
	v_or_b32_e32 v116, 48, v156
	v_ashrrev_i32_e32 v117, 31, v116
	v_mov_b32_e32 v168, v96
	v_mov_b32_e32 v178, v160
	v_lshlrev_b64 v[100:101], 11, v[116:117]
	v_lshl_add_u64 v[120:121], v[100:101], 0, v[154:155]
	v_lshl_add_u64 v[124:125], v[120:121], 1, s[42:43]
	v_lshl_add_u64 v[126:127], s[44:45], 0, v[120:121]
	v_or_b32_e32 v120, 0x80, v120
	v_lshl_add_u64 v[118:119], v[120:121], 1, s[42:43]
	v_lshl_add_u64 v[120:121], s[44:45], 0, v[120:121]
	global_load_dwordx4 v[104:107], v[124:125], off
	global_load_dwordx2 v[128:129], v[126:127], off
	global_load_dwordx4 v[100:103], v[118:119], off
	global_load_dwordx2 v[122:123], v[120:121], off
	s_waitcnt vmcnt(7)
	v_lshlrev_b32_e32 v157, 16, v112
	s_waitcnt vmcnt(6)
	v_cvt_pk_f32_fp8_e32 v[166:167], v164
	v_and_b32_e32 v112, 0xffff0000, v112
	v_mov_b32_e32 v169, v166
	v_pk_mul_f32 v[168:169], v[168:169], v[178:179]
	v_mov_b32_e32 v166, v97
	v_add_f32_e32 v96, v169, v157
	v_add_f32_e32 v157, v168, v96
	v_pk_mul_f32 v[96:97], v[166:167], v[178:179]
	v_cvt_pk_f32_fp8_sdwa v[166:167], v164 src0_sel:WORD_1
	v_add_f32_e32 v97, v97, v112
	v_add_f32_e32 v97, v96, v97
	v_cvt_pk_bf16_f32 v96, v157, v97
	v_mul_f32_e32 v160, v97, v97
	v_and_b32_e32 v112, 0xffff0000, v96
	v_sub_f32_e32 v97, v97, v112
	v_lshlrev_b32_e32 v112, 16, v96
	v_sub_f32_e32 v112, v157, v112
	v_mul_f32_e32 v97, 0x43800000, v97
	v_mul_f32_e32 v112, 0x43800000, v112
	v_fmac_f32_e32 v160, v157, v157
	v_med3_f32 v97, v97, s68, v235
	v_med3_f32 v157, v112, s68, v235
	v_mov_b32_e32 v112, v1
	v_mov_b32_e32 v168, v98
	v_mov_b32_e32 v169, v166
	v_cvt_pk_fp8_f32 v112, v157, v97
	v_lshlrev_b32_e32 v97, 16, v113
	v_pk_mul_f32 v[168:169], v[168:169], v[178:179]
	v_mov_b32_e32 v166, v99
	v_and_b32_e32 v113, 0xffff0000, v113
	v_add_f32_e32 v97, v169, v97
	v_pk_mul_f32 v[98:99], v[166:167], v[178:179]
	v_add_f32_e32 v157, v168, v97
	v_add_f32_e32 v97, v99, v113
	v_add_f32_e32 v98, v98, v97
	v_mul_f32_e32 v97, v98, v98
	v_fmac_f32_e32 v97, v157, v157
	v_add_f32_e32 v113, v160, v97
	v_cvt_pk_bf16_f32 v97, v157, v98
	v_mov_b32_e32 v166, v92
	v_lshlrev_b32_e32 v99, 16, v97
	v_sub_f32_e32 v99, v157, v99
	v_and_b32_e32 v157, 0xffff0000, v97
	v_sub_f32_e32 v98, v98, v157
	v_mul_f32_e32 v99, 0x43800000, v99
	v_mul_f32_e32 v98, 0x43800000, v98
	v_med3_f32 v99, v99, s68, v235
	v_med3_f32 v98, v98, s68, v235
	v_cvt_pk_fp8_f32 v112, v99, v98 op_sel:[0,0,1]
	v_cvt_pk_f32_fp8_e32 v[98:99], v165
	v_lshlrev_b32_e32 v157, 16, v114
	v_and_b32_e32 v114, 0xffff0000, v114
	v_and_b32_e32 v160, 0xffff0000, v115
	v_mov_b32_e32 v167, v98
	v_pk_mul_f32 v[166:167], v[166:167], v[178:179]
	v_mov_b32_e32 v98, v93
; __device__ __forceinline__ unsigned cvt_pk_bf16(float lo, float hi) { unsigned r; asm volatile("v_cvt_pk_bf16_f32 %0, %1, %2" : "=v"(r) : "v"(lo), "v"(hi)); return r; }
;     __device__ __forceinline__ void core(const f32x4 (&acc)[2][2][4][2], const Unit& u, int wr, int wc, int fr, int fq, const float (&rsc)[2][4]) const {
;     ...
;                 for (int bj = 0; bj < 2; ++bj) { const size_t idx = (size_t)row * D + col0 + bj * HALF;
;                     unsigned hw[4]; int lw[2] = {0, 0};
; #pragma unroll
;                     for (int pq = 0; pq < 4; ++pq) {
;                         float h0, h1;
;                         if (F32IN) { h0 = (pq < 2) ? xa[m][bj][2 * pq] : xb[m][bj][2 * pq - 4]; h1 = (pq < 2) ? xa[m][bj][2 * pq + 1] : xb[m][bj][2 * pq - 3]; }
;                         else { const unsigned a = va[m][bj][pq]; const int bw = (int)vb[m][bj][pq >> 1]; const hf32x2 lp = (pq & 1) ? __builtin_amdgcn_cvt_pk_f32_fp8(bw, true) : __builtin_amdgcn_cvt_pk_f32_fp8(bw, false);
;                             h0 = __uint_as_float(a << 16) + lp.x * 0.00390625f; h1 = __uint_as_float(a & 0xffff0000u) + lp.y * 0.00390625f; }
;                         const float o0 = h0 + acc[ai][bj][mh + m][pq >> 1][(2 * pq) & 3] * rs1, o1 = h1 + acc[ai][bj][mh + m][pq >> 1][(2 * pq + 1) & 3] * rs1;
;                         sq += o0 * o0 + o1 * o1;
;                         const unsigned hi = cvt_pk_bf16(o0, o1);
;                         hw[pq] = hi;
;                         const float r0 = __builtin_amdgcn_fmed3f((o0 - __uint_as_float(hi << 16)) * 256.0f, -448.0f, 448.0f), r1 = __builtin_amdgcn_fmed3f((o1 - __uint_as_float(hi & 0xffff0000u)) * 256.0f, -448.0f, 448.0f);
;                         lw[pq >> 1] = (pq & 1) ? __builtin_amdgcn_cvt_pk_fp8_f32(r0, r1, lw[pq >> 1], true) : __builtin_amdgcn_cvt_pk_fp8_f32(r0, r1, lw[pq >> 1], false);
;                     }
;                     *(u32x4*)(Hb + idx) = (u32x4){hw[0], hw[1], hw[2], hw[3]}; *(u32x2*)(Hl + idx) = (u32x2){(unsigned)lw[0], (unsigned)lw[1]}; }
;                 sq += __shfl_xor(sq, 16); sq += __shfl_xor(sq, 32); if (fq == 0) ss[(size_t)row * 32 + u.pn * 4 + wc] = sq; }
	v_add_f32_e32 v92, v167, v157
	v_add_f32_e32 v157, v166, v92
	v_pk_mul_f32 v[92:93], v[98:99], v[178:179]
	s_nop 0
	v_add_f32_e32 v93, v93, v114
	v_add_f32_e32 v92, v92, v93
	v_mul_f32_e32 v93, v92, v92
	v_fmac_f32_e32 v93, v157, v157
	v_add_f32_e32 v99, v113, v93
	v_cvt_pk_bf16_f32 v98, v157, v92
	v_mov_b32_e32 v113, v1
	v_and_b32_e32 v93, 0xffff0000, v98
	v_sub_f32_e32 v92, v92, v93
	v_lshlrev_b32_e32 v93, 16, v98
	v_sub_f32_e32 v93, v157, v93
	v_mul_f32_e32 v92, 0x43800000, v92
	v_mul_f32_e32 v93, 0x43800000, v93
	v_med3_f32 v92, v92, s68, v235
	v_med3_f32 v93, v93, s68, v235
	v_cvt_pk_fp8_f32 v113, v93, v92
	v_cvt_pk_f32_fp8_sdwa v[92:93], v165 src0_sel:WORD_1
	v_lshlrev_b32_e32 v157, 16, v115
	v_mov_b32_e32 v114, v94
	v_mov_b32_e32 v115, v92
	v_pk_mul_f32 v[114:115], v[114:115], v[178:179]
	s_nop 0
	v_add_f32_e32 v92, v115, v157
	v_add_f32_e32 v94, v114, v92
	v_mov_b32_e32 v92, v95
	v_pk_mul_f32 v[92:93], v[92:93], v[178:179]
	s_nop 0
	v_add_f32_e32 v93, v93, v160
	v_add_f32_e32 v92, v92, v93
	v_mul_f32_e32 v93, v92, v92
	v_fmac_f32_e32 v93, v94, v94
	v_add_f32_e32 v114, v99, v93
	v_cvt_pk_bf16_f32 v99, v94, v92
	s_nop 0
	v_lshlrev_b32_e32 v93, 16, v99
	v_sub_f32_e32 v93, v94, v93
	v_and_b32_e32 v94, 0xffff0000, v99
	v_sub_f32_e32 v92, v92, v94
	v_mul_f32_e32 v93, 0x43800000, v93
	v_mul_f32_e32 v92, 0x43800000, v92
	v_med3_f32 v93, v93, s68, v235
	v_med3_f32 v92, v92, s68, v235
	v_cvt_pk_fp8_f32 v113, v93, v92 op_sel:[0,0,1]
	s_waitcnt vmcnt(4)
	v_cvt_pk_f32_fp8_e32 v[92:93], v136
	v_mov_b32_e32 v94, v88
	global_store_dwordx4 v[138:139], v[96:99], off sc1
	global_store_dwordx2 v[162:163], v[112:113], off
	v_mov_b32_e32 v95, v92
	v_lshlrev_b32_e32 v96, 16, v108
	v_pk_mul_f32 v[94:95], v[94:95], v[178:179]
	v_mov_b32_e32 v92, v89
	v_add_f32_e32 v88, v95, v96
	v_and_b32_e32 v97, 0xffff0000, v108
	v_add_f32_e32 v94, v94, v88
	v_pk_mul_f32 v[88:89], v[92:93], v[178:179]
	v_mov_b32_e32 v96, v90
	v_add_f32_e32 v89, v89, v97
	v_add_f32_e32 v89, v88, v89
	v_mul_f32_e32 v88, v89, v89
	v_fmac_f32_e32 v88, v94, v94
	v_add_f32_e32 v93, v114, v88
	v_cvt_pk_bf16_f32 v88, v94, v89
	v_and_b32_e32 v98, 0xffff0000, v109
	v_and_b32_e32 v92, 0xffff0000, v88
	v_sub_f32_e32 v89, v89, v92
	v_lshlrev_b32_e32 v92, 16, v88
	v_sub_f32_e32 v92, v94, v92
	v_mul_f32_e32 v89, 0x43800000, v89
	v_mul_f32_e32 v92, 0x43800000, v92
	v_med3_f32 v89, v89, s68, v235
	v_med3_f32 v94, v92, s68, v235
	v_mov_b32_e32 v92, v1
	v_cvt_pk_fp8_f32 v92, v94, v89
	v_cvt_pk_f32_fp8_sdwa v[94:95], v136 src0_sel:WORD_1
	v_lshlrev_b32_e32 v89, 16, v109
	v_mov_b32_e32 v97, v94
	v_pk_mul_f32 v[96:97], v[96:97], v[178:179]
	v_mov_b32_e32 v94, v91
	v_add_f32_e32 v89, v97, v89
	v_pk_mul_f32 v[90:91], v[94:95], v[178:179]
	v_add_f32_e32 v96, v96, v89
	v_add_f32_e32 v89, v91, v98
	v_add_f32_e32 v90, v90, v89
	v_mul_f32_e32 v89, v90, v90
	v_fmac_f32_e32 v89, v96, v96
	v_add_f32_e32 v93, v93, v89
	v_cvt_pk_bf16_f32 v89, v96, v90
	v_and_b32_e32 v97, 0xffff0000, v110
	v_lshlrev_b32_e32 v91, 16, v89
	v_and_b32_e32 v94, 0xffff0000, v89
	v_sub_f32_e32 v91, v96, v91
	v_sub_f32_e32 v90, v90, v94
	v_mul_f32_e32 v91, 0x43800000, v91
	v_mul_f32_e32 v90, 0x43800000, v90
	v_med3_f32 v91, v91, s68, v235
	v_med3_f32 v90, v90, s68, v235
	v_cvt_pk_fp8_f32 v92, v91, v90 op_sel:[0,0,1]
	v_cvt_pk_f32_fp8_e32 v[90:91], v137
	v_mov_b32_e32 v94, v84
	v_lshlrev_b32_e32 v96, 16, v110
	v_mov_b32_e32 v95, v90
	v_pk_mul_f32 v[94:95], v[94:95], v[178:179]
	v_mov_b32_e32 v90, v85
	v_add_f32_e32 v84, v95, v96
	v_add_f32_e32 v94, v94, v84
	v_pk_mul_f32 v[84:85], v[90:91], v[178:179]
	v_lshlrev_b32_e32 v96, 16, v111
	v_add_f32_e32 v85, v85, v97
	v_add_f32_e32 v84, v84, v85
	v_mul_f32_e32 v85, v84, v84
	v_fmac_f32_e32 v85, v94, v94
	v_add_f32_e32 v91, v93, v85
	v_cvt_pk_bf16_f32 v90, v94, v84
	v_mov_b32_e32 v93, v1
	v_and_b32_e32 v85, 0xffff0000, v90
	v_sub_f32_e32 v84, v84, v85
	v_lshlrev_b32_e32 v85, 16, v90
	v_sub_f32_e32 v85, v94, v85
	v_mul_f32_e32 v84, 0x43800000, v84
	v_mul_f32_e32 v85, 0x43800000, v85
	v_med3_f32 v84, v84, s68, v235
	v_med3_f32 v85, v85, s68, v235
	v_cvt_pk_fp8_f32 v93, v85, v84
	v_cvt_pk_f32_fp8_sdwa v[84:85], v137 src0_sel:WORD_1
	v_mov_b32_e32 v94, v86
	v_and_b32_e32 v97, 0xffff0000, v111
	v_mov_b32_e32 v95, v84
	v_pk_mul_f32 v[94:95], v[94:95], v[178:179]
	s_nop 0
	v_add_f32_e32 v84, v95, v96
	v_add_f32_e32 v86, v94, v84
	v_mov_b32_e32 v84, v87
	v_pk_mul_f32 v[84:85], v[84:85], v[178:179]
	s_nop 0
	v_add_f32_e32 v85, v85, v97
	v_add_f32_e32 v84, v84, v85
	v_mul_f32_e32 v85, v84, v84
	v_fmac_f32_e32 v85, v86, v86
	v_add_f32_e32 v85, v91, v85
	v_cvt_pk_bf16_f32 v91, v86, v84
	s_nop 0
	v_lshlrev_b32_e32 v87, 16, v91
	v_sub_f32_e32 v86, v86, v87
	v_and_b32_e32 v87, 0xffff0000, v91
	v_sub_f32_e32 v84, v84, v87
	v_mul_f32_e32 v86, 0x43800000, v86
	v_mul_f32_e32 v84, 0x43800000, v84
	v_med3_f32 v86, v86, s68, v235
	v_med3_f32 v84, v84, s68, v235
	v_cvt_pk_fp8_f32 v93, v86, v84 op_sel:[0,0,1]
	ds_bpermute_b32 v84, v0, v85
	global_store_dwordx4 v[132:133], v[88:91], off sc1
	global_store_dwordx2 v[134:135], v[92:93], off
	s_waitcnt lgkmcnt(0)
	v_add_f32_e32 v84, v85, v84
	ds_bpermute_b32 v85, v176, v84
	s_and_saveexec_b64 s[2:3], s[38:39]
	s_cbranch_execz .LBB0_1000
	s_waitcnt lgkmcnt(0)
	v_add_f32_e32 v86, v84, v85
	s_lshl_b32 s20, s58, 2
	v_lshlrev_b64 v[84:85], 7, v[130:131]
	s_ashr_i32 s21, s20, 31
	v_lshl_add_u64 v[84:85], s[46:47], 0, v[84:85]
	v_lshl_add_u64 v[84:85], s[20:21], 2, v[84:85]
	s_lshl_b32 s18, s37, 2
	v_lshl_add_u64 v[84:85], v[84:85], 0, s[18:19]
	global_store_dword v[84:85], v86, off
; __device__ __forceinline__ unsigned cvt_pk_bf16(float lo, float hi) { unsigned r; asm volatile("v_cvt_pk_bf16_f32 %0, %1, %2" : "=v"(r) : "v"(lo), "v"(hi)); return r; }
;     __device__ __forceinline__ void core(const f32x4 (&acc)[2][2][4][2], const Unit& u, int wr, int wc, int fr, int fq, const float (&rsc)[2][4]) const {
;     ...
;                 for (int bj = 0; bj < 2; ++bj) { const size_t idx = (size_t)row * D + col0 + bj * HALF;
;                     unsigned hw[4]; int lw[2] = {0, 0};
; #pragma unroll
;                     for (int pq = 0; pq < 4; ++pq) {
;                         float h0, h1;
;                         if (F32IN) { h0 = (pq < 2) ? xa[m][bj][2 * pq] : xb[m][bj][2 * pq - 4]; h1 = (pq < 2) ? xa[m][bj][2 * pq + 1] : xb[m][bj][2 * pq - 3]; }
;                         else { const unsigned a = va[m][bj][pq]; const int bw = (int)vb[m][bj][pq >> 1]; const hf32x2 lp = (pq & 1) ? __builtin_amdgcn_cvt_pk_f32_fp8(bw, true) : __builtin_amdgcn_cvt_pk_f32_fp8(bw, false);
;                             h0 = __uint_as_float(a << 16) + lp.x * 0.00390625f; h1 = __uint_as_float(a & 0xffff0000u) + lp.y * 0.00390625f; }
;                         const float o0 = h0 + acc[ai][bj][mh + m][pq >> 1][(2 * pq) & 3] * rs1, o1 = h1 + acc[ai][bj][mh + m][pq >> 1][(2 * pq + 1) & 3] * rs1;
;                         sq += o0 * o0 + o1 * o1;
;                         const unsigned hi = cvt_pk_bf16(o0, o1);
;                         hw[pq] = hi;
;                         const float r0 = __builtin_amdgcn_fmed3f((o0 - __uint_as_float(hi << 16)) * 256.0f, -448.0f, 448.0f), r1 = __builtin_amdgcn_fmed3f((o1 - __uint_as_float(hi & 0xffff0000u)) * 256.0f, -448.0f, 448.0f);
;                         lw[pq >> 1] = (pq & 1) ? __builtin_amdgcn_cvt_pk_fp8_f32(r0, r1, lw[pq >> 1], true) : __builtin_amdgcn_cvt_pk_fp8_f32(r0, r1, lw[pq >> 1], false);
;                     }
;                     *(u32x4*)(Hb + idx) = (u32x4){hw[0], hw[1], hw[2], hw[3]}; *(u32x2*)(Hl + idx) = (u32x2){(unsigned)lw[0], (unsigned)lw[1]}; }
;                 sq += __shfl_xor(sq, 16); sq += __shfl_xor(sq, 32); if (fq == 0) ss[(size_t)row * 32 + u.pn * 4 + wc] = sq; }
.LBB0_1000:
	s_or_b64 exec, exec, s[2:3]
	s_waitcnt vmcnt(6) lgkmcnt(0)
	v_cvt_pk_f32_fp8_e32 v[84:85], v128
	v_mov_b32_e32 v86, v80
	v_mov_b32_e32 v178, v161
	v_lshlrev_b32_e32 v88, 16, v104
	v_mov_b32_e32 v87, v84
	v_pk_mul_f32 v[86:87], v[86:87], v[178:179]
	v_mov_b32_e32 v84, v81
	v_add_f32_e32 v80, v87, v88
	v_and_b32_e32 v89, 0xffff0000, v104
	v_add_f32_e32 v86, v86, v80
	v_pk_mul_f32 v[80:81], v[84:85], v[178:179]
	v_mov_b32_e32 v88, v82
	v_add_f32_e32 v81, v81, v89
	v_add_f32_e32 v81, v80, v81
	v_cvt_pk_bf16_f32 v80, v86, v81
	v_mul_f32_e32 v85, v81, v81
	v_and_b32_e32 v84, 0xffff0000, v80
	v_sub_f32_e32 v81, v81, v84
	v_lshlrev_b32_e32 v84, 16, v80
	v_sub_f32_e32 v84, v86, v84
	v_mul_f32_e32 v81, 0x43800000, v81
	v_mul_f32_e32 v84, 0x43800000, v84
	v_fmac_f32_e32 v85, v86, v86
	v_med3_f32 v81, v81, s68, v235
	v_med3_f32 v86, v84, s68, v235
	v_mov_b32_e32 v84, v1
	v_cvt_pk_fp8_f32 v84, v86, v81
	v_cvt_pk_f32_fp8_sdwa v[86:87], v128 src0_sel:WORD_1
	v_lshlrev_b32_e32 v81, 16, v105
	v_and_b32_e32 v90, 0xffff0000, v105
	v_mov_b32_e32 v89, v86
	v_pk_mul_f32 v[88:89], v[88:89], v[178:179]
	v_mov_b32_e32 v86, v83
	v_add_f32_e32 v81, v89, v81
	v_pk_mul_f32 v[82:83], v[86:87], v[178:179]
	v_add_f32_e32 v88, v88, v81
	v_add_f32_e32 v81, v83, v90
	v_add_f32_e32 v82, v82, v81
	v_mul_f32_e32 v81, v82, v82
	v_fmac_f32_e32 v81, v88, v88
	v_add_f32_e32 v85, v85, v81
	v_cvt_pk_bf16_f32 v81, v88, v82
	v_and_b32_e32 v89, 0xffff0000, v106
	v_lshlrev_b32_e32 v83, 16, v81
	v_and_b32_e32 v86, 0xffff0000, v81
	v_sub_f32_e32 v83, v88, v83
	v_sub_f32_e32 v82, v82, v86
	v_mul_f32_e32 v83, 0x43800000, v83
	v_mul_f32_e32 v82, 0x43800000, v82
	v_med3_f32 v83, v83, s68, v235
	v_med3_f32 v82, v82, s68, v235
	v_cvt_pk_fp8_f32 v84, v83, v82 op_sel:[0,0,1]
	v_cvt_pk_f32_fp8_e32 v[82:83], v129
	v_mov_b32_e32 v86, v76
	v_lshlrev_b32_e32 v88, 16, v106
	v_mov_b32_e32 v87, v82
	v_pk_mul_f32 v[86:87], v[86:87], v[178:179]
	v_mov_b32_e32 v82, v77
	v_add_f32_e32 v76, v87, v88
	v_add_f32_e32 v86, v86, v76
	v_pk_mul_f32 v[76:77], v[82:83], v[178:179]
	v_lshlrev_b32_e32 v83, 16, v107
	v_add_f32_e32 v77, v77, v89
	v_add_f32_e32 v76, v76, v77
	v_mul_f32_e32 v77, v76, v76
	v_fmac_f32_e32 v77, v86, v86
	v_add_f32_e32 v88, v85, v77
	v_cvt_pk_bf16_f32 v82, v86, v76
	v_mov_b32_e32 v85, v1
	v_and_b32_e32 v77, 0xffff0000, v82
	v_sub_f32_e32 v76, v76, v77
	v_lshlrev_b32_e32 v77, 16, v82
	v_sub_f32_e32 v77, v86, v77
	v_mul_f32_e32 v76, 0x43800000, v76
	v_mul_f32_e32 v77, 0x43800000, v77
	v_med3_f32 v76, v76, s68, v235
	v_med3_f32 v77, v77, s68, v235
	v_cvt_pk_fp8_f32 v85, v77, v76
	v_cvt_pk_f32_fp8_sdwa v[76:77], v129 src0_sel:WORD_1
	v_mov_b32_e32 v86, v78
	v_and_b32_e32 v89, 0xffff0000, v107
	v_mov_b32_e32 v87, v76
	v_pk_mul_f32 v[86:87], v[86:87], v[178:179]
	s_nop 0
	v_add_f32_e32 v76, v87, v83
	v_add_f32_e32 v78, v86, v76
	v_mov_b32_e32 v76, v79
	v_pk_mul_f32 v[76:77], v[76:77], v[178:179]
	s_nop 0
	v_add_f32_e32 v77, v77, v89
	v_add_f32_e32 v76, v76, v77
	v_cvt_pk_bf16_f32 v83, v78, v76
	v_mul_f32_e32 v77, v76, v76
	v_lshlrev_b32_e32 v79, 16, v83
	v_and_b32_e32 v86, 0xffff0000, v83
	v_sub_f32_e32 v79, v78, v79
	v_sub_f32_e32 v76, v76, v86
	v_mul_f32_e32 v79, 0x43800000, v79
	v_mul_f32_e32 v76, 0x43800000, v76
	v_med3_f32 v79, v79, s68, v235
	v_med3_f32 v76, v76, s68, v235
	v_fmac_f32_e32 v77, v78, v78
	v_cvt_pk_fp8_f32 v85, v79, v76 op_sel:[0,0,1]
	v_add_f32_e32 v86, v88, v77
	s_waitcnt vmcnt(4)
	v_cvt_pk_f32_fp8_e32 v[76:77], v122
	v_mov_b32_e32 v78, v72
	global_store_dwordx4 v[124:125], v[80:83], off sc1
	global_store_dwordx2 v[126:127], v[84:85], off
	v_mov_b32_e32 v79, v76
	v_lshlrev_b32_e32 v80, 16, v100
	v_pk_mul_f32 v[78:79], v[78:79], v[178:179]
	v_mov_b32_e32 v76, v73
	v_add_f32_e32 v72, v79, v80
	v_and_b32_e32 v81, 0xffff0000, v100
	v_add_f32_e32 v78, v78, v72
	v_pk_mul_f32 v[72:73], v[76:77], v[178:179]
	v_mov_b32_e32 v80, v74
	v_add_f32_e32 v73, v73, v81
	v_add_f32_e32 v73, v72, v73
	v_mul_f32_e32 v72, v73, v73
	v_fmac_f32_e32 v72, v78, v78
	v_add_f32_e32 v77, v86, v72
	v_cvt_pk_bf16_f32 v72, v78, v73
	v_and_b32_e32 v82, 0xffff0000, v101
	v_and_b32_e32 v76, 0xffff0000, v72
	v_sub_f32_e32 v73, v73, v76
	v_lshlrev_b32_e32 v76, 16, v72
	v_sub_f32_e32 v76, v78, v76
	v_mul_f32_e32 v73, 0x43800000, v73
	v_mul_f32_e32 v76, 0x43800000, v76
	v_med3_f32 v73, v73, s68, v235
	v_med3_f32 v78, v76, s68, v235
	v_mov_b32_e32 v76, v1
	v_cvt_pk_fp8_f32 v76, v78, v73
	v_cvt_pk_f32_fp8_sdwa v[78:79], v122 src0_sel:WORD_1
	v_lshlrev_b32_e32 v73, 16, v101
	v_mov_b32_e32 v81, v78
	v_pk_mul_f32 v[80:81], v[80:81], v[178:179]
	v_mov_b32_e32 v78, v75
	v_add_f32_e32 v73, v81, v73
	v_pk_mul_f32 v[74:75], v[78:79], v[178:179]
	v_add_f32_e32 v80, v80, v73
	v_add_f32_e32 v73, v75, v82
	v_add_f32_e32 v74, v74, v73
	v_mul_f32_e32 v73, v74, v74
	v_fmac_f32_e32 v73, v80, v80
	v_add_f32_e32 v77, v77, v73
	v_cvt_pk_bf16_f32 v73, v80, v74
	v_and_b32_e32 v81, 0xffff0000, v102
	v_lshlrev_b32_e32 v75, 16, v73
	v_and_b32_e32 v78, 0xffff0000, v73
	v_sub_f32_e32 v75, v80, v75
	v_sub_f32_e32 v74, v74, v78
	v_mul_f32_e32 v75, 0x43800000, v75
	v_mul_f32_e32 v74, 0x43800000, v74
	v_med3_f32 v75, v75, s68, v235
	v_med3_f32 v74, v74, s68, v235
	v_cvt_pk_fp8_f32 v76, v75, v74 op_sel:[0,0,1]
	v_cvt_pk_f32_fp8_e32 v[74:75], v123
	v_mov_b32_e32 v78, v68
	v_lshlrev_b32_e32 v80, 16, v102
	v_mov_b32_e32 v79, v74
	v_pk_mul_f32 v[78:79], v[78:79], v[178:179]
	v_mov_b32_e32 v74, v69
	v_add_f32_e32 v68, v79, v80
	v_add_f32_e32 v78, v78, v68
	v_pk_mul_f32 v[68:69], v[74:75], v[178:179]
	v_lshlrev_b32_e32 v80, 16, v103
	v_add_f32_e32 v69, v69, v81
	v_add_f32_e32 v68, v68, v69
	v_mul_f32_e32 v69, v68, v68
	v_fmac_f32_e32 v69, v78, v78
	v_add_f32_e32 v75, v77, v69
	v_cvt_pk_bf16_f32 v74, v78, v68
	v_mov_b32_e32 v77, v1
	v_and_b32_e32 v69, 0xffff0000, v74
	v_sub_f32_e32 v68, v68, v69
	v_lshlrev_b32_e32 v69, 16, v74
	v_sub_f32_e32 v69, v78, v69
	v_mul_f32_e32 v68, 0x43800000, v68
	v_mul_f32_e32 v69, 0x43800000, v69
	v_med3_f32 v68, v68, s68, v235
	v_med3_f32 v69, v69, s68, v235
	v_cvt_pk_fp8_f32 v77, v69, v68
	v_cvt_pk_f32_fp8_sdwa v[68:69], v123 src0_sel:WORD_1
	v_mov_b32_e32 v78, v70
	v_and_b32_e32 v81, 0xffff0000, v103
	v_mov_b32_e32 v79, v68
	v_pk_mul_f32 v[78:79], v[78:79], v[178:179]
	s_nop 0
	v_add_f32_e32 v68, v79, v80
	v_add_f32_e32 v70, v78, v68
	v_mov_b32_e32 v68, v71
	v_pk_mul_f32 v[68:69], v[68:69], v[178:179]
	s_nop 0
	v_add_f32_e32 v69, v69, v81
	v_add_f32_e32 v68, v68, v69
	v_mul_f32_e32 v69, v68, v68
	v_fmac_f32_e32 v69, v70, v70
	v_add_f32_e32 v69, v75, v69
	v_cvt_pk_bf16_f32 v75, v70, v68
	ds_bpermute_b32 v78, v0, v69
	v_lshlrev_b32_e32 v71, 16, v75
	v_sub_f32_e32 v70, v70, v71
	v_and_b32_e32 v71, 0xffff0000, v75
	v_sub_f32_e32 v68, v68, v71
	v_mul_f32_e32 v70, 0x43800000, v70
	v_mul_f32_e32 v68, 0x43800000, v68
	v_med3_f32 v70, v70, s68, v235
	v_med3_f32 v68, v68, s68, v235
	v_cvt_pk_fp8_f32 v77, v70, v68 op_sel:[0,0,1]
	s_waitcnt lgkmcnt(0)
;     __device__ __forceinline__ void core(const f32x4 (&acc)[2][2][4][2], const Unit& u, int wr, int wc, int fr, int fq, const float (&rsc)[2][4]) const {
;     ...
;         for (int ai = 0; ai < 2; ++ai)
; #pragma unroll
;         for (int mh = 0; mh < 4; mh += MB) {
;             u32x4 va[MB][2]; u32x2 vb[MB][2];
;             f32x4 xa[MB][2], xb[MB][2];
; #pragma unroll
;             for (int m = 0; m < MB; ++m)
; #pragma unroll
;                 for (int bj = 0; bj < 2; ++bj) { const size_t idx = (size_t)(row0 + ai * HALF + (mh + m) * 16) * D + col0 + bj * HALF;
;                     if (F32IN) { xa[m][bj] = *(const f32x4*)(Xin + idx); xb[m][bj] = *(const f32x4*)(Xin + idx + 4); }
;                     else { va[m][bj] = *(const u32x4*)(Hb + idx); vb[m][bj] = *(const u32x2*)(Hl + idx); } }
; #pragma unroll
;             for (int m = 0; m < MB; ++m) { const int row = row0 + ai * HALF + (mh + m) * 16; float sq = 0.f;
;                 const float rs1 = rsc[ai][mh + m];
; #pragma unroll
;                 for (int bj = 0; bj < 2; ++bj) { const size_t idx = (size_t)row * D + col0 + bj * HALF;
;                     unsigned hw[4]; int lw[2] = {0, 0};
; #pragma unroll
;                     for (int pq = 0; pq < 4; ++pq) {
;                         float h0, h1;
;                         if (F32IN) { h0 = (pq < 2) ? xa[m][bj][2 * pq] : xb[m][bj][2 * pq - 4]; h1 = (pq < 2) ? xa[m][bj][2 * pq + 1] : xb[m][bj][2 * pq - 3]; }
;                         else { const unsigned a = va[m][bj][pq]; const int bw = (int)vb[m][bj][pq >> 1]; const hf32x2 lp = (pq & 1) ? __builtin_amdgcn_cvt_pk_f32_fp8(bw, true) : __builtin_amdgcn_cvt_pk_f32_fp8(bw, false);
;                             h0 = __uint_as_float(a << 16) + lp.x * 0.00390625f; h1 = __uint_as_float(a & 0xffff0000u) + lp.y * 0.00390625f; }
;                         const float o0 = h0 + acc[ai][bj][mh + m][pq >> 1][(2 * pq) & 3] * rs1, o1 = h1 + acc[ai][bj][mh + m][pq >> 1][(2 * pq + 1) & 3] * rs1;
;                         sq += o0 * o0 + o1 * o1;
;                         const unsigned hi = cvt_pk_bf16(o0, o1);
;                         hw[pq] = hi;
;                         const float r0 = __builtin_amdgcn_fmed3f((o0 - __uint_as_float(hi << 16)) * 256.0f, -448.0f, 448.0f), r1 = __builtin_amdgcn_fmed3f((o1 - __uint_as_float(hi & 0xffff0000u)) * 256.0f, -448.0f, 448.0f);
	v_add_f32_e32 v68, v69, v78
	ds_bpermute_b32 v69, v176, v68
	global_store_dwordx4 v[118:119], v[72:75], off sc1
	global_store_dwordx2 v[120:121], v[76:77], off
	s_and_saveexec_b64 s[2:3], s[38:39]
	s_cbranch_execz .LBB0_1002
	s_waitcnt lgkmcnt(0)
	v_add_f32_e32 v70, v68, v69
	s_lshl_b32 s20, s58, 2
	v_lshlrev_b64 v[68:69], 7, v[116:117]
	s_ashr_i32 s21, s20, 31
	v_lshl_add_u64 v[68:69], s[46:47], 0, v[68:69]
	v_lshl_add_u64 v[68:69], s[20:21], 2, v[68:69]
	s_lshl_b32 s18, s37, 2
	v_lshl_add_u64 v[68:69], v[68:69], 0, s[18:19]
	global_store_dword v[68:69], v70, off
.LBB0_1002:
	s_or_b64 exec, exec, s[2:3]
	v_add_u32_e32 v98, 0x80, v156
	v_ashrrev_i32_e32 v99, 31, v98
	s_waitcnt lgkmcnt(0)
	v_lshlrev_b64 v[68:69], 11, v[98:99]
	v_lshl_add_u64 v[68:69], v[68:69], 0, v[154:155]
	v_lshl_add_u64 v[106:107], v[68:69], 1, s[42:43]
	v_lshl_add_u64 v[108:109], s[44:45], 0, v[68:69]
	global_load_dwordx4 v[80:83], v[106:107], off
	global_load_dwordx2 v[110:111], v[108:109], off
	v_or_b32_e32 v68, 0x80, v68
	v_lshl_add_u64 v[100:101], v[68:69], 1, s[42:43]
	v_lshl_add_u64 v[102:103], s[44:45], 0, v[68:69]
	global_load_dwordx4 v[76:79], v[100:101], off
	global_load_dwordx2 v[104:105], v[102:103], off
	v_add_u32_e32 v84, 0x90, v156
	v_ashrrev_i32_e32 v85, 31, v84
	v_mov_b32_e32 v114, v64
	v_mov_b32_e32 v178, v158
	v_lshlrev_b64 v[68:69], 11, v[84:85]
	v_lshl_add_u64 v[88:89], v[68:69], 0, v[154:155]
	v_lshl_add_u64 v[92:93], v[88:89], 1, s[42:43]
	v_lshl_add_u64 v[94:95], s[44:45], 0, v[88:89]
	v_or_b32_e32 v88, 0x80, v88
	v_lshl_add_u64 v[86:87], v[88:89], 1, s[42:43]
	v_lshl_add_u64 v[88:89], s[44:45], 0, v[88:89]
	global_load_dwordx4 v[72:75], v[92:93], off
	global_load_dwordx2 v[96:97], v[94:95], off
	global_load_dwordx4 v[68:71], v[86:87], off
	global_load_dwordx2 v[90:91], v[88:89], off
	s_waitcnt vmcnt(7)
	v_lshlrev_b32_e32 v116, 16, v80
	s_waitcnt vmcnt(6)
	v_cvt_pk_f32_fp8_e32 v[112:113], v110
	v_and_b32_e32 v80, 0xffff0000, v80
	v_mov_b32_e32 v115, v112
	v_pk_mul_f32 v[114:115], v[114:115], v[178:179]
	v_mov_b32_e32 v112, v65
	v_add_f32_e32 v64, v115, v116
	v_add_f32_e32 v114, v114, v64
	v_pk_mul_f32 v[64:65], v[112:113], v[178:179]
	s_nop 0
	v_add_f32_e32 v65, v65, v80
	v_add_f32_e32 v65, v64, v65
	v_cvt_pk_bf16_f32 v64, v114, v65
	v_mul_f32_e32 v116, v65, v65
	v_and_b32_e32 v80, 0xffff0000, v64
	v_sub_f32_e32 v65, v65, v80
	v_lshlrev_b32_e32 v80, 16, v64
	v_sub_f32_e32 v80, v114, v80
	v_mul_f32_e32 v65, 0x43800000, v65
	v_mul_f32_e32 v80, 0x43800000, v80
	v_med3_f32 v65, v65, s68, v235
	v_med3_f32 v112, v80, s68, v235
	v_mov_b32_e32 v80, v1
	v_cvt_pk_fp8_f32 v80, v112, v65
	v_cvt_pk_f32_fp8_sdwa v[112:113], v110 src0_sel:WORD_1
	v_fmac_f32_e32 v116, v114, v114
	v_mov_b32_e32 v114, v66
	v_lshlrev_b32_e32 v65, 16, v81
	v_mov_b32_e32 v115, v112
	v_pk_mul_f32 v[114:115], v[114:115], v[178:179]
	v_mov_b32_e32 v112, v67
	v_and_b32_e32 v81, 0xffff0000, v81
	v_add_f32_e32 v65, v115, v65
	v_pk_mul_f32 v[66:67], v[112:113], v[178:179]
	v_add_f32_e32 v110, v114, v65
	v_add_f32_e32 v65, v67, v81
	v_add_f32_e32 v66, v66, v65
	v_mul_f32_e32 v65, v66, v66
	v_fmac_f32_e32 v65, v110, v110
	v_add_f32_e32 v81, v116, v65
	v_cvt_pk_bf16_f32 v65, v110, v66
	v_mov_b32_e32 v112, v60
	v_lshlrev_b32_e32 v67, 16, v65
	v_sub_f32_e32 v67, v110, v67
	v_and_b32_e32 v110, 0xffff0000, v65
	v_sub_f32_e32 v66, v66, v110
	v_mul_f32_e32 v67, 0x43800000, v67
	v_mul_f32_e32 v66, 0x43800000, v66
	v_med3_f32 v67, v67, s68, v235
	v_med3_f32 v66, v66, s68, v235
	v_cvt_pk_fp8_f32 v80, v67, v66 op_sel:[0,0,1]
	v_cvt_pk_f32_fp8_e32 v[66:67], v111
	v_lshlrev_b32_e32 v110, 16, v82
	v_and_b32_e32 v82, 0xffff0000, v82
	v_mov_b32_e32 v113, v66
	v_pk_mul_f32 v[112:113], v[112:113], v[178:179]
	v_mov_b32_e32 v66, v61
	v_add_f32_e32 v60, v113, v110
	v_add_f32_e32 v110, v112, v60
	v_pk_mul_f32 v[60:61], v[66:67], v[178:179]
	s_nop 0
	v_add_f32_e32 v61, v61, v82
	v_add_f32_e32 v60, v60, v61
	v_mul_f32_e32 v61, v60, v60
	v_fmac_f32_e32 v61, v110, v110
	v_add_f32_e32 v67, v81, v61
	v_cvt_pk_bf16_f32 v66, v110, v60
	v_mov_b32_e32 v81, v1
	v_and_b32_e32 v61, 0xffff0000, v66
	v_sub_f32_e32 v60, v60, v61
	v_lshlrev_b32_e32 v61, 16, v66
	v_sub_f32_e32 v61, v110, v61
	v_mul_f32_e32 v60, 0x43800000, v60
	v_mul_f32_e32 v61, 0x43800000, v61
	v_med3_f32 v60, v60, s68, v235
	v_med3_f32 v61, v61, s68, v235
	v_cvt_pk_fp8_f32 v81, v61, v60
	v_cvt_pk_f32_fp8_sdwa v[60:61], v111 src0_sel:WORD_1
	v_lshlrev_b32_e32 v110, 16, v83
	v_and_b32_e32 v111, 0xffff0000, v83
	v_mov_b32_e32 v82, v62
	v_mov_b32_e32 v83, v60
	v_pk_mul_f32 v[82:83], v[82:83], v[178:179]
	s_nop 0
	v_add_f32_e32 v60, v83, v110
	v_add_f32_e32 v62, v82, v60
	v_mov_b32_e32 v60, v63
	v_pk_mul_f32 v[60:61], v[60:61], v[178:179]
	s_nop 0
	v_add_f32_e32 v61, v61, v111
	v_add_f32_e32 v60, v60, v61
	v_mul_f32_e32 v61, v60, v60
	v_fmac_f32_e32 v61, v62, v62
	v_add_f32_e32 v82, v67, v61
	v_cvt_pk_bf16_f32 v67, v62, v60
	s_nop 0
	v_lshlrev_b32_e32 v61, 16, v67
	v_sub_f32_e32 v61, v62, v61
	v_and_b32_e32 v62, 0xffff0000, v67
	v_sub_f32_e32 v60, v60, v62
	v_mul_f32_e32 v61, 0x43800000, v61
	v_mul_f32_e32 v60, 0x43800000, v60
	v_med3_f32 v61, v61, s68, v235
	v_med3_f32 v60, v60, s68, v235
	v_cvt_pk_fp8_f32 v81, v61, v60 op_sel:[0,0,1]
	s_waitcnt vmcnt(4)
; __device__ __forceinline__ unsigned cvt_pk_bf16(float lo, float hi) { unsigned r; asm volatile("v_cvt_pk_bf16_f32 %0, %1, %2" : "=v"(r) : "v"(lo), "v"(hi)); return r; }
;     __device__ __forceinline__ void core(const f32x4 (&acc)[2][2][4][2], const Unit& u, int wr, int wc, int fr, int fq, const float (&rsc)[2][4]) const {
;     ...
;                 for (int bj = 0; bj < 2; ++bj) { const size_t idx = (size_t)row * D + col0 + bj * HALF;
;                     unsigned hw[4]; int lw[2] = {0, 0};
; #pragma unroll
;                     for (int pq = 0; pq < 4; ++pq) {
;                         float h0, h1;
;                         if (F32IN) { h0 = (pq < 2) ? xa[m][bj][2 * pq] : xb[m][bj][2 * pq - 4]; h1 = (pq < 2) ? xa[m][bj][2 * pq + 1] : xb[m][bj][2 * pq - 3]; }
;                         else { const unsigned a = va[m][bj][pq]; const int bw = (int)vb[m][bj][pq >> 1]; const hf32x2 lp = (pq & 1) ? __builtin_amdgcn_cvt_pk_f32_fp8(bw, true) : __builtin_amdgcn_cvt_pk_f32_fp8(bw, false);
;                             h0 = __uint_as_float(a << 16) + lp.x * 0.00390625f; h1 = __uint_as_float(a & 0xffff0000u) + lp.y * 0.00390625f; }
;                         const float o0 = h0 + acc[ai][bj][mh + m][pq >> 1][(2 * pq) & 3] * rs1, o1 = h1 + acc[ai][bj][mh + m][pq >> 1][(2 * pq + 1) & 3] * rs1;
;                         sq += o0 * o0 + o1 * o1;
;                         const unsigned hi = cvt_pk_bf16(o0, o1);
;                         hw[pq] = hi;
;                         const float r0 = __builtin_amdgcn_fmed3f((o0 - __uint_as_float(hi << 16)) * 256.0f, -448.0f, 448.0f), r1 = __builtin_amdgcn_fmed3f((o1 - __uint_as_float(hi & 0xffff0000u)) * 256.0f, -448.0f, 448.0f);
;                         lw[pq >> 1] = (pq & 1) ? __builtin_amdgcn_cvt_pk_fp8_f32(r0, r1, lw[pq >> 1], true) : __builtin_amdgcn_cvt_pk_fp8_f32(r0, r1, lw[pq >> 1], false);
;                     }
;                     *(u32x4*)(Hb + idx) = (u32x4){hw[0], hw[1], hw[2], hw[3]}; *(u32x2*)(Hl + idx) = (u32x2){(unsigned)lw[0], (unsigned)lw[1]}; }
;                 sq += __shfl_xor(sq, 16); sq += __shfl_xor(sq, 32); if (fq == 0) ss[(size_t)row * 32 + u.pn * 4 + wc] = sq; }
	v_cvt_pk_f32_fp8_e32 v[60:61], v104
	v_mov_b32_e32 v62, v56
	global_store_dwordx4 v[106:107], v[64:67], off sc1
	global_store_dwordx2 v[108:109], v[80:81], off
	v_mov_b32_e32 v63, v60
	v_lshlrev_b32_e32 v64, 16, v76
	v_pk_mul_f32 v[62:63], v[62:63], v[178:179]
	v_mov_b32_e32 v60, v57
	v_add_f32_e32 v56, v63, v64
	v_and_b32_e32 v65, 0xffff0000, v76
	v_add_f32_e32 v62, v62, v56
	v_pk_mul_f32 v[56:57], v[60:61], v[178:179]
	v_mov_b32_e32 v64, v58
	v_add_f32_e32 v57, v57, v65
	v_add_f32_e32 v57, v56, v57
	v_mul_f32_e32 v56, v57, v57
	v_fmac_f32_e32 v56, v62, v62
	v_add_f32_e32 v61, v82, v56
	v_cvt_pk_bf16_f32 v56, v62, v57
	v_and_b32_e32 v66, 0xffff0000, v77
	v_and_b32_e32 v60, 0xffff0000, v56
	v_sub_f32_e32 v57, v57, v60
	v_lshlrev_b32_e32 v60, 16, v56
	v_sub_f32_e32 v60, v62, v60
	v_mul_f32_e32 v57, 0x43800000, v57
	v_mul_f32_e32 v60, 0x43800000, v60
	v_med3_f32 v57, v57, s68, v235
	v_med3_f32 v62, v60, s68, v235
	v_mov_b32_e32 v60, v1
	v_cvt_pk_fp8_f32 v60, v62, v57
	v_cvt_pk_f32_fp8_sdwa v[62:63], v104 src0_sel:WORD_1
	v_lshlrev_b32_e32 v57, 16, v77
	v_mov_b32_e32 v65, v62
	v_pk_mul_f32 v[64:65], v[64:65], v[178:179]
	v_mov_b32_e32 v62, v59
	v_add_f32_e32 v57, v65, v57
	v_pk_mul_f32 v[58:59], v[62:63], v[178:179]
	v_add_f32_e32 v64, v64, v57
	v_add_f32_e32 v57, v59, v66
	v_add_f32_e32 v58, v58, v57
	v_mul_f32_e32 v57, v58, v58
	v_fmac_f32_e32 v57, v64, v64
	v_add_f32_e32 v61, v61, v57
	v_cvt_pk_bf16_f32 v57, v64, v58
	v_and_b32_e32 v65, 0xffff0000, v78
	v_lshlrev_b32_e32 v59, 16, v57
	v_and_b32_e32 v62, 0xffff0000, v57
	v_sub_f32_e32 v59, v64, v59
	v_sub_f32_e32 v58, v58, v62
	v_mul_f32_e32 v59, 0x43800000, v59
	v_mul_f32_e32 v58, 0x43800000, v58
	v_med3_f32 v59, v59, s68, v235
	v_med3_f32 v58, v58, s68, v235
	v_cvt_pk_fp8_f32 v60, v59, v58 op_sel:[0,0,1]
	v_cvt_pk_f32_fp8_e32 v[58:59], v105
	v_mov_b32_e32 v62, v52
	v_lshlrev_b32_e32 v64, 16, v78
	v_mov_b32_e32 v63, v58
	v_pk_mul_f32 v[62:63], v[62:63], v[178:179]
	v_mov_b32_e32 v58, v53
	v_add_f32_e32 v52, v63, v64
	v_add_f32_e32 v62, v62, v52
	v_pk_mul_f32 v[52:53], v[58:59], v[178:179]
	v_lshlrev_b32_e32 v64, 16, v79
	v_add_f32_e32 v53, v53, v65
	v_add_f32_e32 v52, v52, v53
	v_mul_f32_e32 v53, v52, v52
	v_fmac_f32_e32 v53, v62, v62
	v_add_f32_e32 v59, v61, v53
	v_cvt_pk_bf16_f32 v58, v62, v52
	v_mov_b32_e32 v61, v1
	v_and_b32_e32 v53, 0xffff0000, v58
	v_sub_f32_e32 v52, v52, v53
	v_lshlrev_b32_e32 v53, 16, v58
	v_sub_f32_e32 v53, v62, v53
	v_mul_f32_e32 v52, 0x43800000, v52
	v_mul_f32_e32 v53, 0x43800000, v53
	v_med3_f32 v52, v52, s68, v235
	v_med3_f32 v53, v53, s68, v235
	v_cvt_pk_fp8_f32 v61, v53, v52
	v_cvt_pk_f32_fp8_sdwa v[52:53], v105 src0_sel:WORD_1
	v_mov_b32_e32 v62, v54
	v_and_b32_e32 v65, 0xffff0000, v79
	v_mov_b32_e32 v63, v52
	v_pk_mul_f32 v[62:63], v[62:63], v[178:179]
	s_nop 0
	v_add_f32_e32 v52, v63, v64
	v_add_f32_e32 v54, v62, v52
	v_mov_b32_e32 v52, v55
	v_pk_mul_f32 v[52:53], v[52:53], v[178:179]
	s_nop 0
	v_add_f32_e32 v53, v53, v65
	v_add_f32_e32 v52, v52, v53
	v_mul_f32_e32 v53, v52, v52
	v_fmac_f32_e32 v53, v54, v54
	v_add_f32_e32 v53, v59, v53
	v_cvt_pk_bf16_f32 v59, v54, v52
	s_nop 0
	v_lshlrev_b32_e32 v55, 16, v59
	v_sub_f32_e32 v54, v54, v55
	v_and_b32_e32 v55, 0xffff0000, v59
	v_sub_f32_e32 v52, v52, v55
	v_mul_f32_e32 v54, 0x43800000, v54
	v_mul_f32_e32 v52, 0x43800000, v52
	v_med3_f32 v54, v54, s68, v235
	v_med3_f32 v52, v52, s68, v235
	v_cvt_pk_fp8_f32 v61, v54, v52 op_sel:[0,0,1]
	ds_bpermute_b32 v52, v0, v53
	global_store_dwordx4 v[100:101], v[56:59], off sc1
	global_store_dwordx2 v[102:103], v[60:61], off
	s_waitcnt lgkmcnt(0)
	v_add_f32_e32 v52, v53, v52
	ds_bpermute_b32 v53, v176, v52
	s_and_saveexec_b64 s[2:3], s[38:39]
	s_cbranch_execz .LBB0_1004
	s_waitcnt lgkmcnt(0)
	v_add_f32_e32 v54, v52, v53
	s_lshl_b32 s20, s58, 2
	v_lshlrev_b64 v[52:53], 7, v[98:99]
	s_ashr_i32 s21, s20, 31
	v_lshl_add_u64 v[52:53], s[46:47], 0, v[52:53]
	v_lshl_add_u64 v[52:53], s[20:21], 2, v[52:53]
	s_lshl_b32 s18, s37, 2
	v_lshl_add_u64 v[52:53], v[52:53], 0, s[18:19]
	global_store_dword v[52:53], v54, off
.LBB0_1004:
	s_or_b64 exec, exec, s[2:3]
	s_waitcnt vmcnt(6) lgkmcnt(0)
	v_cvt_pk_f32_fp8_e32 v[52:53], v96
	v_mov_b32_e32 v54, v48
	v_mov_b32_e32 v178, v159
	v_lshlrev_b32_e32 v56, 16, v72
	v_mov_b32_e32 v55, v52
	v_pk_mul_f32 v[54:55], v[54:55], v[178:179]
	v_mov_b32_e32 v52, v49
	v_add_f32_e32 v48, v55, v56
	v_and_b32_e32 v57, 0xffff0000, v72
	v_add_f32_e32 v54, v54, v48
	v_pk_mul_f32 v[48:49], v[52:53], v[178:179]
	v_mov_b32_e32 v56, v50
	v_add_f32_e32 v49, v49, v57
	v_add_f32_e32 v49, v48, v49
	v_cvt_pk_bf16_f32 v48, v54, v49
	v_mul_f32_e32 v53, v49, v49
	v_and_b32_e32 v52, 0xffff0000, v48
	v_sub_f32_e32 v49, v49, v52
	v_lshlrev_b32_e32 v52, 16, v48
	v_sub_f32_e32 v52, v54, v52
	v_mul_f32_e32 v49, 0x43800000, v49
	v_mul_f32_e32 v52, 0x43800000, v52
	v_fmac_f32_e32 v53, v54, v54
	v_med3_f32 v49, v49, s68, v235
	v_med3_f32 v54, v52, s68, v235
	v_mov_b32_e32 v52, v1
	v_cvt_pk_fp8_f32 v52, v54, v49
	v_cvt_pk_f32_fp8_sdwa v[54:55], v96 src0_sel:WORD_1
	v_lshlrev_b32_e32 v49, 16, v73
	v_and_b32_e32 v58, 0xffff0000, v73
	v_mov_b32_e32 v57, v54
	v_pk_mul_f32 v[56:57], v[56:57], v[178:179]
	v_mov_b32_e32 v54, v51
	v_add_f32_e32 v49, v57, v49
	v_pk_mul_f32 v[50:51], v[54:55], v[178:179]
	v_add_f32_e32 v56, v56, v49
	v_add_f32_e32 v49, v51, v58
	v_add_f32_e32 v50, v50, v49
	v_mul_f32_e32 v49, v50, v50
	v_fmac_f32_e32 v49, v56, v56
	v_add_f32_e32 v53, v53, v49
	v_cvt_pk_bf16_f32 v49, v56, v50
	v_and_b32_e32 v57, 0xffff0000, v74
	v_lshlrev_b32_e32 v51, 16, v49
	v_and_b32_e32 v54, 0xffff0000, v49
	v_sub_f32_e32 v51, v56, v51
	v_sub_f32_e32 v50, v50, v54
; __device__ __forceinline__ unsigned cvt_pk_bf16(float lo, float hi) { unsigned r; asm volatile("v_cvt_pk_bf16_f32 %0, %1, %2" : "=v"(r) : "v"(lo), "v"(hi)); return r; }
;     __device__ __forceinline__ void core(const f32x4 (&acc)[2][2][4][2], const Unit& u, int wr, int wc, int fr, int fq, const float (&rsc)[2][4]) const {
;     ...
;                 for (int bj = 0; bj < 2; ++bj) { const size_t idx = (size_t)row * D + col0 + bj * HALF;
;                     unsigned hw[4]; int lw[2] = {0, 0};
; #pragma unroll
;                     for (int pq = 0; pq < 4; ++pq) {
;                         float h0, h1;
;                         if (F32IN) { h0 = (pq < 2) ? xa[m][bj][2 * pq] : xb[m][bj][2 * pq - 4]; h1 = (pq < 2) ? xa[m][bj][2 * pq + 1] : xb[m][bj][2 * pq - 3]; }
;                         else { const unsigned a = va[m][bj][pq]; const int bw = (int)vb[m][bj][pq >> 1]; const hf32x2 lp = (pq & 1) ? __builtin_amdgcn_cvt_pk_f32_fp8(bw, true) : __builtin_amdgcn_cvt_pk_f32_fp8(bw, false);
;                             h0 = __uint_as_float(a << 16) + lp.x * 0.00390625f; h1 = __uint_as_float(a & 0xffff0000u) + lp.y * 0.00390625f; }
;                         const float o0 = h0 + acc[ai][bj][mh + m][pq >> 1][(2 * pq) & 3] * rs1, o1 = h1 + acc[ai][bj][mh + m][pq >> 1][(2 * pq + 1) & 3] * rs1;
;                         sq += o0 * o0 + o1 * o1;
;                         const unsigned hi = cvt_pk_bf16(o0, o1);
;                         hw[pq] = hi;
;                         const float r0 = __builtin_amdgcn_fmed3f((o0 - __uint_as_float(hi << 16)) * 256.0f, -448.0f, 448.0f), r1 = __builtin_amdgcn_fmed3f((o1 - __uint_as_float(hi & 0xffff0000u)) * 256.0f, -448.0f, 448.0f);
;                         lw[pq >> 1] = (pq & 1) ? __builtin_amdgcn_cvt_pk_fp8_f32(r0, r1, lw[pq >> 1], true) : __builtin_amdgcn_cvt_pk_fp8_f32(r0, r1, lw[pq >> 1], false);
;                     }
;                     *(u32x4*)(Hb + idx) = (u32x4){hw[0], hw[1], hw[2], hw[3]}; *(u32x2*)(Hl + idx) = (u32x2){(unsigned)lw[0], (unsigned)lw[1]}; }
;                 sq += __shfl_xor(sq, 16); sq += __shfl_xor(sq, 32); if (fq == 0) ss[(size_t)row * 32 + u.pn * 4 + wc] = sq; }
	v_mul_f32_e32 v51, 0x43800000, v51
	v_mul_f32_e32 v50, 0x43800000, v50
	v_med3_f32 v51, v51, s68, v235
	v_med3_f32 v50, v50, s68, v235
	v_cvt_pk_fp8_f32 v52, v51, v50 op_sel:[0,0,1]
	v_cvt_pk_f32_fp8_e32 v[50:51], v97
	v_mov_b32_e32 v54, v44
	v_lshlrev_b32_e32 v56, 16, v74
	v_mov_b32_e32 v55, v50
	v_pk_mul_f32 v[54:55], v[54:55], v[178:179]
	v_mov_b32_e32 v50, v45
	v_add_f32_e32 v44, v55, v56
	v_add_f32_e32 v54, v54, v44
	v_pk_mul_f32 v[44:45], v[50:51], v[178:179]
	v_lshlrev_b32_e32 v51, 16, v75
	v_add_f32_e32 v45, v45, v57
	v_add_f32_e32 v44, v44, v45
	v_mul_f32_e32 v45, v44, v44
	v_fmac_f32_e32 v45, v54, v54
	v_add_f32_e32 v56, v53, v45
	v_cvt_pk_bf16_f32 v50, v54, v44
	v_mov_b32_e32 v53, v1
	v_and_b32_e32 v45, 0xffff0000, v50
	v_sub_f32_e32 v44, v44, v45
	v_lshlrev_b32_e32 v45, 16, v50
	v_sub_f32_e32 v45, v54, v45
	v_mul_f32_e32 v44, 0x43800000, v44
	v_mul_f32_e32 v45, 0x43800000, v45
	v_med3_f32 v44, v44, s68, v235
	v_med3_f32 v45, v45, s68, v235
	v_cvt_pk_fp8_f32 v53, v45, v44
	v_cvt_pk_f32_fp8_sdwa v[44:45], v97 src0_sel:WORD_1
	v_mov_b32_e32 v54, v46
	v_and_b32_e32 v57, 0xffff0000, v75
	v_mov_b32_e32 v55, v44
	v_pk_mul_f32 v[54:55], v[54:55], v[178:179]
	s_nop 0
	v_add_f32_e32 v44, v55, v51
	v_add_f32_e32 v46, v54, v44
	v_mov_b32_e32 v44, v47
	v_pk_mul_f32 v[44:45], v[44:45], v[178:179]
	s_nop 0
	v_add_f32_e32 v45, v45, v57
	v_add_f32_e32 v44, v44, v45
	v_cvt_pk_bf16_f32 v51, v46, v44
	v_mul_f32_e32 v45, v44, v44
	v_lshlrev_b32_e32 v47, 16, v51
	v_and_b32_e32 v54, 0xffff0000, v51
	v_sub_f32_e32 v47, v46, v47
	v_sub_f32_e32 v44, v44, v54
	v_mul_f32_e32 v47, 0x43800000, v47
	v_mul_f32_e32 v44, 0x43800000, v44
	v_med3_f32 v47, v47, s68, v235
	v_med3_f32 v44, v44, s68, v235
	v_fmac_f32_e32 v45, v46, v46
	v_cvt_pk_fp8_f32 v53, v47, v44 op_sel:[0,0,1]
	v_add_f32_e32 v54, v56, v45
	s_waitcnt vmcnt(4)
	v_cvt_pk_f32_fp8_e32 v[44:45], v90
	v_mov_b32_e32 v46, v40
	global_store_dwordx4 v[92:93], v[48:51], off sc1
	global_store_dwordx2 v[94:95], v[52:53], off
	v_mov_b32_e32 v47, v44
	v_lshlrev_b32_e32 v48, 16, v68
	v_pk_mul_f32 v[46:47], v[46:47], v[178:179]
	v_mov_b32_e32 v44, v41
	v_add_f32_e32 v40, v47, v48
	v_and_b32_e32 v49, 0xffff0000, v68
	v_add_f32_e32 v46, v46, v40
	v_pk_mul_f32 v[40:41], v[44:45], v[178:179]
	v_mov_b32_e32 v48, v42
	v_add_f32_e32 v41, v41, v49
	v_add_f32_e32 v41, v40, v41
	v_mul_f32_e32 v40, v41, v41
	v_fmac_f32_e32 v40, v46, v46
	v_add_f32_e32 v45, v54, v40
	v_cvt_pk_bf16_f32 v40, v46, v41
	v_and_b32_e32 v50, 0xffff0000, v69
	v_and_b32_e32 v44, 0xffff0000, v40
	v_sub_f32_e32 v41, v41, v44
	v_lshlrev_b32_e32 v44, 16, v40
	v_sub_f32_e32 v44, v46, v44
	v_mul_f32_e32 v41, 0x43800000, v41
	v_mul_f32_e32 v44, 0x43800000, v44
	v_med3_f32 v41, v41, s68, v235
	v_med3_f32 v46, v44, s68, v235
	v_mov_b32_e32 v44, v1
	v_cvt_pk_fp8_f32 v44, v46, v41
	v_cvt_pk_f32_fp8_sdwa v[46:47], v90 src0_sel:WORD_1
	v_lshlrev_b32_e32 v41, 16, v69
	v_mov_b32_e32 v49, v46
	v_pk_mul_f32 v[48:49], v[48:49], v[178:179]
	v_mov_b32_e32 v46, v43
	v_add_f32_e32 v41, v49, v41
	v_pk_mul_f32 v[42:43], v[46:47], v[178:179]
	v_add_f32_e32 v48, v48, v41
	v_add_f32_e32 v41, v43, v50
	v_add_f32_e32 v42, v42, v41
	v_mul_f32_e32 v41, v42, v42
	v_fmac_f32_e32 v41, v48, v48
	v_add_f32_e32 v45, v45, v41
	v_cvt_pk_bf16_f32 v41, v48, v42
	v_and_b32_e32 v49, 0xffff0000, v70
	v_lshlrev_b32_e32 v43, 16, v41
	v_and_b32_e32 v46, 0xffff0000, v41
	v_sub_f32_e32 v43, v48, v43
	v_sub_f32_e32 v42, v42, v46
	v_mul_f32_e32 v43, 0x43800000, v43
	v_mul_f32_e32 v42, 0x43800000, v42
	v_med3_f32 v43, v43, s68, v235
	v_med3_f32 v42, v42, s68, v235
	v_cvt_pk_fp8_f32 v44, v43, v42 op_sel:[0,0,1]
	v_cvt_pk_f32_fp8_e32 v[42:43], v91
	v_mov_b32_e32 v46, v36
	v_lshlrev_b32_e32 v48, 16, v70
	v_mov_b32_e32 v47, v42
	v_pk_mul_f32 v[46:47], v[46:47], v[178:179]
	v_mov_b32_e32 v42, v37
	v_add_f32_e32 v36, v47, v48
	v_add_f32_e32 v46, v46, v36
	v_pk_mul_f32 v[36:37], v[42:43], v[178:179]
	v_lshlrev_b32_e32 v48, 16, v71
	v_add_f32_e32 v37, v37, v49
	v_add_f32_e32 v36, v36, v37
	v_mul_f32_e32 v37, v36, v36
	v_fmac_f32_e32 v37, v46, v46
	v_add_f32_e32 v43, v45, v37
	v_cvt_pk_bf16_f32 v42, v46, v36
	v_mov_b32_e32 v45, v1
	v_and_b32_e32 v37, 0xffff0000, v42
	v_sub_f32_e32 v36, v36, v37
	v_lshlrev_b32_e32 v37, 16, v42
	v_sub_f32_e32 v37, v46, v37
	v_mul_f32_e32 v36, 0x43800000, v36
	v_mul_f32_e32 v37, 0x43800000, v37
	v_med3_f32 v36, v36, s68, v235
	v_med3_f32 v37, v37, s68, v235
	v_cvt_pk_fp8_f32 v45, v37, v36
	v_cvt_pk_f32_fp8_sdwa v[36:37], v91 src0_sel:WORD_1
	v_mov_b32_e32 v46, v38
	v_and_b32_e32 v49, 0xffff0000, v71
	v_mov_b32_e32 v47, v36
	v_pk_mul_f32 v[46:47], v[46:47], v[178:179]
	s_nop 0
	v_add_f32_e32 v36, v47, v48
	v_add_f32_e32 v38, v46, v36
	v_mov_b32_e32 v36, v39
	v_pk_mul_f32 v[36:37], v[36:37], v[178:179]
	s_nop 0
	v_add_f32_e32 v37, v37, v49
	v_add_f32_e32 v36, v36, v37
	v_mul_f32_e32 v37, v36, v36
	v_fmac_f32_e32 v37, v38, v38
	v_add_f32_e32 v37, v43, v37
	v_cvt_pk_bf16_f32 v43, v38, v36
	ds_bpermute_b32 v46, v0, v37
	v_lshlrev_b32_e32 v39, 16, v43
	v_sub_f32_e32 v38, v38, v39
	v_and_b32_e32 v39, 0xffff0000, v43
	v_sub_f32_e32 v36, v36, v39
	v_mul_f32_e32 v38, 0x43800000, v38
	v_mul_f32_e32 v36, 0x43800000, v36
	v_med3_f32 v38, v38, s68, v235
	v_med3_f32 v36, v36, s68, v235
	v_cvt_pk_fp8_f32 v45, v38, v36 op_sel:[0,0,1]
	s_waitcnt lgkmcnt(0)
	v_add_f32_e32 v36, v37, v46
	ds_bpermute_b32 v37, v176, v36
	global_store_dwordx4 v[86:87], v[40:43], off sc1
	global_store_dwordx2 v[88:89], v[44:45], off
	s_and_saveexec_b64 s[2:3], s[38:39]
	s_cbranch_execz .LBB0_1006
	s_waitcnt lgkmcnt(0)
	v_add_f32_e32 v38, v36, v37
	s_lshl_b32 s20, s58, 2
	v_lshlrev_b64 v[36:37], 7, v[84:85]
	s_ashr_i32 s21, s20, 31
	v_lshl_add_u64 v[36:37], s[46:47], 0, v[36:37]
	v_lshl_add_u64 v[36:37], s[20:21], 2, v[36:37]
	s_lshl_b32 s18, s37, 2
	v_lshl_add_u64 v[36:37], v[36:37], 0, s[18:19]
	global_store_dword v[36:37], v38, off
;     __device__ __forceinline__ void core(const f32x4 (&acc)[2][2][4][2], const Unit& u, int wr, int wc, int fr, int fq, const float (&rsc)[2][4]) const {
;     ...
;         for (int ai = 0; ai < 2; ++ai)
; #pragma unroll
;         for (int mh = 0; mh < 4; mh += MB) {
;             u32x4 va[MB][2]; u32x2 vb[MB][2];
;             f32x4 xa[MB][2], xb[MB][2];
; #pragma unroll
;             for (int m = 0; m < MB; ++m)
; #pragma unroll
;                 for (int bj = 0; bj < 2; ++bj) { const size_t idx = (size_t)(row0 + ai * HALF + (mh + m) * 16) * D + col0 + bj * HALF;
;                     if (F32IN) { xa[m][bj] = *(const f32x4*)(Xin + idx); xb[m][bj] = *(const f32x4*)(Xin + idx + 4); }
;                     else { va[m][bj] = *(const u32x4*)(Hb + idx); vb[m][bj] = *(const u32x2*)(Hl + idx); } }
; #pragma unroll
;             for (int m = 0; m < MB; ++m) { const int row = row0 + ai * HALF + (mh + m) * 16; float sq = 0.f;
;                 const float rs1 = rsc[ai][mh + m];
; #pragma unroll
;                 for (int bj = 0; bj < 2; ++bj) { const size_t idx = (size_t)row * D + col0 + bj * HALF;
;                     unsigned hw[4]; int lw[2] = {0, 0};
; #pragma unroll
;                     for (int pq = 0; pq < 4; ++pq) {
;                         float h0, h1;
;                         if (F32IN) { h0 = (pq < 2) ? xa[m][bj][2 * pq] : xb[m][bj][2 * pq - 4]; h1 = (pq < 2) ? xa[m][bj][2 * pq + 1] : xb[m][bj][2 * pq - 3]; }
;                         else { const unsigned a = va[m][bj][pq]; const int bw = (int)vb[m][bj][pq >> 1]; const hf32x2 lp = (pq & 1) ? __builtin_amdgcn_cvt_pk_f32_fp8(bw, true) : __builtin_amdgcn_cvt_pk_f32_fp8(bw, false);
;                             h0 = __uint_as_float(a << 16) + lp.x * 0.00390625f; h1 = __uint_as_float(a & 0xffff0000u) + lp.y * 0.00390625f; }
;                         const float o0 = h0 + acc[ai][bj][mh + m][pq >> 1][(2 * pq) & 3] * rs1, o1 = h1 + acc[ai][bj][mh + m][pq >> 1][(2 * pq + 1) & 3] * rs1;
;                         sq += o0 * o0 + o1 * o1;
;                         const unsigned hi = cvt_pk_bf16(o0, o1);
;                         hw[pq] = hi;
;                         const float r0 = __builtin_amdgcn_fmed3f((o0 - __uint_as_float(hi << 16)) * 256.0f, -448.0f, 448.0f), r1 = __builtin_amdgcn_fmed3f((o1 - __uint_as_float(hi & 0xffff0000u)) * 256.0f, -448.0f, 448.0f);
.LBB0_1006:
	s_or_b64 exec, exec, s[2:3]
	v_add_u32_e32 v66, 0xa0, v156
	v_ashrrev_i32_e32 v67, 31, v66
	s_waitcnt lgkmcnt(0)
	v_lshlrev_b64 v[36:37], 11, v[66:67]
	v_lshl_add_u64 v[36:37], v[36:37], 0, v[154:155]
	v_lshl_add_u64 v[74:75], v[36:37], 1, s[42:43]
	v_lshl_add_u64 v[76:77], s[44:45], 0, v[36:37]
	global_load_dwordx4 v[48:51], v[74:75], off
	global_load_dwordx2 v[78:79], v[76:77], off
	v_or_b32_e32 v36, 0x80, v36
	v_lshl_add_u64 v[68:69], v[36:37], 1, s[42:43]
	v_lshl_add_u64 v[70:71], s[44:45], 0, v[36:37]
	global_load_dwordx4 v[44:47], v[68:69], off
	global_load_dwordx2 v[72:73], v[70:71], off
	v_add_u32_e32 v52, 0xb0, v156
	v_ashrrev_i32_e32 v53, 31, v52
	v_lshlrev_b64 v[36:37], 11, v[52:53]
	v_lshl_add_u64 v[56:57], v[36:37], 0, v[154:155]
	v_mov_b32_e32 v82, v32
	v_mov_b32_e32 v178, v2
	v_lshl_add_u64 v[60:61], v[56:57], 1, s[42:43]
	v_lshl_add_u64 v[62:63], s[44:45], 0, v[56:57]
	v_or_b32_e32 v56, 0x80, v56
	v_lshl_add_u64 v[54:55], v[56:57], 1, s[42:43]
	v_lshl_add_u64 v[56:57], s[44:45], 0, v[56:57]
	global_load_dwordx4 v[40:43], v[60:61], off
	global_load_dwordx2 v[64:65], v[62:63], off
	global_load_dwordx4 v[36:39], v[54:55], off
	global_load_dwordx2 v[58:59], v[56:57], off
	s_waitcnt vmcnt(7)
	v_lshlrev_b32_e32 v84, 16, v48
	s_waitcnt vmcnt(6)
	v_cvt_pk_f32_fp8_e32 v[80:81], v78
	v_and_b32_e32 v48, 0xffff0000, v48
	v_mov_b32_e32 v83, v80
	v_mov_b32_e32 v80, v33
	v_pk_mul_f32 v[82:83], v[82:83], v[178:179]
	v_pk_mul_f32 v[32:33], v[80:81], v[178:179]
	v_add_f32_e32 v2, v83, v84
	v_add_f32_e32 v33, v33, v48
	v_add_f32_e32 v2, v82, v2
	v_add_f32_e32 v33, v32, v33
	v_cvt_pk_bf16_f32 v32, v2, v33
	v_cvt_pk_f32_fp8_sdwa v[80:81], v78 src0_sel:WORD_1
	v_and_b32_e32 v48, 0xffff0000, v32
	v_mul_f32_e32 v84, v33, v33
	v_sub_f32_e32 v33, v33, v48
	v_lshlrev_b32_e32 v48, 16, v32
	v_fmac_f32_e32 v84, v2, v2
	v_sub_f32_e32 v2, v2, v48
	v_mul_f32_e32 v33, 0x43800000, v33
	v_mul_f32_e32 v2, 0x43800000, v2
	v_med3_f32 v33, v33, s68, v235
	v_med3_f32 v2, v2, s68, v235
	v_mov_b32_e32 v48, v1
	v_mov_b32_e32 v83, v80
	v_mov_b32_e32 v80, v35
	v_cvt_pk_fp8_f32 v48, v2, v33
	v_and_b32_e32 v33, 0xffff0000, v49
	v_mov_b32_e32 v82, v34
	v_pk_mul_f32 v[34:35], v[80:81], v[178:179]
	v_lshlrev_b32_e32 v2, 16, v49
	v_pk_mul_f32 v[82:83], v[82:83], v[178:179]
	v_add_f32_e32 v33, v35, v33
	v_add_f32_e32 v2, v83, v2
	v_add_f32_e32 v34, v34, v33
	v_add_f32_e32 v2, v82, v2
	v_mul_f32_e32 v33, v34, v34
	v_fmac_f32_e32 v33, v2, v2
	v_add_f32_e32 v49, v84, v33
	v_cvt_pk_bf16_f32 v33, v2, v34
	v_mov_b32_e32 v80, v28
	v_lshlrev_b32_e32 v35, 16, v33
	v_sub_f32_e32 v2, v2, v35
	v_and_b32_e32 v35, 0xffff0000, v33
	v_sub_f32_e32 v34, v34, v35
	v_mul_f32_e32 v2, 0x43800000, v2
	v_mul_f32_e32 v34, 0x43800000, v34
	v_med3_f32 v2, v2, s68, v235
	v_med3_f32 v34, v34, s68, v235
	v_cvt_pk_fp8_f32 v48, v2, v34 op_sel:[0,0,1]
	v_cvt_pk_f32_fp8_e32 v[34:35], v79
	v_lshlrev_b32_e32 v2, 16, v50
	v_and_b32_e32 v50, 0xffff0000, v50
	v_and_b32_e32 v78, 0xffff0000, v51
	v_mov_b32_e32 v81, v34
	v_mov_b32_e32 v34, v29
	v_pk_mul_f32 v[28:29], v[34:35], v[178:179]
	v_pk_mul_f32 v[80:81], v[80:81], v[178:179]
	v_add_f32_e32 v29, v29, v50
	v_add_f32_e32 v2, v81, v2
	v_add_f32_e32 v28, v28, v29
	v_add_f32_e32 v2, v80, v2
	v_mul_f32_e32 v29, v28, v28
	v_fmac_f32_e32 v29, v2, v2
	v_add_f32_e32 v35, v49, v29
	v_cvt_pk_bf16_f32 v34, v2, v28
	v_mov_b32_e32 v49, v1
	v_and_b32_e32 v29, 0xffff0000, v34
	v_sub_f32_e32 v28, v28, v29
	v_lshlrev_b32_e32 v29, 16, v34
	v_sub_f32_e32 v2, v2, v29
	v_mul_f32_e32 v28, 0x43800000, v28
	v_mul_f32_e32 v2, 0x43800000, v2
	v_med3_f32 v28, v28, s68, v235
	v_med3_f32 v2, v2, s68, v235
	v_cvt_pk_fp8_f32 v49, v2, v28
	v_cvt_pk_f32_fp8_sdwa v[28:29], v79 src0_sel:WORD_1
	v_lshlrev_b32_e32 v2, 16, v51
	v_mov_b32_e32 v50, v30
	v_mov_b32_e32 v30, v24
	v_mov_b32_e32 v51, v28
	v_mov_b32_e32 v28, v31
	v_pk_mul_f32 v[28:29], v[28:29], v[178:179]
	v_pk_mul_f32 v[50:51], v[50:51], v[178:179]
	v_add_f32_e32 v29, v29, v78
	v_add_f32_e32 v2, v51, v2
	v_add_f32_e32 v28, v28, v29
	v_add_f32_e32 v2, v50, v2
	v_mul_f32_e32 v29, v28, v28
	v_fmac_f32_e32 v29, v2, v2
	v_add_f32_e32 v50, v35, v29
	v_cvt_pk_bf16_f32 v35, v2, v28
	s_nop 0
	v_lshlrev_b32_e32 v29, 16, v35
	v_sub_f32_e32 v2, v2, v29
	v_and_b32_e32 v29, 0xffff0000, v35
	v_sub_f32_e32 v28, v28, v29
	v_mul_f32_e32 v2, 0x43800000, v2
	v_mul_f32_e32 v28, 0x43800000, v28
	v_med3_f32 v2, v2, s68, v235
	v_med3_f32 v28, v28, s68, v235
	v_cvt_pk_fp8_f32 v49, v2, v28 op_sel:[0,0,1]
	s_waitcnt vmcnt(4)
; __device__ __forceinline__ unsigned cvt_pk_bf16(float lo, float hi) { unsigned r; asm volatile("v_cvt_pk_bf16_f32 %0, %1, %2" : "=v"(r) : "v"(lo), "v"(hi)); return r; }
;     __device__ __forceinline__ void core(const f32x4 (&acc)[2][2][4][2], const Unit& u, int wr, int wc, int fr, int fq, const float (&rsc)[2][4]) const {
;     ...
;                 for (int bj = 0; bj < 2; ++bj) { const size_t idx = (size_t)row * D + col0 + bj * HALF;
;                     unsigned hw[4]; int lw[2] = {0, 0};
; #pragma unroll
;                     for (int pq = 0; pq < 4; ++pq) {
;                         float h0, h1;
;                         if (F32IN) { h0 = (pq < 2) ? xa[m][bj][2 * pq] : xb[m][bj][2 * pq - 4]; h1 = (pq < 2) ? xa[m][bj][2 * pq + 1] : xb[m][bj][2 * pq - 3]; }
;                         else { const unsigned a = va[m][bj][pq]; const int bw = (int)vb[m][bj][pq >> 1]; const hf32x2 lp = (pq & 1) ? __builtin_amdgcn_cvt_pk_f32_fp8(bw, true) : __builtin_amdgcn_cvt_pk_f32_fp8(bw, false);
;                             h0 = __uint_as_float(a << 16) + lp.x * 0.00390625f; h1 = __uint_as_float(a & 0xffff0000u) + lp.y * 0.00390625f; }
;                         const float o0 = h0 + acc[ai][bj][mh + m][pq >> 1][(2 * pq) & 3] * rs1, o1 = h1 + acc[ai][bj][mh + m][pq >> 1][(2 * pq + 1) & 3] * rs1;
;                         sq += o0 * o0 + o1 * o1;
;                         const unsigned hi = cvt_pk_bf16(o0, o1);
;                         hw[pq] = hi;
;                         const float r0 = __builtin_amdgcn_fmed3f((o0 - __uint_as_float(hi << 16)) * 256.0f, -448.0f, 448.0f), r1 = __builtin_amdgcn_fmed3f((o1 - __uint_as_float(hi & 0xffff0000u)) * 256.0f, -448.0f, 448.0f);
;                         lw[pq >> 1] = (pq & 1) ? __builtin_amdgcn_cvt_pk_fp8_f32(r0, r1, lw[pq >> 1], true) : __builtin_amdgcn_cvt_pk_fp8_f32(r0, r1, lw[pq >> 1], false);
;                     }
;                     *(u32x4*)(Hb + idx) = (u32x4){hw[0], hw[1], hw[2], hw[3]}; *(u32x2*)(Hl + idx) = (u32x2){(unsigned)lw[0], (unsigned)lw[1]}; }
;                 sq += __shfl_xor(sq, 16); sq += __shfl_xor(sq, 32); if (fq == 0) ss[(size_t)row * 32 + u.pn * 4 + wc] = sq; }
	v_cvt_pk_f32_fp8_e32 v[28:29], v72
	global_store_dwordx4 v[74:75], v[32:35], off sc1
	global_store_dwordx2 v[76:77], v[48:49], off
	s_nop 0
	v_and_b32_e32 v32, 0xffff0000, v44
	v_mov_b32_e32 v31, v28
	v_mov_b32_e32 v28, v25
	v_pk_mul_f32 v[24:25], v[28:29], v[178:179]
	v_lshlrev_b32_e32 v2, 16, v44
	v_pk_mul_f32 v[30:31], v[30:31], v[178:179]
	v_add_f32_e32 v25, v25, v32
	v_add_f32_e32 v2, v31, v2
	v_add_f32_e32 v25, v24, v25
	v_add_f32_e32 v2, v30, v2
	v_mul_f32_e32 v24, v25, v25
	v_fmac_f32_e32 v24, v2, v2
	v_add_f32_e32 v29, v50, v24
	v_cvt_pk_bf16_f32 v24, v2, v25
	v_cvt_pk_f32_fp8_sdwa v[30:31], v72 src0_sel:WORD_1
	v_and_b32_e32 v28, 0xffff0000, v24
	v_sub_f32_e32 v25, v25, v28
	v_lshlrev_b32_e32 v28, 16, v24
	v_sub_f32_e32 v2, v2, v28
	v_mul_f32_e32 v25, 0x43800000, v25
	v_mul_f32_e32 v2, 0x43800000, v2
	v_med3_f32 v25, v25, s68, v235
	v_med3_f32 v2, v2, s68, v235
	v_mov_b32_e32 v28, v1
	v_mov_b32_e32 v33, v30
	v_mov_b32_e32 v30, v27
	v_cvt_pk_fp8_f32 v28, v2, v25
	v_and_b32_e32 v25, 0xffff0000, v45
	v_mov_b32_e32 v32, v26
	v_pk_mul_f32 v[26:27], v[30:31], v[178:179]
	v_lshlrev_b32_e32 v2, 16, v45
	v_pk_mul_f32 v[32:33], v[32:33], v[178:179]
	v_add_f32_e32 v25, v27, v25
	v_add_f32_e32 v2, v33, v2
	v_add_f32_e32 v26, v26, v25
	v_add_f32_e32 v2, v32, v2
	v_mul_f32_e32 v25, v26, v26
	v_fmac_f32_e32 v25, v2, v2
	v_add_f32_e32 v29, v29, v25
	v_cvt_pk_bf16_f32 v25, v2, v26
	v_and_b32_e32 v32, 0xffff0000, v46
	v_lshlrev_b32_e32 v27, 16, v25
	v_sub_f32_e32 v2, v2, v27
	v_and_b32_e32 v27, 0xffff0000, v25
	v_sub_f32_e32 v26, v26, v27
	v_mul_f32_e32 v2, 0x43800000, v2
	v_mul_f32_e32 v26, 0x43800000, v26
	v_med3_f32 v2, v2, s68, v235
	v_med3_f32 v26, v26, s68, v235
	v_cvt_pk_fp8_f32 v28, v2, v26 op_sel:[0,0,1]
	v_cvt_pk_f32_fp8_e32 v[26:27], v73
	v_mov_b32_e32 v30, v20
	v_lshlrev_b32_e32 v2, 16, v46
	v_mov_b32_e32 v31, v26
	v_mov_b32_e32 v26, v21
	v_pk_mul_f32 v[20:21], v[26:27], v[178:179]
	v_pk_mul_f32 v[30:31], v[30:31], v[178:179]
	v_add_f32_e32 v21, v21, v32
	v_add_f32_e32 v2, v31, v2
	v_add_f32_e32 v20, v20, v21
	v_add_f32_e32 v2, v30, v2
	v_mul_f32_e32 v21, v20, v20
	v_fmac_f32_e32 v21, v2, v2
	v_add_f32_e32 v27, v29, v21
	v_cvt_pk_bf16_f32 v26, v2, v20
	v_mov_b32_e32 v29, v1
	v_and_b32_e32 v21, 0xffff0000, v26
	v_sub_f32_e32 v20, v20, v21
	v_lshlrev_b32_e32 v21, 16, v26
	v_sub_f32_e32 v2, v2, v21
	v_mul_f32_e32 v20, 0x43800000, v20
	v_mul_f32_e32 v2, 0x43800000, v2
	v_med3_f32 v20, v20, s68, v235
	v_med3_f32 v2, v2, s68, v235
	v_cvt_pk_fp8_f32 v29, v2, v20
	v_cvt_pk_f32_fp8_sdwa v[20:21], v73 src0_sel:WORD_1
	v_and_b32_e32 v32, 0xffff0000, v47
	v_mov_b32_e32 v30, v22
	v_lshlrev_b32_e32 v2, 16, v47
	v_mov_b32_e32 v31, v20
	v_mov_b32_e32 v20, v23
	v_pk_mul_f32 v[20:21], v[20:21], v[178:179]
	v_pk_mul_f32 v[30:31], v[30:31], v[178:179]
	v_add_f32_e32 v21, v21, v32
	v_add_f32_e32 v2, v31, v2
	v_add_f32_e32 v20, v20, v21
	v_add_f32_e32 v2, v30, v2
	v_mul_f32_e32 v21, v20, v20
	v_fmac_f32_e32 v21, v2, v2
	v_add_f32_e32 v21, v27, v21
	v_cvt_pk_bf16_f32 v27, v2, v20
	s_nop 0
	v_lshlrev_b32_e32 v22, 16, v27
	v_sub_f32_e32 v2, v2, v22
	v_and_b32_e32 v22, 0xffff0000, v27
	v_sub_f32_e32 v20, v20, v22
	v_mul_f32_e32 v2, 0x43800000, v2
	v_mul_f32_e32 v20, 0x43800000, v20
	v_med3_f32 v2, v2, s68, v235
	v_med3_f32 v20, v20, s68, v235
	v_cvt_pk_fp8_f32 v29, v2, v20 op_sel:[0,0,1]
	ds_bpermute_b32 v2, v0, v21
	global_store_dwordx4 v[68:69], v[24:27], off sc1
	global_store_dwordx2 v[70:71], v[28:29], off
	s_waitcnt lgkmcnt(0)
	v_add_f32_e32 v2, v21, v2
	ds_bpermute_b32 v20, v176, v2
	s_and_saveexec_b64 s[2:3], s[38:39]
	s_cbranch_execz .LBB0_1008
	s_waitcnt lgkmcnt(0)
	v_add_f32_e32 v2, v2, v20
	s_lshl_b32 s20, s58, 2
	v_lshlrev_b64 v[20:21], 7, v[66:67]
	s_ashr_i32 s21, s20, 31
	v_lshl_add_u64 v[20:21], s[46:47], 0, v[20:21]
	v_lshl_add_u64 v[20:21], s[20:21], 2, v[20:21]
	s_lshl_b32 s18, s37, 2
	v_lshl_add_u64 v[20:21], v[20:21], 0, s[18:19]
	global_store_dword v[20:21], v2, off
.LBB0_1008:
	s_or_b64 exec, exec, s[2:3]
	s_waitcnt vmcnt(6) lgkmcnt(0)
	v_cvt_pk_f32_fp8_e32 v[20:21], v64
	v_mov_b32_e32 v22, v16
	v_mov_b32_e32 v178, v3
	v_lshlrev_b32_e32 v24, 16, v40
	v_mov_b32_e32 v23, v20
	v_pk_mul_f32 v[2:3], v[22:23], v[178:179]
	v_mov_b32_e32 v20, v17
	v_add_f32_e32 v3, v3, v24
	v_and_b32_e32 v25, 0xffff0000, v40
	v_add_f32_e32 v22, v2, v3
	v_pk_mul_f32 v[2:3], v[20:21], v[178:179]
	v_and_b32_e32 v24, 0xffff0000, v41
	v_add_f32_e32 v3, v3, v25
	v_add_f32_e32 v2, v2, v3
	v_cvt_pk_bf16_f32 v16, v22, v2
	v_mul_f32_e32 v3, v2, v2
	v_and_b32_e32 v17, 0xffff0000, v16
	v_sub_f32_e32 v2, v2, v17
	v_mul_f32_e32 v2, 0x43800000, v2
	v_med3_f32 v17, v2, s68, v235
	v_lshlrev_b32_e32 v2, 16, v16
	v_sub_f32_e32 v2, v22, v2
	v_mul_f32_e32 v2, 0x43800000, v2
	v_med3_f32 v20, v2, s68, v235
	v_mov_b32_e32 v2, v1
	v_cvt_pk_fp8_f32 v2, v20, v17
	v_cvt_pk_f32_fp8_sdwa v[20:21], v64 src0_sel:WORD_1
	v_fmac_f32_e32 v3, v22, v22
	v_mov_b32_e32 v22, v18
	v_lshlrev_b32_e32 v17, 16, v41
	v_mov_b32_e32 v23, v20
	v_pk_mul_f32 v[22:23], v[22:23], v[178:179]
	v_mov_b32_e32 v20, v19
	v_add_f32_e32 v17, v23, v17
	v_pk_mul_f32 v[18:19], v[20:21], v[178:179]
	v_add_f32_e32 v22, v22, v17
	v_add_f32_e32 v17, v19, v24
	v_add_f32_e32 v18, v18, v17
	v_mul_f32_e32 v17, v18, v18
	v_fmac_f32_e32 v17, v22, v22
	v_add_f32_e32 v3, v3, v17
	v_cvt_pk_bf16_f32 v17, v22, v18
	v_and_b32_e32 v23, 0xffff0000, v42
	v_lshlrev_b32_e32 v19, 16, v17
	v_and_b32_e32 v20, 0xffff0000, v17
	v_sub_f32_e32 v19, v22, v19
	v_sub_f32_e32 v18, v18, v20
	v_mul_f32_e32 v19, 0x43800000, v19
	v_mul_f32_e32 v18, 0x43800000, v18
; __device__ __forceinline__ unsigned cvt_pk_bf16(float lo, float hi) { unsigned r; asm volatile("v_cvt_pk_bf16_f32 %0, %1, %2" : "=v"(r) : "v"(lo), "v"(hi)); return r; }
;     __device__ __forceinline__ void core(const f32x4 (&acc)[2][2][4][2], const Unit& u, int wr, int wc, int fr, int fq, const float (&rsc)[2][4]) const {
;     ...
;                 for (int bj = 0; bj < 2; ++bj) { const size_t idx = (size_t)row * D + col0 + bj * HALF;
;                     unsigned hw[4]; int lw[2] = {0, 0};
; #pragma unroll
;                     for (int pq = 0; pq < 4; ++pq) {
;                         float h0, h1;
;                         if (F32IN) { h0 = (pq < 2) ? xa[m][bj][2 * pq] : xb[m][bj][2 * pq - 4]; h1 = (pq < 2) ? xa[m][bj][2 * pq + 1] : xb[m][bj][2 * pq - 3]; }
;                         else { const unsigned a = va[m][bj][pq]; const int bw = (int)vb[m][bj][pq >> 1]; const hf32x2 lp = (pq & 1) ? __builtin_amdgcn_cvt_pk_f32_fp8(bw, true) : __builtin_amdgcn_cvt_pk_f32_fp8(bw, false);
;                             h0 = __uint_as_float(a << 16) + lp.x * 0.00390625f; h1 = __uint_as_float(a & 0xffff0000u) + lp.y * 0.00390625f; }
;                         const float o0 = h0 + acc[ai][bj][mh + m][pq >> 1][(2 * pq) & 3] * rs1, o1 = h1 + acc[ai][bj][mh + m][pq >> 1][(2 * pq + 1) & 3] * rs1;
;                         sq += o0 * o0 + o1 * o1;
;                         const unsigned hi = cvt_pk_bf16(o0, o1);
;                         hw[pq] = hi;
;                         const float r0 = __builtin_amdgcn_fmed3f((o0 - __uint_as_float(hi << 16)) * 256.0f, -448.0f, 448.0f), r1 = __builtin_amdgcn_fmed3f((o1 - __uint_as_float(hi & 0xffff0000u)) * 256.0f, -448.0f, 448.0f);
;                         lw[pq >> 1] = (pq & 1) ? __builtin_amdgcn_cvt_pk_fp8_f32(r0, r1, lw[pq >> 1], true) : __builtin_amdgcn_cvt_pk_fp8_f32(r0, r1, lw[pq >> 1], false);
;                     }
;                     *(u32x4*)(Hb + idx) = (u32x4){hw[0], hw[1], hw[2], hw[3]}; *(u32x2*)(Hl + idx) = (u32x2){(unsigned)lw[0], (unsigned)lw[1]}; }
;                 sq += __shfl_xor(sq, 16); sq += __shfl_xor(sq, 32); if (fq == 0) ss[(size_t)row * 32 + u.pn * 4 + wc] = sq; }
	v_med3_f32 v19, v19, s68, v235
	v_med3_f32 v18, v18, s68, v235
	v_cvt_pk_fp8_f32 v2, v19, v18 op_sel:[0,0,1]
	v_cvt_pk_f32_fp8_e32 v[18:19], v65
	v_mov_b32_e32 v20, v12
	v_lshlrev_b32_e32 v22, 16, v42
	v_mov_b32_e32 v21, v18
	v_pk_mul_f32 v[20:21], v[20:21], v[178:179]
	v_mov_b32_e32 v18, v13
	v_add_f32_e32 v12, v21, v22
	v_add_f32_e32 v20, v20, v12
	v_pk_mul_f32 v[12:13], v[18:19], v[178:179]
	v_lshlrev_b32_e32 v19, 16, v43
	v_add_f32_e32 v13, v13, v23
	v_add_f32_e32 v12, v12, v13
	v_mul_f32_e32 v13, v12, v12
	v_fmac_f32_e32 v13, v20, v20
	v_add_f32_e32 v22, v3, v13
	v_cvt_pk_bf16_f32 v18, v20, v12
	v_and_b32_e32 v23, 0xffff0000, v43
	v_and_b32_e32 v3, 0xffff0000, v18
	v_sub_f32_e32 v3, v12, v3
	v_mul_f32_e32 v3, 0x43800000, v3
	v_med3_f32 v12, v3, s68, v235
	v_lshlrev_b32_e32 v3, 16, v18
	v_sub_f32_e32 v3, v20, v3
	v_mul_f32_e32 v3, 0x43800000, v3
	v_med3_f32 v13, v3, s68, v235
	v_mov_b32_e32 v3, v1
	v_cvt_pk_fp8_f32 v3, v13, v12
	v_cvt_pk_f32_fp8_sdwa v[12:13], v65 src0_sel:WORD_1
	v_mov_b32_e32 v20, v14
	v_mov_b32_e32 v21, v12
	v_pk_mul_f32 v[20:21], v[20:21], v[178:179]
	s_nop 0
	v_add_f32_e32 v12, v21, v19
	v_add_f32_e32 v14, v20, v12
	v_mov_b32_e32 v12, v15
	v_pk_mul_f32 v[12:13], v[12:13], v[178:179]
	s_nop 0
	v_add_f32_e32 v13, v13, v23
	v_add_f32_e32 v12, v12, v13
	v_cvt_pk_bf16_f32 v19, v14, v12
	v_mul_f32_e32 v13, v12, v12
	v_lshlrev_b32_e32 v15, 16, v19
	v_and_b32_e32 v20, 0xffff0000, v19
	v_sub_f32_e32 v15, v14, v15
	v_sub_f32_e32 v12, v12, v20
	v_mul_f32_e32 v15, 0x43800000, v15
	v_mul_f32_e32 v12, 0x43800000, v12
	v_med3_f32 v15, v15, s68, v235
	v_med3_f32 v12, v12, s68, v235
	v_cvt_pk_fp8_f32 v3, v15, v12 op_sel:[0,0,1]
	global_store_dwordx4 v[60:61], v[16:19], off sc1
	global_store_dwordx2 v[62:63], v[2:3], off
	s_waitcnt vmcnt(6)
	v_cvt_pk_f32_fp8_e32 v[2:3], v58
	v_fmac_f32_e32 v13, v14, v14
	v_add_f32_e32 v14, v22, v13
	v_mov_b32_e32 v12, v8
	v_mov_b32_e32 v13, v2
	v_lshlrev_b32_e32 v15, 16, v36
	v_pk_mul_f32 v[12:13], v[12:13], v[178:179]
	v_and_b32_e32 v16, 0xffff0000, v36
	v_add_f32_e32 v2, v13, v15
	v_add_f32_e32 v12, v12, v2
	v_mov_b32_e32 v2, v9
	v_pk_mul_f32 v[2:3], v[2:3], v[178:179]
	v_lshlrev_b32_e32 v13, 16, v37
	v_add_f32_e32 v3, v3, v16
	v_add_f32_e32 v2, v2, v3
	v_mul_f32_e32 v3, v2, v2
	v_fmac_f32_e32 v3, v12, v12
	v_add_f32_e32 v9, v14, v3
	v_cvt_pk_bf16_f32 v8, v12, v2
	v_mov_b32_e32 v14, v10
	v_and_b32_e32 v3, 0xffff0000, v8
	v_sub_f32_e32 v2, v2, v3
	v_lshlrev_b32_e32 v3, 16, v8
	v_sub_f32_e32 v3, v12, v3
	v_mul_f32_e32 v2, 0x43800000, v2
	v_mul_f32_e32 v3, 0x43800000, v3
	v_med3_f32 v2, v2, s68, v235
	v_med3_f32 v3, v3, s68, v235
	v_mov_b32_e32 v12, v1
	v_cvt_pk_fp8_f32 v12, v3, v2
	v_cvt_pk_f32_fp8_sdwa v[2:3], v58 src0_sel:WORD_1
	v_and_b32_e32 v16, 0xffff0000, v37
	v_mov_b32_e32 v15, v2
	v_pk_mul_f32 v[14:15], v[14:15], v[178:179]
	s_nop 0
	v_add_f32_e32 v2, v15, v13
	v_add_f32_e32 v10, v14, v2
	v_mov_b32_e32 v2, v11
	v_pk_mul_f32 v[2:3], v[2:3], v[178:179]
	v_lshlrev_b32_e32 v14, 16, v38
	v_add_f32_e32 v3, v3, v16
	v_add_f32_e32 v2, v2, v3
	v_mul_f32_e32 v3, v2, v2
	v_fmac_f32_e32 v3, v10, v10
	v_add_f32_e32 v13, v9, v3
	v_cvt_pk_bf16_f32 v9, v10, v2
	v_and_b32_e32 v15, 0xffff0000, v38
	v_lshlrev_b32_e32 v3, 16, v9
	v_sub_f32_e32 v3, v10, v3
	v_and_b32_e32 v10, 0xffff0000, v9
	v_sub_f32_e32 v2, v2, v10
	v_mul_f32_e32 v3, 0x43800000, v3
	v_mul_f32_e32 v2, 0x43800000, v2
	v_med3_f32 v3, v3, s68, v235
	v_med3_f32 v2, v2, s68, v235
	v_cvt_pk_fp8_f32 v12, v3, v2 op_sel:[0,0,1]
	v_cvt_pk_f32_fp8_e32 v[2:3], v59
	v_mov_b32_e32 v10, v4
	v_mov_b32_e32 v11, v2
	v_pk_mul_f32 v[10:11], v[10:11], v[178:179]
	s_nop 0
	v_add_f32_e32 v2, v11, v14
	v_add_f32_e32 v4, v10, v2
	v_mov_b32_e32 v2, v5
	v_pk_mul_f32 v[2:3], v[2:3], v[178:179]
	v_lshlrev_b32_e32 v14, 16, v39
	v_add_f32_e32 v3, v3, v15
	v_add_f32_e32 v2, v2, v3
	v_mul_f32_e32 v3, v2, v2
	v_fmac_f32_e32 v3, v4, v4
	v_add_f32_e32 v11, v13, v3
	v_cvt_pk_bf16_f32 v10, v4, v2
	v_mov_b32_e32 v13, v1
	v_and_b32_e32 v3, 0xffff0000, v10
	v_sub_f32_e32 v2, v2, v3
	v_lshlrev_b32_e32 v3, 16, v10
	v_sub_f32_e32 v3, v4, v3
	v_mul_f32_e32 v2, 0x43800000, v2
	v_mul_f32_e32 v3, 0x43800000, v3
	v_med3_f32 v2, v2, s68, v235
	v_med3_f32 v3, v3, s68, v235
	v_cvt_pk_fp8_f32 v13, v3, v2
	v_cvt_pk_f32_fp8_sdwa v[2:3], v59 src0_sel:WORD_1
	v_mov_b32_e32 v4, v6
	v_and_b32_e32 v15, 0xffff0000, v39
	v_mov_b32_e32 v5, v2
	v_pk_mul_f32 v[4:5], v[4:5], v[178:179]
	s_nop 0
	v_add_f32_e32 v2, v5, v14
	v_add_f32_e32 v4, v4, v2
	v_mov_b32_e32 v2, v7
	v_pk_mul_f32 v[2:3], v[2:3], v[178:179]
	s_nop 0
	v_add_f32_e32 v3, v3, v15
	v_add_f32_e32 v2, v2, v3
	v_mul_f32_e32 v3, v2, v2
	v_fmac_f32_e32 v3, v4, v4
	v_add_f32_e32 v3, v11, v3
	ds_bpermute_b32 v0, v0, v3
	v_cvt_pk_bf16_f32 v11, v4, v2
	s_waitcnt lgkmcnt(0)
	v_add_f32_e32 v0, v3, v0
	v_lshlrev_b32_e32 v5, 16, v11
	v_sub_f32_e32 v4, v4, v5
	v_and_b32_e32 v5, 0xffff0000, v11
	v_sub_f32_e32 v2, v2, v5
	v_mul_f32_e32 v4, 0x43800000, v4
	v_mul_f32_e32 v2, 0x43800000, v2
	v_med3_f32 v4, v4, s68, v235
	v_med3_f32 v2, v2, s68, v235
	v_cvt_pk_fp8_f32 v13, v4, v2 op_sel:[0,0,1]
	ds_bpermute_b32 v2, v176, v0
	global_store_dwordx4 v[54:55], v[8:11], off sc1
	global_store_dwordx2 v[56:57], v[12:13], off
	s_and_saveexec_b64 s[2:3], s[38:39]
	s_cbranch_execz .LBB0_1010
	s_waitcnt lgkmcnt(0)
	v_add_f32_e32 v0, v0, v2
	s_lshl_b32 s20, s58, 2
	v_lshlrev_b64 v[2:3], 7, v[52:53]
	s_ashr_i32 s21, s20, 31
	v_lshl_add_u64 v[2:3], s[46:47], 0, v[2:3]
	v_lshl_add_u64 v[2:3], s[20:21], 2, v[2:3]
	s_lshl_b32 s18, s37, 2
	v_lshl_add_u64 v[2:3], v[2:3], 0, s[18:19]
	global_store_dword v[2:3], v0, off

; __device__ __forceinline__ unsigned cvt_pk_bf16(float lo, float hi) { unsigned r; asm volatile("v_cvt_pk_bf16_f32 %0, %1, %2" : "=v"(r) : "v"(lo), "v"(hi)); return r; }
;     __device__ __forceinline__ void core(const f32x4 (&acc)[2][2][4][2], const Unit& u, int wr, int wc, int fr, int fq, const float (&rsc)[2][4]) const {
;         const int row0 = u.pm * BM + wr * 64 + fr, col0 = u.pn * BM + wc * 32 + 8 * fq;
; #pragma unroll
;         for (int ai = 0; ai < 2; ++ai)
; #pragma unroll
;         for (int mh = 0; mh < 4; mh += MB) {
;             u32x4 va[MB][2]; u32x2 vb[MB][2];
;             f32x4 xa[MB][2], xb[MB][2];
; #pragma unroll
;             for (int m = 0; m < MB; ++m)
; #pragma unroll
;                 for (int bj = 0; bj < 2; ++bj) { const size_t idx = (size_t)(row0 + ai * HALF + (mh + m) * 16) * D + col0 + bj * HALF;
;                     if (F32IN) { xa[m][bj] = *(const f32x4*)(Xin + idx); xb[m][bj] = *(const f32x4*)(Xin + idx + 4); }
;                     else { va[m][bj] = *(const u32x4*)(Hb + idx); vb[m][bj] = *(const u32x2*)(Hl + idx); } }
; #pragma unroll
;             for (int m = 0; m < MB; ++m) { const int row = row0 + ai * HALF + (mh + m) * 16; float sq = 0.f;
;                 const float rs1 = rsc[ai][mh + m];
; #pragma unroll
;                 for (int bj = 0; bj < 2; ++bj) { const size_t idx = (size_t)row * D + col0 + bj * HALF;
;                     unsigned hw[4]; int lw[2] = {0, 0};
; #pragma unroll
;                     for (int pq = 0; pq < 4; ++pq) {
;                         float h0, h1;
;                         if (F32IN) { h0 = (pq < 2) ? xa[m][bj][2 * pq] : xb[m][bj][2 * pq - 4]; h1 = (pq < 2) ? xa[m][bj][2 * pq + 1] : xb[m][bj][2 * pq - 3]; }
;                         else { const unsigned a = va[m][bj][pq]; const int bw = (int)vb[m][bj][pq >> 1]; const hf32x2 lp = (pq & 1) ? __builtin_amdgcn_cvt_pk_f32_fp8(bw, true) : __builtin_amdgcn_cvt_pk_f32_fp8(bw, false);
;                             h0 = __uint_as_float(a << 16) + lp.x * 0.00390625f; h1 = __uint_as_float(a & 0xffff0000u) + lp.y * 0.00390625f; }
;                         const float o0 = h0 + acc[ai][bj][mh + m][pq >> 1][(2 * pq) & 3] * rs1, o1 = h1 + acc[ai][bj][mh + m][pq >> 1][(2 * pq + 1) & 3] * rs1;
;                         sq += o0 * o0 + o1 * o1;
;                         const unsigned hi = cvt_pk_bf16(o0, o1);
;                         hw[pq] = hi;
.LBB0_1040:
	v_lshl_add_u32 v164, s12, 8, v183
	v_lshl_or_b32 v162, s56, 8, v189
	v_ashrrev_i32_e32 v163, 31, v162
	v_ashrrev_i32_e32 v165, 31, v164
	v_lshl_add_u64 v[166:167], v[162:163], 2, s[28:29]
	v_lshlrev_b64 v[2:3], 13, v[164:165]
	v_lshl_add_u64 v[132:133], v[166:167], 0, v[2:3]
	global_load_dwordx4 v[184:187], v[132:133], off
	global_load_dwordx4 v[192:195], v[132:133], off offset:16
	global_load_dwordx4 v[196:199], v[132:133], off offset:512
	s_add_i32 s18, s18, s65
	v_lshl_add_u32 v0, v178, 2, s18
	v_add_u32_e32 v0, 0xc00, v0
	ds_read2_b32 v[174:175], v0 offset1:16
	ds_read2_b32 v[170:171], v0 offset0:32 offset1:48
	ds_read2_b32 v[168:169], v0 offset0:128 offset1:144
	ds_read2_b32 v[2:3], v0 offset0:160 offset1:176
	global_load_dwordx4 v[200:203], v[132:133], off offset:528
	v_or_b32_e32 v172, 16, v164
	v_ashrrev_i32_e32 v173, 31, v172
	v_lshlrev_b64 v[136:137], 13, v[172:173]
	v_lshlrev_b64 v[134:135], 11, v[164:165]
	v_lshl_add_u64 v[136:137], v[166:167], 0, v[136:137]
	v_lshl_add_u64 v[204:205], v[134:135], 0, v[162:163]
	global_load_dwordx4 v[140:143], v[136:137], off offset:16
	global_load_dwordx4 v[144:147], v[136:137], off
	global_load_dwordx4 v[132:135], v[136:137], off offset:528
	s_nop 0
	global_load_dwordx4 v[136:139], v[136:137], off offset:512
	v_lshl_add_u64 v[206:207], v[204:205], 1, s[42:43]
	v_mov_b32_e32 v180, v1
	v_mov_b32_e32 v181, v1
	v_lshl_add_u64 v[208:209], s[44:45], 0, v[204:205]
	v_or_b32_e32 v204, 0x80, v204
	s_waitcnt vmcnt(0) lgkmcnt(0)
	v_fma_f32 v0, v128, v174, v184
	v_fma_f32 v128, v129, v174, v185
	v_fma_f32 v129, v130, v174, v186
	v_fmac_f32_e32 v187, v131, v174
	v_fma_f32 v130, v124, v174, v192
	v_fma_f32 v131, v125, v174, v193
	v_fma_f32 v182, v126, v174, v194
	v_fmac_f32_e32 v195, v127, v174
	v_fma_f32 v184, v120, v174, v196
	v_mul_f32_e32 v120, v128, v128
	v_cvt_pk_bf16_f32 v124, v0, v128
	v_cvt_pk_bf16_f32 v125, v129, v187
	v_cvt_pk_bf16_f32 v126, v130, v131
	v_cvt_pk_bf16_f32 v127, v182, v195
	v_fmac_f32_e32 v120, v0, v0
	v_and_b32_e32 v193, 0xffff0000, v124
	v_lshlrev_b32_e32 v194, 16, v124
	v_and_b32_e32 v210, 0xffff0000, v126
	v_lshlrev_b32_e32 v211, 16, v126
	v_lshlrev_b32_e32 v212, 16, v127
	v_and_b32_e32 v213, 0xffff0000, v127
	global_store_dwordx4 v[206:207], v[124:127], off sc1
	v_sub_f32_e32 v0, v0, v194
	v_mul_f32_e32 v0, 0x43800000, v0
	v_sub_f32_e32 v124, v128, v193
	v_sub_f32_e32 v127, v131, v210
	v_sub_f32_e32 v128, v130, v211
	v_mul_f32_e32 v124, 0x43800000, v124
	v_mul_f32_e32 v127, 0x43800000, v127
	v_mul_f32_e32 v128, 0x43800000, v128
	v_med3_f32 v124, v124, s68, v235
	v_med3_f32 v0, v0, s68, v235
	v_med3_f32 v127, v127, s68, v235
	v_med3_f32 v128, v128, s68, v235
	v_fma_f32 v121, v121, v174, v197
	v_mul_f32_e32 v185, v187, v187
	v_mul_f32_e32 v186, v131, v131
	v_lshlrev_b32_e32 v196, 16, v125
	v_and_b32_e32 v197, 0xffff0000, v125
	v_cvt_pk_fp8_f32 v180, v0, v124
	v_cvt_pk_fp8_f32 v181, v128, v127
	v_fmac_f32_e32 v185, v129, v129
	v_fmac_f32_e32 v186, v130, v130
	v_sub_f32_e32 v125, v129, v196
	v_sub_f32_e32 v126, v187, v197
	v_sub_f32_e32 v129, v182, v212
	v_sub_f32_e32 v130, v195, v213
	v_mul_f32_e32 v125, 0x43800000, v125
	v_mul_f32_e32 v126, 0x43800000, v126
	v_mul_f32_e32 v129, 0x43800000, v129
	v_mul_f32_e32 v130, 0x43800000, v130
	v_med3_f32 v125, v125, s68, v235
	v_med3_f32 v126, v126, s68, v235
	v_med3_f32 v0, v129, s68, v235
	v_med3_f32 v124, v130, s68, v235
	v_cvt_pk_fp8_f32 v180, v125, v126 op_sel:[0,0,1]
	v_cvt_pk_fp8_f32 v181, v0, v124 op_sel:[0,0,1]
	v_add_f32_e32 v120, v120, v185
	v_add_f32_e32 v0, v120, v186
	v_mul_f32_e32 v192, v121, v121
	global_store_dwordx2 v[208:209], v[180:181], off
	v_cvt_pk_bf16_f32 v120, v184, v121
	v_mul_f32_e32 v191, v195, v195
	v_and_b32_e32 v124, 0xffff0000, v120
	v_sub_f32_e32 v121, v121, v124
	v_lshlrev_b32_e32 v124, 16, v120
	v_sub_f32_e32 v124, v184, v124
	v_mul_f32_e32 v121, 0x43800000, v121
	v_mul_f32_e32 v124, 0x43800000, v124
	v_fmac_f32_e32 v191, v182, v182
	v_med3_f32 v121, v121, s68, v235
	v_med3_f32 v125, v124, s68, v235
	v_mov_b32_e32 v124, v1
	v_fmac_f32_e32 v199, v123, v174
	v_fmac_f32_e32 v192, v184, v184
	v_add_f32_e32 v0, v191, v0
	v_cvt_pk_fp8_f32 v124, v125, v121
	v_fma_f32 v122, v122, v174, v198
	v_mul_f32_e32 v121, v199, v199
	v_add_f32_e32 v0, v192, v0
	v_fmac_f32_e32 v121, v122, v122
	v_add_f32_e32 v0, v121, v0
	v_cvt_pk_bf16_f32 v121, v122, v199
	v_fma_f32 v117, v117, v174, v201
	v_lshlrev_b32_e32 v123, 16, v121
	v_sub_f32_e32 v122, v122, v123
	v_and_b32_e32 v123, 0xffff0000, v121
	v_sub_f32_e32 v123, v199, v123
	v_mul_f32_e32 v122, 0x43800000, v122
	v_mul_f32_e32 v123, 0x43800000, v123
	v_med3_f32 v122, v122, s68, v235
	v_med3_f32 v123, v123, s68, v235
	v_cvt_pk_fp8_f32 v124, v122, v123 op_sel:[0,0,1]
	v_fma_f32 v116, v116, v174, v200
	v_mul_f32_e32 v122, v117, v117
	v_fmac_f32_e32 v122, v116, v116
	v_add_f32_e32 v0, v122, v0
	v_cvt_pk_bf16_f32 v122, v116, v117
	v_mov_b32_e32 v125, v1
	v_and_b32_e32 v123, 0xffff0000, v122
	v_sub_f32_e32 v117, v117, v123
	v_lshlrev_b32_e32 v123, 16, v122
	v_sub_f32_e32 v116, v116, v123
	v_mul_f32_e32 v117, 0x43800000, v117
	v_mul_f32_e32 v116, 0x43800000, v116
	v_med3_f32 v117, v117, s68, v235
	v_med3_f32 v116, v116, s68, v235
	v_fmac_f32_e32 v203, v119, v174
	v_cvt_pk_fp8_f32 v125, v116, v117
	v_fma_f32 v116, v118, v174, v202
	v_mul_f32_e32 v117, v203, v203
	v_fmac_f32_e32 v117, v116, v116
	v_add_f32_e32 v117, v117, v0
	v_cvt_pk_bf16_f32 v123, v116, v203
	v_and_b32_e32 v119, 64, v226
	v_lshlrev_b32_e32 v0, 16, v123
	v_sub_f32_e32 v0, v116, v0
	v_mul_f32_e32 v0, 0x43800000, v0
	v_med3_f32 v116, v0, s68, v235
	v_and_b32_e32 v0, 0xffff0000, v123
	v_sub_f32_e32 v118, v203, v0
	v_xor_b32_e32 v0, 16, v226
	v_add_u32_e32 v119, 64, v119
	v_cmp_lt_i32_e32 vcc, v0, v119
	v_mul_f32_e32 v118, 0x43800000, v118
	v_med3_f32 v118, v118, s68, v235
	v_cndmask_b32_e32 v0, v226, v0, vcc
	v_lshlrev_b32_e32 v0, 2, v0
	ds_bpermute_b32 v126, v0, v117
	v_cvt_pk_fp8_f32 v125, v116, v118 op_sel:[0,0,1]
	s_waitcnt lgkmcnt(0)
	v_add_f32_e32 v116, v117, v126
	v_xor_b32_e32 v117, 32, v226
	v_cmp_lt_i32_e32 vcc, v117, v119
	v_lshl_add_u64 v[118:119], v[204:205], 1, s[42:43]
	global_store_dwordx4 v[118:119], v[120:123], off sc1
	v_cndmask_b32_e32 v117, v226, v117, vcc
	v_lshlrev_b32_e32 v174, 2, v117
	ds_bpermute_b32 v117, v174, v116
	v_lshl_add_u64 v[118:119], s[44:45], 0, v[204:205]
	global_store_dwordx2 v[118:119], v[124:125], off
	s_and_saveexec_b64 s[2:3], s[38:39]
	v_readlane_b32 s74, v255, 12
	v_readlane_b32 s76, v255, 14
	v_readlane_b32 s72, v255, 11
	v_readlane_b32 s75, v255, 13
	v_readlane_b32 s77, v255, 15
	v_readlane_b32 s73, v255, 16
	s_cbranch_execz .LBB0_1042
	s_waitcnt lgkmcnt(0)
	v_add_f32_e32 v118, v116, v117
	s_lshl_b32 s20, s56, 2
	v_lshlrev_b64 v[116:117], 7, v[164:165]
	s_ashr_i32 s21, s20, 31
	v_lshl_add_u64 v[116:117], s[8:9], 0, v[116:117]
	v_lshl_add_u64 v[116:117], s[20:21], 2, v[116:117]
	s_lshl_b32 s18, s37, 2
	v_lshl_add_u64 v[116:117], v[116:117], 0, s[18:19]
	global_store_dword v[116:117], v118, off
; __device__ __forceinline__ unsigned cvt_pk_bf16(float lo, float hi) { unsigned r; asm volatile("v_cvt_pk_bf16_f32 %0, %1, %2" : "=v"(r) : "v"(lo), "v"(hi)); return r; }
;     __device__ __forceinline__ void core(const f32x4 (&acc)[2][2][4][2], const Unit& u, int wr, int wc, int fr, int fq, const float (&rsc)[2][4]) const {
;     ...
;             for (int m = 0; m < MB; ++m) { const int row = row0 + ai * HALF + (mh + m) * 16; float sq = 0.f;
;                 const float rs1 = rsc[ai][mh + m];
; #pragma unroll
;                 for (int bj = 0; bj < 2; ++bj) { const size_t idx = (size_t)row * D + col0 + bj * HALF;
;                     unsigned hw[4]; int lw[2] = {0, 0};
; #pragma unroll
;                     for (int pq = 0; pq < 4; ++pq) {
;                         float h0, h1;
;                         if (F32IN) { h0 = (pq < 2) ? xa[m][bj][2 * pq] : xb[m][bj][2 * pq - 4]; h1 = (pq < 2) ? xa[m][bj][2 * pq + 1] : xb[m][bj][2 * pq - 3]; }
;                         else { const unsigned a = va[m][bj][pq]; const int bw = (int)vb[m][bj][pq >> 1]; const hf32x2 lp = (pq & 1) ? __builtin_amdgcn_cvt_pk_f32_fp8(bw, true) : __builtin_amdgcn_cvt_pk_f32_fp8(bw, false);
;                             h0 = __uint_as_float(a << 16) + lp.x * 0.00390625f; h1 = __uint_as_float(a & 0xffff0000u) + lp.y * 0.00390625f; }
;                         const float o0 = h0 + acc[ai][bj][mh + m][pq >> 1][(2 * pq) & 3] * rs1, o1 = h1 + acc[ai][bj][mh + m][pq >> 1][(2 * pq + 1) & 3] * rs1;
;                         sq += o0 * o0 + o1 * o1;
;                         const unsigned hi = cvt_pk_bf16(o0, o1);
;                         hw[pq] = hi;
;                         const float r0 = __builtin_amdgcn_fmed3f((o0 - __uint_as_float(hi << 16)) * 256.0f, -448.0f, 448.0f), r1 = __builtin_amdgcn_fmed3f((o1 - __uint_as_float(hi & 0xffff0000u)) * 256.0f, -448.0f, 448.0f);
;                         lw[pq >> 1] = (pq & 1) ? __builtin_amdgcn_cvt_pk_fp8_f32(r0, r1, lw[pq >> 1], true) : __builtin_amdgcn_cvt_pk_fp8_f32(r0, r1, lw[pq >> 1], false);
;                     }
;                     *(u32x4*)(Hb + idx) = (u32x4){hw[0], hw[1], hw[2], hw[3]}; *(u32x2*)(Hl + idx) = (u32x2){(unsigned)lw[0], (unsigned)lw[1]}; }
;                 sq += __shfl_xor(sq, 16); sq += __shfl_xor(sq, 32); if (fq == 0) ss[(size_t)row * 32 + u.pn * 4 + wc] = sq; }
.LBB0_1042:
	s_or_b64 exec, exec, s[2:3]
	v_fma_f32 v118, v112, v175, v144
	v_fma_f32 v113, v113, v175, v145
	v_cvt_pk_bf16_f32 v112, v118, v113
	v_mul_f32_e32 v119, v113, v113
	v_and_b32_e32 v120, 0xffff0000, v112
	v_sub_f32_e32 v113, v113, v120
	v_lshlrev_b32_e32 v120, 16, v112
	v_fmac_f32_e32 v119, v118, v118
	v_sub_f32_e32 v118, v118, v120
	v_mul_f32_e32 v113, 0x43800000, v113
	v_mul_f32_e32 v118, 0x43800000, v118
	v_med3_f32 v113, v113, s68, v235
	v_med3_f32 v120, v118, s68, v235
	v_mov_b32_e32 v118, v1
	v_fmac_f32_e32 v147, v115, v175
	v_cvt_pk_fp8_f32 v118, v120, v113
	v_fma_f32 v114, v114, v175, v146
	v_mul_f32_e32 v113, v147, v147
	v_fmac_f32_e32 v113, v114, v114
	v_add_f32_e32 v115, v119, v113
	v_cvt_pk_bf16_f32 v113, v114, v147
	v_fma_f32 v109, v109, v175, v141
	v_lshlrev_b32_e32 v119, 16, v113
	v_sub_f32_e32 v114, v114, v119
	v_and_b32_e32 v119, 0xffff0000, v113
	v_sub_f32_e32 v119, v147, v119
	v_mul_f32_e32 v114, 0x43800000, v114
	v_mul_f32_e32 v119, 0x43800000, v119
	v_med3_f32 v114, v114, s68, v235
	v_med3_f32 v119, v119, s68, v235
	v_cvt_pk_fp8_f32 v118, v114, v119 op_sel:[0,0,1]
	v_fma_f32 v108, v108, v175, v140
	v_mul_f32_e32 v114, v109, v109
	v_fmac_f32_e32 v114, v108, v108
	v_add_f32_e32 v115, v115, v114
	v_cvt_pk_bf16_f32 v114, v108, v109
	v_fmac_f32_e32 v143, v111, v175
	v_and_b32_e32 v119, 0xffff0000, v114
	v_sub_f32_e32 v109, v109, v119
	v_lshlrev_b32_e32 v119, 16, v114
	v_sub_f32_e32 v108, v108, v119
	v_mul_f32_e32 v109, 0x43800000, v109
	v_mul_f32_e32 v108, 0x43800000, v108
	v_med3_f32 v109, v109, s68, v235
	v_med3_f32 v108, v108, s68, v235
	v_mov_b32_e32 v119, v1
	v_cvt_pk_fp8_f32 v119, v108, v109
	v_fma_f32 v108, v110, v175, v142
	v_mul_f32_e32 v109, v143, v143
	v_fmac_f32_e32 v109, v108, v108
	v_add_f32_e32 v110, v109, v115
	v_cvt_pk_bf16_f32 v115, v108, v143
	s_waitcnt lgkmcnt(0)
	v_lshlrev_b64 v[116:117], 11, v[172:173]
	v_lshlrev_b32_e32 v109, 16, v115
	v_sub_f32_e32 v108, v108, v109
	v_and_b32_e32 v109, 0xffff0000, v115
	v_sub_f32_e32 v109, v143, v109
	v_mul_f32_e32 v108, 0x43800000, v108
	v_mul_f32_e32 v109, 0x43800000, v109
	v_med3_f32 v108, v108, s68, v235
	v_med3_f32 v109, v109, s68, v235
	v_cvt_pk_fp8_f32 v119, v108, v109 op_sel:[0,0,1]
	v_lshl_add_u64 v[116:117], v[116:117], 0, v[162:163]
	v_lshl_add_u64 v[108:109], v[116:117], 1, s[42:43]
	global_store_dwordx4 v[108:109], v[112:115], off sc1
	v_lshl_add_u64 v[108:109], s[44:45], 0, v[116:117]
	v_fma_f32 v105, v105, v175, v137
	global_store_dwordx2 v[108:109], v[118:119], off
	v_fma_f32 v108, v104, v175, v136
	v_mul_f32_e32 v104, v105, v105
	v_fmac_f32_e32 v104, v108, v108
	v_add_f32_e32 v109, v104, v110
	v_cvt_pk_bf16_f32 v104, v108, v105
	v_fmac_f32_e32 v139, v107, v175
	v_and_b32_e32 v110, 0xffff0000, v104
	v_sub_f32_e32 v105, v105, v110
	v_lshlrev_b32_e32 v110, 16, v104
	v_sub_f32_e32 v108, v108, v110
	v_mul_f32_e32 v105, 0x43800000, v105
	v_mul_f32_e32 v108, 0x43800000, v108
	v_med3_f32 v105, v105, s68, v235
	v_med3_f32 v110, v108, s68, v235
	v_mov_b32_e32 v108, v1
	v_cvt_pk_fp8_f32 v108, v110, v105
	v_fma_f32 v106, v106, v175, v138
	v_mul_f32_e32 v105, v139, v139
	v_fmac_f32_e32 v105, v106, v106
	v_add_f32_e32 v107, v105, v109
	v_cvt_pk_bf16_f32 v105, v106, v139
	v_fma_f32 v101, v101, v175, v133
	v_lshlrev_b32_e32 v109, 16, v105
	v_sub_f32_e32 v106, v106, v109
	v_and_b32_e32 v109, 0xffff0000, v105
	v_sub_f32_e32 v109, v139, v109
	v_mul_f32_e32 v106, 0x43800000, v106
	v_mul_f32_e32 v109, 0x43800000, v109
	v_med3_f32 v106, v106, s68, v235
	v_med3_f32 v109, v109, s68, v235
	v_cvt_pk_fp8_f32 v108, v106, v109 op_sel:[0,0,1]
	v_fma_f32 v100, v100, v175, v132
	v_mul_f32_e32 v106, v101, v101
	v_fmac_f32_e32 v106, v100, v100
	v_add_f32_e32 v107, v106, v107
	v_cvt_pk_bf16_f32 v106, v100, v101
	v_fmac_f32_e32 v135, v103, v175
	v_and_b32_e32 v109, 0xffff0000, v106
	v_sub_f32_e32 v101, v101, v109
	v_lshlrev_b32_e32 v109, 16, v106
	v_sub_f32_e32 v100, v100, v109
	v_mul_f32_e32 v101, 0x43800000, v101
	v_mul_f32_e32 v100, 0x43800000, v100
	v_med3_f32 v101, v101, s68, v235
	v_med3_f32 v100, v100, s68, v235
	v_mov_b32_e32 v109, v1
	v_cvt_pk_fp8_f32 v109, v100, v101
	v_fma_f32 v100, v102, v175, v134
	v_mul_f32_e32 v101, v135, v135
	v_fmac_f32_e32 v101, v100, v100
	v_add_f32_e32 v101, v101, v107
	v_cvt_pk_bf16_f32 v107, v100, v135
	ds_bpermute_b32 v103, v0, v101
	v_lshlrev_b32_e32 v102, 16, v107
	v_sub_f32_e32 v100, v100, v102
	v_and_b32_e32 v102, 0xffff0000, v107
	v_sub_f32_e32 v102, v135, v102
	v_mul_f32_e32 v100, 0x43800000, v100
	v_mul_f32_e32 v102, 0x43800000, v102
	v_med3_f32 v100, v100, s68, v235
	v_med3_f32 v102, v102, s68, v235
	v_cvt_pk_fp8_f32 v109, v100, v102 op_sel:[0,0,1]
	s_waitcnt lgkmcnt(0)
	v_add_f32_e32 v100, v101, v103
	ds_bpermute_b32 v101, v174, v100
	v_or_b32_e32 v116, 0x80, v116
	v_lshl_add_u64 v[102:103], v[116:117], 1, s[42:43]
	global_store_dwordx4 v[102:103], v[104:107], off sc1
	v_lshl_add_u64 v[102:103], s[44:45], 0, v[116:117]
	global_store_dwordx2 v[102:103], v[108:109], off
	s_and_saveexec_b64 s[2:3], s[38:39]
	s_cbranch_execz .LBB0_1044
	s_waitcnt lgkmcnt(0)
	v_add_f32_e32 v102, v100, v101
	s_lshl_b32 s20, s56, 2
	v_lshlrev_b64 v[100:101], 7, v[172:173]
	s_ashr_i32 s21, s20, 31
	v_lshl_add_u64 v[100:101], s[8:9], 0, v[100:101]
	v_lshl_add_u64 v[100:101], s[20:21], 2, v[100:101]
	s_lshl_b32 s18, s37, 2
	v_lshl_add_u64 v[100:101], v[100:101], 0, s[18:19]
	global_store_dword v[100:101], v102, off
;     __device__ __forceinline__ void core(const f32x4 (&acc)[2][2][4][2], const Unit& u, int wr, int wc, int fr, int fq, const float (&rsc)[2][4]) const {
;     ...
;             for (int m = 0; m < MB; ++m)
; #pragma unroll
;                 for (int bj = 0; bj < 2; ++bj) { const size_t idx = (size_t)(row0 + ai * HALF + (mh + m) * 16) * D + col0 + bj * HALF;
;                     if (F32IN) { xa[m][bj] = *(const f32x4*)(Xin + idx); xb[m][bj] = *(const f32x4*)(Xin + idx + 4); }
;                     else { va[m][bj] = *(const u32x4*)(Hb + idx); vb[m][bj] = *(const u32x2*)(Hl + idx); } }
; #pragma unroll
;             for (int m = 0; m < MB; ++m) { const int row = row0 + ai * HALF + (mh + m) * 16; float sq = 0.f;
;                 const float rs1 = rsc[ai][mh + m];
; #pragma unroll
;                 for (int bj = 0; bj < 2; ++bj) { const size_t idx = (size_t)row * D + col0 + bj * HALF;
;                     unsigned hw[4]; int lw[2] = {0, 0};
; #pragma unroll
;                     for (int pq = 0; pq < 4; ++pq) {
;                         float h0, h1;
;                         if (F32IN) { h0 = (pq < 2) ? xa[m][bj][2 * pq] : xb[m][bj][2 * pq - 4]; h1 = (pq < 2) ? xa[m][bj][2 * pq + 1] : xb[m][bj][2 * pq - 3]; }
;                         else { const unsigned a = va[m][bj][pq]; const int bw = (int)vb[m][bj][pq >> 1]; const hf32x2 lp = (pq & 1) ? __builtin_amdgcn_cvt_pk_f32_fp8(bw, true) : __builtin_amdgcn_cvt_pk_f32_fp8(bw, false);
;                             h0 = __uint_as_float(a << 16) + lp.x * 0.00390625f; h1 = __uint_as_float(a & 0xffff0000u) + lp.y * 0.00390625f; }
;                         const float o0 = h0 + acc[ai][bj][mh + m][pq >> 1][(2 * pq) & 3] * rs1, o1 = h1 + acc[ai][bj][mh + m][pq >> 1][(2 * pq + 1) & 3] * rs1;
;                         sq += o0 * o0 + o1 * o1;
;                         const unsigned hi = cvt_pk_bf16(o0, o1);
;                         hw[pq] = hi;
;                         const float r0 = __builtin_amdgcn_fmed3f((o0 - __uint_as_float(hi << 16)) * 256.0f, -448.0f, 448.0f), r1 = __builtin_amdgcn_fmed3f((o1 - __uint_as_float(hi & 0xffff0000u)) * 256.0f, -448.0f, 448.0f);
;                         lw[pq >> 1] = (pq & 1) ? __builtin_amdgcn_cvt_pk_fp8_f32(r0, r1, lw[pq >> 1], true) : __builtin_amdgcn_cvt_pk_fp8_f32(r0, r1, lw[pq >> 1], false);
;                     }
.LBB0_1044:
	s_or_b64 exec, exec, s[2:3]
	v_or_b32_e32 v130, 32, v164
	v_ashrrev_i32_e32 v131, 31, v130
	s_waitcnt lgkmcnt(0)
	v_lshlrev_b64 v[100:101], 13, v[130:131]
	v_lshl_add_u64 v[100:101], v[166:167], 0, v[100:101]
	global_load_dwordx4 v[124:127], v[100:101], off offset:16
	global_load_dwordx4 v[134:137], v[100:101], off
	global_load_dwordx4 v[116:119], v[100:101], off offset:528
	global_load_dwordx4 v[120:123], v[100:101], off offset:512
	v_or_b32_e32 v128, 48, v164
	v_ashrrev_i32_e32 v129, 31, v128
	v_lshlrev_b64 v[100:101], 13, v[128:129]
	v_lshl_add_u64 v[104:105], v[166:167], 0, v[100:101]
	global_load_dwordx4 v[108:111], v[104:105], off offset:16
	global_load_dwordx4 v[112:115], v[104:105], off
	global_load_dwordx4 v[100:103], v[104:105], off offset:528
	s_nop 0
	global_load_dwordx4 v[104:107], v[104:105], off offset:512
	v_lshlrev_b64 v[132:133], 11, v[130:131]
	v_lshl_add_u64 v[132:133], v[132:133], 0, v[162:163]
	s_waitcnt vmcnt(7)
	v_fma_f32 v93, v93, v170, v125
	s_waitcnt vmcnt(6)
	v_fma_f32 v134, v96, v170, v134
	v_fma_f32 v97, v97, v170, v135
	v_cvt_pk_bf16_f32 v96, v134, v97
	v_mul_f32_e32 v135, v97, v97
	v_and_b32_e32 v138, 0xffff0000, v96
	v_sub_f32_e32 v97, v97, v138
	v_lshlrev_b32_e32 v138, 16, v96
	v_fmac_f32_e32 v135, v134, v134
	v_sub_f32_e32 v134, v134, v138
	v_mul_f32_e32 v97, 0x43800000, v97
	v_mul_f32_e32 v134, 0x43800000, v134
	v_med3_f32 v97, v97, s68, v235
	v_med3_f32 v138, v134, s68, v235
	v_mov_b32_e32 v134, v1
	v_fmac_f32_e32 v137, v99, v170
	v_cvt_pk_fp8_f32 v134, v138, v97
	v_fma_f32 v98, v98, v170, v136
	v_mul_f32_e32 v97, v137, v137
	v_fmac_f32_e32 v97, v98, v98
	v_add_f32_e32 v99, v135, v97
	v_cvt_pk_bf16_f32 v97, v98, v137
	v_fma_f32 v92, v92, v170, v124
	v_lshlrev_b32_e32 v135, 16, v97
	v_sub_f32_e32 v98, v98, v135
	v_and_b32_e32 v135, 0xffff0000, v97
	v_sub_f32_e32 v135, v137, v135
	v_mul_f32_e32 v98, 0x43800000, v98
	v_mul_f32_e32 v135, 0x43800000, v135
	v_med3_f32 v98, v98, s68, v235
	v_med3_f32 v135, v135, s68, v235
	v_cvt_pk_fp8_f32 v134, v98, v135 op_sel:[0,0,1]
	v_mul_f32_e32 v98, v93, v93
	v_fmac_f32_e32 v98, v92, v92
	v_add_f32_e32 v99, v99, v98
	v_cvt_pk_bf16_f32 v98, v92, v93
	v_mov_b32_e32 v135, v1
	v_and_b32_e32 v124, 0xffff0000, v98
	v_sub_f32_e32 v93, v93, v124
	v_lshlrev_b32_e32 v124, 16, v98
	v_sub_f32_e32 v92, v92, v124
	v_mul_f32_e32 v93, 0x43800000, v93
	v_mul_f32_e32 v92, 0x43800000, v92
	v_med3_f32 v93, v93, s68, v235
	v_med3_f32 v92, v92, s68, v235
	v_fmac_f32_e32 v127, v95, v170
	v_cvt_pk_fp8_f32 v135, v92, v93
	v_fma_f32 v92, v94, v170, v126
	v_mul_f32_e32 v93, v127, v127
	v_fmac_f32_e32 v93, v92, v92
	v_add_f32_e32 v94, v93, v99
	v_cvt_pk_bf16_f32 v99, v92, v127
	s_waitcnt vmcnt(4)
	v_fma_f32 v89, v89, v170, v121
	v_lshlrev_b32_e32 v93, 16, v99
	v_sub_f32_e32 v92, v92, v93
	v_and_b32_e32 v93, 0xffff0000, v99
	v_sub_f32_e32 v93, v127, v93
	v_mul_f32_e32 v92, 0x43800000, v92
	v_mul_f32_e32 v93, 0x43800000, v93
	v_med3_f32 v92, v92, s68, v235
	v_med3_f32 v93, v93, s68, v235
	v_cvt_pk_fp8_f32 v135, v92, v93 op_sel:[0,0,1]
	v_lshl_add_u64 v[92:93], v[132:133], 1, s[42:43]
	global_store_dwordx4 v[92:93], v[96:99], off sc1
	v_lshl_add_u64 v[92:93], s[44:45], 0, v[132:133]
	global_store_dwordx2 v[92:93], v[134:135], off
	v_fma_f32 v92, v88, v170, v120
	v_mul_f32_e32 v88, v89, v89
	v_fmac_f32_e32 v88, v92, v92
	v_add_f32_e32 v93, v88, v94
	v_cvt_pk_bf16_f32 v88, v92, v89
	v_fmac_f32_e32 v123, v91, v170
	v_and_b32_e32 v94, 0xffff0000, v88
	v_sub_f32_e32 v89, v89, v94
	v_lshlrev_b32_e32 v94, 16, v88
	v_sub_f32_e32 v92, v92, v94
	v_mul_f32_e32 v89, 0x43800000, v89
	v_mul_f32_e32 v92, 0x43800000, v92
	v_med3_f32 v89, v89, s68, v235
	v_med3_f32 v94, v92, s68, v235
	v_mov_b32_e32 v92, v1
	v_cvt_pk_fp8_f32 v92, v94, v89
	v_fma_f32 v90, v90, v170, v122
	v_mul_f32_e32 v89, v123, v123
	v_fmac_f32_e32 v89, v90, v90
	v_add_f32_e32 v91, v89, v93
	v_cvt_pk_bf16_f32 v89, v90, v123
	v_fma_f32 v85, v85, v170, v117
	v_lshlrev_b32_e32 v93, 16, v89
	v_sub_f32_e32 v90, v90, v93
	v_and_b32_e32 v93, 0xffff0000, v89
	v_sub_f32_e32 v93, v123, v93
	v_mul_f32_e32 v90, 0x43800000, v90
	v_mul_f32_e32 v93, 0x43800000, v93
	v_med3_f32 v90, v90, s68, v235
	v_med3_f32 v93, v93, s68, v235
	v_cvt_pk_fp8_f32 v92, v90, v93 op_sel:[0,0,1]
	v_fma_f32 v84, v84, v170, v116
	v_mul_f32_e32 v90, v85, v85
	v_fmac_f32_e32 v90, v84, v84
	v_add_f32_e32 v91, v90, v91
	v_cvt_pk_bf16_f32 v90, v84, v85
	v_fmac_f32_e32 v119, v87, v170
	v_and_b32_e32 v93, 0xffff0000, v90
	v_sub_f32_e32 v85, v85, v93
	v_lshlrev_b32_e32 v93, 16, v90
	v_sub_f32_e32 v84, v84, v93
	v_mul_f32_e32 v85, 0x43800000, v85
	v_mul_f32_e32 v84, 0x43800000, v84
	v_med3_f32 v85, v85, s68, v235
	v_med3_f32 v84, v84, s68, v235
	v_mov_b32_e32 v93, v1
	v_cvt_pk_fp8_f32 v93, v84, v85
	v_fma_f32 v84, v86, v170, v118
	v_mul_f32_e32 v85, v119, v119
	v_fmac_f32_e32 v85, v84, v84
	v_add_f32_e32 v86, v85, v91
	v_cvt_pk_bf16_f32 v91, v84, v119
	v_or_b32_e32 v132, 0x80, v132
	v_lshlrev_b32_e32 v85, 16, v91
	v_sub_f32_e32 v84, v84, v85
	v_and_b32_e32 v85, 0xffff0000, v91
	v_sub_f32_e32 v85, v119, v85
	v_mul_f32_e32 v84, 0x43800000, v84
	v_mul_f32_e32 v85, 0x43800000, v85
	v_med3_f32 v84, v84, s68, v235
	v_med3_f32 v85, v85, s68, v235
	v_cvt_pk_fp8_f32 v93, v84, v85 op_sel:[0,0,1]
	v_lshl_add_u64 v[84:85], v[132:133], 1, s[42:43]
	global_store_dwordx4 v[84:85], v[88:91], off sc1
	v_lshl_add_u64 v[84:85], s[44:45], 0, v[132:133]
	global_store_dwordx2 v[84:85], v[92:93], off
	ds_bpermute_b32 v84, v0, v86
	s_waitcnt lgkmcnt(0)
	v_add_f32_e32 v84, v86, v84
	ds_bpermute_b32 v85, v174, v84
	s_and_saveexec_b64 s[2:3], s[38:39]
	s_cbranch_execz .LBB0_1046
	s_waitcnt lgkmcnt(0)
	v_add_f32_e32 v86, v84, v85
	s_lshl_b32 s20, s56, 2
	v_lshlrev_b64 v[84:85], 7, v[130:131]
	s_ashr_i32 s21, s20, 31
	v_lshl_add_u64 v[84:85], s[8:9], 0, v[84:85]
	v_lshl_add_u64 v[84:85], s[20:21], 2, v[84:85]
	s_lshl_b32 s18, s37, 2
	v_lshl_add_u64 v[84:85], v[84:85], 0, s[18:19]
	global_store_dword v[84:85], v86, off
; __device__ __forceinline__ unsigned cvt_pk_bf16(float lo, float hi) { unsigned r; asm volatile("v_cvt_pk_bf16_f32 %0, %1, %2" : "=v"(r) : "v"(lo), "v"(hi)); return r; }
;     __device__ __forceinline__ void core(const f32x4 (&acc)[2][2][4][2], const Unit& u, int wr, int wc, int fr, int fq, const float (&rsc)[2][4]) const {
;     ...
;             for (int m = 0; m < MB; ++m) { const int row = row0 + ai * HALF + (mh + m) * 16; float sq = 0.f;
;                 const float rs1 = rsc[ai][mh + m];
; #pragma unroll
;                 for (int bj = 0; bj < 2; ++bj) { const size_t idx = (size_t)row * D + col0 + bj * HALF;
;                     unsigned hw[4]; int lw[2] = {0, 0};
; #pragma unroll
;                     for (int pq = 0; pq < 4; ++pq) {
;                         float h0, h1;
;                         if (F32IN) { h0 = (pq < 2) ? xa[m][bj][2 * pq] : xb[m][bj][2 * pq - 4]; h1 = (pq < 2) ? xa[m][bj][2 * pq + 1] : xb[m][bj][2 * pq - 3]; }
;                         else { const unsigned a = va[m][bj][pq]; const int bw = (int)vb[m][bj][pq >> 1]; const hf32x2 lp = (pq & 1) ? __builtin_amdgcn_cvt_pk_f32_fp8(bw, true) : __builtin_amdgcn_cvt_pk_f32_fp8(bw, false);
;                             h0 = __uint_as_float(a << 16) + lp.x * 0.00390625f; h1 = __uint_as_float(a & 0xffff0000u) + lp.y * 0.00390625f; }
;                         const float o0 = h0 + acc[ai][bj][mh + m][pq >> 1][(2 * pq) & 3] * rs1, o1 = h1 + acc[ai][bj][mh + m][pq >> 1][(2 * pq + 1) & 3] * rs1;
;                         sq += o0 * o0 + o1 * o1;
;                         const unsigned hi = cvt_pk_bf16(o0, o1);
;                         hw[pq] = hi;
;                         const float r0 = __builtin_amdgcn_fmed3f((o0 - __uint_as_float(hi << 16)) * 256.0f, -448.0f, 448.0f), r1 = __builtin_amdgcn_fmed3f((o1 - __uint_as_float(hi & 0xffff0000u)) * 256.0f, -448.0f, 448.0f);
;                         lw[pq >> 1] = (pq & 1) ? __builtin_amdgcn_cvt_pk_fp8_f32(r0, r1, lw[pq >> 1], true) : __builtin_amdgcn_cvt_pk_fp8_f32(r0, r1, lw[pq >> 1], false);
;                     }
;                     *(u32x4*)(Hb + idx) = (u32x4){hw[0], hw[1], hw[2], hw[3]}; *(u32x2*)(Hl + idx) = (u32x2){(unsigned)lw[0], (unsigned)lw[1]}; }
;                 sq += __shfl_xor(sq, 16); sq += __shfl_xor(sq, 32); if (fq == 0) ss[(size_t)row * 32 + u.pn * 4 + wc] = sq; }
.LBB0_1046:
	s_or_b64 exec, exec, s[2:3]
	s_waitcnt vmcnt(6)
	v_fma_f32 v86, v80, v171, v112
	v_fma_f32 v81, v81, v171, v113
	v_cvt_pk_bf16_f32 v80, v86, v81
	v_mul_f32_e32 v87, v81, v81
	v_and_b32_e32 v88, 0xffff0000, v80
	v_sub_f32_e32 v81, v81, v88
	v_lshlrev_b32_e32 v88, 16, v80
	v_fmac_f32_e32 v87, v86, v86
	v_sub_f32_e32 v86, v86, v88
	v_mul_f32_e32 v81, 0x43800000, v81
	v_mul_f32_e32 v86, 0x43800000, v86
	v_med3_f32 v81, v81, s68, v235
	v_med3_f32 v88, v86, s68, v235
	v_mov_b32_e32 v86, v1
	v_fmac_f32_e32 v115, v83, v171
	v_cvt_pk_fp8_f32 v86, v88, v81
	v_fma_f32 v82, v82, v171, v114
	v_mul_f32_e32 v81, v115, v115
	v_fmac_f32_e32 v81, v82, v82
	v_add_f32_e32 v83, v87, v81
	v_cvt_pk_bf16_f32 v81, v82, v115
	v_fma_f32 v77, v77, v171, v109
	v_lshlrev_b32_e32 v87, 16, v81
	v_sub_f32_e32 v82, v82, v87
	v_and_b32_e32 v87, 0xffff0000, v81
	v_sub_f32_e32 v87, v115, v87
	v_mul_f32_e32 v82, 0x43800000, v82
	v_mul_f32_e32 v87, 0x43800000, v87
	v_med3_f32 v82, v82, s68, v235
	v_med3_f32 v87, v87, s68, v235
	v_cvt_pk_fp8_f32 v86, v82, v87 op_sel:[0,0,1]
	v_fma_f32 v76, v76, v171, v108
	v_mul_f32_e32 v82, v77, v77
	v_fmac_f32_e32 v82, v76, v76
	v_add_f32_e32 v83, v83, v82
	v_cvt_pk_bf16_f32 v82, v76, v77
	v_fmac_f32_e32 v111, v79, v171
	v_and_b32_e32 v87, 0xffff0000, v82
	v_sub_f32_e32 v77, v77, v87
	v_lshlrev_b32_e32 v87, 16, v82
	v_sub_f32_e32 v76, v76, v87
	v_mul_f32_e32 v77, 0x43800000, v77
	v_mul_f32_e32 v76, 0x43800000, v76
	v_med3_f32 v77, v77, s68, v235
	v_med3_f32 v76, v76, s68, v235
	v_mov_b32_e32 v87, v1
	v_cvt_pk_fp8_f32 v87, v76, v77
	v_fma_f32 v76, v78, v171, v110
	v_mul_f32_e32 v77, v111, v111
	v_fmac_f32_e32 v77, v76, v76
	v_add_f32_e32 v78, v77, v83
	v_cvt_pk_bf16_f32 v83, v76, v111
	s_waitcnt lgkmcnt(0)
	v_lshlrev_b64 v[84:85], 11, v[128:129]
	v_lshlrev_b32_e32 v77, 16, v83
	v_sub_f32_e32 v76, v76, v77
	v_and_b32_e32 v77, 0xffff0000, v83
	v_sub_f32_e32 v77, v111, v77
	v_mul_f32_e32 v76, 0x43800000, v76
	v_mul_f32_e32 v77, 0x43800000, v77
	v_med3_f32 v76, v76, s68, v235
	v_med3_f32 v77, v77, s68, v235
	v_cvt_pk_fp8_f32 v87, v76, v77 op_sel:[0,0,1]
	v_lshl_add_u64 v[84:85], v[84:85], 0, v[162:163]
	v_lshl_add_u64 v[76:77], v[84:85], 1, s[42:43]
	global_store_dwordx4 v[76:77], v[80:83], off sc1
	v_lshl_add_u64 v[76:77], s[44:45], 0, v[84:85]
	s_waitcnt vmcnt(5)
	v_fma_f32 v73, v73, v171, v105
	global_store_dwordx2 v[76:77], v[86:87], off
	v_fma_f32 v76, v72, v171, v104
	v_mul_f32_e32 v72, v73, v73
	v_fmac_f32_e32 v72, v76, v76
	v_add_f32_e32 v77, v72, v78
	v_cvt_pk_bf16_f32 v72, v76, v73
	v_fmac_f32_e32 v107, v75, v171
	v_and_b32_e32 v78, 0xffff0000, v72
	v_sub_f32_e32 v73, v73, v78
	v_lshlrev_b32_e32 v78, 16, v72
	v_sub_f32_e32 v76, v76, v78
	v_mul_f32_e32 v73, 0x43800000, v73
	v_mul_f32_e32 v76, 0x43800000, v76
	v_med3_f32 v73, v73, s68, v235
	v_med3_f32 v78, v76, s68, v235
	v_mov_b32_e32 v76, v1
	v_cvt_pk_fp8_f32 v76, v78, v73
	v_fma_f32 v74, v74, v171, v106
	v_mul_f32_e32 v73, v107, v107
	v_fmac_f32_e32 v73, v74, v74
	v_add_f32_e32 v75, v73, v77
	v_cvt_pk_bf16_f32 v73, v74, v107
	v_fma_f32 v69, v69, v171, v101
	v_lshlrev_b32_e32 v77, 16, v73
	v_sub_f32_e32 v74, v74, v77
	v_and_b32_e32 v77, 0xffff0000, v73
	v_sub_f32_e32 v77, v107, v77
	v_mul_f32_e32 v74, 0x43800000, v74
	v_mul_f32_e32 v77, 0x43800000, v77
	v_med3_f32 v74, v74, s68, v235
	v_med3_f32 v77, v77, s68, v235
	v_cvt_pk_fp8_f32 v76, v74, v77 op_sel:[0,0,1]
	v_fma_f32 v68, v68, v171, v100
	v_mul_f32_e32 v74, v69, v69
	v_fmac_f32_e32 v74, v68, v68
	v_add_f32_e32 v75, v74, v75
	v_cvt_pk_bf16_f32 v74, v68, v69
	v_fmac_f32_e32 v103, v71, v171
	v_and_b32_e32 v77, 0xffff0000, v74
	v_sub_f32_e32 v69, v69, v77
	v_lshlrev_b32_e32 v77, 16, v74
	v_sub_f32_e32 v68, v68, v77
	v_mul_f32_e32 v69, 0x43800000, v69
	v_mul_f32_e32 v68, 0x43800000, v68
	v_med3_f32 v69, v69, s68, v235
	v_med3_f32 v68, v68, s68, v235
	v_mov_b32_e32 v77, v1
	v_cvt_pk_fp8_f32 v77, v68, v69
	v_fma_f32 v68, v70, v171, v102
	v_mul_f32_e32 v69, v103, v103
	v_fmac_f32_e32 v69, v68, v68
	v_add_f32_e32 v69, v69, v75
	v_cvt_pk_bf16_f32 v75, v68, v103
	ds_bpermute_b32 v71, v0, v69
	v_lshlrev_b32_e32 v70, 16, v75
	v_sub_f32_e32 v68, v68, v70
	v_and_b32_e32 v70, 0xffff0000, v75
	v_sub_f32_e32 v70, v103, v70
	v_mul_f32_e32 v68, 0x43800000, v68
	v_mul_f32_e32 v70, 0x43800000, v70
	v_med3_f32 v68, v68, s68, v235
	v_med3_f32 v70, v70, s68, v235
	v_cvt_pk_fp8_f32 v77, v68, v70 op_sel:[0,0,1]
	s_waitcnt lgkmcnt(0)
	v_add_f32_e32 v68, v69, v71
	ds_bpermute_b32 v69, v174, v68
	v_or_b32_e32 v84, 0x80, v84
	v_lshl_add_u64 v[70:71], v[84:85], 1, s[42:43]
	global_store_dwordx4 v[70:71], v[72:75], off sc1
	v_lshl_add_u64 v[70:71], s[44:45], 0, v[84:85]
	global_store_dwordx2 v[70:71], v[76:77], off
	s_and_saveexec_b64 s[2:3], s[38:39]
	s_cbranch_execz .LBB0_1048
	s_waitcnt lgkmcnt(0)
	v_add_f32_e32 v70, v68, v69
	s_lshl_b32 s20, s56, 2
	v_lshlrev_b64 v[68:69], 7, v[128:129]
	s_ashr_i32 s21, s20, 31
	v_lshl_add_u64 v[68:69], s[8:9], 0, v[68:69]
	v_lshl_add_u64 v[68:69], s[20:21], 2, v[68:69]
	s_lshl_b32 s18, s37, 2
	v_lshl_add_u64 v[68:69], v[68:69], 0, s[18:19]
	global_store_dword v[68:69], v70, off
;     __device__ __forceinline__ void core(const f32x4 (&acc)[2][2][4][2], const Unit& u, int wr, int wc, int fr, int fq, const float (&rsc)[2][4]) const {
;     ...
;             for (int m = 0; m < MB; ++m)
; #pragma unroll
;                 for (int bj = 0; bj < 2; ++bj) { const size_t idx = (size_t)(row0 + ai * HALF + (mh + m) * 16) * D + col0 + bj * HALF;
;                     if (F32IN) { xa[m][bj] = *(const f32x4*)(Xin + idx); xb[m][bj] = *(const f32x4*)(Xin + idx + 4); }
;                     else { va[m][bj] = *(const u32x4*)(Hb + idx); vb[m][bj] = *(const u32x2*)(Hl + idx); } }
; #pragma unroll
;             for (int m = 0; m < MB; ++m) { const int row = row0 + ai * HALF + (mh + m) * 16; float sq = 0.f;
;                 const float rs1 = rsc[ai][mh + m];
; #pragma unroll
;                 for (int bj = 0; bj < 2; ++bj) { const size_t idx = (size_t)row * D + col0 + bj * HALF;
;                     unsigned hw[4]; int lw[2] = {0, 0};
; #pragma unroll
;                     for (int pq = 0; pq < 4; ++pq) {
;                         float h0, h1;
;                         if (F32IN) { h0 = (pq < 2) ? xa[m][bj][2 * pq] : xb[m][bj][2 * pq - 4]; h1 = (pq < 2) ? xa[m][bj][2 * pq + 1] : xb[m][bj][2 * pq - 3]; }
;                         else { const unsigned a = va[m][bj][pq]; const int bw = (int)vb[m][bj][pq >> 1]; const hf32x2 lp = (pq & 1) ? __builtin_amdgcn_cvt_pk_f32_fp8(bw, true) : __builtin_amdgcn_cvt_pk_f32_fp8(bw, false);
;                             h0 = __uint_as_float(a << 16) + lp.x * 0.00390625f; h1 = __uint_as_float(a & 0xffff0000u) + lp.y * 0.00390625f; }
;                         const float o0 = h0 + acc[ai][bj][mh + m][pq >> 1][(2 * pq) & 3] * rs1, o1 = h1 + acc[ai][bj][mh + m][pq >> 1][(2 * pq + 1) & 3] * rs1;
;                         sq += o0 * o0 + o1 * o1;
;                         const unsigned hi = cvt_pk_bf16(o0, o1);
;                         hw[pq] = hi;
;                         const float r0 = __builtin_amdgcn_fmed3f((o0 - __uint_as_float(hi << 16)) * 256.0f, -448.0f, 448.0f), r1 = __builtin_amdgcn_fmed3f((o1 - __uint_as_float(hi & 0xffff0000u)) * 256.0f, -448.0f, 448.0f);
;                         lw[pq >> 1] = (pq & 1) ? __builtin_amdgcn_cvt_pk_fp8_f32(r0, r1, lw[pq >> 1], true) : __builtin_amdgcn_cvt_pk_fp8_f32(r0, r1, lw[pq >> 1], false);
;                     }
.LBB0_1048:
	s_or_b64 exec, exec, s[2:3]
	v_add_u32_e32 v98, 0x80, v164
	v_ashrrev_i32_e32 v99, 31, v98
	s_waitcnt lgkmcnt(0)
	v_lshlrev_b64 v[68:69], 13, v[98:99]
	v_lshl_add_u64 v[68:69], v[166:167], 0, v[68:69]
	global_load_dwordx4 v[92:95], v[68:69], off offset:16
	global_load_dwordx4 v[102:105], v[68:69], off
	global_load_dwordx4 v[84:87], v[68:69], off offset:528
	global_load_dwordx4 v[88:91], v[68:69], off offset:512
	v_add_u32_e32 v96, 0x90, v164
	v_ashrrev_i32_e32 v97, 31, v96
	v_lshlrev_b64 v[68:69], 13, v[96:97]
	v_lshl_add_u64 v[72:73], v[166:167], 0, v[68:69]
	global_load_dwordx4 v[76:79], v[72:73], off offset:16
	global_load_dwordx4 v[80:83], v[72:73], off
	global_load_dwordx4 v[68:71], v[72:73], off offset:528
	s_nop 0
	global_load_dwordx4 v[72:75], v[72:73], off offset:512
	v_lshlrev_b64 v[100:101], 11, v[98:99]
	v_lshl_add_u64 v[100:101], v[100:101], 0, v[162:163]
	s_waitcnt vmcnt(7)
	v_fma_f32 v61, v61, v168, v93
	s_waitcnt vmcnt(6)
	v_fma_f32 v102, v64, v168, v102
	v_fma_f32 v65, v65, v168, v103
	v_cvt_pk_bf16_f32 v64, v102, v65
	v_mul_f32_e32 v103, v65, v65
	v_and_b32_e32 v106, 0xffff0000, v64
	v_sub_f32_e32 v65, v65, v106
	v_lshlrev_b32_e32 v106, 16, v64
	v_fmac_f32_e32 v103, v102, v102
	v_sub_f32_e32 v102, v102, v106
	v_mul_f32_e32 v65, 0x43800000, v65
	v_mul_f32_e32 v102, 0x43800000, v102
	v_med3_f32 v65, v65, s68, v235
	v_med3_f32 v106, v102, s68, v235
	v_mov_b32_e32 v102, v1
	v_fmac_f32_e32 v105, v67, v168
	v_cvt_pk_fp8_f32 v102, v106, v65
	v_fma_f32 v66, v66, v168, v104
	v_mul_f32_e32 v65, v105, v105
	v_fmac_f32_e32 v65, v66, v66
	v_add_f32_e32 v67, v103, v65
	v_cvt_pk_bf16_f32 v65, v66, v105
	v_fma_f32 v60, v60, v168, v92
	v_lshlrev_b32_e32 v103, 16, v65
	v_sub_f32_e32 v66, v66, v103
	v_and_b32_e32 v103, 0xffff0000, v65
	v_sub_f32_e32 v103, v105, v103
	v_mul_f32_e32 v66, 0x43800000, v66
	v_mul_f32_e32 v103, 0x43800000, v103
	v_med3_f32 v66, v66, s68, v235
	v_med3_f32 v103, v103, s68, v235
	v_cvt_pk_fp8_f32 v102, v66, v103 op_sel:[0,0,1]
	v_mul_f32_e32 v66, v61, v61
	v_fmac_f32_e32 v66, v60, v60
	v_add_f32_e32 v67, v67, v66
	v_cvt_pk_bf16_f32 v66, v60, v61
	v_mov_b32_e32 v103, v1
	v_and_b32_e32 v92, 0xffff0000, v66
	v_sub_f32_e32 v61, v61, v92
	v_lshlrev_b32_e32 v92, 16, v66
	v_sub_f32_e32 v60, v60, v92
	v_mul_f32_e32 v61, 0x43800000, v61
	v_mul_f32_e32 v60, 0x43800000, v60
	v_med3_f32 v61, v61, s68, v235
	v_med3_f32 v60, v60, s68, v235
	v_fmac_f32_e32 v95, v63, v168
	v_cvt_pk_fp8_f32 v103, v60, v61
	v_fma_f32 v60, v62, v168, v94
	v_mul_f32_e32 v61, v95, v95
	v_fmac_f32_e32 v61, v60, v60
	v_add_f32_e32 v62, v61, v67
	v_cvt_pk_bf16_f32 v67, v60, v95
	s_waitcnt vmcnt(4)
	v_fma_f32 v57, v57, v168, v89
	v_lshlrev_b32_e32 v61, 16, v67
	v_sub_f32_e32 v60, v60, v61
	v_and_b32_e32 v61, 0xffff0000, v67
	v_sub_f32_e32 v61, v95, v61
	v_mul_f32_e32 v60, 0x43800000, v60
	v_mul_f32_e32 v61, 0x43800000, v61
	v_med3_f32 v60, v60, s68, v235
	v_med3_f32 v61, v61, s68, v235
	v_cvt_pk_fp8_f32 v103, v60, v61 op_sel:[0,0,1]
	v_lshl_add_u64 v[60:61], v[100:101], 1, s[42:43]
	global_store_dwordx4 v[60:61], v[64:67], off sc1
	v_lshl_add_u64 v[60:61], s[44:45], 0, v[100:101]
	global_store_dwordx2 v[60:61], v[102:103], off
	v_fma_f32 v60, v56, v168, v88
	v_mul_f32_e32 v56, v57, v57
	v_fmac_f32_e32 v56, v60, v60
	v_add_f32_e32 v61, v56, v62
	v_cvt_pk_bf16_f32 v56, v60, v57
	v_fmac_f32_e32 v91, v59, v168
	v_and_b32_e32 v62, 0xffff0000, v56
	v_sub_f32_e32 v57, v57, v62
	v_lshlrev_b32_e32 v62, 16, v56
	v_sub_f32_e32 v60, v60, v62
	v_mul_f32_e32 v57, 0x43800000, v57
	v_mul_f32_e32 v60, 0x43800000, v60
	v_med3_f32 v57, v57, s68, v235
	v_med3_f32 v62, v60, s68, v235
	v_mov_b32_e32 v60, v1
	v_cvt_pk_fp8_f32 v60, v62, v57
	v_fma_f32 v58, v58, v168, v90
	v_mul_f32_e32 v57, v91, v91
	v_fmac_f32_e32 v57, v58, v58
	v_add_f32_e32 v59, v57, v61
	v_cvt_pk_bf16_f32 v57, v58, v91
	v_fma_f32 v53, v53, v168, v85
	v_lshlrev_b32_e32 v61, 16, v57
	v_sub_f32_e32 v58, v58, v61
	v_and_b32_e32 v61, 0xffff0000, v57
	v_sub_f32_e32 v61, v91, v61
	v_mul_f32_e32 v58, 0x43800000, v58
	v_mul_f32_e32 v61, 0x43800000, v61
	v_med3_f32 v58, v58, s68, v235
	v_med3_f32 v61, v61, s68, v235
	v_cvt_pk_fp8_f32 v60, v58, v61 op_sel:[0,0,1]
	v_fma_f32 v52, v52, v168, v84
	v_mul_f32_e32 v58, v53, v53
	v_fmac_f32_e32 v58, v52, v52
	v_add_f32_e32 v59, v58, v59
	v_cvt_pk_bf16_f32 v58, v52, v53
	v_fmac_f32_e32 v87, v55, v168
	v_and_b32_e32 v61, 0xffff0000, v58
	v_sub_f32_e32 v53, v53, v61
	v_lshlrev_b32_e32 v61, 16, v58
	v_sub_f32_e32 v52, v52, v61
	v_mul_f32_e32 v53, 0x43800000, v53
	v_mul_f32_e32 v52, 0x43800000, v52
	v_med3_f32 v53, v53, s68, v235
	v_med3_f32 v52, v52, s68, v235
	v_mov_b32_e32 v61, v1
	v_cvt_pk_fp8_f32 v61, v52, v53
	v_fma_f32 v52, v54, v168, v86
	v_mul_f32_e32 v53, v87, v87
	v_fmac_f32_e32 v53, v52, v52
	v_add_f32_e32 v54, v53, v59
	v_cvt_pk_bf16_f32 v59, v52, v87
	v_or_b32_e32 v100, 0x80, v100
	v_lshlrev_b32_e32 v53, 16, v59
	v_sub_f32_e32 v52, v52, v53
	v_and_b32_e32 v53, 0xffff0000, v59
	v_sub_f32_e32 v53, v87, v53
	v_mul_f32_e32 v52, 0x43800000, v52
	v_mul_f32_e32 v53, 0x43800000, v53
	v_med3_f32 v52, v52, s68, v235
	v_med3_f32 v53, v53, s68, v235
	v_cvt_pk_fp8_f32 v61, v52, v53 op_sel:[0,0,1]
	v_lshl_add_u64 v[52:53], v[100:101], 1, s[42:43]
	global_store_dwordx4 v[52:53], v[56:59], off sc1
	v_lshl_add_u64 v[52:53], s[44:45], 0, v[100:101]
	global_store_dwordx2 v[52:53], v[60:61], off
	ds_bpermute_b32 v52, v0, v54
	s_waitcnt lgkmcnt(0)
	v_add_f32_e32 v52, v54, v52
	ds_bpermute_b32 v53, v174, v52
	s_and_saveexec_b64 s[2:3], s[38:39]
	s_cbranch_execz .LBB0_1050
	s_waitcnt lgkmcnt(0)
	v_add_f32_e32 v54, v52, v53
	s_lshl_b32 s20, s56, 2
	v_lshlrev_b64 v[52:53], 7, v[98:99]
	s_ashr_i32 s21, s20, 31
	v_lshl_add_u64 v[52:53], s[8:9], 0, v[52:53]
	v_lshl_add_u64 v[52:53], s[20:21], 2, v[52:53]
	s_lshl_b32 s18, s37, 2
	v_lshl_add_u64 v[52:53], v[52:53], 0, s[18:19]
	global_store_dword v[52:53], v54, off
; __device__ __forceinline__ unsigned cvt_pk_bf16(float lo, float hi) { unsigned r; asm volatile("v_cvt_pk_bf16_f32 %0, %1, %2" : "=v"(r) : "v"(lo), "v"(hi)); return r; }
;     __device__ __forceinline__ void core(const f32x4 (&acc)[2][2][4][2], const Unit& u, int wr, int wc, int fr, int fq, const float (&rsc)[2][4]) const {
;     ...
;             for (int m = 0; m < MB; ++m) { const int row = row0 + ai * HALF + (mh + m) * 16; float sq = 0.f;
;                 const float rs1 = rsc[ai][mh + m];
; #pragma unroll
;                 for (int bj = 0; bj < 2; ++bj) { const size_t idx = (size_t)row * D + col0 + bj * HALF;
;                     unsigned hw[4]; int lw[2] = {0, 0};
; #pragma unroll
;                     for (int pq = 0; pq < 4; ++pq) {
;                         float h0, h1;
;                         if (F32IN) { h0 = (pq < 2) ? xa[m][bj][2 * pq] : xb[m][bj][2 * pq - 4]; h1 = (pq < 2) ? xa[m][bj][2 * pq + 1] : xb[m][bj][2 * pq - 3]; }
;                         else { const unsigned a = va[m][bj][pq]; const int bw = (int)vb[m][bj][pq >> 1]; const hf32x2 lp = (pq & 1) ? __builtin_amdgcn_cvt_pk_f32_fp8(bw, true) : __builtin_amdgcn_cvt_pk_f32_fp8(bw, false);
;                             h0 = __uint_as_float(a << 16) + lp.x * 0.00390625f; h1 = __uint_as_float(a & 0xffff0000u) + lp.y * 0.00390625f; }
;                         const float o0 = h0 + acc[ai][bj][mh + m][pq >> 1][(2 * pq) & 3] * rs1, o1 = h1 + acc[ai][bj][mh + m][pq >> 1][(2 * pq + 1) & 3] * rs1;
;                         sq += o0 * o0 + o1 * o1;
;                         const unsigned hi = cvt_pk_bf16(o0, o1);
;                         hw[pq] = hi;
;                         const float r0 = __builtin_amdgcn_fmed3f((o0 - __uint_as_float(hi << 16)) * 256.0f, -448.0f, 448.0f), r1 = __builtin_amdgcn_fmed3f((o1 - __uint_as_float(hi & 0xffff0000u)) * 256.0f, -448.0f, 448.0f);
;                         lw[pq >> 1] = (pq & 1) ? __builtin_amdgcn_cvt_pk_fp8_f32(r0, r1, lw[pq >> 1], true) : __builtin_amdgcn_cvt_pk_fp8_f32(r0, r1, lw[pq >> 1], false);
;                     }
;                     *(u32x4*)(Hb + idx) = (u32x4){hw[0], hw[1], hw[2], hw[3]}; *(u32x2*)(Hl + idx) = (u32x2){(unsigned)lw[0], (unsigned)lw[1]}; }
;                 sq += __shfl_xor(sq, 16); sq += __shfl_xor(sq, 32); if (fq == 0) ss[(size_t)row * 32 + u.pn * 4 + wc] = sq; }
.LBB0_1050:
	s_or_b64 exec, exec, s[2:3]
	s_waitcnt vmcnt(6)
	v_fma_f32 v54, v48, v169, v80
	v_fma_f32 v49, v49, v169, v81
	v_cvt_pk_bf16_f32 v48, v54, v49
	v_mul_f32_e32 v55, v49, v49
	v_and_b32_e32 v56, 0xffff0000, v48
	v_sub_f32_e32 v49, v49, v56
	v_lshlrev_b32_e32 v56, 16, v48
	v_fmac_f32_e32 v55, v54, v54
	v_sub_f32_e32 v54, v54, v56
	v_mul_f32_e32 v49, 0x43800000, v49
	v_mul_f32_e32 v54, 0x43800000, v54
	v_med3_f32 v49, v49, s68, v235
	v_med3_f32 v56, v54, s68, v235
	v_mov_b32_e32 v54, v1
	v_fmac_f32_e32 v83, v51, v169
	v_cvt_pk_fp8_f32 v54, v56, v49
	v_fma_f32 v50, v50, v169, v82
	v_mul_f32_e32 v49, v83, v83
	v_fmac_f32_e32 v49, v50, v50
	v_add_f32_e32 v51, v55, v49
	v_cvt_pk_bf16_f32 v49, v50, v83
	v_fma_f32 v45, v45, v169, v77
	v_lshlrev_b32_e32 v55, 16, v49
	v_sub_f32_e32 v50, v50, v55
	v_and_b32_e32 v55, 0xffff0000, v49
	v_sub_f32_e32 v55, v83, v55
	v_mul_f32_e32 v50, 0x43800000, v50
	v_mul_f32_e32 v55, 0x43800000, v55
	v_med3_f32 v50, v50, s68, v235
	v_med3_f32 v55, v55, s68, v235
	v_cvt_pk_fp8_f32 v54, v50, v55 op_sel:[0,0,1]
	v_fma_f32 v44, v44, v169, v76
	v_mul_f32_e32 v50, v45, v45
	v_fmac_f32_e32 v50, v44, v44
	v_add_f32_e32 v51, v51, v50
	v_cvt_pk_bf16_f32 v50, v44, v45
	v_fmac_f32_e32 v79, v47, v169
	v_and_b32_e32 v55, 0xffff0000, v50
	v_sub_f32_e32 v45, v45, v55
	v_lshlrev_b32_e32 v55, 16, v50
	v_sub_f32_e32 v44, v44, v55
	v_mul_f32_e32 v45, 0x43800000, v45
	v_mul_f32_e32 v44, 0x43800000, v44
	v_med3_f32 v45, v45, s68, v235
	v_med3_f32 v44, v44, s68, v235
	v_mov_b32_e32 v55, v1
	v_cvt_pk_fp8_f32 v55, v44, v45
	v_fma_f32 v44, v46, v169, v78
	v_mul_f32_e32 v45, v79, v79
	v_fmac_f32_e32 v45, v44, v44
	v_add_f32_e32 v46, v45, v51
	v_cvt_pk_bf16_f32 v51, v44, v79
	s_waitcnt lgkmcnt(0)
	v_lshlrev_b64 v[52:53], 11, v[96:97]
	v_lshlrev_b32_e32 v45, 16, v51
	v_sub_f32_e32 v44, v44, v45
	v_and_b32_e32 v45, 0xffff0000, v51
	v_sub_f32_e32 v45, v79, v45
	v_mul_f32_e32 v44, 0x43800000, v44
	v_mul_f32_e32 v45, 0x43800000, v45
	v_med3_f32 v44, v44, s68, v235
	v_med3_f32 v45, v45, s68, v235
	v_cvt_pk_fp8_f32 v55, v44, v45 op_sel:[0,0,1]
	v_lshl_add_u64 v[52:53], v[52:53], 0, v[162:163]
	v_lshl_add_u64 v[44:45], v[52:53], 1, s[42:43]
	global_store_dwordx4 v[44:45], v[48:51], off sc1
	v_lshl_add_u64 v[44:45], s[44:45], 0, v[52:53]
	s_waitcnt vmcnt(5)
	v_fma_f32 v41, v41, v169, v73
	global_store_dwordx2 v[44:45], v[54:55], off
	v_fma_f32 v44, v40, v169, v72
	v_mul_f32_e32 v40, v41, v41
	v_fmac_f32_e32 v40, v44, v44
	v_add_f32_e32 v45, v40, v46
	v_cvt_pk_bf16_f32 v40, v44, v41
	v_fmac_f32_e32 v75, v43, v169
	v_and_b32_e32 v46, 0xffff0000, v40
	v_sub_f32_e32 v41, v41, v46
	v_lshlrev_b32_e32 v46, 16, v40
	v_sub_f32_e32 v44, v44, v46
	v_mul_f32_e32 v41, 0x43800000, v41
	v_mul_f32_e32 v44, 0x43800000, v44
	v_med3_f32 v41, v41, s68, v235
	v_med3_f32 v46, v44, s68, v235
	v_mov_b32_e32 v44, v1
	v_cvt_pk_fp8_f32 v44, v46, v41
	v_fma_f32 v42, v42, v169, v74
	v_mul_f32_e32 v41, v75, v75
	v_fmac_f32_e32 v41, v42, v42
	v_add_f32_e32 v43, v41, v45
	v_cvt_pk_bf16_f32 v41, v42, v75
	v_fma_f32 v37, v37, v169, v69
	v_lshlrev_b32_e32 v45, 16, v41
	v_sub_f32_e32 v42, v42, v45
	v_and_b32_e32 v45, 0xffff0000, v41
	v_sub_f32_e32 v45, v75, v45
	v_mul_f32_e32 v42, 0x43800000, v42
	v_mul_f32_e32 v45, 0x43800000, v45
	v_med3_f32 v42, v42, s68, v235
	v_med3_f32 v45, v45, s68, v235
	v_cvt_pk_fp8_f32 v44, v42, v45 op_sel:[0,0,1]
	v_fma_f32 v36, v36, v169, v68
	v_mul_f32_e32 v42, v37, v37
	v_fmac_f32_e32 v42, v36, v36
	v_add_f32_e32 v43, v42, v43
	v_cvt_pk_bf16_f32 v42, v36, v37
	v_fmac_f32_e32 v71, v39, v169
	v_and_b32_e32 v45, 0xffff0000, v42
	v_sub_f32_e32 v37, v37, v45
	v_lshlrev_b32_e32 v45, 16, v42
	v_sub_f32_e32 v36, v36, v45
	v_mul_f32_e32 v37, 0x43800000, v37
	v_mul_f32_e32 v36, 0x43800000, v36
	v_med3_f32 v37, v37, s68, v235
	v_med3_f32 v36, v36, s68, v235
	v_mov_b32_e32 v45, v1
	v_cvt_pk_fp8_f32 v45, v36, v37
	v_fma_f32 v36, v38, v169, v70
	v_mul_f32_e32 v37, v71, v71
	v_fmac_f32_e32 v37, v36, v36
	v_add_f32_e32 v37, v37, v43
	v_cvt_pk_bf16_f32 v43, v36, v71
	ds_bpermute_b32 v39, v0, v37
	v_lshlrev_b32_e32 v38, 16, v43
	v_sub_f32_e32 v36, v36, v38
	v_and_b32_e32 v38, 0xffff0000, v43
	v_sub_f32_e32 v38, v71, v38
	v_mul_f32_e32 v36, 0x43800000, v36
	v_mul_f32_e32 v38, 0x43800000, v38
	v_med3_f32 v36, v36, s68, v235
	v_med3_f32 v38, v38, s68, v235
	v_cvt_pk_fp8_f32 v45, v36, v38 op_sel:[0,0,1]
	s_waitcnt lgkmcnt(0)
	v_add_f32_e32 v36, v37, v39
	ds_bpermute_b32 v37, v174, v36
	v_or_b32_e32 v52, 0x80, v52
	v_lshl_add_u64 v[38:39], v[52:53], 1, s[42:43]
	global_store_dwordx4 v[38:39], v[40:43], off sc1
	v_lshl_add_u64 v[38:39], s[44:45], 0, v[52:53]
	global_store_dwordx2 v[38:39], v[44:45], off
	s_and_saveexec_b64 s[2:3], s[38:39]
	s_cbranch_execz .LBB0_1052
	s_waitcnt lgkmcnt(0)
	v_add_f32_e32 v38, v36, v37
	s_lshl_b32 s20, s56, 2
	v_lshlrev_b64 v[36:37], 7, v[96:97]
	s_ashr_i32 s21, s20, 31
	v_lshl_add_u64 v[36:37], s[8:9], 0, v[36:37]
	v_lshl_add_u64 v[36:37], s[20:21], 2, v[36:37]
	s_lshl_b32 s18, s37, 2
	v_lshl_add_u64 v[36:37], v[36:37], 0, s[18:19]
	global_store_dword v[36:37], v38, off
;     __device__ __forceinline__ void core(const f32x4 (&acc)[2][2][4][2], const Unit& u, int wr, int wc, int fr, int fq, const float (&rsc)[2][4]) const {
;     ...
;             for (int m = 0; m < MB; ++m)
; #pragma unroll
;                 for (int bj = 0; bj < 2; ++bj) { const size_t idx = (size_t)(row0 + ai * HALF + (mh + m) * 16) * D + col0 + bj * HALF;
;                     if (F32IN) { xa[m][bj] = *(const f32x4*)(Xin + idx); xb[m][bj] = *(const f32x4*)(Xin + idx + 4); }
;                     else { va[m][bj] = *(const u32x4*)(Hb + idx); vb[m][bj] = *(const u32x2*)(Hl + idx); } }
; #pragma unroll
;             for (int m = 0; m < MB; ++m) { const int row = row0 + ai * HALF + (mh + m) * 16; float sq = 0.f;
;                 const float rs1 = rsc[ai][mh + m];
; #pragma unroll
;                 for (int bj = 0; bj < 2; ++bj) { const size_t idx = (size_t)row * D + col0 + bj * HALF;
;                     unsigned hw[4]; int lw[2] = {0, 0};
; #pragma unroll
;                     for (int pq = 0; pq < 4; ++pq) {
;                         float h0, h1;
;                         if (F32IN) { h0 = (pq < 2) ? xa[m][bj][2 * pq] : xb[m][bj][2 * pq - 4]; h1 = (pq < 2) ? xa[m][bj][2 * pq + 1] : xb[m][bj][2 * pq - 3]; }
;                         else { const unsigned a = va[m][bj][pq]; const int bw = (int)vb[m][bj][pq >> 1]; const hf32x2 lp = (pq & 1) ? __builtin_amdgcn_cvt_pk_f32_fp8(bw, true) : __builtin_amdgcn_cvt_pk_f32_fp8(bw, false);
;                             h0 = __uint_as_float(a << 16) + lp.x * 0.00390625f; h1 = __uint_as_float(a & 0xffff0000u) + lp.y * 0.00390625f; }
;                         const float o0 = h0 + acc[ai][bj][mh + m][pq >> 1][(2 * pq) & 3] * rs1, o1 = h1 + acc[ai][bj][mh + m][pq >> 1][(2 * pq + 1) & 3] * rs1;
;                         sq += o0 * o0 + o1 * o1;
;                         const unsigned hi = cvt_pk_bf16(o0, o1);
;                         hw[pq] = hi;
;                         const float r0 = __builtin_amdgcn_fmed3f((o0 - __uint_as_float(hi << 16)) * 256.0f, -448.0f, 448.0f), r1 = __builtin_amdgcn_fmed3f((o1 - __uint_as_float(hi & 0xffff0000u)) * 256.0f, -448.0f, 448.0f);
;                         lw[pq >> 1] = (pq & 1) ? __builtin_amdgcn_cvt_pk_fp8_f32(r0, r1, lw[pq >> 1], true) : __builtin_amdgcn_cvt_pk_fp8_f32(r0, r1, lw[pq >> 1], false);
;                     }
.LBB0_1052:
	s_or_b64 exec, exec, s[2:3]
	v_add_u32_e32 v66, 0xa0, v164
	v_ashrrev_i32_e32 v67, 31, v66
	s_waitcnt lgkmcnt(0)
	v_lshlrev_b64 v[36:37], 13, v[66:67]
	v_lshl_add_u64 v[36:37], v[166:167], 0, v[36:37]
	global_load_dwordx4 v[60:63], v[36:37], off offset:16
	global_load_dwordx4 v[70:73], v[36:37], off
	global_load_dwordx4 v[52:55], v[36:37], off offset:528
	global_load_dwordx4 v[56:59], v[36:37], off offset:512
	v_add_u32_e32 v64, 0xb0, v164
	v_ashrrev_i32_e32 v65, 31, v64
	v_lshlrev_b64 v[36:37], 13, v[64:65]
	v_lshl_add_u64 v[40:41], v[166:167], 0, v[36:37]
	global_load_dwordx4 v[44:47], v[40:41], off offset:16
	global_load_dwordx4 v[48:51], v[40:41], off
	global_load_dwordx4 v[36:39], v[40:41], off offset:528
	s_nop 0
	global_load_dwordx4 v[40:43], v[40:41], off offset:512
	v_lshlrev_b64 v[68:69], 11, v[66:67]
	v_lshl_add_u64 v[68:69], v[68:69], 0, v[162:163]
	s_waitcnt vmcnt(7)
	v_fma_f32 v29, v29, v2, v61
	s_waitcnt vmcnt(6)
	v_fma_f32 v70, v32, v2, v70
	v_fma_f32 v33, v33, v2, v71
	v_cvt_pk_bf16_f32 v32, v70, v33
	v_mul_f32_e32 v71, v33, v33
	v_and_b32_e32 v74, 0xffff0000, v32
	v_sub_f32_e32 v33, v33, v74
	v_lshlrev_b32_e32 v74, 16, v32
	v_fmac_f32_e32 v71, v70, v70
	v_sub_f32_e32 v70, v70, v74
	v_mul_f32_e32 v33, 0x43800000, v33
	v_mul_f32_e32 v70, 0x43800000, v70
	v_med3_f32 v33, v33, s68, v235
	v_med3_f32 v74, v70, s68, v235
	v_mov_b32_e32 v70, v1
	v_fmac_f32_e32 v73, v35, v2
	v_cvt_pk_fp8_f32 v70, v74, v33
	v_fma_f32 v34, v34, v2, v72
	v_mul_f32_e32 v33, v73, v73
	v_fmac_f32_e32 v33, v34, v34
	v_add_f32_e32 v35, v71, v33
	v_cvt_pk_bf16_f32 v33, v34, v73
	v_fma_f32 v28, v28, v2, v60
	v_lshlrev_b32_e32 v71, 16, v33
	v_sub_f32_e32 v34, v34, v71
	v_and_b32_e32 v71, 0xffff0000, v33
	v_sub_f32_e32 v71, v73, v71
	v_mul_f32_e32 v34, 0x43800000, v34
	v_mul_f32_e32 v71, 0x43800000, v71
	v_med3_f32 v34, v34, s68, v235
	v_med3_f32 v71, v71, s68, v235
	v_cvt_pk_fp8_f32 v70, v34, v71 op_sel:[0,0,1]
	v_mul_f32_e32 v34, v29, v29
	v_fmac_f32_e32 v34, v28, v28
	v_add_f32_e32 v35, v35, v34
	v_cvt_pk_bf16_f32 v34, v28, v29
	v_mov_b32_e32 v71, v1
	v_and_b32_e32 v60, 0xffff0000, v34
	v_sub_f32_e32 v29, v29, v60
	v_lshlrev_b32_e32 v60, 16, v34
	v_sub_f32_e32 v28, v28, v60
	v_mul_f32_e32 v29, 0x43800000, v29
	v_mul_f32_e32 v28, 0x43800000, v28
	v_med3_f32 v29, v29, s68, v235
	v_med3_f32 v28, v28, s68, v235
	v_fmac_f32_e32 v63, v31, v2
	v_cvt_pk_fp8_f32 v71, v28, v29
	v_fma_f32 v28, v30, v2, v62
	v_mul_f32_e32 v29, v63, v63
	v_fmac_f32_e32 v29, v28, v28
	v_add_f32_e32 v30, v29, v35
	v_cvt_pk_bf16_f32 v35, v28, v63
	s_waitcnt vmcnt(4)
	v_fma_f32 v25, v25, v2, v57
	v_lshlrev_b32_e32 v29, 16, v35
	v_sub_f32_e32 v28, v28, v29
	v_and_b32_e32 v29, 0xffff0000, v35
	v_sub_f32_e32 v29, v63, v29
	v_mul_f32_e32 v28, 0x43800000, v28
	v_mul_f32_e32 v29, 0x43800000, v29
	v_med3_f32 v28, v28, s68, v235
	v_med3_f32 v29, v29, s68, v235
	v_cvt_pk_fp8_f32 v71, v28, v29 op_sel:[0,0,1]
	v_lshl_add_u64 v[28:29], v[68:69], 1, s[42:43]
	global_store_dwordx4 v[28:29], v[32:35], off sc1
	v_lshl_add_u64 v[28:29], s[44:45], 0, v[68:69]
	global_store_dwordx2 v[28:29], v[70:71], off
	v_fma_f32 v28, v24, v2, v56
	v_mul_f32_e32 v24, v25, v25
	v_fmac_f32_e32 v24, v28, v28
	v_add_f32_e32 v29, v24, v30
	v_cvt_pk_bf16_f32 v24, v28, v25
	v_fmac_f32_e32 v59, v27, v2
	v_and_b32_e32 v30, 0xffff0000, v24
	v_sub_f32_e32 v25, v25, v30
	v_lshlrev_b32_e32 v30, 16, v24
	v_sub_f32_e32 v28, v28, v30
	v_mul_f32_e32 v25, 0x43800000, v25
	v_mul_f32_e32 v28, 0x43800000, v28
	v_med3_f32 v25, v25, s68, v235
	v_med3_f32 v30, v28, s68, v235
	v_mov_b32_e32 v28, v1
	v_cvt_pk_fp8_f32 v28, v30, v25
	v_fma_f32 v26, v26, v2, v58
	v_mul_f32_e32 v25, v59, v59
	v_fmac_f32_e32 v25, v26, v26
	v_add_f32_e32 v27, v25, v29
	v_cvt_pk_bf16_f32 v25, v26, v59
	v_fma_f32 v21, v21, v2, v53
	v_lshlrev_b32_e32 v29, 16, v25
	v_sub_f32_e32 v26, v26, v29
	v_and_b32_e32 v29, 0xffff0000, v25
	v_sub_f32_e32 v29, v59, v29
	v_mul_f32_e32 v26, 0x43800000, v26
	v_mul_f32_e32 v29, 0x43800000, v29
	v_med3_f32 v26, v26, s68, v235
	v_med3_f32 v29, v29, s68, v235
	v_cvt_pk_fp8_f32 v28, v26, v29 op_sel:[0,0,1]
	v_fma_f32 v20, v20, v2, v52
	v_mul_f32_e32 v26, v21, v21
	v_fmac_f32_e32 v26, v20, v20
	v_add_f32_e32 v27, v26, v27
	v_cvt_pk_bf16_f32 v26, v20, v21
	v_fmac_f32_e32 v55, v23, v2
	v_and_b32_e32 v29, 0xffff0000, v26
	v_sub_f32_e32 v21, v21, v29
	v_lshlrev_b32_e32 v29, 16, v26
	v_sub_f32_e32 v20, v20, v29
	v_mul_f32_e32 v21, 0x43800000, v21
	v_mul_f32_e32 v20, 0x43800000, v20
	v_med3_f32 v21, v21, s68, v235
	v_med3_f32 v20, v20, s68, v235
	v_mov_b32_e32 v29, v1
	v_cvt_pk_fp8_f32 v29, v20, v21
	v_fma_f32 v20, v22, v2, v54
	v_mul_f32_e32 v2, v55, v55
	v_fmac_f32_e32 v2, v20, v20
	v_add_f32_e32 v2, v2, v27
	v_cvt_pk_bf16_f32 v27, v20, v55
	v_or_b32_e32 v68, 0x80, v68
	v_lshlrev_b32_e32 v21, 16, v27
	v_sub_f32_e32 v20, v20, v21
	v_and_b32_e32 v21, 0xffff0000, v27
	v_sub_f32_e32 v21, v55, v21
	v_mul_f32_e32 v20, 0x43800000, v20
	v_mul_f32_e32 v21, 0x43800000, v21
	v_med3_f32 v20, v20, s68, v235
	v_med3_f32 v21, v21, s68, v235
	v_cvt_pk_fp8_f32 v29, v20, v21 op_sel:[0,0,1]
	v_lshl_add_u64 v[20:21], v[68:69], 1, s[42:43]
	global_store_dwordx4 v[20:21], v[24:27], off sc1
	v_lshl_add_u64 v[20:21], s[44:45], 0, v[68:69]
	global_store_dwordx2 v[20:21], v[28:29], off
	ds_bpermute_b32 v20, v0, v2
	s_waitcnt lgkmcnt(0)
	v_add_f32_e32 v2, v2, v20
	ds_bpermute_b32 v20, v174, v2
	s_and_saveexec_b64 s[2:3], s[38:39]
	s_cbranch_execz .LBB0_1054
	s_waitcnt lgkmcnt(0)
	v_add_f32_e32 v2, v2, v20
	s_lshl_b32 s20, s56, 2
	v_lshlrev_b64 v[20:21], 7, v[66:67]
	s_ashr_i32 s21, s20, 31
	v_lshl_add_u64 v[20:21], s[8:9], 0, v[20:21]
	v_lshl_add_u64 v[20:21], s[20:21], 2, v[20:21]
	s_lshl_b32 s18, s37, 2
	v_lshl_add_u64 v[20:21], v[20:21], 0, s[18:19]
	global_store_dword v[20:21], v2, off
; __device__ __forceinline__ unsigned cvt_pk_bf16(float lo, float hi) { unsigned r; asm volatile("v_cvt_pk_bf16_f32 %0, %1, %2" : "=v"(r) : "v"(lo), "v"(hi)); return r; }
;     __device__ __forceinline__ void core(const f32x4 (&acc)[2][2][4][2], const Unit& u, int wr, int wc, int fr, int fq, const float (&rsc)[2][4]) const {
;     ...
;             for (int m = 0; m < MB; ++m) { const int row = row0 + ai * HALF + (mh + m) * 16; float sq = 0.f;
;                 const float rs1 = rsc[ai][mh + m];
; #pragma unroll
;                 for (int bj = 0; bj < 2; ++bj) { const size_t idx = (size_t)row * D + col0 + bj * HALF;
;                     unsigned hw[4]; int lw[2] = {0, 0};
; #pragma unroll
;                     for (int pq = 0; pq < 4; ++pq) {
;                         float h0, h1;
;                         if (F32IN) { h0 = (pq < 2) ? xa[m][bj][2 * pq] : xb[m][bj][2 * pq - 4]; h1 = (pq < 2) ? xa[m][bj][2 * pq + 1] : xb[m][bj][2 * pq - 3]; }
;                         else { const unsigned a = va[m][bj][pq]; const int bw = (int)vb[m][bj][pq >> 1]; const hf32x2 lp = (pq & 1) ? __builtin_amdgcn_cvt_pk_f32_fp8(bw, true) : __builtin_amdgcn_cvt_pk_f32_fp8(bw, false);
;                             h0 = __uint_as_float(a << 16) + lp.x * 0.00390625f; h1 = __uint_as_float(a & 0xffff0000u) + lp.y * 0.00390625f; }
;                         const float o0 = h0 + acc[ai][bj][mh + m][pq >> 1][(2 * pq) & 3] * rs1, o1 = h1 + acc[ai][bj][mh + m][pq >> 1][(2 * pq + 1) & 3] * rs1;
;                         sq += o0 * o0 + o1 * o1;
;                         const unsigned hi = cvt_pk_bf16(o0, o1);
;                         hw[pq] = hi;
;                         const float r0 = __builtin_amdgcn_fmed3f((o0 - __uint_as_float(hi << 16)) * 256.0f, -448.0f, 448.0f), r1 = __builtin_amdgcn_fmed3f((o1 - __uint_as_float(hi & 0xffff0000u)) * 256.0f, -448.0f, 448.0f);
;                         lw[pq >> 1] = (pq & 1) ? __builtin_amdgcn_cvt_pk_fp8_f32(r0, r1, lw[pq >> 1], true) : __builtin_amdgcn_cvt_pk_fp8_f32(r0, r1, lw[pq >> 1], false);
;                     }
;                     *(u32x4*)(Hb + idx) = (u32x4){hw[0], hw[1], hw[2], hw[3]}; *(u32x2*)(Hl + idx) = (u32x2){(unsigned)lw[0], (unsigned)lw[1]}; }
;                 sq += __shfl_xor(sq, 16); sq += __shfl_xor(sq, 32); if (fq == 0) ss[(size_t)row * 32 + u.pn * 4 + wc] = sq; }
.LBB0_1054:
	s_or_b64 exec, exec, s[2:3]
	s_waitcnt vmcnt(6)
	v_fma_f32 v2, v16, v3, v48
	v_fma_f32 v17, v17, v3, v49
	v_cvt_pk_bf16_f32 v16, v2, v17
	v_mul_f32_e32 v23, v17, v17
	v_and_b32_e32 v22, 0xffff0000, v16
	v_sub_f32_e32 v17, v17, v22
	v_lshlrev_b32_e32 v22, 16, v16
	v_fmac_f32_e32 v23, v2, v2
	v_sub_f32_e32 v2, v2, v22
	v_mul_f32_e32 v17, 0x43800000, v17
	v_mul_f32_e32 v2, 0x43800000, v2
	v_med3_f32 v17, v17, s68, v235
	v_med3_f32 v2, v2, s68, v235
	v_mov_b32_e32 v22, v1
	v_fmac_f32_e32 v51, v19, v3
	v_cvt_pk_fp8_f32 v22, v2, v17
	v_fma_f32 v2, v18, v3, v50
	v_mul_f32_e32 v17, v51, v51
	v_fmac_f32_e32 v17, v2, v2
	v_add_f32_e32 v18, v23, v17
	v_cvt_pk_bf16_f32 v17, v2, v51
	v_mov_b32_e32 v23, v1
	v_lshlrev_b32_e32 v19, 16, v17
	v_sub_f32_e32 v2, v2, v19
	v_and_b32_e32 v19, 0xffff0000, v17
	v_sub_f32_e32 v19, v51, v19
	v_mul_f32_e32 v2, 0x43800000, v2
	v_mul_f32_e32 v19, 0x43800000, v19
	v_med3_f32 v2, v2, s68, v235
	v_med3_f32 v19, v19, s68, v235
	v_cvt_pk_fp8_f32 v22, v2, v19 op_sel:[0,0,1]
	v_fma_f32 v2, v12, v3, v44
	v_fma_f32 v12, v13, v3, v45
	v_mul_f32_e32 v13, v12, v12
	v_fmac_f32_e32 v13, v2, v2
	v_add_f32_e32 v13, v18, v13
	v_cvt_pk_bf16_f32 v18, v2, v12
	v_fmac_f32_e32 v47, v15, v3
	v_and_b32_e32 v19, 0xffff0000, v18
	v_sub_f32_e32 v12, v12, v19
	v_lshlrev_b32_e32 v19, 16, v18
	v_sub_f32_e32 v2, v2, v19
	v_mul_f32_e32 v12, 0x43800000, v12
	v_mul_f32_e32 v2, 0x43800000, v2
	v_med3_f32 v12, v12, s68, v235
	v_med3_f32 v2, v2, s68, v235
	v_cvt_pk_fp8_f32 v23, v2, v12
	v_fma_f32 v2, v14, v3, v46
	v_mul_f32_e32 v12, v47, v47
	v_fmac_f32_e32 v12, v2, v2
	v_add_f32_e32 v14, v12, v13
	v_cvt_pk_bf16_f32 v19, v2, v47
	s_waitcnt lgkmcnt(0)
	v_lshlrev_b64 v[20:21], 11, v[64:65]
	v_lshlrev_b32_e32 v12, 16, v19
	v_sub_f32_e32 v2, v2, v12
	v_and_b32_e32 v12, 0xffff0000, v19
	v_sub_f32_e32 v12, v47, v12
	v_mul_f32_e32 v2, 0x43800000, v2
	v_mul_f32_e32 v12, 0x43800000, v12
	v_med3_f32 v2, v2, s68, v235
	v_med3_f32 v12, v12, s68, v235
	v_cvt_pk_fp8_f32 v23, v2, v12 op_sel:[0,0,1]
	v_lshl_add_u64 v[20:21], v[20:21], 0, v[162:163]
	s_waitcnt vmcnt(4)
	v_fma_f32 v9, v9, v3, v41
	v_lshl_add_u64 v[12:13], v[20:21], 1, s[42:43]
	v_fma_f32 v2, v8, v3, v40
	v_mul_f32_e32 v8, v9, v9
	global_store_dwordx4 v[12:13], v[16:19], off sc1
	v_lshl_add_u64 v[12:13], s[44:45], 0, v[20:21]
	v_fmac_f32_e32 v8, v2, v2
	global_store_dwordx2 v[12:13], v[22:23], off
	v_add_f32_e32 v13, v8, v14
	v_cvt_pk_bf16_f32 v8, v2, v9
	v_fmac_f32_e32 v43, v11, v3
	v_and_b32_e32 v12, 0xffff0000, v8
	v_sub_f32_e32 v9, v9, v12
	v_lshlrev_b32_e32 v12, 16, v8
	v_sub_f32_e32 v2, v2, v12
	v_mul_f32_e32 v9, 0x43800000, v9
	v_mul_f32_e32 v2, 0x43800000, v2
	v_med3_f32 v9, v9, s68, v235
	v_med3_f32 v2, v2, s68, v235
	v_mov_b32_e32 v12, v1
	v_cvt_pk_fp8_f32 v12, v2, v9
	v_fma_f32 v2, v10, v3, v42
	v_mul_f32_e32 v9, v43, v43
	v_fmac_f32_e32 v9, v2, v2
	v_add_f32_e32 v10, v9, v13
	v_cvt_pk_bf16_f32 v9, v2, v43
	v_mov_b32_e32 v13, v1
	v_lshlrev_b32_e32 v11, 16, v9
	v_sub_f32_e32 v2, v2, v11
	v_and_b32_e32 v11, 0xffff0000, v9
	v_sub_f32_e32 v11, v43, v11
	v_mul_f32_e32 v2, 0x43800000, v2
	v_mul_f32_e32 v11, 0x43800000, v11
	v_med3_f32 v2, v2, s68, v235
	v_med3_f32 v11, v11, s68, v235
	v_cvt_pk_fp8_f32 v12, v2, v11 op_sel:[0,0,1]
	v_fma_f32 v2, v4, v3, v36
	v_fma_f32 v4, v5, v3, v37
	v_mul_f32_e32 v5, v4, v4
	v_fmac_f32_e32 v5, v2, v2
	v_add_f32_e32 v5, v5, v10
	v_cvt_pk_bf16_f32 v10, v2, v4
	v_fmac_f32_e32 v39, v7, v3
	v_and_b32_e32 v11, 0xffff0000, v10
	v_sub_f32_e32 v4, v4, v11
	v_lshlrev_b32_e32 v11, 16, v10
	v_sub_f32_e32 v2, v2, v11
	v_mul_f32_e32 v4, 0x43800000, v4
	v_mul_f32_e32 v2, 0x43800000, v2
	v_med3_f32 v4, v4, s68, v235
	v_med3_f32 v2, v2, s68, v235
	v_cvt_pk_fp8_f32 v13, v2, v4
	v_fma_f32 v2, v6, v3, v38
	v_mul_f32_e32 v3, v39, v39
	v_fmac_f32_e32 v3, v2, v2
	v_add_f32_e32 v3, v3, v5
	ds_bpermute_b32 v0, v0, v3
	v_cvt_pk_bf16_f32 v11, v2, v39
	v_or_b32_e32 v20, 0x80, v20
	v_lshlrev_b32_e32 v4, 16, v11
	v_sub_f32_e32 v2, v2, v4
	v_and_b32_e32 v4, 0xffff0000, v11
	v_sub_f32_e32 v4, v39, v4
	v_mul_f32_e32 v2, 0x43800000, v2
	v_mul_f32_e32 v4, 0x43800000, v4
	v_med3_f32 v2, v2, s68, v235
	v_med3_f32 v4, v4, s68, v235
	s_waitcnt lgkmcnt(0)
	v_add_f32_e32 v0, v3, v0
	v_cvt_pk_fp8_f32 v13, v2, v4 op_sel:[0,0,1]
	ds_bpermute_b32 v2, v174, v0
	v_lshl_add_u64 v[4:5], v[20:21], 1, s[42:43]
	global_store_dwordx4 v[4:5], v[8:11], off sc1
	v_lshl_add_u64 v[4:5], s[44:45], 0, v[20:21]
	global_store_dwordx2 v[4:5], v[12:13], off
	s_and_saveexec_b64 s[2:3], s[38:39]
	s_cbranch_execz .LBB0_1056
	s_waitcnt lgkmcnt(0)
	v_add_f32_e32 v0, v0, v2
	s_lshl_b32 s20, s56, 2
	v_lshlrev_b64 v[2:3], 7, v[64:65]
	s_ashr_i32 s21, s20, 31
	v_lshl_add_u64 v[2:3], s[8:9], 0, v[2:3]
	v_lshl_add_u64 v[2:3], s[20:21], 2, v[2:3]
	s_lshl_b32 s18, s37, 2
	v_lshl_add_u64 v[2:3], v[2:3], 0, s[18:19]
	global_store_dword v[2:3], v0, off

;     __device__ __forceinline__ void core(const f32x4 (&acc)[2][2][4][2], const Unit& u, int wr, int wc, int fr, int fq, const float (&rsc)[2][4]) const {
;     ...
;             for (int m = 0; m < MB; ++m)
; #pragma unroll
;                 for (int bj = 0; bj < 2; ++bj) { const size_t idx = (size_t)(row0 + ai * HALF + (mh + m) * 16) * D + col0 + bj * HALF;
;                     if (F32IN) { xa[m][bj] = *(const f32x4*)(Xin + idx); xb[m][bj] = *(const f32x4*)(Xin + idx + 4); }
;                     else { va[m][bj] = *(const u32x4*)(Hb + idx); vb[m][bj] = *(const u32x2*)(Hl + idx); } }
; #pragma unroll
;             for (int m = 0; m < MB; ++m) { const int row = row0 + ai * HALF + (mh + m) * 16; float sq = 0.f;
;                 const float rs1 = rsc[ai][mh + m];
; #pragma unroll
;                 for (int bj = 0; bj < 2; ++bj) { const size_t idx = (size_t)row * D + col0 + bj * HALF;
;                     unsigned hw[4]; int lw[2] = {0, 0};
; #pragma unroll
;                     for (int pq = 0; pq < 4; ++pq) {
;                         float h0, h1;
;                         if (F32IN) { h0 = (pq < 2) ? xa[m][bj][2 * pq] : xb[m][bj][2 * pq - 4]; h1 = (pq < 2) ? xa[m][bj][2 * pq + 1] : xb[m][bj][2 * pq - 3]; }
;                         else { const unsigned a = va[m][bj][pq]; const int bw = (int)vb[m][bj][pq >> 1]; const hf32x2 lp = (pq & 1) ? __builtin_amdgcn_cvt_pk_f32_fp8(bw, true) : __builtin_amdgcn_cvt_pk_f32_fp8(bw, false);
;                             h0 = __uint_as_float(a << 16) + lp.x * 0.00390625f; h1 = __uint_as_float(a & 0xffff0000u) + lp.y * 0.00390625f; }
;                         const float o0 = h0 + acc[ai][bj][mh + m][pq >> 1][(2 * pq) & 3] * rs1, o1 = h1 + acc[ai][bj][mh + m][pq >> 1][(2 * pq + 1) & 3] * rs1;
;                         sq += o0 * o0 + o1 * o1;
;                         const unsigned hi = cvt_pk_bf16(o0, o1);
;                         hw[pq] = hi;
;                         const float r0 = __builtin_amdgcn_fmed3f((o0 - __uint_as_float(hi << 16)) * 256.0f, -448.0f, 448.0f), r1 = __builtin_amdgcn_fmed3f((o1 - __uint_as_float(hi & 0xffff0000u)) * 256.0f, -448.0f, 448.0f);
;                         lw[pq >> 1] = (pq & 1) ? __builtin_amdgcn_cvt_pk_fp8_f32(r0, r1, lw[pq >> 1], true) : __builtin_amdgcn_cvt_pk_fp8_f32(r0, r1, lw[pq >> 1], false);
;                     }
.LBB0_1255:
	v_lshl_add_u32 v156, s12, 8, v178
	v_ashrrev_i32_e32 v157, 31, v156
	v_lshl_or_b32 v158, s8, 8, v196
	v_ashrrev_i32_e32 v159, 31, v158
	v_lshlrev_b64 v[122:123], 11, v[156:157]
	v_lshl_add_u64 v[122:123], v[122:123], 0, v[158:159]
	v_lshl_add_u64 v[190:191], v[122:123], 1, s[34:35]
	v_lshl_add_u64 v[192:193], s[42:43], 0, v[122:123]
	global_load_dwordx4 v[142:145], v[190:191], off
	global_load_dwordx2 v[194:195], v[192:193], off
	v_or_b32_e32 v122, 0x80, v122
	v_lshl_add_u64 v[174:175], v[122:123], 1, s[34:35]
	v_lshl_add_u64 v[176:177], s[42:43], 0, v[122:123]
	global_load_dwordx4 v[138:141], v[174:175], off
	global_load_dwordx2 v[188:189], v[176:177], off
	v_or_b32_e32 v160, 16, v156
	v_ashrrev_i32_e32 v161, 31, v160
	v_lshlrev_b64 v[122:123], 11, v[160:161]
	v_lshl_add_u64 v[164:165], v[122:123], 0, v[158:159]
	v_lshl_add_u64 v[168:169], v[164:165], 1, s[34:35]
	v_lshl_add_u64 v[170:171], s[42:43], 0, v[164:165]
	v_or_b32_e32 v164, 0x80, v164
	v_lshl_add_u64 v[162:163], v[164:165], 1, s[34:35]
	v_lshl_add_u64 v[164:165], s[42:43], 0, v[164:165]
	global_load_dwordx4 v[130:133], v[168:169], off
	global_load_dwordx2 v[172:173], v[170:171], off
	global_load_dwordx4 v[122:125], v[162:163], off
	global_load_dwordx2 v[166:167], v[164:165], off
	s_waitcnt vmcnt(0)
	v_lshlrev_b32_e32 v182, 16, v142
	v_cvt_pk_f32_fp8_e32 v[180:181], v194
	v_and_b32_e32 v142, 0xffff0000, v142
	v_fmac_f32_e32 v182, 0x3b800000, v180
	v_fmac_f32_e32 v142, 0x3b800000, v181
	v_add_f32_e32 v180, v134, v182
	v_add_f32_e32 v135, v135, v142
	v_cvt_pk_bf16_f32 v134, v180, v135
	v_mul_f32_e32 v182, v135, v135
	v_and_b32_e32 v142, 0xffff0000, v134
	v_sub_f32_e32 v135, v135, v142
	v_lshlrev_b32_e32 v142, 16, v134
	v_sub_f32_e32 v142, v180, v142
	v_mul_f32_e32 v135, 0x43800000, v135
	v_mul_f32_e32 v142, 0x43800000, v142
	v_fmac_f32_e32 v182, v180, v180
	v_med3_f32 v135, v135, s68, v235
	v_med3_f32 v180, v142, s68, v235
	v_mov_b32_e32 v142, v1
	v_cvt_pk_fp8_f32 v142, v180, v135
	v_cvt_pk_f32_fp8_sdwa v[180:181], v194 src0_sel:WORD_1
	v_lshlrev_b32_e32 v135, 16, v143
	v_and_b32_e32 v143, 0xffff0000, v143
	v_fmac_f32_e32 v143, 0x3b800000, v181
	v_fmac_f32_e32 v135, 0x3b800000, v180
	v_add_f32_e32 v137, v137, v143
	v_add_f32_e32 v136, v136, v135
	v_mul_f32_e32 v135, v137, v137
	v_fmac_f32_e32 v135, v136, v136
	v_add_f32_e32 v143, v182, v135
	v_cvt_pk_bf16_f32 v135, v136, v137
	s_nop 0
	v_lshlrev_b32_e32 v180, 16, v135
	v_sub_f32_e32 v136, v136, v180
	v_and_b32_e32 v180, 0xffff0000, v135
	v_sub_f32_e32 v137, v137, v180
	v_mul_f32_e32 v136, 0x43800000, v136
	v_mul_f32_e32 v137, 0x43800000, v137
	v_med3_f32 v136, v136, s68, v235
	v_med3_f32 v137, v137, s68, v235
	v_cvt_pk_fp8_f32 v142, v136, v137 op_sel:[0,0,1]
	v_cvt_pk_f32_fp8_e32 v[136:137], v195
	v_lshlrev_b32_e32 v180, 16, v144
	v_fmac_f32_e32 v180, 0x3b800000, v136
	v_and_b32_e32 v136, 0xffff0000, v144
	v_fmac_f32_e32 v136, 0x3b800000, v137
	v_add_f32_e32 v127, v127, v136
	v_add_f32_e32 v126, v126, v180
	v_mul_f32_e32 v136, v127, v127
	v_fmac_f32_e32 v136, v126, v126
	v_add_f32_e32 v137, v143, v136
	v_cvt_pk_bf16_f32 v136, v126, v127
	v_lshlrev_b32_e32 v144, 16, v145
	v_and_b32_e32 v143, 0xffff0000, v136
	v_sub_f32_e32 v127, v127, v143
	v_lshlrev_b32_e32 v143, 16, v136
	v_sub_f32_e32 v126, v126, v143
	v_mul_f32_e32 v127, 0x43800000, v127
	v_mul_f32_e32 v126, 0x43800000, v126
	v_med3_f32 v127, v127, s68, v235
	v_med3_f32 v126, v126, s68, v235
	v_mov_b32_e32 v143, v1
	v_cvt_pk_fp8_f32 v143, v126, v127
	v_cvt_pk_f32_fp8_sdwa v[126:127], v195 src0_sel:WORD_1
	v_fmac_f32_e32 v144, 0x3b800000, v126
	v_and_b32_e32 v126, 0xffff0000, v145
	v_fmac_f32_e32 v126, 0x3b800000, v127
	v_add_f32_e32 v126, v129, v126
	v_add_f32_e32 v127, v128, v144
	v_mul_f32_e32 v128, v126, v126
	v_fmac_f32_e32 v128, v127, v127
	v_add_f32_e32 v128, v137, v128
	v_cvt_pk_bf16_f32 v137, v127, v126
	s_nop 0
	v_lshlrev_b32_e32 v129, 16, v137
	v_sub_f32_e32 v127, v127, v129
	v_and_b32_e32 v129, 0xffff0000, v137
	v_sub_f32_e32 v126, v126, v129
	v_mul_f32_e32 v127, 0x43800000, v127
	v_mul_f32_e32 v126, 0x43800000, v126
	v_med3_f32 v127, v127, s68, v235
	v_med3_f32 v126, v126, s68, v235
	v_cvt_pk_fp8_f32 v143, v127, v126 op_sel:[0,0,1]
	v_cvt_pk_f32_fp8_e32 v[126:127], v188
	v_lshlrev_b32_e32 v129, 16, v138
	global_store_dwordx4 v[190:191], v[134:137], off sc1
	global_store_dwordx2 v[192:193], v[142:143], off
	v_fmac_f32_e32 v129, 0x3b800000, v126
	v_and_b32_e32 v126, 0xffff0000, v138
	v_fmac_f32_e32 v126, 0x3b800000, v127
	v_add_f32_e32 v119, v119, v126
	v_add_f32_e32 v127, v118, v129
	v_mul_f32_e32 v118, v119, v119
	v_fmac_f32_e32 v118, v127, v127
	v_add_f32_e32 v134, v128, v118
	v_cvt_pk_bf16_f32 v118, v127, v119
	v_cvt_pk_f32_fp8_sdwa v[128:129], v188 src0_sel:WORD_1
	v_and_b32_e32 v126, 0xffff0000, v118
	v_sub_f32_e32 v119, v119, v126
	v_lshlrev_b32_e32 v126, 16, v118
	v_sub_f32_e32 v126, v127, v126
	v_mul_f32_e32 v119, 0x43800000, v119
	v_mul_f32_e32 v126, 0x43800000, v126
	v_med3_f32 v119, v119, s68, v235
	v_med3_f32 v127, v126, s68, v235
	v_mov_b32_e32 v126, v1
	v_cvt_pk_fp8_f32 v126, v127, v119
	v_and_b32_e32 v127, 0xffff0000, v139
	v_lshlrev_b32_e32 v119, 16, v139
	v_fmac_f32_e32 v127, 0x3b800000, v129
	v_fmac_f32_e32 v119, 0x3b800000, v128
	v_add_f32_e32 v121, v121, v127
	v_add_f32_e32 v120, v120, v119
	v_mul_f32_e32 v119, v121, v121
	v_fmac_f32_e32 v119, v120, v120
	v_add_f32_e32 v127, v134, v119
	v_cvt_pk_bf16_f32 v119, v120, v121
	s_nop 0
	v_lshlrev_b32_e32 v128, 16, v119
	v_sub_f32_e32 v120, v120, v128
	v_and_b32_e32 v128, 0xffff0000, v119
	v_sub_f32_e32 v121, v121, v128
	v_mul_f32_e32 v120, 0x43800000, v120
	v_mul_f32_e32 v121, 0x43800000, v121
; __device__ __forceinline__ unsigned cvt_pk_bf16(float lo, float hi) { unsigned r; asm volatile("v_cvt_pk_bf16_f32 %0, %1, %2" : "=v"(r) : "v"(lo), "v"(hi)); return r; }
;     __device__ __forceinline__ void core(const f32x4 (&acc)[2][2][4][2], const Unit& u, int wr, int wc, int fr, int fq, const float (&rsc)[2][4]) const {
;     ...
;             for (int m = 0; m < MB; ++m) { const int row = row0 + ai * HALF + (mh + m) * 16; float sq = 0.f;
;                 const float rs1 = rsc[ai][mh + m];
; #pragma unroll
;                 for (int bj = 0; bj < 2; ++bj) { const size_t idx = (size_t)row * D + col0 + bj * HALF;
;                     unsigned hw[4]; int lw[2] = {0, 0};
; #pragma unroll
;                     for (int pq = 0; pq < 4; ++pq) {
;                         float h0, h1;
;                         if (F32IN) { h0 = (pq < 2) ? xa[m][bj][2 * pq] : xb[m][bj][2 * pq - 4]; h1 = (pq < 2) ? xa[m][bj][2 * pq + 1] : xb[m][bj][2 * pq - 3]; }
;                         else { const unsigned a = va[m][bj][pq]; const int bw = (int)vb[m][bj][pq >> 1]; const hf32x2 lp = (pq & 1) ? __builtin_amdgcn_cvt_pk_f32_fp8(bw, true) : __builtin_amdgcn_cvt_pk_f32_fp8(bw, false);
;                             h0 = __uint_as_float(a << 16) + lp.x * 0.00390625f; h1 = __uint_as_float(a & 0xffff0000u) + lp.y * 0.00390625f; }
;                         const float o0 = h0 + acc[ai][bj][mh + m][pq >> 1][(2 * pq) & 3] * rs1, o1 = h1 + acc[ai][bj][mh + m][pq >> 1][(2 * pq + 1) & 3] * rs1;
;                         sq += o0 * o0 + o1 * o1;
;                         const unsigned hi = cvt_pk_bf16(o0, o1);
;                         hw[pq] = hi;
;                         const float r0 = __builtin_amdgcn_fmed3f((o0 - __uint_as_float(hi << 16)) * 256.0f, -448.0f, 448.0f), r1 = __builtin_amdgcn_fmed3f((o1 - __uint_as_float(hi & 0xffff0000u)) * 256.0f, -448.0f, 448.0f);
;                         lw[pq >> 1] = (pq & 1) ? __builtin_amdgcn_cvt_pk_fp8_f32(r0, r1, lw[pq >> 1], true) : __builtin_amdgcn_cvt_pk_fp8_f32(r0, r1, lw[pq >> 1], false);
;                     }
;                     *(u32x4*)(Hb + idx) = (u32x4){hw[0], hw[1], hw[2], hw[3]}; *(u32x2*)(Hl + idx) = (u32x2){(unsigned)lw[0], (unsigned)lw[1]}; }
;                 sq += __shfl_xor(sq, 16); sq += __shfl_xor(sq, 32); if (fq == 0) ss[(size_t)row * 32 + u.pn * 4 + wc] = sq; }
	v_med3_f32 v120, v120, s68, v235
	v_med3_f32 v121, v121, s68, v235
	v_cvt_pk_fp8_f32 v126, v120, v121 op_sel:[0,0,1]
	v_cvt_pk_f32_fp8_e32 v[120:121], v189
	v_lshlrev_b32_e32 v128, 16, v140
	v_fmac_f32_e32 v128, 0x3b800000, v120
	v_and_b32_e32 v120, 0xffff0000, v140
	v_fmac_f32_e32 v120, 0x3b800000, v121
	v_add_f32_e32 v115, v115, v120
	v_add_f32_e32 v114, v114, v128
	v_mul_f32_e32 v120, v115, v115
	v_fmac_f32_e32 v120, v114, v114
	v_add_f32_e32 v121, v127, v120
	v_cvt_pk_bf16_f32 v120, v114, v115
	v_lshlrev_b32_e32 v128, 16, v141
	v_and_b32_e32 v127, 0xffff0000, v120
	v_sub_f32_e32 v115, v115, v127
	v_lshlrev_b32_e32 v127, 16, v120
	v_sub_f32_e32 v114, v114, v127
	v_mul_f32_e32 v115, 0x43800000, v115
	v_mul_f32_e32 v114, 0x43800000, v114
	v_med3_f32 v115, v115, s68, v235
	v_med3_f32 v114, v114, s68, v235
	v_mov_b32_e32 v127, v1
	v_cvt_pk_fp8_f32 v127, v114, v115
	v_cvt_pk_f32_fp8_sdwa v[114:115], v189 src0_sel:WORD_1
	v_fmac_f32_e32 v128, 0x3b800000, v114
	v_and_b32_e32 v114, 0xffff0000, v141
	v_fmac_f32_e32 v114, 0x3b800000, v115
	v_add_f32_e32 v114, v117, v114
	v_add_f32_e32 v115, v116, v128
	v_mul_f32_e32 v116, v114, v114
	v_fmac_f32_e32 v116, v115, v115
	v_add_f32_e32 v116, v121, v116
	v_cvt_pk_bf16_f32 v121, v115, v114
	s_nop 0
	v_lshlrev_b32_e32 v117, 16, v121
	v_sub_f32_e32 v115, v115, v117
	v_and_b32_e32 v117, 0xffff0000, v121
	v_sub_f32_e32 v114, v114, v117
	v_mul_f32_e32 v115, 0x43800000, v115
	v_mul_f32_e32 v114, 0x43800000, v114
	v_med3_f32 v115, v115, s68, v235
	v_med3_f32 v114, v114, s68, v235
	v_cvt_pk_fp8_f32 v127, v115, v114 op_sel:[0,0,1]
	v_and_b32_e32 v115, 64, v226
	v_xor_b32_e32 v114, 16, v226
	v_add_u32_e32 v115, 64, v115
	v_cmp_lt_i32_e32 vcc, v114, v115
	global_store_dwordx4 v[174:175], v[118:121], off sc1
	global_store_dwordx2 v[176:177], v[126:127], off
	v_cndmask_b32_e32 v114, v226, v114, vcc
	v_lshlrev_b32_e32 v142, 2, v114
	ds_bpermute_b32 v114, v142, v116
	s_waitcnt lgkmcnt(0)
	v_add_f32_e32 v114, v116, v114
	v_xor_b32_e32 v116, 32, v226
	v_cmp_lt_i32_e32 vcc, v116, v115
	s_nop 1
	v_cndmask_b32_e32 v115, v226, v116, vcc
	v_lshlrev_b32_e32 v143, 2, v115
	ds_bpermute_b32 v115, v143, v114
	s_and_saveexec_b64 s[2:3], s[38:39]
	s_cbranch_execz .LBB0_1257
	s_waitcnt lgkmcnt(0)
	v_add_f32_e32 v116, v114, v115
	s_lshl_b32 s20, s8, 2
	v_lshlrev_b64 v[114:115], 7, v[156:157]
	s_ashr_i32 s21, s20, 31
	v_lshl_add_u64 v[114:115], s[44:45], 0, v[114:115]
	v_lshl_add_u64 v[114:115], s[20:21], 2, v[114:115]
	s_lshl_b32 s18, s36, 2
	v_lshl_add_u64 v[114:115], v[114:115], 0, s[18:19]
	global_store_dword v[114:115], v116, off
.LBB0_1257:
	s_or_b64 exec, exec, s[2:3]
	s_waitcnt lgkmcnt(0)
	v_cvt_pk_f32_fp8_e32 v[114:115], v172
	v_lshlrev_b32_e32 v116, 16, v130
	v_fmac_f32_e32 v116, 0x3b800000, v114
	v_and_b32_e32 v114, 0xffff0000, v130
	v_fmac_f32_e32 v114, 0x3b800000, v115
	v_add_f32_e32 v115, v110, v116
	v_add_f32_e32 v111, v111, v114
	v_cvt_pk_bf16_f32 v110, v115, v111
	v_mul_f32_e32 v118, v111, v111
	v_and_b32_e32 v114, 0xffff0000, v110
	v_sub_f32_e32 v111, v111, v114
	v_lshlrev_b32_e32 v114, 16, v110
	v_sub_f32_e32 v114, v115, v114
	v_cvt_pk_f32_fp8_sdwa v[116:117], v172 src0_sel:WORD_1
	v_mul_f32_e32 v111, 0x43800000, v111
	v_mul_f32_e32 v114, 0x43800000, v114
	v_fmac_f32_e32 v118, v115, v115
	v_med3_f32 v111, v111, s68, v235
	v_med3_f32 v115, v114, s68, v235
	v_mov_b32_e32 v114, v1
	v_cvt_pk_fp8_f32 v114, v115, v111
	v_and_b32_e32 v115, 0xffff0000, v131
	v_lshlrev_b32_e32 v111, 16, v131
	v_fmac_f32_e32 v115, 0x3b800000, v117
	v_fmac_f32_e32 v111, 0x3b800000, v116
	v_add_f32_e32 v113, v113, v115
	v_add_f32_e32 v112, v112, v111
	v_mul_f32_e32 v111, v113, v113
	v_fmac_f32_e32 v111, v112, v112
	v_add_f32_e32 v115, v118, v111
	v_cvt_pk_bf16_f32 v111, v112, v113
	s_nop 0
	v_lshlrev_b32_e32 v116, 16, v111
	v_sub_f32_e32 v112, v112, v116
	v_and_b32_e32 v116, 0xffff0000, v111
	v_sub_f32_e32 v113, v113, v116
	v_mul_f32_e32 v112, 0x43800000, v112
	v_mul_f32_e32 v113, 0x43800000, v113
	v_med3_f32 v112, v112, s68, v235
	v_med3_f32 v113, v113, s68, v235
	v_cvt_pk_fp8_f32 v114, v112, v113 op_sel:[0,0,1]
	v_cvt_pk_f32_fp8_e32 v[112:113], v173
	v_lshlrev_b32_e32 v116, 16, v132
	v_fmac_f32_e32 v116, 0x3b800000, v112
	v_and_b32_e32 v112, 0xffff0000, v132
	v_fmac_f32_e32 v112, 0x3b800000, v113
	v_add_f32_e32 v107, v107, v112
	v_add_f32_e32 v106, v106, v116
	v_mul_f32_e32 v112, v107, v107
	v_fmac_f32_e32 v112, v106, v106
	v_add_f32_e32 v113, v115, v112
	v_cvt_pk_bf16_f32 v112, v106, v107
	v_lshlrev_b32_e32 v116, 16, v133
	v_and_b32_e32 v115, 0xffff0000, v112
	v_sub_f32_e32 v107, v107, v115
	v_lshlrev_b32_e32 v115, 16, v112
	v_sub_f32_e32 v106, v106, v115
	v_mul_f32_e32 v107, 0x43800000, v107
	v_mul_f32_e32 v106, 0x43800000, v106
	v_med3_f32 v107, v107, s68, v235
	v_med3_f32 v106, v106, s68, v235
	v_mov_b32_e32 v115, v1
	v_cvt_pk_fp8_f32 v115, v106, v107
	v_cvt_pk_f32_fp8_sdwa v[106:107], v173 src0_sel:WORD_1
	v_fmac_f32_e32 v116, 0x3b800000, v106
	v_and_b32_e32 v106, 0xffff0000, v133
	v_fmac_f32_e32 v106, 0x3b800000, v107
	v_add_f32_e32 v106, v109, v106
	v_add_f32_e32 v107, v108, v116
	v_mul_f32_e32 v108, v106, v106
	v_fmac_f32_e32 v108, v107, v107
	v_add_f32_e32 v108, v113, v108
	v_cvt_pk_bf16_f32 v113, v107, v106
	s_nop 0
	v_lshlrev_b32_e32 v109, 16, v113
	v_sub_f32_e32 v107, v107, v109
	v_and_b32_e32 v109, 0xffff0000, v113
	v_sub_f32_e32 v106, v106, v109
	v_mul_f32_e32 v107, 0x43800000, v107
	v_mul_f32_e32 v106, 0x43800000, v106
	v_med3_f32 v107, v107, s68, v235
	v_med3_f32 v106, v106, s68, v235
	v_cvt_pk_fp8_f32 v115, v107, v106 op_sel:[0,0,1]
	v_cvt_pk_f32_fp8_e32 v[106:107], v166
	v_lshlrev_b32_e32 v109, 16, v122
;     __device__ __forceinline__ void core(const f32x4 (&acc)[2][2][4][2], const Unit& u, int wr, int wc, int fr, int fq, const float (&rsc)[2][4]) const {
;     ...
;             for (int m = 0; m < MB; ++m)
; #pragma unroll
;                 for (int bj = 0; bj < 2; ++bj) { const size_t idx = (size_t)(row0 + ai * HALF + (mh + m) * 16) * D + col0 + bj * HALF;
;                     if (F32IN) { xa[m][bj] = *(const f32x4*)(Xin + idx); xb[m][bj] = *(const f32x4*)(Xin + idx + 4); }
;                     else { va[m][bj] = *(const u32x4*)(Hb + idx); vb[m][bj] = *(const u32x2*)(Hl + idx); } }
; #pragma unroll
;             for (int m = 0; m < MB; ++m) { const int row = row0 + ai * HALF + (mh + m) * 16; float sq = 0.f;
;                 const float rs1 = rsc[ai][mh + m];
; #pragma unroll
;                 for (int bj = 0; bj < 2; ++bj) { const size_t idx = (size_t)row * D + col0 + bj * HALF;
;                     unsigned hw[4]; int lw[2] = {0, 0};
; #pragma unroll
;                     for (int pq = 0; pq < 4; ++pq) {
;                         float h0, h1;
;                         if (F32IN) { h0 = (pq < 2) ? xa[m][bj][2 * pq] : xb[m][bj][2 * pq - 4]; h1 = (pq < 2) ? xa[m][bj][2 * pq + 1] : xb[m][bj][2 * pq - 3]; }
;                         else { const unsigned a = va[m][bj][pq]; const int bw = (int)vb[m][bj][pq >> 1]; const hf32x2 lp = (pq & 1) ? __builtin_amdgcn_cvt_pk_f32_fp8(bw, true) : __builtin_amdgcn_cvt_pk_f32_fp8(bw, false);
;                             h0 = __uint_as_float(a << 16) + lp.x * 0.00390625f; h1 = __uint_as_float(a & 0xffff0000u) + lp.y * 0.00390625f; }
;                         const float o0 = h0 + acc[ai][bj][mh + m][pq >> 1][(2 * pq) & 3] * rs1, o1 = h1 + acc[ai][bj][mh + m][pq >> 1][(2 * pq + 1) & 3] * rs1;
;                         sq += o0 * o0 + o1 * o1;
;                         const unsigned hi = cvt_pk_bf16(o0, o1);
;                         hw[pq] = hi;
;                         const float r0 = __builtin_amdgcn_fmed3f((o0 - __uint_as_float(hi << 16)) * 256.0f, -448.0f, 448.0f), r1 = __builtin_amdgcn_fmed3f((o1 - __uint_as_float(hi & 0xffff0000u)) * 256.0f, -448.0f, 448.0f);
;                         lw[pq >> 1] = (pq & 1) ? __builtin_amdgcn_cvt_pk_fp8_f32(r0, r1, lw[pq >> 1], true) : __builtin_amdgcn_cvt_pk_fp8_f32(r0, r1, lw[pq >> 1], false);
;                     }
	global_store_dwordx4 v[168:169], v[110:113], off sc1
	global_store_dwordx2 v[170:171], v[114:115], off
	v_fmac_f32_e32 v109, 0x3b800000, v106
	v_and_b32_e32 v106, 0xffff0000, v122
	v_fmac_f32_e32 v106, 0x3b800000, v107
	v_add_f32_e32 v103, v103, v106
	v_add_f32_e32 v107, v102, v109
	v_mul_f32_e32 v102, v103, v103
	v_fmac_f32_e32 v102, v107, v107
	v_add_f32_e32 v110, v108, v102
	v_cvt_pk_bf16_f32 v102, v107, v103
	v_cvt_pk_f32_fp8_sdwa v[108:109], v166 src0_sel:WORD_1
	v_and_b32_e32 v106, 0xffff0000, v102
	v_sub_f32_e32 v103, v103, v106
	v_lshlrev_b32_e32 v106, 16, v102
	v_sub_f32_e32 v106, v107, v106
	v_mul_f32_e32 v103, 0x43800000, v103
	v_mul_f32_e32 v106, 0x43800000, v106
	v_med3_f32 v103, v103, s68, v235
	v_med3_f32 v107, v106, s68, v235
	v_mov_b32_e32 v106, v1
	v_cvt_pk_fp8_f32 v106, v107, v103
	v_and_b32_e32 v107, 0xffff0000, v123
	v_lshlrev_b32_e32 v103, 16, v123
	v_fmac_f32_e32 v107, 0x3b800000, v109
	v_fmac_f32_e32 v103, 0x3b800000, v108
	v_add_f32_e32 v105, v105, v107
	v_add_f32_e32 v104, v104, v103
	v_mul_f32_e32 v103, v105, v105
	v_fmac_f32_e32 v103, v104, v104
	v_add_f32_e32 v107, v110, v103
	v_cvt_pk_bf16_f32 v103, v104, v105
	s_nop 0
	v_lshlrev_b32_e32 v108, 16, v103
	v_sub_f32_e32 v104, v104, v108
	v_and_b32_e32 v108, 0xffff0000, v103
	v_sub_f32_e32 v105, v105, v108
	v_mul_f32_e32 v104, 0x43800000, v104
	v_mul_f32_e32 v105, 0x43800000, v105
	v_med3_f32 v104, v104, s68, v235
	v_med3_f32 v105, v105, s68, v235
	v_cvt_pk_fp8_f32 v106, v104, v105 op_sel:[0,0,1]
	v_cvt_pk_f32_fp8_e32 v[104:105], v167
	v_lshlrev_b32_e32 v108, 16, v124
	v_fmac_f32_e32 v108, 0x3b800000, v104
	v_and_b32_e32 v104, 0xffff0000, v124
	v_fmac_f32_e32 v104, 0x3b800000, v105
	v_add_f32_e32 v99, v99, v104
	v_add_f32_e32 v98, v98, v108
	v_mul_f32_e32 v104, v99, v99
	v_fmac_f32_e32 v104, v98, v98
	v_add_f32_e32 v105, v107, v104
	v_cvt_pk_bf16_f32 v104, v98, v99
	v_lshlrev_b32_e32 v108, 16, v125
	v_and_b32_e32 v107, 0xffff0000, v104
	v_sub_f32_e32 v99, v99, v107
	v_lshlrev_b32_e32 v107, 16, v104
	v_sub_f32_e32 v98, v98, v107
	v_mul_f32_e32 v99, 0x43800000, v99
	v_mul_f32_e32 v98, 0x43800000, v98
	v_med3_f32 v99, v99, s68, v235
	v_med3_f32 v98, v98, s68, v235
	v_mov_b32_e32 v107, v1
	v_cvt_pk_fp8_f32 v107, v98, v99
	v_cvt_pk_f32_fp8_sdwa v[98:99], v167 src0_sel:WORD_1
	v_fmac_f32_e32 v108, 0x3b800000, v98
	v_and_b32_e32 v98, 0xffff0000, v125
	v_fmac_f32_e32 v98, 0x3b800000, v99
	v_add_f32_e32 v98, v101, v98
	v_add_f32_e32 v99, v100, v108
	v_mul_f32_e32 v100, v98, v98
	v_fmac_f32_e32 v100, v99, v99
	v_add_f32_e32 v100, v105, v100
	v_cvt_pk_bf16_f32 v105, v99, v98
	s_nop 0
	v_lshlrev_b32_e32 v101, 16, v105
	v_sub_f32_e32 v99, v99, v101
	v_and_b32_e32 v101, 0xffff0000, v105
	v_sub_f32_e32 v98, v98, v101
	v_mul_f32_e32 v99, 0x43800000, v99
	v_mul_f32_e32 v98, 0x43800000, v98
	v_med3_f32 v99, v99, s68, v235
	v_med3_f32 v98, v98, s68, v235
	v_cvt_pk_fp8_f32 v107, v99, v98 op_sel:[0,0,1]
	ds_bpermute_b32 v98, v142, v100
	global_store_dwordx4 v[162:163], v[102:105], off sc1
	global_store_dwordx2 v[164:165], v[106:107], off
	s_waitcnt lgkmcnt(0)
	v_add_f32_e32 v98, v100, v98
	ds_bpermute_b32 v99, v143, v98
	s_and_saveexec_b64 s[2:3], s[38:39]
	s_cbranch_execz .LBB0_1259
	s_waitcnt lgkmcnt(0)
	v_add_f32_e32 v100, v98, v99
	s_lshl_b32 s20, s8, 2
	v_lshlrev_b64 v[98:99], 7, v[160:161]
	s_ashr_i32 s21, s20, 31
	v_lshl_add_u64 v[98:99], s[44:45], 0, v[98:99]
	v_lshl_add_u64 v[98:99], s[20:21], 2, v[98:99]
	s_lshl_b32 s18, s36, 2
	v_lshl_add_u64 v[98:99], v[98:99], 0, s[18:19]
	global_store_dword v[98:99], v100, off
.LBB0_1259:
	s_or_b64 exec, exec, s[2:3]
	v_or_b32_e32 v128, 32, v156
	v_ashrrev_i32_e32 v129, 31, v128
	s_waitcnt lgkmcnt(0)
	v_lshlrev_b64 v[98:99], 11, v[128:129]
	v_lshl_add_u64 v[98:99], v[98:99], 0, v[158:159]
	v_lshl_add_u64 v[136:137], v[98:99], 1, s[34:35]
	v_lshl_add_u64 v[138:139], s[42:43], 0, v[98:99]
	global_load_dwordx4 v[110:113], v[136:137], off
	global_load_dwordx2 v[140:141], v[138:139], off
	v_or_b32_e32 v98, 0x80, v98
	v_lshl_add_u64 v[130:131], v[98:99], 1, s[34:35]
	v_lshl_add_u64 v[132:133], s[42:43], 0, v[98:99]
	global_load_dwordx4 v[106:109], v[130:131], off
	global_load_dwordx2 v[134:135], v[132:133], off
	v_or_b32_e32 v114, 48, v156
	v_ashrrev_i32_e32 v115, 31, v114
	v_lshlrev_b64 v[98:99], 11, v[114:115]
	v_lshl_add_u64 v[118:119], v[98:99], 0, v[158:159]
	v_lshl_add_u64 v[122:123], v[118:119], 1, s[34:35]
	v_lshl_add_u64 v[124:125], s[42:43], 0, v[118:119]
	v_or_b32_e32 v118, 0x80, v118
	v_lshl_add_u64 v[116:117], v[118:119], 1, s[34:35]
	v_lshl_add_u64 v[118:119], s[42:43], 0, v[118:119]
	global_load_dwordx4 v[102:105], v[122:123], off
	global_load_dwordx2 v[126:127], v[124:125], off
	global_load_dwordx4 v[98:101], v[116:117], off
	global_load_dwordx2 v[120:121], v[118:119], off
	s_waitcnt vmcnt(7)
	v_lshlrev_b32_e32 v157, 16, v110
	s_waitcnt vmcnt(6)
; __device__ __forceinline__ unsigned cvt_pk_bf16(float lo, float hi) { unsigned r; asm volatile("v_cvt_pk_bf16_f32 %0, %1, %2" : "=v"(r) : "v"(lo), "v"(hi)); return r; }
;     __device__ __forceinline__ void core(const f32x4 (&acc)[2][2][4][2], const Unit& u, int wr, int wc, int fr, int fq, const float (&rsc)[2][4]) const {
;     ...
;             for (int m = 0; m < MB; ++m) { const int row = row0 + ai * HALF + (mh + m) * 16; float sq = 0.f;
;                 const float rs1 = rsc[ai][mh + m];
; #pragma unroll
;                 for (int bj = 0; bj < 2; ++bj) { const size_t idx = (size_t)row * D + col0 + bj * HALF;
;                     unsigned hw[4]; int lw[2] = {0, 0};
; #pragma unroll
;                     for (int pq = 0; pq < 4; ++pq) {
;                         float h0, h1;
;                         if (F32IN) { h0 = (pq < 2) ? xa[m][bj][2 * pq] : xb[m][bj][2 * pq - 4]; h1 = (pq < 2) ? xa[m][bj][2 * pq + 1] : xb[m][bj][2 * pq - 3]; }
;                         else { const unsigned a = va[m][bj][pq]; const int bw = (int)vb[m][bj][pq >> 1]; const hf32x2 lp = (pq & 1) ? __builtin_amdgcn_cvt_pk_f32_fp8(bw, true) : __builtin_amdgcn_cvt_pk_f32_fp8(bw, false);
;                             h0 = __uint_as_float(a << 16) + lp.x * 0.00390625f; h1 = __uint_as_float(a & 0xffff0000u) + lp.y * 0.00390625f; }
;                         const float o0 = h0 + acc[ai][bj][mh + m][pq >> 1][(2 * pq) & 3] * rs1, o1 = h1 + acc[ai][bj][mh + m][pq >> 1][(2 * pq + 1) & 3] * rs1;
;                         sq += o0 * o0 + o1 * o1;
;                         const unsigned hi = cvt_pk_bf16(o0, o1);
;                         hw[pq] = hi;
;                         const float r0 = __builtin_amdgcn_fmed3f((o0 - __uint_as_float(hi << 16)) * 256.0f, -448.0f, 448.0f), r1 = __builtin_amdgcn_fmed3f((o1 - __uint_as_float(hi & 0xffff0000u)) * 256.0f, -448.0f, 448.0f);
;                         lw[pq >> 1] = (pq & 1) ? __builtin_amdgcn_cvt_pk_fp8_f32(r0, r1, lw[pq >> 1], true) : __builtin_amdgcn_cvt_pk_fp8_f32(r0, r1, lw[pq >> 1], false);
;                     }
;                     *(u32x4*)(Hb + idx) = (u32x4){hw[0], hw[1], hw[2], hw[3]}; *(u32x2*)(Hl + idx) = (u32x2){(unsigned)lw[0], (unsigned)lw[1]}; }
;                 sq += __shfl_xor(sq, 16); sq += __shfl_xor(sq, 32); if (fq == 0) ss[(size_t)row * 32 + u.pn * 4 + wc] = sq; }
	v_cvt_pk_f32_fp8_e32 v[144:145], v140
	v_and_b32_e32 v110, 0xffff0000, v110
	v_fmac_f32_e32 v157, 0x3b800000, v144
	v_fmac_f32_e32 v110, 0x3b800000, v145
	v_add_f32_e32 v144, v94, v157
	v_add_f32_e32 v95, v95, v110
	v_cvt_pk_bf16_f32 v94, v144, v95
	v_mul_f32_e32 v157, v95, v95
	v_and_b32_e32 v110, 0xffff0000, v94
	v_sub_f32_e32 v95, v95, v110
	v_lshlrev_b32_e32 v110, 16, v94
	v_sub_f32_e32 v110, v144, v110
	v_mul_f32_e32 v95, 0x43800000, v95
	v_mul_f32_e32 v110, 0x43800000, v110
	v_fmac_f32_e32 v157, v144, v144
	v_med3_f32 v95, v95, s68, v235
	v_med3_f32 v144, v110, s68, v235
	v_mov_b32_e32 v110, v1
	v_cvt_pk_fp8_f32 v110, v144, v95
	v_cvt_pk_f32_fp8_sdwa v[144:145], v140 src0_sel:WORD_1
	v_lshlrev_b32_e32 v95, 16, v111
	v_and_b32_e32 v111, 0xffff0000, v111
	v_fmac_f32_e32 v111, 0x3b800000, v145
	v_fmac_f32_e32 v95, 0x3b800000, v144
	v_add_f32_e32 v97, v97, v111
	v_add_f32_e32 v96, v96, v95
	v_mul_f32_e32 v95, v97, v97
	v_fmac_f32_e32 v95, v96, v96
	v_add_f32_e32 v111, v157, v95
	v_cvt_pk_bf16_f32 v95, v96, v97
	s_nop 0
	v_lshlrev_b32_e32 v140, 16, v95
	v_sub_f32_e32 v96, v96, v140
	v_and_b32_e32 v140, 0xffff0000, v95
	v_sub_f32_e32 v97, v97, v140
	v_mul_f32_e32 v96, 0x43800000, v96
	v_mul_f32_e32 v97, 0x43800000, v97
	v_med3_f32 v96, v96, s68, v235
	v_med3_f32 v97, v97, s68, v235
	v_cvt_pk_fp8_f32 v110, v96, v97 op_sel:[0,0,1]
	v_cvt_pk_f32_fp8_e32 v[96:97], v141
	v_lshlrev_b32_e32 v140, 16, v112
	v_fmac_f32_e32 v140, 0x3b800000, v96
	v_and_b32_e32 v96, 0xffff0000, v112
	v_fmac_f32_e32 v96, 0x3b800000, v97
	v_add_f32_e32 v91, v91, v96
	v_add_f32_e32 v90, v90, v140
	v_mul_f32_e32 v96, v91, v91
	v_fmac_f32_e32 v96, v90, v90
	v_add_f32_e32 v97, v111, v96
	v_cvt_pk_bf16_f32 v96, v90, v91
	v_lshlrev_b32_e32 v112, 16, v113
	v_and_b32_e32 v111, 0xffff0000, v96
	v_sub_f32_e32 v91, v91, v111
	v_lshlrev_b32_e32 v111, 16, v96
	v_sub_f32_e32 v90, v90, v111
	v_mul_f32_e32 v91, 0x43800000, v91
	v_mul_f32_e32 v90, 0x43800000, v90
	v_med3_f32 v91, v91, s68, v235
	v_med3_f32 v90, v90, s68, v235
	v_mov_b32_e32 v111, v1
	v_cvt_pk_fp8_f32 v111, v90, v91
	v_cvt_pk_f32_fp8_sdwa v[90:91], v141 src0_sel:WORD_1
	v_fmac_f32_e32 v112, 0x3b800000, v90
	v_and_b32_e32 v90, 0xffff0000, v113
	v_fmac_f32_e32 v90, 0x3b800000, v91
	v_add_f32_e32 v90, v93, v90
	v_add_f32_e32 v91, v92, v112
	v_mul_f32_e32 v92, v90, v90
	v_fmac_f32_e32 v92, v91, v91
	v_add_f32_e32 v92, v97, v92
	v_cvt_pk_bf16_f32 v97, v91, v90
	s_nop 0
	v_lshlrev_b32_e32 v93, 16, v97
	v_sub_f32_e32 v91, v91, v93
	v_and_b32_e32 v93, 0xffff0000, v97
	v_sub_f32_e32 v90, v90, v93
	v_mul_f32_e32 v91, 0x43800000, v91
	v_mul_f32_e32 v90, 0x43800000, v90
	v_med3_f32 v91, v91, s68, v235
	v_med3_f32 v90, v90, s68, v235
	v_cvt_pk_fp8_f32 v111, v91, v90 op_sel:[0,0,1]
	s_waitcnt vmcnt(4)
	v_cvt_pk_f32_fp8_e32 v[90:91], v134
	v_lshlrev_b32_e32 v93, 16, v106
	global_store_dwordx4 v[136:137], v[94:97], off sc1
	global_store_dwordx2 v[138:139], v[110:111], off
	v_fmac_f32_e32 v93, 0x3b800000, v90
	v_and_b32_e32 v90, 0xffff0000, v106
	v_fmac_f32_e32 v90, 0x3b800000, v91
	v_add_f32_e32 v87, v87, v90
	v_add_f32_e32 v91, v86, v93
	v_mul_f32_e32 v86, v87, v87
	v_fmac_f32_e32 v86, v91, v91
	v_add_f32_e32 v94, v92, v86
	v_cvt_pk_bf16_f32 v86, v91, v87
	v_cvt_pk_f32_fp8_sdwa v[92:93], v134 src0_sel:WORD_1
	v_and_b32_e32 v90, 0xffff0000, v86
	v_sub_f32_e32 v87, v87, v90
	v_lshlrev_b32_e32 v90, 16, v86
	v_sub_f32_e32 v90, v91, v90
	v_mul_f32_e32 v87, 0x43800000, v87
	v_mul_f32_e32 v90, 0x43800000, v90
	v_med3_f32 v87, v87, s68, v235
	v_med3_f32 v91, v90, s68, v235
	v_mov_b32_e32 v90, v1
	v_cvt_pk_fp8_f32 v90, v91, v87
	v_and_b32_e32 v91, 0xffff0000, v107
	v_lshlrev_b32_e32 v87, 16, v107
	v_fmac_f32_e32 v91, 0x3b800000, v93
	v_fmac_f32_e32 v87, 0x3b800000, v92
	v_add_f32_e32 v89, v89, v91
	v_add_f32_e32 v88, v88, v87
	v_mul_f32_e32 v87, v89, v89
	v_fmac_f32_e32 v87, v88, v88
	v_add_f32_e32 v91, v94, v87
	v_cvt_pk_bf16_f32 v87, v88, v89
	s_nop 0
	v_lshlrev_b32_e32 v92, 16, v87
	v_sub_f32_e32 v88, v88, v92
	v_and_b32_e32 v92, 0xffff0000, v87
	v_sub_f32_e32 v89, v89, v92
	v_mul_f32_e32 v88, 0x43800000, v88
	v_mul_f32_e32 v89, 0x43800000, v89
	v_med3_f32 v88, v88, s68, v235
	v_med3_f32 v89, v89, s68, v235
	v_cvt_pk_fp8_f32 v90, v88, v89 op_sel:[0,0,1]
	v_cvt_pk_f32_fp8_e32 v[88:89], v135
	v_lshlrev_b32_e32 v92, 16, v108
	v_fmac_f32_e32 v92, 0x3b800000, v88
	v_and_b32_e32 v88, 0xffff0000, v108
	v_fmac_f32_e32 v88, 0x3b800000, v89
	v_add_f32_e32 v83, v83, v88
	v_add_f32_e32 v82, v82, v92
	v_mul_f32_e32 v88, v83, v83
	v_fmac_f32_e32 v88, v82, v82
	v_add_f32_e32 v89, v91, v88
	v_cvt_pk_bf16_f32 v88, v82, v83
	v_lshlrev_b32_e32 v92, 16, v109
	v_and_b32_e32 v91, 0xffff0000, v88
	v_sub_f32_e32 v83, v83, v91
	v_lshlrev_b32_e32 v91, 16, v88
	v_sub_f32_e32 v82, v82, v91
	v_mul_f32_e32 v83, 0x43800000, v83
	v_mul_f32_e32 v82, 0x43800000, v82
	v_med3_f32 v83, v83, s68, v235
	v_med3_f32 v82, v82, s68, v235
	v_mov_b32_e32 v91, v1
	v_cvt_pk_fp8_f32 v91, v82, v83
	v_cvt_pk_f32_fp8_sdwa v[82:83], v135 src0_sel:WORD_1
	v_fmac_f32_e32 v92, 0x3b800000, v82
	v_and_b32_e32 v82, 0xffff0000, v109
	v_fmac_f32_e32 v82, 0x3b800000, v83
	v_add_f32_e32 v82, v85, v82
	v_add_f32_e32 v83, v84, v92
	v_mul_f32_e32 v84, v82, v82
	v_fmac_f32_e32 v84, v83, v83
	v_add_f32_e32 v84, v89, v84
	v_cvt_pk_bf16_f32 v89, v83, v82
	s_nop 0
	v_lshlrev_b32_e32 v85, 16, v89
	v_sub_f32_e32 v83, v83, v85
	v_and_b32_e32 v85, 0xffff0000, v89
	v_sub_f32_e32 v82, v82, v85
	v_mul_f32_e32 v83, 0x43800000, v83
	v_mul_f32_e32 v82, 0x43800000, v82
	v_med3_f32 v83, v83, s68, v235
	v_med3_f32 v82, v82, s68, v235
	v_cvt_pk_fp8_f32 v91, v83, v82 op_sel:[0,0,1]
	ds_bpermute_b32 v82, v142, v84
	global_store_dwordx4 v[130:131], v[86:89], off sc1
	global_store_dwordx2 v[132:133], v[90:91], off
	s_waitcnt lgkmcnt(0)
	v_add_f32_e32 v82, v84, v82
	ds_bpermute_b32 v83, v143, v82
	s_and_saveexec_b64 s[2:3], s[38:39]
	s_cbranch_execz .LBB0_1261
	s_waitcnt lgkmcnt(0)
	v_add_f32_e32 v84, v82, v83
	s_lshl_b32 s20, s8, 2
	v_lshlrev_b64 v[82:83], 7, v[128:129]
	s_ashr_i32 s21, s20, 31
	v_lshl_add_u64 v[82:83], s[44:45], 0, v[82:83]
	v_lshl_add_u64 v[82:83], s[20:21], 2, v[82:83]
	s_lshl_b32 s18, s36, 2
	v_lshl_add_u64 v[82:83], v[82:83], 0, s[18:19]
	global_store_dword v[82:83], v84, off
; __device__ __forceinline__ unsigned cvt_pk_bf16(float lo, float hi) { unsigned r; asm volatile("v_cvt_pk_bf16_f32 %0, %1, %2" : "=v"(r) : "v"(lo), "v"(hi)); return r; }
;     __device__ __forceinline__ void core(const f32x4 (&acc)[2][2][4][2], const Unit& u, int wr, int wc, int fr, int fq, const float (&rsc)[2][4]) const {
;     ...
;             for (int m = 0; m < MB; ++m) { const int row = row0 + ai * HALF + (mh + m) * 16; float sq = 0.f;
;                 const float rs1 = rsc[ai][mh + m];
; #pragma unroll
;                 for (int bj = 0; bj < 2; ++bj) { const size_t idx = (size_t)row * D + col0 + bj * HALF;
;                     unsigned hw[4]; int lw[2] = {0, 0};
; #pragma unroll
;                     for (int pq = 0; pq < 4; ++pq) {
;                         float h0, h1;
;                         if (F32IN) { h0 = (pq < 2) ? xa[m][bj][2 * pq] : xb[m][bj][2 * pq - 4]; h1 = (pq < 2) ? xa[m][bj][2 * pq + 1] : xb[m][bj][2 * pq - 3]; }
;                         else { const unsigned a = va[m][bj][pq]; const int bw = (int)vb[m][bj][pq >> 1]; const hf32x2 lp = (pq & 1) ? __builtin_amdgcn_cvt_pk_f32_fp8(bw, true) : __builtin_amdgcn_cvt_pk_f32_fp8(bw, false);
;                             h0 = __uint_as_float(a << 16) + lp.x * 0.00390625f; h1 = __uint_as_float(a & 0xffff0000u) + lp.y * 0.00390625f; }
;                         const float o0 = h0 + acc[ai][bj][mh + m][pq >> 1][(2 * pq) & 3] * rs1, o1 = h1 + acc[ai][bj][mh + m][pq >> 1][(2 * pq + 1) & 3] * rs1;
;                         sq += o0 * o0 + o1 * o1;
;                         const unsigned hi = cvt_pk_bf16(o0, o1);
;                         hw[pq] = hi;
;                         const float r0 = __builtin_amdgcn_fmed3f((o0 - __uint_as_float(hi << 16)) * 256.0f, -448.0f, 448.0f), r1 = __builtin_amdgcn_fmed3f((o1 - __uint_as_float(hi & 0xffff0000u)) * 256.0f, -448.0f, 448.0f);
;                         lw[pq >> 1] = (pq & 1) ? __builtin_amdgcn_cvt_pk_fp8_f32(r0, r1, lw[pq >> 1], true) : __builtin_amdgcn_cvt_pk_fp8_f32(r0, r1, lw[pq >> 1], false);
;                     }
;                     *(u32x4*)(Hb + idx) = (u32x4){hw[0], hw[1], hw[2], hw[3]}; *(u32x2*)(Hl + idx) = (u32x2){(unsigned)lw[0], (unsigned)lw[1]}; }
;                 sq += __shfl_xor(sq, 16); sq += __shfl_xor(sq, 32); if (fq == 0) ss[(size_t)row * 32 + u.pn * 4 + wc] = sq; }
.LBB0_1261:
	s_or_b64 exec, exec, s[2:3]
	s_waitcnt vmcnt(6) lgkmcnt(0)
	v_cvt_pk_f32_fp8_e32 v[82:83], v126
	v_lshlrev_b32_e32 v84, 16, v102
	v_fmac_f32_e32 v84, 0x3b800000, v82
	v_and_b32_e32 v82, 0xffff0000, v102
	v_fmac_f32_e32 v82, 0x3b800000, v83
	v_add_f32_e32 v83, v78, v84
	v_add_f32_e32 v79, v79, v82
	v_cvt_pk_bf16_f32 v78, v83, v79
	v_mul_f32_e32 v86, v79, v79
	v_and_b32_e32 v82, 0xffff0000, v78
	v_sub_f32_e32 v79, v79, v82
	v_lshlrev_b32_e32 v82, 16, v78
	v_sub_f32_e32 v82, v83, v82
	v_cvt_pk_f32_fp8_sdwa v[84:85], v126 src0_sel:WORD_1
	v_mul_f32_e32 v79, 0x43800000, v79
	v_mul_f32_e32 v82, 0x43800000, v82
	v_fmac_f32_e32 v86, v83, v83
	v_med3_f32 v79, v79, s68, v235
	v_med3_f32 v83, v82, s68, v235
	v_mov_b32_e32 v82, v1
	v_cvt_pk_fp8_f32 v82, v83, v79
	v_and_b32_e32 v83, 0xffff0000, v103
	v_lshlrev_b32_e32 v79, 16, v103
	v_fmac_f32_e32 v83, 0x3b800000, v85
	v_fmac_f32_e32 v79, 0x3b800000, v84
	v_add_f32_e32 v81, v81, v83
	v_add_f32_e32 v80, v80, v79
	v_mul_f32_e32 v79, v81, v81
	v_fmac_f32_e32 v79, v80, v80
	v_add_f32_e32 v83, v86, v79
	v_cvt_pk_bf16_f32 v79, v80, v81
	s_nop 0
	v_lshlrev_b32_e32 v84, 16, v79
	v_sub_f32_e32 v80, v80, v84
	v_and_b32_e32 v84, 0xffff0000, v79
	v_sub_f32_e32 v81, v81, v84
	v_mul_f32_e32 v80, 0x43800000, v80
	v_mul_f32_e32 v81, 0x43800000, v81
	v_med3_f32 v80, v80, s68, v235
	v_med3_f32 v81, v81, s68, v235
	v_cvt_pk_fp8_f32 v82, v80, v81 op_sel:[0,0,1]
	v_cvt_pk_f32_fp8_e32 v[80:81], v127
	v_lshlrev_b32_e32 v84, 16, v104
	v_fmac_f32_e32 v84, 0x3b800000, v80
	v_and_b32_e32 v80, 0xffff0000, v104
	v_fmac_f32_e32 v80, 0x3b800000, v81
	v_add_f32_e32 v75, v75, v80
	v_add_f32_e32 v74, v74, v84
	v_mul_f32_e32 v80, v75, v75
	v_fmac_f32_e32 v80, v74, v74
	v_add_f32_e32 v81, v83, v80
	v_cvt_pk_bf16_f32 v80, v74, v75
	v_lshlrev_b32_e32 v84, 16, v105
	v_and_b32_e32 v83, 0xffff0000, v80
	v_sub_f32_e32 v75, v75, v83
	v_lshlrev_b32_e32 v83, 16, v80
	v_sub_f32_e32 v74, v74, v83
	v_mul_f32_e32 v75, 0x43800000, v75
	v_mul_f32_e32 v74, 0x43800000, v74
	v_med3_f32 v75, v75, s68, v235
	v_med3_f32 v74, v74, s68, v235
	v_mov_b32_e32 v83, v1
	v_cvt_pk_fp8_f32 v83, v74, v75
	v_cvt_pk_f32_fp8_sdwa v[74:75], v127 src0_sel:WORD_1
	v_fmac_f32_e32 v84, 0x3b800000, v74
	v_and_b32_e32 v74, 0xffff0000, v105
	v_fmac_f32_e32 v74, 0x3b800000, v75
	v_add_f32_e32 v74, v77, v74
	v_add_f32_e32 v75, v76, v84
	v_mul_f32_e32 v76, v74, v74
	v_fmac_f32_e32 v76, v75, v75
	v_add_f32_e32 v76, v81, v76
	v_cvt_pk_bf16_f32 v81, v75, v74
	s_nop 0
	v_lshlrev_b32_e32 v77, 16, v81
	v_sub_f32_e32 v75, v75, v77
	v_and_b32_e32 v77, 0xffff0000, v81
	v_sub_f32_e32 v74, v74, v77
	v_mul_f32_e32 v75, 0x43800000, v75
	v_mul_f32_e32 v74, 0x43800000, v74
	v_med3_f32 v75, v75, s68, v235
	v_med3_f32 v74, v74, s68, v235
	v_cvt_pk_fp8_f32 v83, v75, v74 op_sel:[0,0,1]
	s_waitcnt vmcnt(4)
	v_cvt_pk_f32_fp8_e32 v[74:75], v120
	v_lshlrev_b32_e32 v77, 16, v98
	global_store_dwordx4 v[122:123], v[78:81], off sc1
	global_store_dwordx2 v[124:125], v[82:83], off
	v_fmac_f32_e32 v77, 0x3b800000, v74
	v_and_b32_e32 v74, 0xffff0000, v98
	v_fmac_f32_e32 v74, 0x3b800000, v75
	v_add_f32_e32 v71, v71, v74
	v_add_f32_e32 v75, v70, v77
	v_mul_f32_e32 v70, v71, v71
	v_fmac_f32_e32 v70, v75, v75
	v_add_f32_e32 v78, v76, v70
	v_cvt_pk_bf16_f32 v70, v75, v71
	v_cvt_pk_f32_fp8_sdwa v[76:77], v120 src0_sel:WORD_1
	v_and_b32_e32 v74, 0xffff0000, v70
	v_sub_f32_e32 v71, v71, v74
	v_lshlrev_b32_e32 v74, 16, v70
	v_sub_f32_e32 v74, v75, v74
	v_mul_f32_e32 v71, 0x43800000, v71
	v_mul_f32_e32 v74, 0x43800000, v74
	v_med3_f32 v71, v71, s68, v235
	v_med3_f32 v75, v74, s68, v235
	v_mov_b32_e32 v74, v1
	v_cvt_pk_fp8_f32 v74, v75, v71
	v_and_b32_e32 v75, 0xffff0000, v99
	v_lshlrev_b32_e32 v71, 16, v99
	v_fmac_f32_e32 v75, 0x3b800000, v77
	v_fmac_f32_e32 v71, 0x3b800000, v76
	v_add_f32_e32 v73, v73, v75
	v_add_f32_e32 v72, v72, v71
	v_mul_f32_e32 v71, v73, v73
	v_fmac_f32_e32 v71, v72, v72
	v_add_f32_e32 v75, v78, v71
	v_cvt_pk_bf16_f32 v71, v72, v73
	s_nop 0
	v_lshlrev_b32_e32 v76, 16, v71
	v_sub_f32_e32 v72, v72, v76
	v_and_b32_e32 v76, 0xffff0000, v71
	v_sub_f32_e32 v73, v73, v76
	v_mul_f32_e32 v72, 0x43800000, v72
	v_mul_f32_e32 v73, 0x43800000, v73
	v_med3_f32 v72, v72, s68, v235
	v_med3_f32 v73, v73, s68, v235
	v_cvt_pk_fp8_f32 v74, v72, v73 op_sel:[0,0,1]
	v_cvt_pk_f32_fp8_e32 v[72:73], v121
	v_lshlrev_b32_e32 v76, 16, v100
	v_fmac_f32_e32 v76, 0x3b800000, v72
	v_and_b32_e32 v72, 0xffff0000, v100
	v_fmac_f32_e32 v72, 0x3b800000, v73
	v_add_f32_e32 v67, v67, v72
	v_add_f32_e32 v66, v66, v76
	v_mul_f32_e32 v72, v67, v67
	v_fmac_f32_e32 v72, v66, v66
	v_add_f32_e32 v73, v75, v72
	v_cvt_pk_bf16_f32 v72, v66, v67
	v_lshlrev_b32_e32 v76, 16, v101
	v_and_b32_e32 v75, 0xffff0000, v72
	v_sub_f32_e32 v67, v67, v75
	v_lshlrev_b32_e32 v75, 16, v72
	v_sub_f32_e32 v66, v66, v75
	v_mul_f32_e32 v67, 0x43800000, v67
	v_mul_f32_e32 v66, 0x43800000, v66
	v_med3_f32 v67, v67, s68, v235
	v_med3_f32 v66, v66, s68, v235
	v_mov_b32_e32 v75, v1
	v_cvt_pk_fp8_f32 v75, v66, v67
	v_cvt_pk_f32_fp8_sdwa v[66:67], v121 src0_sel:WORD_1
	v_fmac_f32_e32 v76, 0x3b800000, v66
	v_and_b32_e32 v66, 0xffff0000, v101
	v_fmac_f32_e32 v66, 0x3b800000, v67
	v_add_f32_e32 v66, v69, v66
	v_add_f32_e32 v67, v68, v76
	v_mul_f32_e32 v68, v66, v66
	v_fmac_f32_e32 v68, v67, v67
	v_add_f32_e32 v68, v73, v68
	v_cvt_pk_bf16_f32 v73, v67, v66
	s_nop 0
	v_lshlrev_b32_e32 v69, 16, v73
	v_sub_f32_e32 v67, v67, v69
	v_and_b32_e32 v69, 0xffff0000, v73
	v_sub_f32_e32 v66, v66, v69
	v_mul_f32_e32 v67, 0x43800000, v67
	v_mul_f32_e32 v66, 0x43800000, v66
	v_med3_f32 v67, v67, s68, v235
	v_med3_f32 v66, v66, s68, v235
	v_cvt_pk_fp8_f32 v75, v67, v66 op_sel:[0,0,1]
	ds_bpermute_b32 v66, v142, v68
	global_store_dwordx4 v[116:117], v[70:73], off sc1
	global_store_dwordx2 v[118:119], v[74:75], off
	s_waitcnt lgkmcnt(0)
	v_add_f32_e32 v66, v68, v66
	ds_bpermute_b32 v67, v143, v66
	s_and_saveexec_b64 s[2:3], s[38:39]
	s_cbranch_execz .LBB0_1263
	s_waitcnt lgkmcnt(0)
	v_add_f32_e32 v68, v66, v67
	s_lshl_b32 s20, s8, 2
	v_lshlrev_b64 v[66:67], 7, v[114:115]
	s_ashr_i32 s21, s20, 31
	v_lshl_add_u64 v[66:67], s[44:45], 0, v[66:67]
	v_lshl_add_u64 v[66:67], s[20:21], 2, v[66:67]
	s_lshl_b32 s18, s36, 2
	v_lshl_add_u64 v[66:67], v[66:67], 0, s[18:19]
	global_store_dword v[66:67], v68, off
;     __device__ __forceinline__ void core(const f32x4 (&acc)[2][2][4][2], const Unit& u, int wr, int wc, int fr, int fq, const float (&rsc)[2][4]) const {
;     ...
;             for (int m = 0; m < MB; ++m)
; #pragma unroll
;                 for (int bj = 0; bj < 2; ++bj) { const size_t idx = (size_t)(row0 + ai * HALF + (mh + m) * 16) * D + col0 + bj * HALF;
;                     if (F32IN) { xa[m][bj] = *(const f32x4*)(Xin + idx); xb[m][bj] = *(const f32x4*)(Xin + idx + 4); }
;                     else { va[m][bj] = *(const u32x4*)(Hb + idx); vb[m][bj] = *(const u32x2*)(Hl + idx); } }
; #pragma unroll
;             for (int m = 0; m < MB; ++m) { const int row = row0 + ai * HALF + (mh + m) * 16; float sq = 0.f;
;                 const float rs1 = rsc[ai][mh + m];
; #pragma unroll
;                 for (int bj = 0; bj < 2; ++bj) { const size_t idx = (size_t)row * D + col0 + bj * HALF;
;                     unsigned hw[4]; int lw[2] = {0, 0};
; #pragma unroll
;                     for (int pq = 0; pq < 4; ++pq) {
;                         float h0, h1;
;                         if (F32IN) { h0 = (pq < 2) ? xa[m][bj][2 * pq] : xb[m][bj][2 * pq - 4]; h1 = (pq < 2) ? xa[m][bj][2 * pq + 1] : xb[m][bj][2 * pq - 3]; }
;                         else { const unsigned a = va[m][bj][pq]; const int bw = (int)vb[m][bj][pq >> 1]; const hf32x2 lp = (pq & 1) ? __builtin_amdgcn_cvt_pk_f32_fp8(bw, true) : __builtin_amdgcn_cvt_pk_f32_fp8(bw, false);
;                             h0 = __uint_as_float(a << 16) + lp.x * 0.00390625f; h1 = __uint_as_float(a & 0xffff0000u) + lp.y * 0.00390625f; }
;                         const float o0 = h0 + acc[ai][bj][mh + m][pq >> 1][(2 * pq) & 3] * rs1, o1 = h1 + acc[ai][bj][mh + m][pq >> 1][(2 * pq + 1) & 3] * rs1;
;                         sq += o0 * o0 + o1 * o1;
;                         const unsigned hi = cvt_pk_bf16(o0, o1);
;                         hw[pq] = hi;
;                         const float r0 = __builtin_amdgcn_fmed3f((o0 - __uint_as_float(hi << 16)) * 256.0f, -448.0f, 448.0f), r1 = __builtin_amdgcn_fmed3f((o1 - __uint_as_float(hi & 0xffff0000u)) * 256.0f, -448.0f, 448.0f);
;                         lw[pq >> 1] = (pq & 1) ? __builtin_amdgcn_cvt_pk_fp8_f32(r0, r1, lw[pq >> 1], true) : __builtin_amdgcn_cvt_pk_fp8_f32(r0, r1, lw[pq >> 1], false);
;                     }
.LBB0_1263:
	s_or_b64 exec, exec, s[2:3]
	v_add_u32_e32 v96, 0x80, v156
	v_ashrrev_i32_e32 v97, 31, v96
	s_waitcnt lgkmcnt(0)
	v_lshlrev_b64 v[66:67], 11, v[96:97]
	v_lshl_add_u64 v[66:67], v[66:67], 0, v[158:159]
	v_lshl_add_u64 v[104:105], v[66:67], 1, s[34:35]
	v_lshl_add_u64 v[106:107], s[42:43], 0, v[66:67]
	global_load_dwordx4 v[78:81], v[104:105], off
	global_load_dwordx2 v[108:109], v[106:107], off
	v_or_b32_e32 v66, 0x80, v66
	v_lshl_add_u64 v[98:99], v[66:67], 1, s[34:35]
	v_lshl_add_u64 v[100:101], s[42:43], 0, v[66:67]
	global_load_dwordx4 v[74:77], v[98:99], off
	global_load_dwordx2 v[102:103], v[100:101], off
	v_add_u32_e32 v82, 0x90, v156
	v_ashrrev_i32_e32 v83, 31, v82
	v_lshlrev_b64 v[66:67], 11, v[82:83]
	v_lshl_add_u64 v[86:87], v[66:67], 0, v[158:159]
	v_lshl_add_u64 v[90:91], v[86:87], 1, s[34:35]
	v_lshl_add_u64 v[92:93], s[42:43], 0, v[86:87]
	v_or_b32_e32 v86, 0x80, v86
	v_lshl_add_u64 v[84:85], v[86:87], 1, s[34:35]
	v_lshl_add_u64 v[86:87], s[42:43], 0, v[86:87]
	global_load_dwordx4 v[70:73], v[90:91], off
	global_load_dwordx2 v[94:95], v[92:93], off
	global_load_dwordx4 v[66:69], v[84:85], off
	global_load_dwordx2 v[88:89], v[86:87], off
	s_waitcnt vmcnt(7)
	v_lshlrev_b32_e32 v112, 16, v78
	s_waitcnt vmcnt(6)
	v_cvt_pk_f32_fp8_e32 v[110:111], v108
	v_and_b32_e32 v78, 0xffff0000, v78
	v_fmac_f32_e32 v112, 0x3b800000, v110
	v_fmac_f32_e32 v78, 0x3b800000, v111
	v_add_f32_e32 v110, v62, v112
	v_add_f32_e32 v63, v63, v78
	v_cvt_pk_bf16_f32 v62, v110, v63
	v_mul_f32_e32 v112, v63, v63
	v_and_b32_e32 v78, 0xffff0000, v62
	v_sub_f32_e32 v63, v63, v78
	v_lshlrev_b32_e32 v78, 16, v62
	v_sub_f32_e32 v78, v110, v78
	v_mul_f32_e32 v63, 0x43800000, v63
	v_mul_f32_e32 v78, 0x43800000, v78
	v_fmac_f32_e32 v112, v110, v110
	v_med3_f32 v63, v63, s68, v235
	v_med3_f32 v110, v78, s68, v235
	v_mov_b32_e32 v78, v1
	v_cvt_pk_fp8_f32 v78, v110, v63
	v_cvt_pk_f32_fp8_sdwa v[110:111], v108 src0_sel:WORD_1
	v_lshlrev_b32_e32 v63, 16, v79
	v_and_b32_e32 v79, 0xffff0000, v79
	v_fmac_f32_e32 v79, 0x3b800000, v111
	v_fmac_f32_e32 v63, 0x3b800000, v110
	v_add_f32_e32 v65, v65, v79
	v_add_f32_e32 v64, v64, v63
	v_mul_f32_e32 v63, v65, v65
	v_fmac_f32_e32 v63, v64, v64
	v_add_f32_e32 v79, v112, v63
	v_cvt_pk_bf16_f32 v63, v64, v65
	s_nop 0
	v_lshlrev_b32_e32 v108, 16, v63
	v_sub_f32_e32 v64, v64, v108
	v_and_b32_e32 v108, 0xffff0000, v63
	v_sub_f32_e32 v65, v65, v108
	v_mul_f32_e32 v64, 0x43800000, v64
	v_mul_f32_e32 v65, 0x43800000, v65
	v_med3_f32 v64, v64, s68, v235
	v_med3_f32 v65, v65, s68, v235
	v_cvt_pk_fp8_f32 v78, v64, v65 op_sel:[0,0,1]
	v_cvt_pk_f32_fp8_e32 v[64:65], v109
	v_lshlrev_b32_e32 v108, 16, v80
	v_fmac_f32_e32 v108, 0x3b800000, v64
	v_and_b32_e32 v64, 0xffff0000, v80
	v_fmac_f32_e32 v64, 0x3b800000, v65
	v_add_f32_e32 v59, v59, v64
	v_add_f32_e32 v58, v58, v108
	v_mul_f32_e32 v64, v59, v59
	v_fmac_f32_e32 v64, v58, v58
	v_add_f32_e32 v65, v79, v64
	v_cvt_pk_bf16_f32 v64, v58, v59
	v_lshlrev_b32_e32 v80, 16, v81
	v_and_b32_e32 v79, 0xffff0000, v64
	v_sub_f32_e32 v59, v59, v79
	v_lshlrev_b32_e32 v79, 16, v64
	v_sub_f32_e32 v58, v58, v79
	v_mul_f32_e32 v59, 0x43800000, v59
	v_mul_f32_e32 v58, 0x43800000, v58
	v_med3_f32 v59, v59, s68, v235
	v_med3_f32 v58, v58, s68, v235
	v_mov_b32_e32 v79, v1
	v_cvt_pk_fp8_f32 v79, v58, v59
	v_cvt_pk_f32_fp8_sdwa v[58:59], v109 src0_sel:WORD_1
	v_fmac_f32_e32 v80, 0x3b800000, v58
	v_and_b32_e32 v58, 0xffff0000, v81
	v_fmac_f32_e32 v58, 0x3b800000, v59
	v_add_f32_e32 v58, v61, v58
	v_add_f32_e32 v59, v60, v80
	v_mul_f32_e32 v60, v58, v58
	v_fmac_f32_e32 v60, v59, v59
	v_add_f32_e32 v60, v65, v60
	v_cvt_pk_bf16_f32 v65, v59, v58
	s_nop 0
	v_lshlrev_b32_e32 v61, 16, v65
	v_sub_f32_e32 v59, v59, v61
	v_and_b32_e32 v61, 0xffff0000, v65
	v_sub_f32_e32 v58, v58, v61
	v_mul_f32_e32 v59, 0x43800000, v59
	v_mul_f32_e32 v58, 0x43800000, v58
	v_med3_f32 v59, v59, s68, v235
	v_med3_f32 v58, v58, s68, v235
	v_cvt_pk_fp8_f32 v79, v59, v58 op_sel:[0,0,1]
	s_waitcnt vmcnt(4)
	v_cvt_pk_f32_fp8_e32 v[58:59], v102
	v_lshlrev_b32_e32 v61, 16, v74
	global_store_dwordx4 v[104:105], v[62:65], off sc1
	global_store_dwordx2 v[106:107], v[78:79], off
	v_fmac_f32_e32 v61, 0x3b800000, v58
	v_and_b32_e32 v58, 0xffff0000, v74
	v_fmac_f32_e32 v58, 0x3b800000, v59
	v_add_f32_e32 v55, v55, v58
	v_add_f32_e32 v59, v54, v61
	v_mul_f32_e32 v54, v55, v55
	v_fmac_f32_e32 v54, v59, v59
	v_add_f32_e32 v62, v60, v54
	v_cvt_pk_bf16_f32 v54, v59, v55
	v_cvt_pk_f32_fp8_sdwa v[60:61], v102 src0_sel:WORD_1
	v_and_b32_e32 v58, 0xffff0000, v54
	v_sub_f32_e32 v55, v55, v58
	v_lshlrev_b32_e32 v58, 16, v54
	v_sub_f32_e32 v58, v59, v58
	v_mul_f32_e32 v55, 0x43800000, v55
	v_mul_f32_e32 v58, 0x43800000, v58
	v_med3_f32 v55, v55, s68, v235
	v_med3_f32 v59, v58, s68, v235
	v_mov_b32_e32 v58, v1
	v_cvt_pk_fp8_f32 v58, v59, v55
	v_and_b32_e32 v59, 0xffff0000, v75
	v_lshlrev_b32_e32 v55, 16, v75
	v_fmac_f32_e32 v59, 0x3b800000, v61
	v_fmac_f32_e32 v55, 0x3b800000, v60
	v_add_f32_e32 v57, v57, v59
	v_add_f32_e32 v56, v56, v55
	v_mul_f32_e32 v55, v57, v57
	v_fmac_f32_e32 v55, v56, v56
	v_add_f32_e32 v59, v62, v55
	v_cvt_pk_bf16_f32 v55, v56, v57
	s_nop 0
	v_lshlrev_b32_e32 v60, 16, v55
	v_sub_f32_e32 v56, v56, v60
	v_and_b32_e32 v60, 0xffff0000, v55
	v_sub_f32_e32 v57, v57, v60
	v_mul_f32_e32 v56, 0x43800000, v56
	v_mul_f32_e32 v57, 0x43800000, v57
	v_med3_f32 v56, v56, s68, v235
	v_med3_f32 v57, v57, s68, v235
	v_cvt_pk_fp8_f32 v58, v56, v57 op_sel:[0,0,1]
	v_cvt_pk_f32_fp8_e32 v[56:57], v103
	v_lshlrev_b32_e32 v60, 16, v76
	v_fmac_f32_e32 v60, 0x3b800000, v56
	v_and_b32_e32 v56, 0xffff0000, v76
	v_fmac_f32_e32 v56, 0x3b800000, v57
	v_add_f32_e32 v51, v51, v56
	v_add_f32_e32 v50, v50, v60
	v_mul_f32_e32 v56, v51, v51
	v_fmac_f32_e32 v56, v50, v50
	v_add_f32_e32 v57, v59, v56
	v_cvt_pk_bf16_f32 v56, v50, v51
	v_lshlrev_b32_e32 v60, 16, v77
	v_and_b32_e32 v59, 0xffff0000, v56
	v_sub_f32_e32 v51, v51, v59
	v_lshlrev_b32_e32 v59, 16, v56
	v_sub_f32_e32 v50, v50, v59
	v_mul_f32_e32 v51, 0x43800000, v51
	v_mul_f32_e32 v50, 0x43800000, v50
	v_med3_f32 v51, v51, s68, v235
	v_med3_f32 v50, v50, s68, v235
	v_mov_b32_e32 v59, v1
	v_cvt_pk_fp8_f32 v59, v50, v51
	v_cvt_pk_f32_fp8_sdwa v[50:51], v103 src0_sel:WORD_1
	v_fmac_f32_e32 v60, 0x3b800000, v50
	v_and_b32_e32 v50, 0xffff0000, v77
	v_fmac_f32_e32 v50, 0x3b800000, v51
	v_add_f32_e32 v50, v53, v50
	v_add_f32_e32 v51, v52, v60
	v_mul_f32_e32 v52, v50, v50
	v_fmac_f32_e32 v52, v51, v51
	v_add_f32_e32 v52, v57, v52
	v_cvt_pk_bf16_f32 v57, v51, v50
	s_nop 0
	v_lshlrev_b32_e32 v53, 16, v57
	v_sub_f32_e32 v51, v51, v53
	v_and_b32_e32 v53, 0xffff0000, v57
	v_sub_f32_e32 v50, v50, v53
	v_mul_f32_e32 v51, 0x43800000, v51
	v_mul_f32_e32 v50, 0x43800000, v50
	v_med3_f32 v51, v51, s68, v235
	v_med3_f32 v50, v50, s68, v235
	v_cvt_pk_fp8_f32 v59, v51, v50 op_sel:[0,0,1]
	ds_bpermute_b32 v50, v142, v52
	global_store_dwordx4 v[98:99], v[54:57], off sc1
	global_store_dwordx2 v[100:101], v[58:59], off
	s_waitcnt lgkmcnt(0)
; __device__ __forceinline__ unsigned cvt_pk_bf16(float lo, float hi) { unsigned r; asm volatile("v_cvt_pk_bf16_f32 %0, %1, %2" : "=v"(r) : "v"(lo), "v"(hi)); return r; }
;     __device__ __forceinline__ void core(const f32x4 (&acc)[2][2][4][2], const Unit& u, int wr, int wc, int fr, int fq, const float (&rsc)[2][4]) const {
;     ...
;             for (int m = 0; m < MB; ++m) { const int row = row0 + ai * HALF + (mh + m) * 16; float sq = 0.f;
;                 const float rs1 = rsc[ai][mh + m];
; #pragma unroll
;                 for (int bj = 0; bj < 2; ++bj) { const size_t idx = (size_t)row * D + col0 + bj * HALF;
;                     unsigned hw[4]; int lw[2] = {0, 0};
; #pragma unroll
;                     for (int pq = 0; pq < 4; ++pq) {
;                         float h0, h1;
;                         if (F32IN) { h0 = (pq < 2) ? xa[m][bj][2 * pq] : xb[m][bj][2 * pq - 4]; h1 = (pq < 2) ? xa[m][bj][2 * pq + 1] : xb[m][bj][2 * pq - 3]; }
;                         else { const unsigned a = va[m][bj][pq]; const int bw = (int)vb[m][bj][pq >> 1]; const hf32x2 lp = (pq & 1) ? __builtin_amdgcn_cvt_pk_f32_fp8(bw, true) : __builtin_amdgcn_cvt_pk_f32_fp8(bw, false);
;                             h0 = __uint_as_float(a << 16) + lp.x * 0.00390625f; h1 = __uint_as_float(a & 0xffff0000u) + lp.y * 0.00390625f; }
;                         const float o0 = h0 + acc[ai][bj][mh + m][pq >> 1][(2 * pq) & 3] * rs1, o1 = h1 + acc[ai][bj][mh + m][pq >> 1][(2 * pq + 1) & 3] * rs1;
;                         sq += o0 * o0 + o1 * o1;
;                         const unsigned hi = cvt_pk_bf16(o0, o1);
;                         hw[pq] = hi;
;                         const float r0 = __builtin_amdgcn_fmed3f((o0 - __uint_as_float(hi << 16)) * 256.0f, -448.0f, 448.0f), r1 = __builtin_amdgcn_fmed3f((o1 - __uint_as_float(hi & 0xffff0000u)) * 256.0f, -448.0f, 448.0f);
;                         lw[pq >> 1] = (pq & 1) ? __builtin_amdgcn_cvt_pk_fp8_f32(r0, r1, lw[pq >> 1], true) : __builtin_amdgcn_cvt_pk_fp8_f32(r0, r1, lw[pq >> 1], false);
;                     }
;                     *(u32x4*)(Hb + idx) = (u32x4){hw[0], hw[1], hw[2], hw[3]}; *(u32x2*)(Hl + idx) = (u32x2){(unsigned)lw[0], (unsigned)lw[1]}; }
;                 sq += __shfl_xor(sq, 16); sq += __shfl_xor(sq, 32); if (fq == 0) ss[(size_t)row * 32 + u.pn * 4 + wc] = sq; }
	v_add_f32_e32 v50, v52, v50
	ds_bpermute_b32 v51, v143, v50
	s_and_saveexec_b64 s[2:3], s[38:39]
	s_cbranch_execz .LBB0_1265
	s_waitcnt lgkmcnt(0)
	v_add_f32_e32 v52, v50, v51
	s_lshl_b32 s20, s8, 2
	v_lshlrev_b64 v[50:51], 7, v[96:97]
	s_ashr_i32 s21, s20, 31
	v_lshl_add_u64 v[50:51], s[44:45], 0, v[50:51]
	v_lshl_add_u64 v[50:51], s[20:21], 2, v[50:51]
	s_lshl_b32 s18, s36, 2
	v_lshl_add_u64 v[50:51], v[50:51], 0, s[18:19]
	global_store_dword v[50:51], v52, off
.LBB0_1265:
	s_or_b64 exec, exec, s[2:3]
	s_waitcnt vmcnt(6) lgkmcnt(0)
	v_cvt_pk_f32_fp8_e32 v[50:51], v94
	v_lshlrev_b32_e32 v52, 16, v70
	v_fmac_f32_e32 v52, 0x3b800000, v50
	v_and_b32_e32 v50, 0xffff0000, v70
	v_fmac_f32_e32 v50, 0x3b800000, v51
	v_add_f32_e32 v51, v46, v52
	v_add_f32_e32 v47, v47, v50
	v_cvt_pk_bf16_f32 v46, v51, v47
	v_mul_f32_e32 v54, v47, v47
	v_and_b32_e32 v50, 0xffff0000, v46
	v_sub_f32_e32 v47, v47, v50
	v_lshlrev_b32_e32 v50, 16, v46
	v_sub_f32_e32 v50, v51, v50
	v_cvt_pk_f32_fp8_sdwa v[52:53], v94 src0_sel:WORD_1
	v_mul_f32_e32 v47, 0x43800000, v47
	v_mul_f32_e32 v50, 0x43800000, v50
	v_fmac_f32_e32 v54, v51, v51
	v_med3_f32 v47, v47, s68, v235
	v_med3_f32 v51, v50, s68, v235
	v_mov_b32_e32 v50, v1
	v_cvt_pk_fp8_f32 v50, v51, v47
	v_and_b32_e32 v51, 0xffff0000, v71
	v_lshlrev_b32_e32 v47, 16, v71
	v_fmac_f32_e32 v51, 0x3b800000, v53
	v_fmac_f32_e32 v47, 0x3b800000, v52
	v_add_f32_e32 v49, v49, v51
	v_add_f32_e32 v48, v48, v47
	v_mul_f32_e32 v47, v49, v49
	v_fmac_f32_e32 v47, v48, v48
	v_add_f32_e32 v51, v54, v47
	v_cvt_pk_bf16_f32 v47, v48, v49
	s_nop 0
	v_lshlrev_b32_e32 v52, 16, v47
	v_sub_f32_e32 v48, v48, v52
	v_and_b32_e32 v52, 0xffff0000, v47
	v_sub_f32_e32 v49, v49, v52
	v_mul_f32_e32 v48, 0x43800000, v48
	v_mul_f32_e32 v49, 0x43800000, v49
	v_med3_f32 v48, v48, s68, v235
	v_med3_f32 v49, v49, s68, v235
	v_cvt_pk_fp8_f32 v50, v48, v49 op_sel:[0,0,1]
	v_cvt_pk_f32_fp8_e32 v[48:49], v95
	v_lshlrev_b32_e32 v52, 16, v72
	v_fmac_f32_e32 v52, 0x3b800000, v48
	v_and_b32_e32 v48, 0xffff0000, v72
	v_fmac_f32_e32 v48, 0x3b800000, v49
	v_add_f32_e32 v43, v43, v48
	v_add_f32_e32 v42, v42, v52
	v_mul_f32_e32 v48, v43, v43
	v_fmac_f32_e32 v48, v42, v42
	v_add_f32_e32 v49, v51, v48
	v_cvt_pk_bf16_f32 v48, v42, v43
	v_lshlrev_b32_e32 v52, 16, v73
	v_and_b32_e32 v51, 0xffff0000, v48
	v_sub_f32_e32 v43, v43, v51
	v_lshlrev_b32_e32 v51, 16, v48
	v_sub_f32_e32 v42, v42, v51
	v_mul_f32_e32 v43, 0x43800000, v43
	v_mul_f32_e32 v42, 0x43800000, v42
	v_med3_f32 v43, v43, s68, v235
	v_med3_f32 v42, v42, s68, v235
	v_mov_b32_e32 v51, v1
	v_cvt_pk_fp8_f32 v51, v42, v43
	v_cvt_pk_f32_fp8_sdwa v[42:43], v95 src0_sel:WORD_1
	v_fmac_f32_e32 v52, 0x3b800000, v42
	v_and_b32_e32 v42, 0xffff0000, v73
	v_fmac_f32_e32 v42, 0x3b800000, v43
	v_add_f32_e32 v42, v45, v42
	v_add_f32_e32 v43, v44, v52
	v_mul_f32_e32 v44, v42, v42
	v_fmac_f32_e32 v44, v43, v43
	v_add_f32_e32 v44, v49, v44
	v_cvt_pk_bf16_f32 v49, v43, v42
	s_nop 0
	v_lshlrev_b32_e32 v45, 16, v49
	v_sub_f32_e32 v43, v43, v45
	v_and_b32_e32 v45, 0xffff0000, v49
	v_sub_f32_e32 v42, v42, v45
	v_mul_f32_e32 v43, 0x43800000, v43
	v_mul_f32_e32 v42, 0x43800000, v42
	v_med3_f32 v43, v43, s68, v235
	v_med3_f32 v42, v42, s68, v235
	v_cvt_pk_fp8_f32 v51, v43, v42 op_sel:[0,0,1]
	s_waitcnt vmcnt(4)
	v_cvt_pk_f32_fp8_e32 v[42:43], v88
	v_lshlrev_b32_e32 v45, 16, v66
	global_store_dwordx4 v[90:91], v[46:49], off sc1
	global_store_dwordx2 v[92:93], v[50:51], off
	v_fmac_f32_e32 v45, 0x3b800000, v42
	v_and_b32_e32 v42, 0xffff0000, v66
	v_fmac_f32_e32 v42, 0x3b800000, v43
	v_add_f32_e32 v39, v39, v42
	v_add_f32_e32 v43, v38, v45
	v_mul_f32_e32 v38, v39, v39
	v_fmac_f32_e32 v38, v43, v43
	v_add_f32_e32 v46, v44, v38
	v_cvt_pk_bf16_f32 v38, v43, v39
	v_cvt_pk_f32_fp8_sdwa v[44:45], v88 src0_sel:WORD_1
	v_and_b32_e32 v42, 0xffff0000, v38
	v_sub_f32_e32 v39, v39, v42
	v_lshlrev_b32_e32 v42, 16, v38
	v_sub_f32_e32 v42, v43, v42
	v_mul_f32_e32 v39, 0x43800000, v39
	v_mul_f32_e32 v42, 0x43800000, v42
	v_med3_f32 v39, v39, s68, v235
	v_med3_f32 v43, v42, s68, v235
	v_mov_b32_e32 v42, v1
	v_cvt_pk_fp8_f32 v42, v43, v39
	v_and_b32_e32 v43, 0xffff0000, v67
	v_lshlrev_b32_e32 v39, 16, v67
	v_fmac_f32_e32 v43, 0x3b800000, v45
	v_fmac_f32_e32 v39, 0x3b800000, v44
	v_add_f32_e32 v41, v41, v43
	v_add_f32_e32 v40, v40, v39
	v_mul_f32_e32 v39, v41, v41
	v_fmac_f32_e32 v39, v40, v40
	v_add_f32_e32 v43, v46, v39
	v_cvt_pk_bf16_f32 v39, v40, v41
	s_nop 0
	v_lshlrev_b32_e32 v44, 16, v39
	v_sub_f32_e32 v40, v40, v44
	v_and_b32_e32 v44, 0xffff0000, v39
	v_sub_f32_e32 v41, v41, v44
	v_mul_f32_e32 v40, 0x43800000, v40
	v_mul_f32_e32 v41, 0x43800000, v41
	v_med3_f32 v40, v40, s68, v235
	v_med3_f32 v41, v41, s68, v235
	v_cvt_pk_fp8_f32 v42, v40, v41 op_sel:[0,0,1]
	v_cvt_pk_f32_fp8_e32 v[40:41], v89
	v_lshlrev_b32_e32 v44, 16, v68
	v_fmac_f32_e32 v44, 0x3b800000, v40
	v_and_b32_e32 v40, 0xffff0000, v68
	v_fmac_f32_e32 v40, 0x3b800000, v41
	v_add_f32_e32 v35, v35, v40
	v_add_f32_e32 v34, v34, v44
	v_mul_f32_e32 v40, v35, v35
	v_fmac_f32_e32 v40, v34, v34
	v_add_f32_e32 v41, v43, v40
	v_cvt_pk_bf16_f32 v40, v34, v35
	v_lshlrev_b32_e32 v44, 16, v69
	v_and_b32_e32 v43, 0xffff0000, v40
	v_sub_f32_e32 v35, v35, v43
	v_lshlrev_b32_e32 v43, 16, v40
	v_sub_f32_e32 v34, v34, v43
	v_mul_f32_e32 v35, 0x43800000, v35
	v_mul_f32_e32 v34, 0x43800000, v34
	v_med3_f32 v35, v35, s68, v235
	v_med3_f32 v34, v34, s68, v235
	v_mov_b32_e32 v43, v1
	v_cvt_pk_fp8_f32 v43, v34, v35
	v_cvt_pk_f32_fp8_sdwa v[34:35], v89 src0_sel:WORD_1
	v_fmac_f32_e32 v44, 0x3b800000, v34
	v_and_b32_e32 v34, 0xffff0000, v69
	v_fmac_f32_e32 v34, 0x3b800000, v35
	v_add_f32_e32 v34, v37, v34
	v_add_f32_e32 v35, v36, v44
	v_mul_f32_e32 v36, v34, v34
	v_fmac_f32_e32 v36, v35, v35
	v_add_f32_e32 v36, v41, v36
	v_cvt_pk_bf16_f32 v41, v35, v34
	s_nop 0
	v_lshlrev_b32_e32 v37, 16, v41
	v_sub_f32_e32 v35, v35, v37
	v_and_b32_e32 v37, 0xffff0000, v41
	v_sub_f32_e32 v34, v34, v37
	v_mul_f32_e32 v35, 0x43800000, v35
	v_mul_f32_e32 v34, 0x43800000, v34
	v_med3_f32 v35, v35, s68, v235
	v_med3_f32 v34, v34, s68, v235
	v_cvt_pk_fp8_f32 v43, v35, v34 op_sel:[0,0,1]
	ds_bpermute_b32 v34, v142, v36
	global_store_dwordx4 v[84:85], v[38:41], off sc1
	global_store_dwordx2 v[86:87], v[42:43], off
	s_waitcnt lgkmcnt(0)
	v_add_f32_e32 v34, v36, v34
	ds_bpermute_b32 v35, v143, v34
	s_and_saveexec_b64 s[2:3], s[38:39]
	s_cbranch_execz .LBB0_1267
	s_waitcnt lgkmcnt(0)
	v_add_f32_e32 v36, v34, v35
	s_lshl_b32 s20, s8, 2
	v_lshlrev_b64 v[34:35], 7, v[82:83]
	s_ashr_i32 s21, s20, 31
	v_lshl_add_u64 v[34:35], s[44:45], 0, v[34:35]
	v_lshl_add_u64 v[34:35], s[20:21], 2, v[34:35]
	s_lshl_b32 s18, s36, 2
	v_lshl_add_u64 v[34:35], v[34:35], 0, s[18:19]
	global_store_dword v[34:35], v36, off
;     __device__ __forceinline__ void core(const f32x4 (&acc)[2][2][4][2], const Unit& u, int wr, int wc, int fr, int fq, const float (&rsc)[2][4]) const {
;     ...
;             for (int m = 0; m < MB; ++m)
; #pragma unroll
;                 for (int bj = 0; bj < 2; ++bj) { const size_t idx = (size_t)(row0 + ai * HALF + (mh + m) * 16) * D + col0 + bj * HALF;
;                     if (F32IN) { xa[m][bj] = *(const f32x4*)(Xin + idx); xb[m][bj] = *(const f32x4*)(Xin + idx + 4); }
;                     else { va[m][bj] = *(const u32x4*)(Hb + idx); vb[m][bj] = *(const u32x2*)(Hl + idx); } }
; #pragma unroll
;             for (int m = 0; m < MB; ++m) { const int row = row0 + ai * HALF + (mh + m) * 16; float sq = 0.f;
;                 const float rs1 = rsc[ai][mh + m];
; #pragma unroll
;                 for (int bj = 0; bj < 2; ++bj) { const size_t idx = (size_t)row * D + col0 + bj * HALF;
;                     unsigned hw[4]; int lw[2] = {0, 0};
; #pragma unroll
;                     for (int pq = 0; pq < 4; ++pq) {
;                         float h0, h1;
;                         if (F32IN) { h0 = (pq < 2) ? xa[m][bj][2 * pq] : xb[m][bj][2 * pq - 4]; h1 = (pq < 2) ? xa[m][bj][2 * pq + 1] : xb[m][bj][2 * pq - 3]; }
;                         else { const unsigned a = va[m][bj][pq]; const int bw = (int)vb[m][bj][pq >> 1]; const hf32x2 lp = (pq & 1) ? __builtin_amdgcn_cvt_pk_f32_fp8(bw, true) : __builtin_amdgcn_cvt_pk_f32_fp8(bw, false);
;                             h0 = __uint_as_float(a << 16) + lp.x * 0.00390625f; h1 = __uint_as_float(a & 0xffff0000u) + lp.y * 0.00390625f; }
;                         const float o0 = h0 + acc[ai][bj][mh + m][pq >> 1][(2 * pq) & 3] * rs1, o1 = h1 + acc[ai][bj][mh + m][pq >> 1][(2 * pq + 1) & 3] * rs1;
;                         sq += o0 * o0 + o1 * o1;
;                         const unsigned hi = cvt_pk_bf16(o0, o1);
;                         hw[pq] = hi;
;                         const float r0 = __builtin_amdgcn_fmed3f((o0 - __uint_as_float(hi << 16)) * 256.0f, -448.0f, 448.0f), r1 = __builtin_amdgcn_fmed3f((o1 - __uint_as_float(hi & 0xffff0000u)) * 256.0f, -448.0f, 448.0f);
;                         lw[pq >> 1] = (pq & 1) ? __builtin_amdgcn_cvt_pk_fp8_f32(r0, r1, lw[pq >> 1], true) : __builtin_amdgcn_cvt_pk_fp8_f32(r0, r1, lw[pq >> 1], false);
;                     }
.LBB0_1267:
	s_or_b64 exec, exec, s[2:3]
	v_add_u32_e32 v64, 0xa0, v156
	v_ashrrev_i32_e32 v65, 31, v64
	s_waitcnt lgkmcnt(0)
	v_lshlrev_b64 v[34:35], 11, v[64:65]
	v_lshl_add_u64 v[34:35], v[34:35], 0, v[158:159]
	v_lshl_add_u64 v[72:73], v[34:35], 1, s[34:35]
	v_lshl_add_u64 v[74:75], s[42:43], 0, v[34:35]
	global_load_dwordx4 v[46:49], v[72:73], off
	global_load_dwordx2 v[76:77], v[74:75], off
	v_or_b32_e32 v34, 0x80, v34
	v_lshl_add_u64 v[66:67], v[34:35], 1, s[34:35]
	v_lshl_add_u64 v[68:69], s[42:43], 0, v[34:35]
	global_load_dwordx4 v[42:45], v[66:67], off
	global_load_dwordx2 v[70:71], v[68:69], off
	v_add_u32_e32 v50, 0xb0, v156
	v_ashrrev_i32_e32 v51, 31, v50
	v_lshlrev_b64 v[34:35], 11, v[50:51]
	v_lshl_add_u64 v[54:55], v[34:35], 0, v[158:159]
	v_lshl_add_u64 v[58:59], v[54:55], 1, s[34:35]
	v_lshl_add_u64 v[60:61], s[42:43], 0, v[54:55]
	v_or_b32_e32 v54, 0x80, v54
	v_lshl_add_u64 v[52:53], v[54:55], 1, s[34:35]
	v_lshl_add_u64 v[54:55], s[42:43], 0, v[54:55]
	global_load_dwordx4 v[38:41], v[58:59], off
	global_load_dwordx2 v[62:63], v[60:61], off
	global_load_dwordx4 v[34:37], v[52:53], off
	global_load_dwordx2 v[56:57], v[54:55], off
	s_waitcnt vmcnt(7)
	v_lshlrev_b32_e32 v80, 16, v46
	s_waitcnt vmcnt(6)
	v_cvt_pk_f32_fp8_e32 v[78:79], v76
	v_and_b32_e32 v46, 0xffff0000, v46
	v_fmac_f32_e32 v80, 0x3b800000, v78
	v_fmac_f32_e32 v46, 0x3b800000, v79
	v_add_f32_e32 v78, v30, v80
	v_add_f32_e32 v31, v31, v46
	v_cvt_pk_bf16_f32 v30, v78, v31
	v_mul_f32_e32 v80, v31, v31
	v_and_b32_e32 v46, 0xffff0000, v30
	v_sub_f32_e32 v31, v31, v46
	v_lshlrev_b32_e32 v46, 16, v30
	v_sub_f32_e32 v46, v78, v46
	v_mul_f32_e32 v31, 0x43800000, v31
	v_mul_f32_e32 v46, 0x43800000, v46
	v_fmac_f32_e32 v80, v78, v78
	v_med3_f32 v31, v31, s68, v235
	v_med3_f32 v78, v46, s68, v235
	v_mov_b32_e32 v46, v1
	v_cvt_pk_fp8_f32 v46, v78, v31
	v_cvt_pk_f32_fp8_sdwa v[78:79], v76 src0_sel:WORD_1
	v_lshlrev_b32_e32 v31, 16, v47
	v_and_b32_e32 v47, 0xffff0000, v47
	v_fmac_f32_e32 v47, 0x3b800000, v79
	v_fmac_f32_e32 v31, 0x3b800000, v78
	v_add_f32_e32 v33, v33, v47
	v_add_f32_e32 v32, v32, v31
	v_mul_f32_e32 v31, v33, v33
	v_fmac_f32_e32 v31, v32, v32
	v_add_f32_e32 v47, v80, v31
	v_cvt_pk_bf16_f32 v31, v32, v33
	s_nop 0
	v_lshlrev_b32_e32 v76, 16, v31
	v_sub_f32_e32 v32, v32, v76
	v_and_b32_e32 v76, 0xffff0000, v31
	v_sub_f32_e32 v33, v33, v76
	v_mul_f32_e32 v32, 0x43800000, v32
	v_mul_f32_e32 v33, 0x43800000, v33
	v_med3_f32 v32, v32, s68, v235
	v_med3_f32 v33, v33, s68, v235
	v_cvt_pk_fp8_f32 v46, v32, v33 op_sel:[0,0,1]
	v_cvt_pk_f32_fp8_e32 v[32:33], v77
	v_lshlrev_b32_e32 v76, 16, v48
	v_fmac_f32_e32 v76, 0x3b800000, v32
	v_and_b32_e32 v32, 0xffff0000, v48
	v_fmac_f32_e32 v32, 0x3b800000, v33
	v_add_f32_e32 v27, v27, v32
	v_add_f32_e32 v26, v26, v76
	v_mul_f32_e32 v32, v27, v27
	v_fmac_f32_e32 v32, v26, v26
	v_add_f32_e32 v33, v47, v32
	v_cvt_pk_bf16_f32 v32, v26, v27
	v_lshlrev_b32_e32 v48, 16, v49
	v_and_b32_e32 v47, 0xffff0000, v32
	v_sub_f32_e32 v27, v27, v47
	v_lshlrev_b32_e32 v47, 16, v32
	v_sub_f32_e32 v26, v26, v47
	v_mul_f32_e32 v27, 0x43800000, v27
	v_mul_f32_e32 v26, 0x43800000, v26
	v_med3_f32 v27, v27, s68, v235
	v_med3_f32 v26, v26, s68, v235
	v_mov_b32_e32 v47, v1
	v_cvt_pk_fp8_f32 v47, v26, v27
	v_cvt_pk_f32_fp8_sdwa v[26:27], v77 src0_sel:WORD_1
	v_fmac_f32_e32 v48, 0x3b800000, v26
	v_and_b32_e32 v26, 0xffff0000, v49
	v_fmac_f32_e32 v26, 0x3b800000, v27
	v_add_f32_e32 v26, v29, v26
	v_add_f32_e32 v27, v28, v48
	v_mul_f32_e32 v28, v26, v26
	v_fmac_f32_e32 v28, v27, v27
	v_add_f32_e32 v28, v33, v28
	v_cvt_pk_bf16_f32 v33, v27, v26
	s_nop 0
	v_lshlrev_b32_e32 v29, 16, v33
	v_sub_f32_e32 v27, v27, v29
	v_and_b32_e32 v29, 0xffff0000, v33
	v_sub_f32_e32 v26, v26, v29
	v_mul_f32_e32 v27, 0x43800000, v27
	v_mul_f32_e32 v26, 0x43800000, v26
	v_med3_f32 v27, v27, s68, v235
	v_med3_f32 v26, v26, s68, v235
	v_cvt_pk_fp8_f32 v47, v27, v26 op_sel:[0,0,1]
	s_waitcnt vmcnt(4)
	v_cvt_pk_f32_fp8_e32 v[26:27], v70
	v_lshlrev_b32_e32 v29, 16, v42
	global_store_dwordx4 v[72:73], v[30:33], off sc1
	global_store_dwordx2 v[74:75], v[46:47], off
	v_fmac_f32_e32 v29, 0x3b800000, v26
	v_and_b32_e32 v26, 0xffff0000, v42
	v_fmac_f32_e32 v26, 0x3b800000, v27
	v_add_f32_e32 v23, v23, v26
	v_add_f32_e32 v27, v22, v29
	v_mul_f32_e32 v22, v23, v23
	v_fmac_f32_e32 v22, v27, v27
	v_add_f32_e32 v30, v28, v22
	v_cvt_pk_bf16_f32 v22, v27, v23
	v_cvt_pk_f32_fp8_sdwa v[28:29], v70 src0_sel:WORD_1
	v_and_b32_e32 v26, 0xffff0000, v22
	v_sub_f32_e32 v23, v23, v26
	v_lshlrev_b32_e32 v26, 16, v22
	v_sub_f32_e32 v26, v27, v26
	v_mul_f32_e32 v23, 0x43800000, v23
	v_mul_f32_e32 v26, 0x43800000, v26
	v_med3_f32 v23, v23, s68, v235
	v_med3_f32 v27, v26, s68, v235
	v_mov_b32_e32 v26, v1
	v_cvt_pk_fp8_f32 v26, v27, v23
	v_and_b32_e32 v27, 0xffff0000, v43
	v_lshlrev_b32_e32 v23, 16, v43
	v_fmac_f32_e32 v27, 0x3b800000, v29
	v_fmac_f32_e32 v23, 0x3b800000, v28
	v_add_f32_e32 v25, v25, v27
	v_add_f32_e32 v24, v24, v23
	v_mul_f32_e32 v23, v25, v25
	v_fmac_f32_e32 v23, v24, v24
	v_add_f32_e32 v27, v30, v23
	v_cvt_pk_bf16_f32 v23, v24, v25
	s_nop 0
	v_lshlrev_b32_e32 v28, 16, v23
	v_sub_f32_e32 v24, v24, v28
	v_and_b32_e32 v28, 0xffff0000, v23
	v_sub_f32_e32 v25, v25, v28
	v_mul_f32_e32 v24, 0x43800000, v24
	v_mul_f32_e32 v25, 0x43800000, v25
	v_med3_f32 v24, v24, s68, v235
	v_med3_f32 v25, v25, s68, v235
	v_cvt_pk_fp8_f32 v26, v24, v25 op_sel:[0,0,1]
	v_cvt_pk_f32_fp8_e32 v[24:25], v71
	v_lshlrev_b32_e32 v28, 16, v44
	v_fmac_f32_e32 v28, 0x3b800000, v24
	v_and_b32_e32 v24, 0xffff0000, v44
	v_fmac_f32_e32 v24, 0x3b800000, v25
	v_add_f32_e32 v19, v19, v24
	v_add_f32_e32 v18, v18, v28
	v_mul_f32_e32 v24, v19, v19
	v_fmac_f32_e32 v24, v18, v18
	v_add_f32_e32 v25, v27, v24
	v_cvt_pk_bf16_f32 v24, v18, v19
	v_lshlrev_b32_e32 v28, 16, v45
	v_and_b32_e32 v27, 0xffff0000, v24
	v_sub_f32_e32 v19, v19, v27
	v_lshlrev_b32_e32 v27, 16, v24
	v_sub_f32_e32 v18, v18, v27
	v_mul_f32_e32 v19, 0x43800000, v19
	v_mul_f32_e32 v18, 0x43800000, v18
	v_med3_f32 v19, v19, s68, v235
	v_med3_f32 v18, v18, s68, v235
	v_mov_b32_e32 v27, v1
	v_cvt_pk_fp8_f32 v27, v18, v19
	v_cvt_pk_f32_fp8_sdwa v[18:19], v71 src0_sel:WORD_1
	v_fmac_f32_e32 v28, 0x3b800000, v18
	v_and_b32_e32 v18, 0xffff0000, v45
	v_fmac_f32_e32 v18, 0x3b800000, v19
	v_add_f32_e32 v18, v21, v18
	v_add_f32_e32 v19, v20, v28
	v_mul_f32_e32 v20, v18, v18
	v_fmac_f32_e32 v20, v19, v19
	v_add_f32_e32 v20, v25, v20
	v_cvt_pk_bf16_f32 v25, v19, v18
	s_nop 0
	v_lshlrev_b32_e32 v21, 16, v25
	v_sub_f32_e32 v19, v19, v21
	v_and_b32_e32 v21, 0xffff0000, v25
	v_sub_f32_e32 v18, v18, v21
	v_mul_f32_e32 v19, 0x43800000, v19
	v_mul_f32_e32 v18, 0x43800000, v18
	v_med3_f32 v19, v19, s68, v235
	v_med3_f32 v18, v18, s68, v235
	v_cvt_pk_fp8_f32 v27, v19, v18 op_sel:[0,0,1]
	ds_bpermute_b32 v18, v142, v20
	global_store_dwordx4 v[66:67], v[22:25], off sc1
	global_store_dwordx2 v[68:69], v[26:27], off
	s_waitcnt lgkmcnt(0)
	v_add_f32_e32 v18, v20, v18
	ds_bpermute_b32 v19, v143, v18
	s_and_saveexec_b64 s[2:3], s[38:39]
	s_cbranch_execz .LBB0_1269
; __device__ __forceinline__ unsigned cvt_pk_bf16(float lo, float hi) { unsigned r; asm volatile("v_cvt_pk_bf16_f32 %0, %1, %2" : "=v"(r) : "v"(lo), "v"(hi)); return r; }
;     __device__ __forceinline__ void core(const f32x4 (&acc)[2][2][4][2], const Unit& u, int wr, int wc, int fr, int fq, const float (&rsc)[2][4]) const {
;     ...
;             for (int m = 0; m < MB; ++m) { const int row = row0 + ai * HALF + (mh + m) * 16; float sq = 0.f;
;                 const float rs1 = rsc[ai][mh + m];
; #pragma unroll
;                 for (int bj = 0; bj < 2; ++bj) { const size_t idx = (size_t)row * D + col0 + bj * HALF;
;                     unsigned hw[4]; int lw[2] = {0, 0};
; #pragma unroll
;                     for (int pq = 0; pq < 4; ++pq) {
;                         float h0, h1;
;                         if (F32IN) { h0 = (pq < 2) ? xa[m][bj][2 * pq] : xb[m][bj][2 * pq - 4]; h1 = (pq < 2) ? xa[m][bj][2 * pq + 1] : xb[m][bj][2 * pq - 3]; }
;                         else { const unsigned a = va[m][bj][pq]; const int bw = (int)vb[m][bj][pq >> 1]; const hf32x2 lp = (pq & 1) ? __builtin_amdgcn_cvt_pk_f32_fp8(bw, true) : __builtin_amdgcn_cvt_pk_f32_fp8(bw, false);
;                             h0 = __uint_as_float(a << 16) + lp.x * 0.00390625f; h1 = __uint_as_float(a & 0xffff0000u) + lp.y * 0.00390625f; }
;                         const float o0 = h0 + acc[ai][bj][mh + m][pq >> 1][(2 * pq) & 3] * rs1, o1 = h1 + acc[ai][bj][mh + m][pq >> 1][(2 * pq + 1) & 3] * rs1;
;                         sq += o0 * o0 + o1 * o1;
;                         const unsigned hi = cvt_pk_bf16(o0, o1);
;                         hw[pq] = hi;
;                         const float r0 = __builtin_amdgcn_fmed3f((o0 - __uint_as_float(hi << 16)) * 256.0f, -448.0f, 448.0f), r1 = __builtin_amdgcn_fmed3f((o1 - __uint_as_float(hi & 0xffff0000u)) * 256.0f, -448.0f, 448.0f);
;                         lw[pq >> 1] = (pq & 1) ? __builtin_amdgcn_cvt_pk_fp8_f32(r0, r1, lw[pq >> 1], true) : __builtin_amdgcn_cvt_pk_fp8_f32(r0, r1, lw[pq >> 1], false);
;                     }
;                     *(u32x4*)(Hb + idx) = (u32x4){hw[0], hw[1], hw[2], hw[3]}; *(u32x2*)(Hl + idx) = (u32x2){(unsigned)lw[0], (unsigned)lw[1]}; }
;                 sq += __shfl_xor(sq, 16); sq += __shfl_xor(sq, 32); if (fq == 0) ss[(size_t)row * 32 + u.pn * 4 + wc] = sq; }
	s_waitcnt lgkmcnt(0)
	v_add_f32_e32 v20, v18, v19
	s_lshl_b32 s20, s8, 2
	v_lshlrev_b64 v[18:19], 7, v[64:65]
	s_ashr_i32 s21, s20, 31
	v_lshl_add_u64 v[18:19], s[44:45], 0, v[18:19]
	v_lshl_add_u64 v[18:19], s[20:21], 2, v[18:19]
	s_lshl_b32 s18, s36, 2
	v_lshl_add_u64 v[18:19], v[18:19], 0, s[18:19]
	global_store_dword v[18:19], v20, off
.LBB0_1269:
	s_or_b64 exec, exec, s[2:3]
	s_waitcnt vmcnt(6) lgkmcnt(0)
	v_cvt_pk_f32_fp8_e32 v[18:19], v62
	v_lshlrev_b32_e32 v20, 16, v38
	v_fmac_f32_e32 v20, 0x3b800000, v18
	v_and_b32_e32 v18, 0xffff0000, v38
	v_fmac_f32_e32 v18, 0x3b800000, v19
	v_add_f32_e32 v19, v14, v20
	v_add_f32_e32 v15, v15, v18
	v_cvt_pk_bf16_f32 v14, v19, v15
	v_mul_f32_e32 v22, v15, v15
	v_and_b32_e32 v18, 0xffff0000, v14
	v_sub_f32_e32 v15, v15, v18
	v_lshlrev_b32_e32 v18, 16, v14
	v_sub_f32_e32 v18, v19, v18
	v_cvt_pk_f32_fp8_sdwa v[20:21], v62 src0_sel:WORD_1
	v_mul_f32_e32 v15, 0x43800000, v15
	v_mul_f32_e32 v18, 0x43800000, v18
	v_fmac_f32_e32 v22, v19, v19
	v_med3_f32 v15, v15, s68, v235
	v_med3_f32 v19, v18, s68, v235
	v_mov_b32_e32 v18, v1
	v_cvt_pk_fp8_f32 v18, v19, v15
	v_and_b32_e32 v19, 0xffff0000, v39
	v_lshlrev_b32_e32 v15, 16, v39
	v_fmac_f32_e32 v19, 0x3b800000, v21
	v_fmac_f32_e32 v15, 0x3b800000, v20
	v_add_f32_e32 v17, v17, v19
	v_add_f32_e32 v16, v16, v15
	v_mul_f32_e32 v15, v17, v17
	v_fmac_f32_e32 v15, v16, v16
	v_add_f32_e32 v19, v22, v15
	v_cvt_pk_bf16_f32 v15, v16, v17
	s_nop 0
	v_lshlrev_b32_e32 v20, 16, v15
	v_sub_f32_e32 v16, v16, v20
	v_and_b32_e32 v20, 0xffff0000, v15
	v_sub_f32_e32 v17, v17, v20
	v_mul_f32_e32 v16, 0x43800000, v16
	v_mul_f32_e32 v17, 0x43800000, v17
	v_med3_f32 v16, v16, s68, v235
	v_med3_f32 v17, v17, s68, v235
	v_cvt_pk_fp8_f32 v18, v16, v17 op_sel:[0,0,1]
	v_cvt_pk_f32_fp8_e32 v[16:17], v63
	v_lshlrev_b32_e32 v20, 16, v40
	v_fmac_f32_e32 v20, 0x3b800000, v16
	v_and_b32_e32 v16, 0xffff0000, v40
	v_fmac_f32_e32 v16, 0x3b800000, v17
	v_add_f32_e32 v11, v11, v16
	v_add_f32_e32 v10, v10, v20
	v_mul_f32_e32 v16, v11, v11
	v_fmac_f32_e32 v16, v10, v10
	v_add_f32_e32 v17, v19, v16
	v_cvt_pk_bf16_f32 v16, v10, v11
	v_lshlrev_b32_e32 v20, 16, v41
	v_and_b32_e32 v19, 0xffff0000, v16
	v_sub_f32_e32 v11, v11, v19
	v_lshlrev_b32_e32 v19, 16, v16
	v_sub_f32_e32 v10, v10, v19
	v_mul_f32_e32 v11, 0x43800000, v11
	v_mul_f32_e32 v10, 0x43800000, v10
	v_med3_f32 v11, v11, s68, v235
	v_med3_f32 v10, v10, s68, v235
	v_mov_b32_e32 v19, v1
	v_cvt_pk_fp8_f32 v19, v10, v11
	v_cvt_pk_f32_fp8_sdwa v[10:11], v63 src0_sel:WORD_1
	v_fmac_f32_e32 v20, 0x3b800000, v10
	v_and_b32_e32 v10, 0xffff0000, v41
	v_fmac_f32_e32 v10, 0x3b800000, v11
	v_add_f32_e32 v10, v13, v10
	v_add_f32_e32 v11, v12, v20
	v_mul_f32_e32 v12, v10, v10
	v_fmac_f32_e32 v12, v11, v11
	v_add_f32_e32 v12, v17, v12
	v_cvt_pk_bf16_f32 v17, v11, v10
	s_nop 0
	v_lshlrev_b32_e32 v13, 16, v17
	v_sub_f32_e32 v11, v11, v13
	v_and_b32_e32 v13, 0xffff0000, v17
	v_sub_f32_e32 v10, v10, v13
	v_mul_f32_e32 v11, 0x43800000, v11
	v_mul_f32_e32 v10, 0x43800000, v10
	v_med3_f32 v11, v11, s68, v235
	v_med3_f32 v10, v10, s68, v235
	v_cvt_pk_fp8_f32 v19, v11, v10 op_sel:[0,0,1]
	s_waitcnt vmcnt(4)
	v_cvt_pk_f32_fp8_e32 v[10:11], v56
	v_lshlrev_b32_e32 v13, 16, v34
	global_store_dwordx4 v[58:59], v[14:17], off sc1
	global_store_dwordx2 v[60:61], v[18:19], off
	v_fmac_f32_e32 v13, 0x3b800000, v10
	v_and_b32_e32 v10, 0xffff0000, v34
	v_fmac_f32_e32 v10, 0x3b800000, v11
	v_add_f32_e32 v7, v7, v10
	v_add_f32_e32 v11, v6, v13
	v_mul_f32_e32 v6, v7, v7
	v_fmac_f32_e32 v6, v11, v11
	v_add_f32_e32 v14, v12, v6
	v_cvt_pk_bf16_f32 v6, v11, v7
	v_cvt_pk_f32_fp8_sdwa v[12:13], v56 src0_sel:WORD_1
	v_and_b32_e32 v10, 0xffff0000, v6
	v_sub_f32_e32 v7, v7, v10
	v_lshlrev_b32_e32 v10, 16, v6
	v_sub_f32_e32 v10, v11, v10
	v_mul_f32_e32 v7, 0x43800000, v7
	v_mul_f32_e32 v10, 0x43800000, v10
	v_med3_f32 v7, v7, s68, v235
	v_med3_f32 v11, v10, s68, v235
	v_mov_b32_e32 v10, v1
	v_cvt_pk_fp8_f32 v10, v11, v7
	v_and_b32_e32 v11, 0xffff0000, v35
	v_lshlrev_b32_e32 v7, 16, v35
	v_fmac_f32_e32 v11, 0x3b800000, v13
	v_fmac_f32_e32 v7, 0x3b800000, v12
	v_add_f32_e32 v9, v9, v11
	v_add_f32_e32 v8, v8, v7
	v_mul_f32_e32 v7, v9, v9
	v_fmac_f32_e32 v7, v8, v8
	v_add_f32_e32 v11, v14, v7
	v_cvt_pk_bf16_f32 v7, v8, v9
	s_nop 0
	v_lshlrev_b32_e32 v12, 16, v7
	v_sub_f32_e32 v8, v8, v12
	v_and_b32_e32 v12, 0xffff0000, v7
	v_sub_f32_e32 v9, v9, v12
	v_mul_f32_e32 v8, 0x43800000, v8
	v_mul_f32_e32 v9, 0x43800000, v9
	v_med3_f32 v8, v8, s68, v235
	v_med3_f32 v9, v9, s68, v235
	v_cvt_pk_fp8_f32 v10, v8, v9 op_sel:[0,0,1]
	v_cvt_pk_f32_fp8_e32 v[8:9], v57
	v_lshlrev_b32_e32 v12, 16, v36
	v_fmac_f32_e32 v12, 0x3b800000, v8
	v_and_b32_e32 v8, 0xffff0000, v36
	v_fmac_f32_e32 v8, 0x3b800000, v9
	v_add_f32_e32 v3, v3, v8
	v_add_f32_e32 v2, v2, v12
	v_mul_f32_e32 v8, v3, v3
	v_fmac_f32_e32 v8, v2, v2
	v_add_f32_e32 v9, v11, v8
	v_cvt_pk_bf16_f32 v8, v2, v3
	v_lshlrev_b32_e32 v12, 16, v37
	v_and_b32_e32 v11, 0xffff0000, v8
	v_sub_f32_e32 v3, v3, v11
	v_lshlrev_b32_e32 v11, 16, v8
	v_sub_f32_e32 v2, v2, v11
	v_mul_f32_e32 v3, 0x43800000, v3
	v_mul_f32_e32 v2, 0x43800000, v2
	v_med3_f32 v3, v3, s68, v235
	v_med3_f32 v2, v2, s68, v235
	v_mov_b32_e32 v11, v1
	v_cvt_pk_fp8_f32 v11, v2, v3
	v_cvt_pk_f32_fp8_sdwa v[2:3], v57 src0_sel:WORD_1
	v_fmac_f32_e32 v12, 0x3b800000, v2
	v_and_b32_e32 v2, 0xffff0000, v37
	v_fmac_f32_e32 v2, 0x3b800000, v3
	v_add_f32_e32 v2, v5, v2
	v_add_f32_e32 v3, v4, v12
	v_mul_f32_e32 v4, v2, v2
	v_fmac_f32_e32 v4, v3, v3
	v_add_f32_e32 v4, v9, v4
	v_cvt_pk_bf16_f32 v9, v3, v2
	s_nop 0
	v_lshlrev_b32_e32 v5, 16, v9
	v_sub_f32_e32 v3, v3, v5
	v_and_b32_e32 v5, 0xffff0000, v9
	v_sub_f32_e32 v2, v2, v5
	v_mul_f32_e32 v3, 0x43800000, v3
	v_mul_f32_e32 v2, 0x43800000, v2
	v_med3_f32 v3, v3, s68, v235
	v_med3_f32 v2, v2, s68, v235
	v_cvt_pk_fp8_f32 v11, v3, v2 op_sel:[0,0,1]
	ds_bpermute_b32 v2, v142, v4
	global_store_dwordx4 v[52:53], v[6:9], off sc1
	global_store_dwordx2 v[54:55], v[10:11], off
	s_waitcnt lgkmcnt(0)
	v_add_f32_e32 v2, v4, v2
	ds_bpermute_b32 v3, v143, v2
	s_and_saveexec_b64 s[2:3], s[38:39]
	s_cbranch_execz .LBB0_1271
	s_waitcnt lgkmcnt(0)
	v_add_f32_e32 v4, v2, v3
	s_lshl_b32 s20, s8, 2
	v_lshlrev_b64 v[2:3], 7, v[50:51]
	s_ashr_i32 s21, s20, 31
	v_lshl_add_u64 v[2:3], s[44:45], 0, v[2:3]
	v_lshl_add_u64 v[2:3], s[20:21], 2, v[2:3]
	s_lshl_b32 s18, s36, 2
	v_lshl_add_u64 v[2:3], v[2:3], 0, s[18:19]
	global_store_dword v[2:3], v4, off

;     __device__ __forceinline__ void operator()(const f32x4 (&acc)[2][2][4][2], const Unit& u, int wr, int wc, int fr, int fq) const {
;     ...
;         if (ssin) {
; #pragma unroll
;             for (int ai = 0; ai < 2; ++ai) {
;                 f32x4 q0[4], q1[4];
; #pragma unroll
;                 for (int m = 0; m < 4; ++m) { const float* sp = ssin + (size_t)(row0 + ai * HALF + m * 16) * 32 + fq * 8; q0[m] = *(const f32x4*)sp; q1[m] = *(const f32x4*)(sp + 4); }
; #pragma unroll
;                 for (int m = 0; m < 4; ++m) { float t = ((q0[m][0] + q0[m][1]) + (q0[m][2] + q0[m][3])) + ((q1[m][0] + q1[m][1]) + (q1[m][2] + q1[m][3]));
;                     t += __shfl_xor(t, 16); t += __shfl_xor(t, 32); rsc[ai][m] = 1.0f / (t * (1.0f / D) + EPS); }
;                 asm volatile("" ::: "memory");
;             }
.LBB0_1425:
	v_and_b32_e32 v131, 64, v226
	v_xor_b32_e32 v130, 16, v226
	v_add_u32_e32 v131, 64, v131
	v_cmp_lt_i32_e32 vcc, v130, v131
	v_lshl_add_u32 v132, s12, 8, v183
	v_ashrrev_i32_e32 v133, 31, v132
	v_cndmask_b32_e32 v130, v226, v130, vcc
	v_lshlrev_b32_e32 v240, 2, v130
	v_xor_b32_e32 v130, 32, v226
	v_cmp_lt_i32_e32 vcc, v130, v131
	v_lshlrev_b64 v[196:197], 7, v[132:133]
	v_or_b32_e32 v192, 32, v132
	v_cndmask_b32_e32 v130, v226, v130, vcc
	v_lshlrev_b32_e32 v239, 2, v130
	v_lshl_add_u64 v[130:131], v[152:153], 0, v[196:197]
	global_load_dwordx4 v[134:137], v[130:131], off
	global_load_dwordx4 v[138:141], v[130:131], off offset:16
	v_or_b32_e32 v130, 16, v132
	v_ashrrev_i32_e32 v131, 31, v130
	v_lshlrev_b64 v[194:195], 7, v[130:131]
	v_lshl_add_u64 v[158:159], v[152:153], 0, v[194:195]
	global_load_dwordx4 v[142:145], v[158:159], off offset:16
	s_nop 0
	global_load_dwordx4 v[158:161], v[158:159], off
	v_ashrrev_i32_e32 v193, 31, v192
	v_lshlrev_b64 v[188:189], 7, v[192:193]
	v_lshl_add_u64 v[166:167], v[152:153], 0, v[188:189]
	global_load_dwordx4 v[162:165], v[166:167], off offset:16
	s_nop 0
	global_load_dwordx4 v[166:169], v[166:167], off
	v_or_b32_e32 v190, 48, v132
	v_ashrrev_i32_e32 v191, 31, v190
	v_lshlrev_b64 v[176:177], 7, v[190:191]
	v_lshl_add_u64 v[174:175], v[152:153], 0, v[176:177]
	global_load_dwordx4 v[170:173], v[174:175], off offset:16
	global_load_dwordx4 v[184:187], v[174:175], off
	v_lshlrev_b64 v[130:131], 11, v[130:131]
	s_waitcnt vmcnt(0)
	v_mov_b32_e32 v174, v134
	v_mov_b32_e32 v175, v138
	v_mov_b32_e32 v138, v135
	v_pk_add_f32 v[134:135], v[174:175], v[138:139]
	v_mov_b32_e32 v138, v136
	v_mov_b32_e32 v139, v140
	v_mov_b32_e32 v140, v137
	v_pk_add_f32 v[136:137], v[138:139], v[140:141]
	v_add_u32_e32 v174, 0x80, v132
	v_pk_add_f32 v[134:135], v[134:135], v[136:137]
	v_ashrrev_i32_e32 v175, 31, v174
	v_add_f32_e32 v134, v134, v135
	ds_bpermute_b32 v135, v240, v134
	s_waitcnt lgkmcnt(0)
	v_add_f32_e32 v134, v134, v135
	ds_bpermute_b32 v135, v239, v134
	s_waitcnt lgkmcnt(0)
	v_add_f32_e32 v134, v134, v135
	v_fmamk_f32 v134, v134, 0x3a000000, v223
	v_div_scale_f32 v135, s[2:3], v134, v134, 1.0
	v_rcp_f32_e32 v136, v135
	s_nop 0
	v_fma_f32 v137, -v135, v136, 1.0
	v_fmac_f32_e32 v136, v137, v136
	v_div_scale_f32 v137, vcc, 1.0, v134, 1.0
	v_mul_f32_e32 v138, v137, v136
	v_fma_f32 v139, -v135, v138, v137
	v_fmac_f32_e32 v138, v139, v136
	v_fma_f32 v135, -v135, v138, v137
	v_div_fmas_f32 v135, v135, v136, v138
	v_div_fixup_f32 v178, v135, v134, 1.0
	v_add_f32_e32 v134, v158, v159
	v_add_f32_e32 v135, v160, v161
	v_add_f32_e32 v134, v134, v135
	v_add_f32_e32 v135, v142, v143
	v_add_f32_e32 v136, v144, v145
	v_add_f32_e32 v135, v135, v136
	v_add_f32_e32 v134, v134, v135
	ds_bpermute_b32 v135, v240, v134
	v_add_f32_e32 v136, v164, v165
	v_add_u32_e32 v164, 0xa0, v132
	v_ashrrev_i32_e32 v165, 31, v164
	v_lshlrev_b64 v[160:161], 7, v[164:165]
	s_waitcnt lgkmcnt(0)
	v_add_f32_e32 v253, v134, v135
	v_add_f32_e32 v134, v166, v167
	v_add_f32_e32 v135, v168, v169
	v_add_f32_e32 v134, v134, v135
	v_add_f32_e32 v135, v162, v163
	v_add_f32_e32 v135, v135, v136
	v_add_f32_e32 v134, v134, v135
	ds_bpermute_b32 v135, v240, v134
	v_add_f32_e32 v136, v172, v173
	v_lshlrev_b64 v[168:169], 7, v[174:175]
	v_lshl_add_u64 v[138:139], v[152:153], 0, v[168:169]
	v_add_u32_e32 v172, 0x90, v132
	s_waitcnt lgkmcnt(0)
	v_add_f32_e32 v251, v134, v135
	v_add_f32_e32 v134, v184, v185
	v_add_f32_e32 v135, v186, v187
	v_add_f32_e32 v134, v134, v135
	v_add_f32_e32 v135, v170, v171
	v_add_f32_e32 v135, v135, v136
	v_add_f32_e32 v134, v134, v135
	ds_bpermute_b32 v135, v240, v134
	v_ashrrev_i32_e32 v173, 31, v172
	v_lshlrev_b64 v[166:167], 7, v[172:173]
	v_lshl_add_u64 v[158:159], v[152:153], 0, v[166:167]
	v_add_u32_e32 v162, 0xb0, v132
	s_waitcnt lgkmcnt(0)
	v_add_f32_e32 v249, v134, v135
	global_load_dwordx4 v[134:137], v[138:139], off offset:16
	s_nop 0
	global_load_dwordx4 v[138:141], v[138:139], off
	s_nop 0
	global_load_dwordx4 v[142:145], v[158:159], off offset:16
	global_load_dwordx4 v[184:187], v[158:159], off
	v_lshl_add_u64 v[158:159], v[152:153], 0, v[160:161]
	global_load_dwordx4 v[198:201], v[158:159], off offset:16
	global_load_dwordx4 v[202:205], v[158:159], off
	v_ashrrev_i32_e32 v163, 31, v162
	v_lshlrev_b64 v[158:159], 7, v[162:163]
	v_lshl_add_u64 v[170:171], v[152:153], 0, v[158:159]
	global_load_dwordx4 v[206:209], v[170:171], off offset:16
	global_load_dwordx4 v[210:213], v[170:171], off
	v_lshl_or_b32 v170, s8, 8, v237
	v_ashrrev_i32_e32 v171, 31, v170
	v_lshlrev_b64 v[132:133], 11, v[132:133]
	v_lshl_add_u64 v[132:133], v[132:133], 0, v[170:171]
	v_lshl_add_u64 v[180:181], v[130:131], 0, v[170:171]
	ds_bpermute_b32 v225, v239, v253
	ds_bpermute_b32 v252, v239, v251
	ds_bpermute_b32 v250, v239, v249
	s_waitcnt vmcnt(7)
	v_add_f32_e32 v134, v134, v135
	s_waitcnt vmcnt(6)
	v_add_f32_e32 v138, v138, v139
	v_add_f32_e32 v139, v140, v141
	v_add_f32_e32 v135, v136, v137
	v_add_f32_e32 v138, v138, v139
	v_add_f32_e32 v134, v134, v135
	v_add_f32_e32 v134, v138, v134
	ds_bpermute_b32 v135, v240, v134
	s_waitcnt vmcnt(5)
	v_add_f32_e32 v136, v144, v145
	s_waitcnt lgkmcnt(0)
	v_add_f32_e32 v247, v134, v135
	s_waitcnt vmcnt(4)
	v_add_f32_e32 v134, v184, v185
	v_add_f32_e32 v135, v186, v187
	v_add_f32_e32 v134, v134, v135
	v_add_f32_e32 v135, v142, v143
	v_add_f32_e32 v135, v135, v136
	v_add_f32_e32 v134, v134, v135
	ds_bpermute_b32 v135, v240, v134
	s_waitcnt vmcnt(3)
	v_add_f32_e32 v136, v200, v201
	v_mov_b32_e32 v184, v126
	ds_bpermute_b32 v248, v239, v247
	s_waitcnt lgkmcnt(1)
	v_add_f32_e32 v245, v134, v135
	s_waitcnt vmcnt(2)
;     __device__ __forceinline__ void core(const f32x4 (&acc)[2][2][4][2], const Unit& u, int wr, int wc, int fr, int fq, const float (&rsc)[2][4]) const {
;     ...
;                 for (int bj = 0; bj < 2; ++bj) { const size_t idx = (size_t)(row0 + ai * HALF + (mh + m) * 16) * D + col0 + bj * HALF;
;                     if (F32IN) { xa[m][bj] = *(const f32x4*)(Xin + idx); xb[m][bj] = *(const f32x4*)(Xin + idx + 4); }
;                     else { va[m][bj] = *(const u32x4*)(Hb + idx); vb[m][bj] = *(const u32x2*)(Hl + idx); } }
; #pragma unroll
;             for (int m = 0; m < MB; ++m) { const int row = row0 + ai * HALF + (mh + m) * 16; float sq = 0.f;
;                 const float rs1 = rsc[ai][mh + m];
; #pragma unroll
;                 for (int bj = 0; bj < 2; ++bj) { const size_t idx = (size_t)row * D + col0 + bj * HALF;
;                     unsigned hw[4]; int lw[2] = {0, 0};
; #pragma unroll
;                     for (int pq = 0; pq < 4; ++pq) {
;                         float h0, h1;
;                         if (F32IN) { h0 = (pq < 2) ? xa[m][bj][2 * pq] : xb[m][bj][2 * pq - 4]; h1 = (pq < 2) ? xa[m][bj][2 * pq + 1] : xb[m][bj][2 * pq - 3]; }
;                         else { const unsigned a = va[m][bj][pq]; const int bw = (int)vb[m][bj][pq >> 1]; const hf32x2 lp = (pq & 1) ? __builtin_amdgcn_cvt_pk_f32_fp8(bw, true) : __builtin_amdgcn_cvt_pk_f32_fp8(bw, false);
;                             h0 = __uint_as_float(a << 16) + lp.x * 0.00390625f; h1 = __uint_as_float(a & 0xffff0000u) + lp.y * 0.00390625f; }
;                         const float o0 = h0 + acc[ai][bj][mh + m][pq >> 1][(2 * pq) & 3] * rs1, o1 = h1 + acc[ai][bj][mh + m][pq >> 1][(2 * pq + 1) & 3] * rs1;
;                         sq += o0 * o0 + o1 * o1;
;                         const unsigned hi = cvt_pk_bf16(o0, o1);
;                         hw[pq] = hi;
;                         const float r0 = __builtin_amdgcn_fmed3f((o0 - __uint_as_float(hi << 16)) * 256.0f, -448.0f, 448.0f), r1 = __builtin_amdgcn_fmed3f((o1 - __uint_as_float(hi & 0xffff0000u)) * 256.0f, -448.0f, 448.0f);
;                         lw[pq >> 1] = (pq & 1) ? __builtin_amdgcn_cvt_pk_fp8_f32(r0, r1, lw[pq >> 1], true) : __builtin_amdgcn_cvt_pk_fp8_f32(r0, r1, lw[pq >> 1], false);
;                     }
	v_add_f32_e32 v134, v202, v203
	v_add_f32_e32 v135, v204, v205
	v_add_f32_e32 v134, v134, v135
	v_add_f32_e32 v135, v198, v199
	v_add_f32_e32 v135, v135, v136
	v_add_f32_e32 v134, v134, v135
	ds_bpermute_b32 v135, v240, v134
	s_waitcnt vmcnt(1)
	v_add_f32_e32 v136, v208, v209
	v_lshl_add_u64 v[202:203], v[132:133], 1, s[34:35]
	v_lshl_add_u64 v[204:205], s[42:43], 0, v[132:133]
	v_or_b32_e32 v132, 0x80, v132
	s_waitcnt lgkmcnt(0)
	v_add_f32_e32 v243, v134, v135
	s_waitcnt vmcnt(0)
	v_add_f32_e32 v134, v210, v211
	v_add_f32_e32 v135, v212, v213
	v_add_f32_e32 v134, v134, v135
	v_add_f32_e32 v135, v206, v207
	v_add_f32_e32 v135, v135, v136
	v_add_f32_e32 v134, v134, v135
	ds_bpermute_b32 v135, v240, v134
	global_load_dwordx2 v[210:211], v[204:205], off
	v_lshl_add_u64 v[216:217], v[132:133], 1, s[34:35]
	v_lshl_add_u64 v[218:219], s[42:43], 0, v[132:133]
	global_load_dwordx4 v[142:145], v[216:217], off
	global_load_dwordx2 v[220:221], v[218:219], off
	s_waitcnt lgkmcnt(0)
	v_add_f32_e32 v241, v134, v135
	global_load_dwordx4 v[134:137], v[202:203], off
	v_lshl_add_u64 v[208:209], v[180:181], 1, s[34:35]
	v_lshl_add_u64 v[212:213], s[42:43], 0, v[180:181]
	v_or_b32_e32 v180, 0x80, v180
	v_lshl_add_u64 v[198:199], v[180:181], 1, s[34:35]
	v_lshl_add_u64 v[200:201], s[42:43], 0, v[180:181]
	global_load_dwordx4 v[138:141], v[208:209], off
	global_load_dwordx2 v[214:215], v[212:213], off
	global_load_dwordx4 v[130:133], v[198:199], off
	global_load_dwordx2 v[206:207], v[200:201], off
	ds_bpermute_b32 v246, v239, v245
	ds_bpermute_b32 v244, v239, v243
	ds_bpermute_b32 v242, v239, v241
	s_waitcnt vmcnt(7)
	v_cvt_pk_f32_fp8_e32 v[180:181], v210
	v_mov_b32_e32 v185, v180
	v_pk_mul_f32 v[184:185], v[184:185], v[178:179]
	s_waitcnt vmcnt(4)
	v_lshlrev_b32_e32 v182, 16, v134
	v_add_f32_e32 v126, v185, v182
	v_mov_b32_e32 v180, v127
	v_and_b32_e32 v134, 0xffff0000, v134
	v_add_f32_e32 v182, v184, v126
	v_pk_mul_f32 v[126:127], v[180:181], v[178:179]
	v_mov_b32_e32 v184, v128
	v_add_f32_e32 v127, v127, v134
	v_add_f32_e32 v127, v126, v127
	v_cvt_pk_bf16_f32 v126, v182, v127
	v_mul_f32_e32 v186, v127, v127
	v_and_b32_e32 v134, 0xffff0000, v126
	v_sub_f32_e32 v127, v127, v134
	v_lshlrev_b32_e32 v134, 16, v126
	v_sub_f32_e32 v134, v182, v134
	v_mul_f32_e32 v127, 0x43800000, v127
	v_mul_f32_e32 v134, 0x43800000, v134
	v_med3_f32 v127, v127, s68, v235
	v_med3_f32 v180, v134, s68, v235
	v_mov_b32_e32 v134, v1
	v_cvt_pk_fp8_f32 v134, v180, v127
	v_cvt_pk_f32_fp8_sdwa v[180:181], v210 src0_sel:WORD_1
	v_lshlrev_b32_e32 v127, 16, v135
	v_and_b32_e32 v135, 0xffff0000, v135
	v_fmac_f32_e32 v186, v182, v182
	v_mov_b32_e32 v185, v180
	v_pk_mul_f32 v[184:185], v[184:185], v[178:179]
	v_mov_b32_e32 v180, v129
	v_add_f32_e32 v127, v185, v127
	v_pk_mul_f32 v[128:129], v[180:181], v[178:179]
	v_add_f32_e32 v182, v184, v127
	v_add_f32_e32 v127, v129, v135
	v_add_f32_e32 v128, v128, v127
	v_mul_f32_e32 v127, v128, v128
	v_fmac_f32_e32 v127, v182, v182
	v_add_f32_e32 v135, v186, v127
	v_cvt_pk_bf16_f32 v127, v182, v128
	s_nop 0
	v_lshlrev_b32_e32 v129, 16, v127
	v_and_b32_e32 v180, 0xffff0000, v127
	v_sub_f32_e32 v129, v182, v129
	v_sub_f32_e32 v128, v128, v180
	v_mul_f32_e32 v129, 0x43800000, v129
	v_mul_f32_e32 v128, 0x43800000, v128
	v_med3_f32 v129, v129, s68, v235
	v_med3_f32 v128, v128, s68, v235
	v_cvt_pk_fp8_f32 v134, v129, v128 op_sel:[0,0,1]
	v_cvt_pk_f32_fp8_e32 v[128:129], v211
	v_mov_b32_e32 v180, v122
	v_lshlrev_b32_e32 v182, 16, v136
	v_and_b32_e32 v136, 0xffff0000, v136
	v_mov_b32_e32 v181, v128
	v_pk_mul_f32 v[180:181], v[180:181], v[178:179]
	v_mov_b32_e32 v128, v123
	v_add_f32_e32 v122, v181, v182
	v_add_f32_e32 v180, v180, v122
	v_pk_mul_f32 v[122:123], v[128:129], v[178:179]
	v_and_b32_e32 v181, 0xffff0000, v137
	v_add_f32_e32 v123, v123, v136
	v_add_f32_e32 v122, v122, v123
	v_mul_f32_e32 v123, v122, v122
	v_fmac_f32_e32 v123, v180, v180
	v_add_f32_e32 v129, v135, v123
	v_cvt_pk_bf16_f32 v128, v180, v122
	v_mov_b32_e32 v135, v1
	v_and_b32_e32 v123, 0xffff0000, v128
	v_sub_f32_e32 v122, v122, v123
	v_lshlrev_b32_e32 v123, 16, v128
	v_sub_f32_e32 v123, v180, v123
	v_mul_f32_e32 v122, 0x43800000, v122
	v_mul_f32_e32 v123, 0x43800000, v123
	v_med3_f32 v122, v122, s68, v235
	v_med3_f32 v123, v123, s68, v235
	v_cvt_pk_fp8_f32 v135, v123, v122
	v_cvt_pk_f32_fp8_sdwa v[122:123], v211 src0_sel:WORD_1
	v_lshlrev_b32_e32 v180, 16, v137
	v_mov_b32_e32 v136, v124
	v_mov_b32_e32 v137, v122
	v_pk_mul_f32 v[136:137], v[136:137], v[178:179]
	s_nop 0
	v_add_f32_e32 v122, v137, v180
	v_add_f32_e32 v124, v136, v122
	v_mov_b32_e32 v122, v125
	v_pk_mul_f32 v[122:123], v[122:123], v[178:179]
	s_nop 0
	v_add_f32_e32 v123, v123, v181
	v_add_f32_e32 v122, v122, v123
	v_mul_f32_e32 v123, v122, v122
	v_fmac_f32_e32 v123, v124, v124
	v_add_f32_e32 v136, v129, v123
	v_cvt_pk_bf16_f32 v129, v124, v122
	s_nop 0
	v_lshlrev_b32_e32 v123, 16, v129
	v_sub_f32_e32 v123, v124, v123
	v_and_b32_e32 v124, 0xffff0000, v129
	v_sub_f32_e32 v122, v122, v124
	v_mul_f32_e32 v123, 0x43800000, v123
	v_mul_f32_e32 v122, 0x43800000, v122
	v_med3_f32 v123, v123, s68, v235
	v_med3_f32 v122, v122, s68, v235
	v_cvt_pk_fp8_f32 v135, v123, v122 op_sel:[0,0,1]
	v_cvt_pk_f32_fp8_e32 v[122:123], v220
	v_mov_b32_e32 v124, v118
	global_store_dwordx4 v[202:203], v[126:129], off sc1
	global_store_dwordx2 v[204:205], v[134:135], off
	v_mov_b32_e32 v125, v122
	v_lshlrev_b32_e32 v126, 16, v142
	v_pk_mul_f32 v[124:125], v[124:125], v[178:179]
	v_mov_b32_e32 v122, v119
	v_add_f32_e32 v118, v125, v126
	v_and_b32_e32 v127, 0xffff0000, v142
	v_add_f32_e32 v124, v124, v118
	v_pk_mul_f32 v[118:119], v[122:123], v[178:179]
; __device__ __forceinline__ unsigned cvt_pk_bf16(float lo, float hi) { unsigned r; asm volatile("v_cvt_pk_bf16_f32 %0, %1, %2" : "=v"(r) : "v"(lo), "v"(hi)); return r; }
;     __device__ __forceinline__ void core(const f32x4 (&acc)[2][2][4][2], const Unit& u, int wr, int wc, int fr, int fq, const float (&rsc)[2][4]) const {
;     ...
;             for (int m = 0; m < MB; ++m) { const int row = row0 + ai * HALF + (mh + m) * 16; float sq = 0.f;
;                 const float rs1 = rsc[ai][mh + m];
; #pragma unroll
;                 for (int bj = 0; bj < 2; ++bj) { const size_t idx = (size_t)row * D + col0 + bj * HALF;
;                     unsigned hw[4]; int lw[2] = {0, 0};
; #pragma unroll
;                     for (int pq = 0; pq < 4; ++pq) {
;                         float h0, h1;
;                         if (F32IN) { h0 = (pq < 2) ? xa[m][bj][2 * pq] : xb[m][bj][2 * pq - 4]; h1 = (pq < 2) ? xa[m][bj][2 * pq + 1] : xb[m][bj][2 * pq - 3]; }
;                         else { const unsigned a = va[m][bj][pq]; const int bw = (int)vb[m][bj][pq >> 1]; const hf32x2 lp = (pq & 1) ? __builtin_amdgcn_cvt_pk_f32_fp8(bw, true) : __builtin_amdgcn_cvt_pk_f32_fp8(bw, false);
;                             h0 = __uint_as_float(a << 16) + lp.x * 0.00390625f; h1 = __uint_as_float(a & 0xffff0000u) + lp.y * 0.00390625f; }
;                         const float o0 = h0 + acc[ai][bj][mh + m][pq >> 1][(2 * pq) & 3] * rs1, o1 = h1 + acc[ai][bj][mh + m][pq >> 1][(2 * pq + 1) & 3] * rs1;
;                         sq += o0 * o0 + o1 * o1;
;                         const unsigned hi = cvt_pk_bf16(o0, o1);
;                         hw[pq] = hi;
;                         const float r0 = __builtin_amdgcn_fmed3f((o0 - __uint_as_float(hi << 16)) * 256.0f, -448.0f, 448.0f), r1 = __builtin_amdgcn_fmed3f((o1 - __uint_as_float(hi & 0xffff0000u)) * 256.0f, -448.0f, 448.0f);
;                         lw[pq >> 1] = (pq & 1) ? __builtin_amdgcn_cvt_pk_fp8_f32(r0, r1, lw[pq >> 1], true) : __builtin_amdgcn_cvt_pk_fp8_f32(r0, r1, lw[pq >> 1], false);
;                     }
;                     *(u32x4*)(Hb + idx) = (u32x4){hw[0], hw[1], hw[2], hw[3]}; *(u32x2*)(Hl + idx) = (u32x2){(unsigned)lw[0], (unsigned)lw[1]}; }
;                 sq += __shfl_xor(sq, 16); sq += __shfl_xor(sq, 32); if (fq == 0) ss[(size_t)row * 32 + u.pn * 4 + wc] = sq; }
	v_mov_b32_e32 v126, v120
	v_add_f32_e32 v119, v119, v127
	v_add_f32_e32 v119, v118, v119
	v_mul_f32_e32 v118, v119, v119
	v_fmac_f32_e32 v118, v124, v124
	v_add_f32_e32 v123, v136, v118
	v_cvt_pk_bf16_f32 v118, v124, v119
	v_and_b32_e32 v128, 0xffff0000, v143
	v_and_b32_e32 v122, 0xffff0000, v118
	v_sub_f32_e32 v119, v119, v122
	v_lshlrev_b32_e32 v122, 16, v118
	v_sub_f32_e32 v122, v124, v122
	v_mul_f32_e32 v119, 0x43800000, v119
	v_mul_f32_e32 v122, 0x43800000, v122
	v_med3_f32 v119, v119, s68, v235
	v_med3_f32 v124, v122, s68, v235
	v_mov_b32_e32 v122, v1
	v_cvt_pk_fp8_f32 v122, v124, v119
	v_cvt_pk_f32_fp8_sdwa v[124:125], v220 src0_sel:WORD_1
	v_lshlrev_b32_e32 v119, 16, v143
	v_mov_b32_e32 v127, v124
	v_pk_mul_f32 v[126:127], v[126:127], v[178:179]
	v_mov_b32_e32 v124, v121
	v_add_f32_e32 v119, v127, v119
	v_pk_mul_f32 v[120:121], v[124:125], v[178:179]
	v_add_f32_e32 v126, v126, v119
	v_add_f32_e32 v119, v121, v128
	v_add_f32_e32 v120, v120, v119
	v_mul_f32_e32 v119, v120, v120
	v_fmac_f32_e32 v119, v126, v126
	v_add_f32_e32 v123, v123, v119
	v_cvt_pk_bf16_f32 v119, v126, v120
	v_and_b32_e32 v127, 0xffff0000, v144
	v_lshlrev_b32_e32 v121, 16, v119
	v_and_b32_e32 v124, 0xffff0000, v119
	v_sub_f32_e32 v121, v126, v121
	v_sub_f32_e32 v120, v120, v124
	v_mul_f32_e32 v121, 0x43800000, v121
	v_mul_f32_e32 v120, 0x43800000, v120
	v_med3_f32 v121, v121, s68, v235
	v_med3_f32 v120, v120, s68, v235
	v_cvt_pk_fp8_f32 v122, v121, v120 op_sel:[0,0,1]
	v_cvt_pk_f32_fp8_e32 v[120:121], v221
	v_mov_b32_e32 v124, v114
	v_lshlrev_b32_e32 v126, 16, v144
	v_mov_b32_e32 v125, v120
	v_pk_mul_f32 v[124:125], v[124:125], v[178:179]
	v_mov_b32_e32 v120, v115
	v_add_f32_e32 v114, v125, v126
	v_add_f32_e32 v124, v124, v114
	v_pk_mul_f32 v[114:115], v[120:121], v[178:179]
	v_lshlrev_b32_e32 v126, 16, v145
	v_add_f32_e32 v115, v115, v127
	v_add_f32_e32 v114, v114, v115
	v_mul_f32_e32 v115, v114, v114
	v_fmac_f32_e32 v115, v124, v124
	v_add_f32_e32 v121, v123, v115
	v_cvt_pk_bf16_f32 v120, v124, v114
	v_mov_b32_e32 v123, v1
	v_and_b32_e32 v115, 0xffff0000, v120
	v_sub_f32_e32 v114, v114, v115
	v_lshlrev_b32_e32 v115, 16, v120
	v_sub_f32_e32 v115, v124, v115
	v_mul_f32_e32 v114, 0x43800000, v114
	v_mul_f32_e32 v115, 0x43800000, v115
	v_med3_f32 v114, v114, s68, v235
	v_med3_f32 v115, v115, s68, v235
	v_cvt_pk_fp8_f32 v123, v115, v114
	v_cvt_pk_f32_fp8_sdwa v[114:115], v221 src0_sel:WORD_1
	v_mov_b32_e32 v124, v116
	v_and_b32_e32 v127, 0xffff0000, v145
	v_mov_b32_e32 v125, v114
	v_pk_mul_f32 v[124:125], v[124:125], v[178:179]
	s_nop 0
	v_add_f32_e32 v114, v125, v126
	v_add_f32_e32 v116, v124, v114
	v_mov_b32_e32 v114, v117
	v_pk_mul_f32 v[114:115], v[114:115], v[178:179]
	s_nop 0
	v_add_f32_e32 v115, v115, v127
	v_add_f32_e32 v114, v114, v115
	v_mul_f32_e32 v115, v114, v114
	v_fmac_f32_e32 v115, v116, v116
	v_add_f32_e32 v115, v121, v115
	v_cvt_pk_bf16_f32 v121, v116, v114
	s_nop 0
	v_lshlrev_b32_e32 v117, 16, v121
	v_sub_f32_e32 v116, v116, v117
	v_and_b32_e32 v117, 0xffff0000, v121
	v_sub_f32_e32 v114, v114, v117
	v_mul_f32_e32 v116, 0x43800000, v116
	v_mul_f32_e32 v114, 0x43800000, v114
	v_med3_f32 v116, v116, s68, v235
	v_med3_f32 v114, v114, s68, v235
	v_cvt_pk_fp8_f32 v123, v116, v114 op_sel:[0,0,1]
	ds_bpermute_b32 v114, v240, v115
	global_store_dwordx4 v[216:217], v[118:121], off sc1
	global_store_dwordx2 v[218:219], v[122:123], off
	s_waitcnt lgkmcnt(0)
	v_add_f32_e32 v114, v115, v114
	ds_bpermute_b32 v115, v239, v114
	s_and_saveexec_b64 s[2:3], s[38:39]
	s_cbranch_execz .LBB0_1427
	s_lshl_b32 s20, s8, 2
	s_waitcnt lgkmcnt(0)
	v_add_f32_e32 v116, v114, v115
	s_ashr_i32 s21, s20, 31
	v_lshl_add_u64 v[114:115], s[44:45], 0, v[196:197]
	v_lshl_add_u64 v[114:115], s[20:21], 2, v[114:115]
	s_lshl_b32 s18, s36, 2
	v_lshl_add_u64 v[114:115], v[114:115], 0, s[18:19]
	global_store_dword v[114:115], v116, off
.LBB0_1427:
	s_or_b64 exec, exec, s[2:3]
	v_add_f32_e32 v114, v253, v225
	v_fmamk_f32 v114, v114, 0x3a000000, v223
	s_waitcnt lgkmcnt(0)
	v_div_scale_f32 v115, s[2:3], v114, v114, 1.0
	v_rcp_f32_e32 v116, v115
	v_div_scale_f32 v117, vcc, 1.0, v114, 1.0
	s_waitcnt vmcnt(7)
	v_and_b32_e32 v120, 0xffff0000, v139
	v_fma_f32 v118, -v115, v116, 1.0
	v_fmac_f32_e32 v116, v118, v116
	v_mul_f32_e32 v118, v117, v116
	v_fma_f32 v119, -v115, v118, v117
	v_fmac_f32_e32 v118, v119, v116
	v_fma_f32 v115, -v115, v118, v117
	v_div_fmas_f32 v115, v115, v116, v118
	v_div_fixup_f32 v178, v115, v114, 1.0
	s_waitcnt vmcnt(6)
; __device__ __forceinline__ unsigned cvt_pk_bf16(float lo, float hi) { unsigned r; asm volatile("v_cvt_pk_bf16_f32 %0, %1, %2" : "=v"(r) : "v"(lo), "v"(hi)); return r; }
;     __device__ __forceinline__ void core(const f32x4 (&acc)[2][2][4][2], const Unit& u, int wr, int wc, int fr, int fq, const float (&rsc)[2][4]) const {
;     ...
;             for (int m = 0; m < MB; ++m) { const int row = row0 + ai * HALF + (mh + m) * 16; float sq = 0.f;
;                 const float rs1 = rsc[ai][mh + m];
; #pragma unroll
;                 for (int bj = 0; bj < 2; ++bj) { const size_t idx = (size_t)row * D + col0 + bj * HALF;
;                     unsigned hw[4]; int lw[2] = {0, 0};
; #pragma unroll
;                     for (int pq = 0; pq < 4; ++pq) {
;                         float h0, h1;
;                         if (F32IN) { h0 = (pq < 2) ? xa[m][bj][2 * pq] : xb[m][bj][2 * pq - 4]; h1 = (pq < 2) ? xa[m][bj][2 * pq + 1] : xb[m][bj][2 * pq - 3]; }
;                         else { const unsigned a = va[m][bj][pq]; const int bw = (int)vb[m][bj][pq >> 1]; const hf32x2 lp = (pq & 1) ? __builtin_amdgcn_cvt_pk_f32_fp8(bw, true) : __builtin_amdgcn_cvt_pk_f32_fp8(bw, false);
;                             h0 = __uint_as_float(a << 16) + lp.x * 0.00390625f; h1 = __uint_as_float(a & 0xffff0000u) + lp.y * 0.00390625f; }
;                         const float o0 = h0 + acc[ai][bj][mh + m][pq >> 1][(2 * pq) & 3] * rs1, o1 = h1 + acc[ai][bj][mh + m][pq >> 1][(2 * pq + 1) & 3] * rs1;
;                         sq += o0 * o0 + o1 * o1;
;                         const unsigned hi = cvt_pk_bf16(o0, o1);
;                         hw[pq] = hi;
;                         const float r0 = __builtin_amdgcn_fmed3f((o0 - __uint_as_float(hi << 16)) * 256.0f, -448.0f, 448.0f), r1 = __builtin_amdgcn_fmed3f((o1 - __uint_as_float(hi & 0xffff0000u)) * 256.0f, -448.0f, 448.0f);
;                         lw[pq >> 1] = (pq & 1) ? __builtin_amdgcn_cvt_pk_fp8_f32(r0, r1, lw[pq >> 1], true) : __builtin_amdgcn_cvt_pk_fp8_f32(r0, r1, lw[pq >> 1], false);
;                     }
;                     *(u32x4*)(Hb + idx) = (u32x4){hw[0], hw[1], hw[2], hw[3]}; *(u32x2*)(Hl + idx) = (u32x2){(unsigned)lw[0], (unsigned)lw[1]}; }
	v_cvt_pk_f32_fp8_e32 v[114:115], v214
	v_mov_b32_e32 v116, v110
	v_lshlrev_b32_e32 v118, 16, v138
	v_and_b32_e32 v119, 0xffff0000, v138
	v_mov_b32_e32 v117, v114
	v_pk_mul_f32 v[116:117], v[116:117], v[178:179]
	v_mov_b32_e32 v114, v111
	v_add_f32_e32 v110, v117, v118
	v_add_f32_e32 v116, v116, v110
	v_pk_mul_f32 v[110:111], v[114:115], v[178:179]
	v_mov_b32_e32 v118, v112
	v_add_f32_e32 v111, v111, v119
	v_add_f32_e32 v111, v110, v111
	v_cvt_pk_bf16_f32 v110, v116, v111
	v_mul_f32_e32 v115, v111, v111
	v_and_b32_e32 v114, 0xffff0000, v110
	v_sub_f32_e32 v111, v111, v114
	v_lshlrev_b32_e32 v114, 16, v110
	v_sub_f32_e32 v114, v116, v114
	v_mul_f32_e32 v111, 0x43800000, v111
	v_mul_f32_e32 v114, 0x43800000, v114
	v_fmac_f32_e32 v115, v116, v116
	v_med3_f32 v111, v111, s68, v235
	v_med3_f32 v116, v114, s68, v235
	v_mov_b32_e32 v114, v1
	v_cvt_pk_fp8_f32 v114, v116, v111
	v_cvt_pk_f32_fp8_sdwa v[116:117], v214 src0_sel:WORD_1
	v_lshlrev_b32_e32 v111, 16, v139
	v_mov_b32_e32 v119, v116
	v_pk_mul_f32 v[118:119], v[118:119], v[178:179]
	v_mov_b32_e32 v116, v113
	v_add_f32_e32 v111, v119, v111
	v_pk_mul_f32 v[112:113], v[116:117], v[178:179]
	v_add_f32_e32 v118, v118, v111
	v_add_f32_e32 v111, v113, v120
	v_add_f32_e32 v112, v112, v111
	v_mul_f32_e32 v111, v112, v112
	v_fmac_f32_e32 v111, v118, v118
	v_add_f32_e32 v115, v115, v111
	v_cvt_pk_bf16_f32 v111, v118, v112
	v_and_b32_e32 v119, 0xffff0000, v140
	v_lshlrev_b32_e32 v113, 16, v111
	v_and_b32_e32 v116, 0xffff0000, v111
	v_sub_f32_e32 v113, v118, v113
	v_sub_f32_e32 v112, v112, v116
	v_mul_f32_e32 v113, 0x43800000, v113
	v_mul_f32_e32 v112, 0x43800000, v112
	v_med3_f32 v113, v113, s68, v235
	v_med3_f32 v112, v112, s68, v235
	v_cvt_pk_fp8_f32 v114, v113, v112 op_sel:[0,0,1]
	v_cvt_pk_f32_fp8_e32 v[112:113], v215
	v_mov_b32_e32 v116, v106
	v_lshlrev_b32_e32 v118, 16, v140
	v_mov_b32_e32 v117, v112
	v_pk_mul_f32 v[116:117], v[116:117], v[178:179]
	v_mov_b32_e32 v112, v107
	v_add_f32_e32 v106, v117, v118
	v_add_f32_e32 v116, v116, v106
	v_pk_mul_f32 v[106:107], v[112:113], v[178:179]
	v_lshlrev_b32_e32 v113, 16, v141
	v_add_f32_e32 v107, v107, v119
	v_add_f32_e32 v106, v106, v107
	v_mul_f32_e32 v107, v106, v106
	v_fmac_f32_e32 v107, v116, v116
	v_add_f32_e32 v118, v115, v107
	v_cvt_pk_bf16_f32 v112, v116, v106
	v_mov_b32_e32 v115, v1
	v_and_b32_e32 v107, 0xffff0000, v112
	v_sub_f32_e32 v106, v106, v107
	v_lshlrev_b32_e32 v107, 16, v112
	v_sub_f32_e32 v107, v116, v107
	v_mul_f32_e32 v106, 0x43800000, v106
	v_mul_f32_e32 v107, 0x43800000, v107
	v_med3_f32 v106, v106, s68, v235
	v_med3_f32 v107, v107, s68, v235
	v_cvt_pk_fp8_f32 v115, v107, v106
	v_cvt_pk_f32_fp8_sdwa v[106:107], v215 src0_sel:WORD_1
	v_mov_b32_e32 v116, v108
	v_and_b32_e32 v119, 0xffff0000, v141
	v_mov_b32_e32 v117, v106
	v_pk_mul_f32 v[116:117], v[116:117], v[178:179]
	s_nop 0
	v_add_f32_e32 v106, v117, v113
	v_add_f32_e32 v108, v116, v106
	v_mov_b32_e32 v106, v109
	v_pk_mul_f32 v[106:107], v[106:107], v[178:179]
	s_nop 0
	v_add_f32_e32 v107, v107, v119
	v_add_f32_e32 v106, v106, v107
	v_cvt_pk_bf16_f32 v113, v108, v106
	v_mul_f32_e32 v107, v106, v106
	v_lshlrev_b32_e32 v109, 16, v113
	v_and_b32_e32 v116, 0xffff0000, v113
	v_sub_f32_e32 v109, v108, v109
	v_sub_f32_e32 v106, v106, v116
	v_mul_f32_e32 v109, 0x43800000, v109
	v_mul_f32_e32 v106, 0x43800000, v106
	v_med3_f32 v109, v109, s68, v235
	v_med3_f32 v106, v106, s68, v235
	v_fmac_f32_e32 v107, v108, v108
	v_cvt_pk_fp8_f32 v115, v109, v106 op_sel:[0,0,1]
	v_add_f32_e32 v116, v118, v107
	s_waitcnt vmcnt(4)
	v_cvt_pk_f32_fp8_e32 v[106:107], v206
	v_mov_b32_e32 v108, v102
	global_store_dwordx4 v[208:209], v[110:113], off sc1
	global_store_dwordx2 v[212:213], v[114:115], off
	v_mov_b32_e32 v109, v106
	v_lshlrev_b32_e32 v110, 16, v130
	v_pk_mul_f32 v[108:109], v[108:109], v[178:179]
	v_mov_b32_e32 v106, v103
	v_add_f32_e32 v102, v109, v110
	v_and_b32_e32 v111, 0xffff0000, v130
	v_add_f32_e32 v108, v108, v102
	v_pk_mul_f32 v[102:103], v[106:107], v[178:179]
	v_mov_b32_e32 v110, v104
	v_add_f32_e32 v103, v103, v111
	v_add_f32_e32 v103, v102, v103
	v_mul_f32_e32 v102, v103, v103
	v_fmac_f32_e32 v102, v108, v108
	v_add_f32_e32 v107, v116, v102
	v_cvt_pk_bf16_f32 v102, v108, v103
	v_and_b32_e32 v112, 0xffff0000, v131
	v_and_b32_e32 v106, 0xffff0000, v102
	v_sub_f32_e32 v103, v103, v106
	v_lshlrev_b32_e32 v106, 16, v102
	v_sub_f32_e32 v106, v108, v106
	v_mul_f32_e32 v103, 0x43800000, v103
	v_mul_f32_e32 v106, 0x43800000, v106
	v_med3_f32 v103, v103, s68, v235
	v_med3_f32 v108, v106, s68, v235
	v_mov_b32_e32 v106, v1
	v_cvt_pk_fp8_f32 v106, v108, v103
	v_cvt_pk_f32_fp8_sdwa v[108:109], v206 src0_sel:WORD_1
	v_lshlrev_b32_e32 v103, 16, v131
	v_mov_b32_e32 v111, v108
	v_pk_mul_f32 v[110:111], v[110:111], v[178:179]
	v_mov_b32_e32 v108, v105
	v_add_f32_e32 v103, v111, v103
	v_pk_mul_f32 v[104:105], v[108:109], v[178:179]
	v_add_f32_e32 v110, v110, v103
	v_add_f32_e32 v103, v105, v112
	v_add_f32_e32 v104, v104, v103
	v_mul_f32_e32 v103, v104, v104
	v_fmac_f32_e32 v103, v110, v110
	v_add_f32_e32 v107, v107, v103
	v_cvt_pk_bf16_f32 v103, v110, v104
	v_and_b32_e32 v111, 0xffff0000, v132
	v_lshlrev_b32_e32 v105, 16, v103
	v_and_b32_e32 v108, 0xffff0000, v103
	v_sub_f32_e32 v105, v110, v105
	v_sub_f32_e32 v104, v104, v108
	v_mul_f32_e32 v105, 0x43800000, v105
	v_mul_f32_e32 v104, 0x43800000, v104
	v_med3_f32 v105, v105, s68, v235
	v_med3_f32 v104, v104, s68, v235
	v_cvt_pk_fp8_f32 v106, v105, v104 op_sel:[0,0,1]
	v_cvt_pk_f32_fp8_e32 v[104:105], v207
	v_mov_b32_e32 v108, v98
	v_lshlrev_b32_e32 v110, 16, v132
	v_mov_b32_e32 v109, v104
	v_pk_mul_f32 v[108:109], v[108:109], v[178:179]
; __device__ __forceinline__ unsigned cvt_pk_bf16(float lo, float hi) { unsigned r; asm volatile("v_cvt_pk_bf16_f32 %0, %1, %2" : "=v"(r) : "v"(lo), "v"(hi)); return r; }
;     __device__ __forceinline__ void core(const f32x4 (&acc)[2][2][4][2], const Unit& u, int wr, int wc, int fr, int fq, const float (&rsc)[2][4]) const {
;     ...
;             for (int m = 0; m < MB; ++m) { const int row = row0 + ai * HALF + (mh + m) * 16; float sq = 0.f;
;                 const float rs1 = rsc[ai][mh + m];
; #pragma unroll
;                 for (int bj = 0; bj < 2; ++bj) { const size_t idx = (size_t)row * D + col0 + bj * HALF;
;                     unsigned hw[4]; int lw[2] = {0, 0};
; #pragma unroll
;                     for (int pq = 0; pq < 4; ++pq) {
;                         float h0, h1;
;                         if (F32IN) { h0 = (pq < 2) ? xa[m][bj][2 * pq] : xb[m][bj][2 * pq - 4]; h1 = (pq < 2) ? xa[m][bj][2 * pq + 1] : xb[m][bj][2 * pq - 3]; }
;                         else { const unsigned a = va[m][bj][pq]; const int bw = (int)vb[m][bj][pq >> 1]; const hf32x2 lp = (pq & 1) ? __builtin_amdgcn_cvt_pk_f32_fp8(bw, true) : __builtin_amdgcn_cvt_pk_f32_fp8(bw, false);
;                             h0 = __uint_as_float(a << 16) + lp.x * 0.00390625f; h1 = __uint_as_float(a & 0xffff0000u) + lp.y * 0.00390625f; }
;                         const float o0 = h0 + acc[ai][bj][mh + m][pq >> 1][(2 * pq) & 3] * rs1, o1 = h1 + acc[ai][bj][mh + m][pq >> 1][(2 * pq + 1) & 3] * rs1;
;                         sq += o0 * o0 + o1 * o1;
;                         const unsigned hi = cvt_pk_bf16(o0, o1);
;                         hw[pq] = hi;
;                         const float r0 = __builtin_amdgcn_fmed3f((o0 - __uint_as_float(hi << 16)) * 256.0f, -448.0f, 448.0f), r1 = __builtin_amdgcn_fmed3f((o1 - __uint_as_float(hi & 0xffff0000u)) * 256.0f, -448.0f, 448.0f);
;                         lw[pq >> 1] = (pq & 1) ? __builtin_amdgcn_cvt_pk_fp8_f32(r0, r1, lw[pq >> 1], true) : __builtin_amdgcn_cvt_pk_fp8_f32(r0, r1, lw[pq >> 1], false);
;                     }
;                     *(u32x4*)(Hb + idx) = (u32x4){hw[0], hw[1], hw[2], hw[3]}; *(u32x2*)(Hl + idx) = (u32x2){(unsigned)lw[0], (unsigned)lw[1]}; }
;                 sq += __shfl_xor(sq, 16); sq += __shfl_xor(sq, 32); if (fq == 0) ss[(size_t)row * 32 + u.pn * 4 + wc] = sq; }
	v_mov_b32_e32 v104, v99
	v_add_f32_e32 v98, v109, v110
	v_add_f32_e32 v108, v108, v98
	v_pk_mul_f32 v[98:99], v[104:105], v[178:179]
	v_lshlrev_b32_e32 v110, 16, v133
	v_add_f32_e32 v99, v99, v111
	v_add_f32_e32 v98, v98, v99
	v_mul_f32_e32 v99, v98, v98
	v_fmac_f32_e32 v99, v108, v108
	v_add_f32_e32 v105, v107, v99
	v_cvt_pk_bf16_f32 v104, v108, v98
	v_mov_b32_e32 v107, v1
	v_and_b32_e32 v99, 0xffff0000, v104
	v_sub_f32_e32 v98, v98, v99
	v_lshlrev_b32_e32 v99, 16, v104
	v_sub_f32_e32 v99, v108, v99
	v_mul_f32_e32 v98, 0x43800000, v98
	v_mul_f32_e32 v99, 0x43800000, v99
	v_med3_f32 v98, v98, s68, v235
	v_med3_f32 v99, v99, s68, v235
	v_cvt_pk_fp8_f32 v107, v99, v98
	v_cvt_pk_f32_fp8_sdwa v[98:99], v207 src0_sel:WORD_1
	v_mov_b32_e32 v108, v100
	v_and_b32_e32 v111, 0xffff0000, v133
	v_mov_b32_e32 v109, v98
	v_pk_mul_f32 v[108:109], v[108:109], v[178:179]
	s_nop 0
	v_add_f32_e32 v98, v109, v110
	v_add_f32_e32 v100, v108, v98
	v_mov_b32_e32 v98, v101
	v_pk_mul_f32 v[98:99], v[98:99], v[178:179]
	s_nop 0
	v_add_f32_e32 v99, v99, v111
	v_add_f32_e32 v98, v98, v99
	v_mul_f32_e32 v99, v98, v98
	v_fmac_f32_e32 v99, v100, v100
	v_add_f32_e32 v99, v105, v99
	v_cvt_pk_bf16_f32 v105, v100, v98
	ds_bpermute_b32 v108, v240, v99
	v_lshlrev_b32_e32 v101, 16, v105
	v_sub_f32_e32 v100, v100, v101
	v_and_b32_e32 v101, 0xffff0000, v105
	v_sub_f32_e32 v98, v98, v101
	v_mul_f32_e32 v100, 0x43800000, v100
	v_mul_f32_e32 v98, 0x43800000, v98
	v_med3_f32 v100, v100, s68, v235
	v_med3_f32 v98, v98, s68, v235
	v_cvt_pk_fp8_f32 v107, v100, v98 op_sel:[0,0,1]
	s_waitcnt lgkmcnt(0)
	v_add_f32_e32 v98, v99, v108
	ds_bpermute_b32 v99, v239, v98
	global_store_dwordx4 v[198:199], v[102:105], off sc1
	global_store_dwordx2 v[200:201], v[106:107], off
	s_and_saveexec_b64 s[2:3], s[38:39]
	s_cbranch_execz .LBB0_1429
	s_lshl_b32 s20, s8, 2
	s_waitcnt lgkmcnt(0)
	v_add_f32_e32 v100, v98, v99
	s_ashr_i32 s21, s20, 31
	v_lshl_add_u64 v[98:99], s[44:45], 0, v[194:195]
	v_lshl_add_u64 v[98:99], s[20:21], 2, v[98:99]
	s_lshl_b32 s18, s36, 2
	v_lshl_add_u64 v[98:99], v[98:99], 0, s[18:19]
	global_store_dword v[98:99], v100, off
.LBB0_1429:
	s_or_b64 exec, exec, s[2:3]
	v_add_f32_e32 v98, v251, v252
	v_fmamk_f32 v98, v98, 0x3a000000, v223
	s_waitcnt lgkmcnt(0)
	v_div_scale_f32 v99, s[2:3], v98, v98, 1.0
	v_rcp_f32_e32 v100, v99
	v_mov_b32_e32 v140, v94
	v_fma_f32 v101, -v99, v100, 1.0
	v_fmac_f32_e32 v100, v101, v100
	v_div_scale_f32 v101, vcc, 1.0, v98, 1.0
	v_mul_f32_e32 v102, v101, v100
	v_fma_f32 v103, -v99, v102, v101
	v_fmac_f32_e32 v102, v103, v100
	v_fma_f32 v99, -v99, v102, v101
	v_div_fmas_f32 v99, v99, v100, v102
	v_div_fixup_f32 v178, v99, v98, 1.0
	v_lshlrev_b64 v[98:99], 11, v[192:193]
	v_lshl_add_u64 v[98:99], v[98:99], 0, v[170:171]
	v_lshl_add_u64 v[132:133], v[98:99], 1, s[34:35]
	v_lshl_add_u64 v[134:135], s[42:43], 0, v[98:99]
	global_load_dwordx4 v[110:113], v[132:133], off
	global_load_dwordx2 v[136:137], v[134:135], off
	v_or_b32_e32 v98, 0x80, v98
	v_lshl_add_u64 v[126:127], v[98:99], 1, s[34:35]
	v_lshl_add_u64 v[128:129], s[42:43], 0, v[98:99]
	global_load_dwordx4 v[106:109], v[126:127], off
	global_load_dwordx2 v[130:131], v[128:129], off
	v_lshlrev_b64 v[98:99], 11, v[190:191]
	v_lshl_add_u64 v[116:117], v[98:99], 0, v[170:171]
	v_lshl_add_u64 v[120:121], v[116:117], 1, s[34:35]
	v_lshl_add_u64 v[122:123], s[42:43], 0, v[116:117]
	v_or_b32_e32 v116, 0x80, v116
	v_lshl_add_u64 v[114:115], v[116:117], 1, s[34:35]
	v_lshl_add_u64 v[116:117], s[42:43], 0, v[116:117]
	global_load_dwordx4 v[102:105], v[120:121], off
	global_load_dwordx2 v[124:125], v[122:123], off
	global_load_dwordx4 v[98:101], v[114:115], off
	global_load_dwordx2 v[118:119], v[116:117], off
	s_waitcnt vmcnt(7)
	v_lshlrev_b32_e32 v142, 16, v110
	s_waitcnt vmcnt(6)
	v_cvt_pk_f32_fp8_e32 v[138:139], v136
	v_and_b32_e32 v110, 0xffff0000, v110
	v_mov_b32_e32 v141, v138
	v_pk_mul_f32 v[140:141], v[140:141], v[178:179]
	v_mov_b32_e32 v138, v95
	v_add_f32_e32 v94, v141, v142
	v_add_f32_e32 v140, v140, v94
	v_pk_mul_f32 v[94:95], v[138:139], v[178:179]
	s_nop 0
	v_add_f32_e32 v95, v95, v110
	v_add_f32_e32 v95, v94, v95
	v_cvt_pk_bf16_f32 v94, v140, v95
	v_mul_f32_e32 v142, v95, v95
	v_and_b32_e32 v110, 0xffff0000, v94
	v_sub_f32_e32 v95, v95, v110
	v_lshlrev_b32_e32 v110, 16, v94
	v_sub_f32_e32 v110, v140, v110
	v_mul_f32_e32 v95, 0x43800000, v95
	v_mul_f32_e32 v110, 0x43800000, v110
	v_med3_f32 v95, v95, s68, v235
	v_med3_f32 v138, v110, s68, v235
	v_mov_b32_e32 v110, v1
	v_cvt_pk_fp8_f32 v110, v138, v95
	v_cvt_pk_f32_fp8_sdwa v[138:139], v136 src0_sel:WORD_1
	v_fmac_f32_e32 v142, v140, v140
	v_mov_b32_e32 v140, v96
	v_lshlrev_b32_e32 v95, 16, v111
	v_mov_b32_e32 v141, v138
	v_pk_mul_f32 v[140:141], v[140:141], v[178:179]
	v_mov_b32_e32 v138, v97
	v_and_b32_e32 v111, 0xffff0000, v111
	v_add_f32_e32 v95, v141, v95
	v_pk_mul_f32 v[96:97], v[138:139], v[178:179]
	v_add_f32_e32 v136, v140, v95
	v_add_f32_e32 v95, v97, v111
	v_add_f32_e32 v96, v96, v95
	v_mul_f32_e32 v95, v96, v96
	v_fmac_f32_e32 v95, v136, v136
	v_add_f32_e32 v111, v142, v95
	v_cvt_pk_bf16_f32 v95, v136, v96
	v_mov_b32_e32 v138, v90
	v_lshlrev_b32_e32 v97, 16, v95
	v_sub_f32_e32 v97, v136, v97
	v_and_b32_e32 v136, 0xffff0000, v95
	v_sub_f32_e32 v96, v96, v136
	v_mul_f32_e32 v97, 0x43800000, v97
	v_mul_f32_e32 v96, 0x43800000, v96
	v_med3_f32 v97, v97, s68, v235
	v_med3_f32 v96, v96, s68, v235
	v_cvt_pk_fp8_f32 v110, v97, v96 op_sel:[0,0,1]
	v_cvt_pk_f32_fp8_e32 v[96:97], v137
	v_lshlrev_b32_e32 v136, 16, v112
	v_and_b32_e32 v112, 0xffff0000, v112
	v_mov_b32_e32 v139, v96
	v_pk_mul_f32 v[138:139], v[138:139], v[178:179]
	v_mov_b32_e32 v96, v91
; __device__ __forceinline__ unsigned cvt_pk_bf16(float lo, float hi) { unsigned r; asm volatile("v_cvt_pk_bf16_f32 %0, %1, %2" : "=v"(r) : "v"(lo), "v"(hi)); return r; }
;     __device__ __forceinline__ void core(const f32x4 (&acc)[2][2][4][2], const Unit& u, int wr, int wc, int fr, int fq, const float (&rsc)[2][4]) const {
;     ...
;             for (int m = 0; m < MB; ++m) { const int row = row0 + ai * HALF + (mh + m) * 16; float sq = 0.f;
;                 const float rs1 = rsc[ai][mh + m];
; #pragma unroll
;                 for (int bj = 0; bj < 2; ++bj) { const size_t idx = (size_t)row * D + col0 + bj * HALF;
;                     unsigned hw[4]; int lw[2] = {0, 0};
; #pragma unroll
;                     for (int pq = 0; pq < 4; ++pq) {
;                         float h0, h1;
;                         if (F32IN) { h0 = (pq < 2) ? xa[m][bj][2 * pq] : xb[m][bj][2 * pq - 4]; h1 = (pq < 2) ? xa[m][bj][2 * pq + 1] : xb[m][bj][2 * pq - 3]; }
;                         else { const unsigned a = va[m][bj][pq]; const int bw = (int)vb[m][bj][pq >> 1]; const hf32x2 lp = (pq & 1) ? __builtin_amdgcn_cvt_pk_f32_fp8(bw, true) : __builtin_amdgcn_cvt_pk_f32_fp8(bw, false);
;                             h0 = __uint_as_float(a << 16) + lp.x * 0.00390625f; h1 = __uint_as_float(a & 0xffff0000u) + lp.y * 0.00390625f; }
;                         const float o0 = h0 + acc[ai][bj][mh + m][pq >> 1][(2 * pq) & 3] * rs1, o1 = h1 + acc[ai][bj][mh + m][pq >> 1][(2 * pq + 1) & 3] * rs1;
;                         sq += o0 * o0 + o1 * o1;
;                         const unsigned hi = cvt_pk_bf16(o0, o1);
;                         hw[pq] = hi;
;                         const float r0 = __builtin_amdgcn_fmed3f((o0 - __uint_as_float(hi << 16)) * 256.0f, -448.0f, 448.0f), r1 = __builtin_amdgcn_fmed3f((o1 - __uint_as_float(hi & 0xffff0000u)) * 256.0f, -448.0f, 448.0f);
;                         lw[pq >> 1] = (pq & 1) ? __builtin_amdgcn_cvt_pk_fp8_f32(r0, r1, lw[pq >> 1], true) : __builtin_amdgcn_cvt_pk_fp8_f32(r0, r1, lw[pq >> 1], false);
;                     }
;                     *(u32x4*)(Hb + idx) = (u32x4){hw[0], hw[1], hw[2], hw[3]}; *(u32x2*)(Hl + idx) = (u32x2){(unsigned)lw[0], (unsigned)lw[1]}; }
;                 sq += __shfl_xor(sq, 16); sq += __shfl_xor(sq, 32); if (fq == 0) ss[(size_t)row * 32 + u.pn * 4 + wc] = sq; }
	v_add_f32_e32 v90, v139, v136
	v_add_f32_e32 v136, v138, v90
	v_pk_mul_f32 v[90:91], v[96:97], v[178:179]
	s_nop 0
	v_add_f32_e32 v91, v91, v112
	v_add_f32_e32 v90, v90, v91
	v_mul_f32_e32 v91, v90, v90
	v_fmac_f32_e32 v91, v136, v136
	v_add_f32_e32 v97, v111, v91
	v_cvt_pk_bf16_f32 v96, v136, v90
	v_mov_b32_e32 v111, v1
	v_and_b32_e32 v91, 0xffff0000, v96
	v_sub_f32_e32 v90, v90, v91
	v_lshlrev_b32_e32 v91, 16, v96
	v_sub_f32_e32 v91, v136, v91
	v_mul_f32_e32 v90, 0x43800000, v90
	v_mul_f32_e32 v91, 0x43800000, v91
	v_med3_f32 v90, v90, s68, v235
	v_med3_f32 v91, v91, s68, v235
	v_cvt_pk_fp8_f32 v111, v91, v90
	v_cvt_pk_f32_fp8_sdwa v[90:91], v137 src0_sel:WORD_1
	v_lshlrev_b32_e32 v136, 16, v113
	v_and_b32_e32 v137, 0xffff0000, v113
	v_mov_b32_e32 v112, v92
	v_mov_b32_e32 v113, v90
	v_pk_mul_f32 v[112:113], v[112:113], v[178:179]
	s_nop 0
	v_add_f32_e32 v90, v113, v136
	v_add_f32_e32 v92, v112, v90
	v_mov_b32_e32 v90, v93
	v_pk_mul_f32 v[90:91], v[90:91], v[178:179]
	s_nop 0
	v_add_f32_e32 v91, v91, v137
	v_add_f32_e32 v90, v90, v91
	v_mul_f32_e32 v91, v90, v90
	v_fmac_f32_e32 v91, v92, v92
	v_add_f32_e32 v112, v97, v91
	v_cvt_pk_bf16_f32 v97, v92, v90
	s_nop 0
	v_lshlrev_b32_e32 v91, 16, v97
	v_sub_f32_e32 v91, v92, v91
	v_and_b32_e32 v92, 0xffff0000, v97
	v_sub_f32_e32 v90, v90, v92
	v_mul_f32_e32 v91, 0x43800000, v91
	v_mul_f32_e32 v90, 0x43800000, v90
	v_med3_f32 v91, v91, s68, v235
	v_med3_f32 v90, v90, s68, v235
	v_cvt_pk_fp8_f32 v111, v91, v90 op_sel:[0,0,1]
	s_waitcnt vmcnt(4)
	v_cvt_pk_f32_fp8_e32 v[90:91], v130
	v_mov_b32_e32 v92, v86
	global_store_dwordx4 v[132:133], v[94:97], off sc1
	global_store_dwordx2 v[134:135], v[110:111], off
	v_mov_b32_e32 v93, v90
	v_lshlrev_b32_e32 v94, 16, v106
	v_pk_mul_f32 v[92:93], v[92:93], v[178:179]
	v_mov_b32_e32 v90, v87
	v_add_f32_e32 v86, v93, v94
	v_and_b32_e32 v95, 0xffff0000, v106
	v_add_f32_e32 v92, v92, v86
	v_pk_mul_f32 v[86:87], v[90:91], v[178:179]
	v_mov_b32_e32 v94, v88
	v_add_f32_e32 v87, v87, v95
	v_add_f32_e32 v87, v86, v87
	v_mul_f32_e32 v86, v87, v87
	v_fmac_f32_e32 v86, v92, v92
	v_add_f32_e32 v91, v112, v86
	v_cvt_pk_bf16_f32 v86, v92, v87
	v_and_b32_e32 v96, 0xffff0000, v107
	v_and_b32_e32 v90, 0xffff0000, v86
	v_sub_f32_e32 v87, v87, v90
	v_lshlrev_b32_e32 v90, 16, v86
	v_sub_f32_e32 v90, v92, v90
	v_mul_f32_e32 v87, 0x43800000, v87
	v_mul_f32_e32 v90, 0x43800000, v90
	v_med3_f32 v87, v87, s68, v235
	v_med3_f32 v92, v90, s68, v235
	v_mov_b32_e32 v90, v1
	v_cvt_pk_fp8_f32 v90, v92, v87
	v_cvt_pk_f32_fp8_sdwa v[92:93], v130 src0_sel:WORD_1
	v_lshlrev_b32_e32 v87, 16, v107
	v_mov_b32_e32 v95, v92
	v_pk_mul_f32 v[94:95], v[94:95], v[178:179]
	v_mov_b32_e32 v92, v89
	v_add_f32_e32 v87, v95, v87
	v_pk_mul_f32 v[88:89], v[92:93], v[178:179]
	v_add_f32_e32 v94, v94, v87
	v_add_f32_e32 v87, v89, v96
	v_add_f32_e32 v88, v88, v87
	v_mul_f32_e32 v87, v88, v88
	v_fmac_f32_e32 v87, v94, v94
	v_add_f32_e32 v91, v91, v87
	v_cvt_pk_bf16_f32 v87, v94, v88
	v_and_b32_e32 v95, 0xffff0000, v108
	v_lshlrev_b32_e32 v89, 16, v87
	v_and_b32_e32 v92, 0xffff0000, v87
	v_sub_f32_e32 v89, v94, v89
	v_sub_f32_e32 v88, v88, v92
	v_mul_f32_e32 v89, 0x43800000, v89
	v_mul_f32_e32 v88, 0x43800000, v88
	v_med3_f32 v89, v89, s68, v235
	v_med3_f32 v88, v88, s68, v235
	v_cvt_pk_fp8_f32 v90, v89, v88 op_sel:[0,0,1]
	v_cvt_pk_f32_fp8_e32 v[88:89], v131
	v_mov_b32_e32 v92, v82
	v_lshlrev_b32_e32 v94, 16, v108
	v_mov_b32_e32 v93, v88
	v_pk_mul_f32 v[92:93], v[92:93], v[178:179]
	v_mov_b32_e32 v88, v83
	v_add_f32_e32 v82, v93, v94
	v_add_f32_e32 v92, v92, v82
	v_pk_mul_f32 v[82:83], v[88:89], v[178:179]
	v_lshlrev_b32_e32 v94, 16, v109
	v_add_f32_e32 v83, v83, v95
	v_add_f32_e32 v82, v82, v83
	v_mul_f32_e32 v83, v82, v82
	v_fmac_f32_e32 v83, v92, v92
	v_add_f32_e32 v89, v91, v83
	v_cvt_pk_bf16_f32 v88, v92, v82
	v_mov_b32_e32 v91, v1
	v_and_b32_e32 v83, 0xffff0000, v88
	v_sub_f32_e32 v82, v82, v83
	v_lshlrev_b32_e32 v83, 16, v88
	v_sub_f32_e32 v83, v92, v83
	v_mul_f32_e32 v82, 0x43800000, v82
	v_mul_f32_e32 v83, 0x43800000, v83
	v_med3_f32 v82, v82, s68, v235
	v_med3_f32 v83, v83, s68, v235
	v_cvt_pk_fp8_f32 v91, v83, v82
	v_cvt_pk_f32_fp8_sdwa v[82:83], v131 src0_sel:WORD_1
	v_mov_b32_e32 v92, v84
	v_and_b32_e32 v95, 0xffff0000, v109
	v_mov_b32_e32 v93, v82
	v_pk_mul_f32 v[92:93], v[92:93], v[178:179]
	s_nop 0
	v_add_f32_e32 v82, v93, v94
	v_add_f32_e32 v84, v92, v82
	v_mov_b32_e32 v82, v85
	v_pk_mul_f32 v[82:83], v[82:83], v[178:179]
	s_nop 0
	v_add_f32_e32 v83, v83, v95
	v_add_f32_e32 v82, v82, v83
	v_mul_f32_e32 v83, v82, v82
	v_fmac_f32_e32 v83, v84, v84
	v_add_f32_e32 v83, v89, v83
	v_cvt_pk_bf16_f32 v89, v84, v82
	s_nop 0
	v_lshlrev_b32_e32 v85, 16, v89
	v_sub_f32_e32 v84, v84, v85
	v_and_b32_e32 v85, 0xffff0000, v89
	v_sub_f32_e32 v82, v82, v85
	v_mul_f32_e32 v84, 0x43800000, v84
	v_mul_f32_e32 v82, 0x43800000, v82
	v_med3_f32 v84, v84, s68, v235
	v_med3_f32 v82, v82, s68, v235
	v_cvt_pk_fp8_f32 v91, v84, v82 op_sel:[0,0,1]
	ds_bpermute_b32 v82, v240, v83
	global_store_dwordx4 v[126:127], v[86:89], off sc1
	global_store_dwordx2 v[128:129], v[90:91], off
	s_waitcnt lgkmcnt(0)
	v_add_f32_e32 v82, v83, v82
	ds_bpermute_b32 v83, v239, v82
	s_and_saveexec_b64 s[2:3], s[38:39]
	s_cbranch_execz .LBB0_1431
	s_lshl_b32 s20, s8, 2
	s_waitcnt lgkmcnt(0)
	v_add_f32_e32 v84, v82, v83
	s_ashr_i32 s21, s20, 31
	v_lshl_add_u64 v[82:83], s[44:45], 0, v[188:189]
	v_lshl_add_u64 v[82:83], s[20:21], 2, v[82:83]
	s_lshl_b32 s18, s36, 2
	v_lshl_add_u64 v[82:83], v[82:83], 0, s[18:19]
	global_store_dword v[82:83], v84, off
;     __device__ __forceinline__ void core(const f32x4 (&acc)[2][2][4][2], const Unit& u, int wr, int wc, int fr, int fq, const float (&rsc)[2][4]) const {
;     ...
;                 for (int bj = 0; bj < 2; ++bj) { const size_t idx = (size_t)(row0 + ai * HALF + (mh + m) * 16) * D + col0 + bj * HALF;
;                     if (F32IN) { xa[m][bj] = *(const f32x4*)(Xin + idx); xb[m][bj] = *(const f32x4*)(Xin + idx + 4); }
;                     else { va[m][bj] = *(const u32x4*)(Hb + idx); vb[m][bj] = *(const u32x2*)(Hl + idx); } }
; #pragma unroll
;             for (int m = 0; m < MB; ++m) { const int row = row0 + ai * HALF + (mh + m) * 16; float sq = 0.f;
;                 const float rs1 = rsc[ai][mh + m];
; #pragma unroll
;                 for (int bj = 0; bj < 2; ++bj) { const size_t idx = (size_t)row * D + col0 + bj * HALF;
;                     unsigned hw[4]; int lw[2] = {0, 0};
; #pragma unroll
;                     for (int pq = 0; pq < 4; ++pq) {
;                         float h0, h1;
;                         if (F32IN) { h0 = (pq < 2) ? xa[m][bj][2 * pq] : xb[m][bj][2 * pq - 4]; h1 = (pq < 2) ? xa[m][bj][2 * pq + 1] : xb[m][bj][2 * pq - 3]; }
;                         else { const unsigned a = va[m][bj][pq]; const int bw = (int)vb[m][bj][pq >> 1]; const hf32x2 lp = (pq & 1) ? __builtin_amdgcn_cvt_pk_f32_fp8(bw, true) : __builtin_amdgcn_cvt_pk_f32_fp8(bw, false);
;                             h0 = __uint_as_float(a << 16) + lp.x * 0.00390625f; h1 = __uint_as_float(a & 0xffff0000u) + lp.y * 0.00390625f; }
;                         const float o0 = h0 + acc[ai][bj][mh + m][pq >> 1][(2 * pq) & 3] * rs1, o1 = h1 + acc[ai][bj][mh + m][pq >> 1][(2 * pq + 1) & 3] * rs1;
;                         sq += o0 * o0 + o1 * o1;
;                         const unsigned hi = cvt_pk_bf16(o0, o1);
;                         hw[pq] = hi;
;                         const float r0 = __builtin_amdgcn_fmed3f((o0 - __uint_as_float(hi << 16)) * 256.0f, -448.0f, 448.0f), r1 = __builtin_amdgcn_fmed3f((o1 - __uint_as_float(hi & 0xffff0000u)) * 256.0f, -448.0f, 448.0f);
;                         lw[pq >> 1] = (pq & 1) ? __builtin_amdgcn_cvt_pk_fp8_f32(r0, r1, lw[pq >> 1], true) : __builtin_amdgcn_cvt_pk_fp8_f32(r0, r1, lw[pq >> 1], false);
;                     }
.LBB0_1431:
	s_or_b64 exec, exec, s[2:3]
	v_add_f32_e32 v82, v249, v250
	v_fmamk_f32 v82, v82, 0x3a000000, v223
	s_waitcnt lgkmcnt(0)
	v_div_scale_f32 v83, s[2:3], v82, v82, 1.0
	v_rcp_f32_e32 v84, v83
	v_div_scale_f32 v85, vcc, 1.0, v82, 1.0
	s_waitcnt vmcnt(7)
	v_and_b32_e32 v88, 0xffff0000, v103
	v_fma_f32 v86, -v83, v84, 1.0
	v_fmac_f32_e32 v84, v86, v84
	v_mul_f32_e32 v86, v85, v84
	v_fma_f32 v87, -v83, v86, v85
	v_fmac_f32_e32 v86, v87, v84
	v_fma_f32 v83, -v83, v86, v85
	v_div_fmas_f32 v83, v83, v84, v86
	v_div_fixup_f32 v178, v83, v82, 1.0
	s_waitcnt vmcnt(6)
	v_cvt_pk_f32_fp8_e32 v[82:83], v124
	v_mov_b32_e32 v84, v78
	v_lshlrev_b32_e32 v86, 16, v102
	v_and_b32_e32 v87, 0xffff0000, v102
	v_mov_b32_e32 v85, v82
	v_pk_mul_f32 v[84:85], v[84:85], v[178:179]
	v_mov_b32_e32 v82, v79
	v_add_f32_e32 v78, v85, v86
	v_add_f32_e32 v84, v84, v78
	v_pk_mul_f32 v[78:79], v[82:83], v[178:179]
	v_mov_b32_e32 v86, v80
	v_add_f32_e32 v79, v79, v87
	v_add_f32_e32 v79, v78, v79
	v_cvt_pk_bf16_f32 v78, v84, v79
	v_mul_f32_e32 v83, v79, v79
	v_and_b32_e32 v82, 0xffff0000, v78
	v_sub_f32_e32 v79, v79, v82
	v_lshlrev_b32_e32 v82, 16, v78
	v_sub_f32_e32 v82, v84, v82
	v_mul_f32_e32 v79, 0x43800000, v79
	v_mul_f32_e32 v82, 0x43800000, v82
	v_fmac_f32_e32 v83, v84, v84
	v_med3_f32 v79, v79, s68, v235
	v_med3_f32 v84, v82, s68, v235
	v_mov_b32_e32 v82, v1
	v_cvt_pk_fp8_f32 v82, v84, v79
	v_cvt_pk_f32_fp8_sdwa v[84:85], v124 src0_sel:WORD_1
	v_lshlrev_b32_e32 v79, 16, v103
	v_mov_b32_e32 v87, v84
	v_pk_mul_f32 v[86:87], v[86:87], v[178:179]
	v_mov_b32_e32 v84, v81
	v_add_f32_e32 v79, v87, v79
	v_pk_mul_f32 v[80:81], v[84:85], v[178:179]
	v_add_f32_e32 v86, v86, v79
	v_add_f32_e32 v79, v81, v88
	v_add_f32_e32 v80, v80, v79
	v_mul_f32_e32 v79, v80, v80
	v_fmac_f32_e32 v79, v86, v86
	v_add_f32_e32 v83, v83, v79
	v_cvt_pk_bf16_f32 v79, v86, v80
	v_and_b32_e32 v87, 0xffff0000, v104
	v_lshlrev_b32_e32 v81, 16, v79
	v_and_b32_e32 v84, 0xffff0000, v79
	v_sub_f32_e32 v81, v86, v81
	v_sub_f32_e32 v80, v80, v84
	v_mul_f32_e32 v81, 0x43800000, v81
	v_mul_f32_e32 v80, 0x43800000, v80
	v_med3_f32 v81, v81, s68, v235
	v_med3_f32 v80, v80, s68, v235
	v_cvt_pk_fp8_f32 v82, v81, v80 op_sel:[0,0,1]
	v_cvt_pk_f32_fp8_e32 v[80:81], v125
	v_mov_b32_e32 v84, v74
	v_lshlrev_b32_e32 v86, 16, v104
	v_mov_b32_e32 v85, v80
	v_pk_mul_f32 v[84:85], v[84:85], v[178:179]
	v_mov_b32_e32 v80, v75
	v_add_f32_e32 v74, v85, v86
	v_add_f32_e32 v84, v84, v74
	v_pk_mul_f32 v[74:75], v[80:81], v[178:179]
	v_lshlrev_b32_e32 v81, 16, v105
	v_add_f32_e32 v75, v75, v87
	v_add_f32_e32 v74, v74, v75
	v_mul_f32_e32 v75, v74, v74
	v_fmac_f32_e32 v75, v84, v84
	v_add_f32_e32 v86, v83, v75
	v_cvt_pk_bf16_f32 v80, v84, v74
	v_mov_b32_e32 v83, v1
	v_and_b32_e32 v75, 0xffff0000, v80
	v_sub_f32_e32 v74, v74, v75
	v_lshlrev_b32_e32 v75, 16, v80
	v_sub_f32_e32 v75, v84, v75
	v_mul_f32_e32 v74, 0x43800000, v74
	v_mul_f32_e32 v75, 0x43800000, v75
	v_med3_f32 v74, v74, s68, v235
	v_med3_f32 v75, v75, s68, v235
	v_cvt_pk_fp8_f32 v83, v75, v74
	v_cvt_pk_f32_fp8_sdwa v[74:75], v125 src0_sel:WORD_1
	v_mov_b32_e32 v84, v76
	v_and_b32_e32 v87, 0xffff0000, v105
	v_mov_b32_e32 v85, v74
	v_pk_mul_f32 v[84:85], v[84:85], v[178:179]
	s_nop 0
	v_add_f32_e32 v74, v85, v81
	v_add_f32_e32 v76, v84, v74
	v_mov_b32_e32 v74, v77
	v_pk_mul_f32 v[74:75], v[74:75], v[178:179]
	s_nop 0
	v_add_f32_e32 v75, v75, v87
	v_add_f32_e32 v74, v74, v75
	v_cvt_pk_bf16_f32 v81, v76, v74
	v_mul_f32_e32 v75, v74, v74
	v_lshlrev_b32_e32 v77, 16, v81
	v_and_b32_e32 v84, 0xffff0000, v81
	v_sub_f32_e32 v77, v76, v77
	v_sub_f32_e32 v74, v74, v84
	v_mul_f32_e32 v77, 0x43800000, v77
	v_mul_f32_e32 v74, 0x43800000, v74
	v_med3_f32 v77, v77, s68, v235
	v_med3_f32 v74, v74, s68, v235
	v_fmac_f32_e32 v75, v76, v76
	v_cvt_pk_fp8_f32 v83, v77, v74 op_sel:[0,0,1]
	v_add_f32_e32 v84, v86, v75
	s_waitcnt vmcnt(4)
	v_cvt_pk_f32_fp8_e32 v[74:75], v118
	v_mov_b32_e32 v76, v70
	global_store_dwordx4 v[120:121], v[78:81], off sc1
	global_store_dwordx2 v[122:123], v[82:83], off
	v_mov_b32_e32 v77, v74
	v_lshlrev_b32_e32 v78, 16, v98
	v_pk_mul_f32 v[76:77], v[76:77], v[178:179]
	v_mov_b32_e32 v74, v71
	v_add_f32_e32 v70, v77, v78
	v_and_b32_e32 v79, 0xffff0000, v98
	v_add_f32_e32 v76, v76, v70
	v_pk_mul_f32 v[70:71], v[74:75], v[178:179]
	v_mov_b32_e32 v78, v72
	v_add_f32_e32 v71, v71, v79
	v_add_f32_e32 v71, v70, v71
	v_mul_f32_e32 v70, v71, v71
	v_fmac_f32_e32 v70, v76, v76
	v_add_f32_e32 v75, v84, v70
	v_cvt_pk_bf16_f32 v70, v76, v71
	v_and_b32_e32 v80, 0xffff0000, v99
	v_and_b32_e32 v74, 0xffff0000, v70
	v_sub_f32_e32 v71, v71, v74
	v_lshlrev_b32_e32 v74, 16, v70
	v_sub_f32_e32 v74, v76, v74
	v_mul_f32_e32 v71, 0x43800000, v71
	v_mul_f32_e32 v74, 0x43800000, v74
	v_med3_f32 v71, v71, s68, v235
	v_med3_f32 v76, v74, s68, v235
	v_mov_b32_e32 v74, v1
	v_cvt_pk_fp8_f32 v74, v76, v71
	v_cvt_pk_f32_fp8_sdwa v[76:77], v118 src0_sel:WORD_1
	v_lshlrev_b32_e32 v71, 16, v99
	v_mov_b32_e32 v79, v76
	v_pk_mul_f32 v[78:79], v[78:79], v[178:179]
	v_mov_b32_e32 v76, v73
	v_add_f32_e32 v71, v79, v71
	v_pk_mul_f32 v[72:73], v[76:77], v[178:179]
	v_add_f32_e32 v78, v78, v71
	v_add_f32_e32 v71, v73, v80
	v_add_f32_e32 v72, v72, v71
	v_mul_f32_e32 v71, v72, v72
	v_fmac_f32_e32 v71, v78, v78
	v_add_f32_e32 v75, v75, v71
	v_cvt_pk_bf16_f32 v71, v78, v72
	v_and_b32_e32 v79, 0xffff0000, v100
	v_lshlrev_b32_e32 v73, 16, v71
	v_and_b32_e32 v76, 0xffff0000, v71
	v_sub_f32_e32 v73, v78, v73
	v_sub_f32_e32 v72, v72, v76
	v_mul_f32_e32 v73, 0x43800000, v73
	v_mul_f32_e32 v72, 0x43800000, v72
	v_med3_f32 v73, v73, s68, v235
	v_med3_f32 v72, v72, s68, v235
	v_cvt_pk_fp8_f32 v74, v73, v72 op_sel:[0,0,1]
;     __device__ __forceinline__ void core(const f32x4 (&acc)[2][2][4][2], const Unit& u, int wr, int wc, int fr, int fq, const float (&rsc)[2][4]) const {
;     ...
;                 for (int bj = 0; bj < 2; ++bj) { const size_t idx = (size_t)(row0 + ai * HALF + (mh + m) * 16) * D + col0 + bj * HALF;
;                     if (F32IN) { xa[m][bj] = *(const f32x4*)(Xin + idx); xb[m][bj] = *(const f32x4*)(Xin + idx + 4); }
;                     else { va[m][bj] = *(const u32x4*)(Hb + idx); vb[m][bj] = *(const u32x2*)(Hl + idx); } }
; #pragma unroll
;             for (int m = 0; m < MB; ++m) { const int row = row0 + ai * HALF + (mh + m) * 16; float sq = 0.f;
;                 const float rs1 = rsc[ai][mh + m];
; #pragma unroll
;                 for (int bj = 0; bj < 2; ++bj) { const size_t idx = (size_t)row * D + col0 + bj * HALF;
;                     unsigned hw[4]; int lw[2] = {0, 0};
; #pragma unroll
;                     for (int pq = 0; pq < 4; ++pq) {
;                         float h0, h1;
;                         if (F32IN) { h0 = (pq < 2) ? xa[m][bj][2 * pq] : xb[m][bj][2 * pq - 4]; h1 = (pq < 2) ? xa[m][bj][2 * pq + 1] : xb[m][bj][2 * pq - 3]; }
;                         else { const unsigned a = va[m][bj][pq]; const int bw = (int)vb[m][bj][pq >> 1]; const hf32x2 lp = (pq & 1) ? __builtin_amdgcn_cvt_pk_f32_fp8(bw, true) : __builtin_amdgcn_cvt_pk_f32_fp8(bw, false);
;                             h0 = __uint_as_float(a << 16) + lp.x * 0.00390625f; h1 = __uint_as_float(a & 0xffff0000u) + lp.y * 0.00390625f; }
;                         const float o0 = h0 + acc[ai][bj][mh + m][pq >> 1][(2 * pq) & 3] * rs1, o1 = h1 + acc[ai][bj][mh + m][pq >> 1][(2 * pq + 1) & 3] * rs1;
;                         sq += o0 * o0 + o1 * o1;
;                         const unsigned hi = cvt_pk_bf16(o0, o1);
;                         hw[pq] = hi;
;                         const float r0 = __builtin_amdgcn_fmed3f((o0 - __uint_as_float(hi << 16)) * 256.0f, -448.0f, 448.0f), r1 = __builtin_amdgcn_fmed3f((o1 - __uint_as_float(hi & 0xffff0000u)) * 256.0f, -448.0f, 448.0f);
;                         lw[pq >> 1] = (pq & 1) ? __builtin_amdgcn_cvt_pk_fp8_f32(r0, r1, lw[pq >> 1], true) : __builtin_amdgcn_cvt_pk_fp8_f32(r0, r1, lw[pq >> 1], false);
;                     }
	v_cvt_pk_f32_fp8_e32 v[72:73], v119
	v_mov_b32_e32 v76, v66
	v_lshlrev_b32_e32 v78, 16, v100
	v_mov_b32_e32 v77, v72
	v_pk_mul_f32 v[76:77], v[76:77], v[178:179]
	v_mov_b32_e32 v72, v67
	v_add_f32_e32 v66, v77, v78
	v_add_f32_e32 v76, v76, v66
	v_pk_mul_f32 v[66:67], v[72:73], v[178:179]
	v_lshlrev_b32_e32 v78, 16, v101
	v_add_f32_e32 v67, v67, v79
	v_add_f32_e32 v66, v66, v67
	v_mul_f32_e32 v67, v66, v66
	v_fmac_f32_e32 v67, v76, v76
	v_add_f32_e32 v73, v75, v67
	v_cvt_pk_bf16_f32 v72, v76, v66
	v_mov_b32_e32 v75, v1
	v_and_b32_e32 v67, 0xffff0000, v72
	v_sub_f32_e32 v66, v66, v67
	v_lshlrev_b32_e32 v67, 16, v72
	v_sub_f32_e32 v67, v76, v67
	v_mul_f32_e32 v66, 0x43800000, v66
	v_mul_f32_e32 v67, 0x43800000, v67
	v_med3_f32 v66, v66, s68, v235
	v_med3_f32 v67, v67, s68, v235
	v_cvt_pk_fp8_f32 v75, v67, v66
	v_cvt_pk_f32_fp8_sdwa v[66:67], v119 src0_sel:WORD_1
	v_mov_b32_e32 v76, v68
	v_and_b32_e32 v79, 0xffff0000, v101
	v_mov_b32_e32 v77, v66
	v_pk_mul_f32 v[76:77], v[76:77], v[178:179]
	s_nop 0
	v_add_f32_e32 v66, v77, v78
	v_add_f32_e32 v68, v76, v66
	v_mov_b32_e32 v66, v69
	v_pk_mul_f32 v[66:67], v[66:67], v[178:179]
	s_nop 0
	v_add_f32_e32 v67, v67, v79
	v_add_f32_e32 v66, v66, v67
	v_mul_f32_e32 v67, v66, v66
	v_fmac_f32_e32 v67, v68, v68
	v_add_f32_e32 v67, v73, v67
	v_cvt_pk_bf16_f32 v73, v68, v66
	ds_bpermute_b32 v76, v240, v67
	v_lshlrev_b32_e32 v69, 16, v73
	v_sub_f32_e32 v68, v68, v69
	v_and_b32_e32 v69, 0xffff0000, v73
	v_sub_f32_e32 v66, v66, v69
	v_mul_f32_e32 v68, 0x43800000, v68
	v_mul_f32_e32 v66, 0x43800000, v66
	v_med3_f32 v68, v68, s68, v235
	v_med3_f32 v66, v66, s68, v235
	v_cvt_pk_fp8_f32 v75, v68, v66 op_sel:[0,0,1]
	s_waitcnt lgkmcnt(0)
	v_add_f32_e32 v66, v67, v76
	ds_bpermute_b32 v67, v239, v66
	global_store_dwordx4 v[114:115], v[70:73], off sc1
	global_store_dwordx2 v[116:117], v[74:75], off
	s_and_saveexec_b64 s[2:3], s[38:39]
	s_cbranch_execz .LBB0_1433
	s_lshl_b32 s20, s8, 2
	s_waitcnt lgkmcnt(0)
	v_add_f32_e32 v68, v66, v67
	s_ashr_i32 s21, s20, 31
	v_lshl_add_u64 v[66:67], s[44:45], 0, v[176:177]
	v_lshl_add_u64 v[66:67], s[20:21], 2, v[66:67]
	s_lshl_b32 s18, s36, 2
	v_lshl_add_u64 v[66:67], v[66:67], 0, s[18:19]
	global_store_dword v[66:67], v68, off
.LBB0_1433:
	s_or_b64 exec, exec, s[2:3]
	v_add_f32_e32 v66, v247, v248
	v_fmamk_f32 v66, v66, 0x3a000000, v223
	s_waitcnt lgkmcnt(0)
	v_div_scale_f32 v67, s[2:3], v66, v66, 1.0
	v_rcp_f32_e32 v68, v67
	v_mov_b32_e32 v108, v62
	v_fma_f32 v69, -v67, v68, 1.0
	v_fmac_f32_e32 v68, v69, v68
	v_div_scale_f32 v69, vcc, 1.0, v66, 1.0
	v_mul_f32_e32 v70, v69, v68
	v_fma_f32 v71, -v67, v70, v69
	v_fmac_f32_e32 v70, v71, v68
	v_fma_f32 v67, -v67, v70, v69
	v_div_fmas_f32 v67, v67, v68, v70
	v_div_fixup_f32 v178, v67, v66, 1.0
	v_lshlrev_b64 v[66:67], 11, v[174:175]
	v_lshl_add_u64 v[66:67], v[66:67], 0, v[170:171]
	v_lshl_add_u64 v[100:101], v[66:67], 1, s[34:35]
	v_lshl_add_u64 v[102:103], s[42:43], 0, v[66:67]
	global_load_dwordx4 v[78:81], v[100:101], off
	global_load_dwordx2 v[104:105], v[102:103], off
	v_or_b32_e32 v66, 0x80, v66
	v_lshl_add_u64 v[94:95], v[66:67], 1, s[34:35]
	v_lshl_add_u64 v[96:97], s[42:43], 0, v[66:67]
	global_load_dwordx4 v[74:77], v[94:95], off
	global_load_dwordx2 v[98:99], v[96:97], off
	v_lshlrev_b64 v[66:67], 11, v[172:173]
	v_lshl_add_u64 v[84:85], v[66:67], 0, v[170:171]
	v_lshl_add_u64 v[88:89], v[84:85], 1, s[34:35]
	v_lshl_add_u64 v[90:91], s[42:43], 0, v[84:85]
	v_or_b32_e32 v84, 0x80, v84
	v_lshl_add_u64 v[82:83], v[84:85], 1, s[34:35]
	v_lshl_add_u64 v[84:85], s[42:43], 0, v[84:85]
	global_load_dwordx4 v[70:73], v[88:89], off
	global_load_dwordx2 v[92:93], v[90:91], off
	global_load_dwordx4 v[66:69], v[82:83], off
	global_load_dwordx2 v[86:87], v[84:85], off
	s_waitcnt vmcnt(7)
	v_lshlrev_b32_e32 v110, 16, v78
	s_waitcnt vmcnt(6)
	v_cvt_pk_f32_fp8_e32 v[106:107], v104
	v_and_b32_e32 v78, 0xffff0000, v78
	v_mov_b32_e32 v109, v106
	v_pk_mul_f32 v[108:109], v[108:109], v[178:179]
	v_mov_b32_e32 v106, v63
	v_add_f32_e32 v62, v109, v110
	v_add_f32_e32 v108, v108, v62
	v_pk_mul_f32 v[62:63], v[106:107], v[178:179]
	s_nop 0
	v_add_f32_e32 v63, v63, v78
	v_add_f32_e32 v63, v62, v63
	v_cvt_pk_bf16_f32 v62, v108, v63
	v_mul_f32_e32 v110, v63, v63
	v_and_b32_e32 v78, 0xffff0000, v62
	v_sub_f32_e32 v63, v63, v78
	v_lshlrev_b32_e32 v78, 16, v62
	v_sub_f32_e32 v78, v108, v78
	v_mul_f32_e32 v63, 0x43800000, v63
	v_mul_f32_e32 v78, 0x43800000, v78
	v_med3_f32 v63, v63, s68, v235
	v_med3_f32 v106, v78, s68, v235
	v_mov_b32_e32 v78, v1
	v_cvt_pk_fp8_f32 v78, v106, v63
	v_cvt_pk_f32_fp8_sdwa v[106:107], v104 src0_sel:WORD_1
	v_fmac_f32_e32 v110, v108, v108
	v_mov_b32_e32 v108, v64
	v_lshlrev_b32_e32 v63, 16, v79
	v_mov_b32_e32 v109, v106
	v_pk_mul_f32 v[108:109], v[108:109], v[178:179]
	v_mov_b32_e32 v106, v65
	v_and_b32_e32 v79, 0xffff0000, v79
	v_add_f32_e32 v63, v109, v63
	v_pk_mul_f32 v[64:65], v[106:107], v[178:179]
	v_add_f32_e32 v104, v108, v63
	v_add_f32_e32 v63, v65, v79
	v_add_f32_e32 v64, v64, v63
	v_mul_f32_e32 v63, v64, v64
	v_fmac_f32_e32 v63, v104, v104
	v_add_f32_e32 v79, v110, v63
	v_cvt_pk_bf16_f32 v63, v104, v64
	v_mov_b32_e32 v106, v58
	v_lshlrev_b32_e32 v65, 16, v63
	v_sub_f32_e32 v65, v104, v65
	v_and_b32_e32 v104, 0xffff0000, v63
	v_sub_f32_e32 v64, v64, v104
	v_mul_f32_e32 v65, 0x43800000, v65
	v_mul_f32_e32 v64, 0x43800000, v64
	v_med3_f32 v65, v65, s68, v235
	v_med3_f32 v64, v64, s68, v235
	v_cvt_pk_fp8_f32 v78, v65, v64 op_sel:[0,0,1]
	v_cvt_pk_f32_fp8_e32 v[64:65], v105
	v_lshlrev_b32_e32 v104, 16, v80
	v_and_b32_e32 v80, 0xffff0000, v80
	v_mov_b32_e32 v107, v64
	v_pk_mul_f32 v[106:107], v[106:107], v[178:179]
;     __device__ __forceinline__ void core(const f32x4 (&acc)[2][2][4][2], const Unit& u, int wr, int wc, int fr, int fq, const float (&rsc)[2][4]) const {
;     ...
;                 for (int bj = 0; bj < 2; ++bj) { const size_t idx = (size_t)(row0 + ai * HALF + (mh + m) * 16) * D + col0 + bj * HALF;
;                     if (F32IN) { xa[m][bj] = *(const f32x4*)(Xin + idx); xb[m][bj] = *(const f32x4*)(Xin + idx + 4); }
;                     else { va[m][bj] = *(const u32x4*)(Hb + idx); vb[m][bj] = *(const u32x2*)(Hl + idx); } }
; #pragma unroll
;             for (int m = 0; m < MB; ++m) { const int row = row0 + ai * HALF + (mh + m) * 16; float sq = 0.f;
;                 const float rs1 = rsc[ai][mh + m];
; #pragma unroll
;                 for (int bj = 0; bj < 2; ++bj) { const size_t idx = (size_t)row * D + col0 + bj * HALF;
;                     unsigned hw[4]; int lw[2] = {0, 0};
; #pragma unroll
;                     for (int pq = 0; pq < 4; ++pq) {
;                         float h0, h1;
;                         if (F32IN) { h0 = (pq < 2) ? xa[m][bj][2 * pq] : xb[m][bj][2 * pq - 4]; h1 = (pq < 2) ? xa[m][bj][2 * pq + 1] : xb[m][bj][2 * pq - 3]; }
;                         else { const unsigned a = va[m][bj][pq]; const int bw = (int)vb[m][bj][pq >> 1]; const hf32x2 lp = (pq & 1) ? __builtin_amdgcn_cvt_pk_f32_fp8(bw, true) : __builtin_amdgcn_cvt_pk_f32_fp8(bw, false);
;                             h0 = __uint_as_float(a << 16) + lp.x * 0.00390625f; h1 = __uint_as_float(a & 0xffff0000u) + lp.y * 0.00390625f; }
;                         const float o0 = h0 + acc[ai][bj][mh + m][pq >> 1][(2 * pq) & 3] * rs1, o1 = h1 + acc[ai][bj][mh + m][pq >> 1][(2 * pq + 1) & 3] * rs1;
;                         sq += o0 * o0 + o1 * o1;
;                         const unsigned hi = cvt_pk_bf16(o0, o1);
;                         hw[pq] = hi;
;                         const float r0 = __builtin_amdgcn_fmed3f((o0 - __uint_as_float(hi << 16)) * 256.0f, -448.0f, 448.0f), r1 = __builtin_amdgcn_fmed3f((o1 - __uint_as_float(hi & 0xffff0000u)) * 256.0f, -448.0f, 448.0f);
;                         lw[pq >> 1] = (pq & 1) ? __builtin_amdgcn_cvt_pk_fp8_f32(r0, r1, lw[pq >> 1], true) : __builtin_amdgcn_cvt_pk_fp8_f32(r0, r1, lw[pq >> 1], false);
;                     }
	v_mov_b32_e32 v64, v59
	v_add_f32_e32 v58, v107, v104
	v_add_f32_e32 v104, v106, v58
	v_pk_mul_f32 v[58:59], v[64:65], v[178:179]
	s_nop 0
	v_add_f32_e32 v59, v59, v80
	v_add_f32_e32 v58, v58, v59
	v_mul_f32_e32 v59, v58, v58
	v_fmac_f32_e32 v59, v104, v104
	v_add_f32_e32 v65, v79, v59
	v_cvt_pk_bf16_f32 v64, v104, v58
	v_mov_b32_e32 v79, v1
	v_and_b32_e32 v59, 0xffff0000, v64
	v_sub_f32_e32 v58, v58, v59
	v_lshlrev_b32_e32 v59, 16, v64
	v_sub_f32_e32 v59, v104, v59
	v_mul_f32_e32 v58, 0x43800000, v58
	v_mul_f32_e32 v59, 0x43800000, v59
	v_med3_f32 v58, v58, s68, v235
	v_med3_f32 v59, v59, s68, v235
	v_cvt_pk_fp8_f32 v79, v59, v58
	v_cvt_pk_f32_fp8_sdwa v[58:59], v105 src0_sel:WORD_1
	v_lshlrev_b32_e32 v104, 16, v81
	v_and_b32_e32 v105, 0xffff0000, v81
	v_mov_b32_e32 v80, v60
	v_mov_b32_e32 v81, v58
	v_pk_mul_f32 v[80:81], v[80:81], v[178:179]
	s_nop 0
	v_add_f32_e32 v58, v81, v104
	v_add_f32_e32 v60, v80, v58
	v_mov_b32_e32 v58, v61
	v_pk_mul_f32 v[58:59], v[58:59], v[178:179]
	s_nop 0
	v_add_f32_e32 v59, v59, v105
	v_add_f32_e32 v58, v58, v59
	v_mul_f32_e32 v59, v58, v58
	v_fmac_f32_e32 v59, v60, v60
	v_add_f32_e32 v80, v65, v59
	v_cvt_pk_bf16_f32 v65, v60, v58
	s_nop 0
	v_lshlrev_b32_e32 v59, 16, v65
	v_sub_f32_e32 v59, v60, v59
	v_and_b32_e32 v60, 0xffff0000, v65
	v_sub_f32_e32 v58, v58, v60
	v_mul_f32_e32 v59, 0x43800000, v59
	v_mul_f32_e32 v58, 0x43800000, v58
	v_med3_f32 v59, v59, s68, v235
	v_med3_f32 v58, v58, s68, v235
	v_cvt_pk_fp8_f32 v79, v59, v58 op_sel:[0,0,1]
	s_waitcnt vmcnt(4)
	v_cvt_pk_f32_fp8_e32 v[58:59], v98
	v_mov_b32_e32 v60, v54
	global_store_dwordx4 v[100:101], v[62:65], off sc1
	global_store_dwordx2 v[102:103], v[78:79], off
	v_mov_b32_e32 v61, v58
	v_lshlrev_b32_e32 v62, 16, v74
	v_pk_mul_f32 v[60:61], v[60:61], v[178:179]
	v_mov_b32_e32 v58, v55
	v_add_f32_e32 v54, v61, v62
	v_and_b32_e32 v63, 0xffff0000, v74
	v_add_f32_e32 v60, v60, v54
	v_pk_mul_f32 v[54:55], v[58:59], v[178:179]
	v_mov_b32_e32 v62, v56
	v_add_f32_e32 v55, v55, v63
	v_add_f32_e32 v55, v54, v55
	v_mul_f32_e32 v54, v55, v55
	v_fmac_f32_e32 v54, v60, v60
	v_add_f32_e32 v59, v80, v54
	v_cvt_pk_bf16_f32 v54, v60, v55
	v_and_b32_e32 v64, 0xffff0000, v75
	v_and_b32_e32 v58, 0xffff0000, v54
	v_sub_f32_e32 v55, v55, v58
	v_lshlrev_b32_e32 v58, 16, v54
	v_sub_f32_e32 v58, v60, v58
	v_mul_f32_e32 v55, 0x43800000, v55
	v_mul_f32_e32 v58, 0x43800000, v58
	v_med3_f32 v55, v55, s68, v235
	v_med3_f32 v60, v58, s68, v235
	v_mov_b32_e32 v58, v1
	v_cvt_pk_fp8_f32 v58, v60, v55
	v_cvt_pk_f32_fp8_sdwa v[60:61], v98 src0_sel:WORD_1
	v_lshlrev_b32_e32 v55, 16, v75
	v_mov_b32_e32 v63, v60
	v_pk_mul_f32 v[62:63], v[62:63], v[178:179]
	v_mov_b32_e32 v60, v57
	v_add_f32_e32 v55, v63, v55
	v_pk_mul_f32 v[56:57], v[60:61], v[178:179]
	v_add_f32_e32 v62, v62, v55
	v_add_f32_e32 v55, v57, v64
	v_add_f32_e32 v56, v56, v55
	v_mul_f32_e32 v55, v56, v56
	v_fmac_f32_e32 v55, v62, v62
	v_add_f32_e32 v59, v59, v55
	v_cvt_pk_bf16_f32 v55, v62, v56
	v_and_b32_e32 v63, 0xffff0000, v76
	v_lshlrev_b32_e32 v57, 16, v55
	v_and_b32_e32 v60, 0xffff0000, v55
	v_sub_f32_e32 v57, v62, v57
	v_sub_f32_e32 v56, v56, v60
	v_mul_f32_e32 v57, 0x43800000, v57
	v_mul_f32_e32 v56, 0x43800000, v56
	v_med3_f32 v57, v57, s68, v235
	v_med3_f32 v56, v56, s68, v235
	v_cvt_pk_fp8_f32 v58, v57, v56 op_sel:[0,0,1]
	v_cvt_pk_f32_fp8_e32 v[56:57], v99
	v_mov_b32_e32 v60, v50
	v_lshlrev_b32_e32 v62, 16, v76
	v_mov_b32_e32 v61, v56
	v_pk_mul_f32 v[60:61], v[60:61], v[178:179]
	v_mov_b32_e32 v56, v51
	v_add_f32_e32 v50, v61, v62
	v_add_f32_e32 v60, v60, v50
	v_pk_mul_f32 v[50:51], v[56:57], v[178:179]
	v_lshlrev_b32_e32 v62, 16, v77
	v_add_f32_e32 v51, v51, v63
	v_add_f32_e32 v50, v50, v51
	v_mul_f32_e32 v51, v50, v50
	v_fmac_f32_e32 v51, v60, v60
	v_add_f32_e32 v57, v59, v51
	v_cvt_pk_bf16_f32 v56, v60, v50
	v_mov_b32_e32 v59, v1
	v_and_b32_e32 v51, 0xffff0000, v56
	v_sub_f32_e32 v50, v50, v51
	v_lshlrev_b32_e32 v51, 16, v56
	v_sub_f32_e32 v51, v60, v51
	v_mul_f32_e32 v50, 0x43800000, v50
	v_mul_f32_e32 v51, 0x43800000, v51
	v_med3_f32 v50, v50, s68, v235
	v_med3_f32 v51, v51, s68, v235
	v_cvt_pk_fp8_f32 v59, v51, v50
	v_cvt_pk_f32_fp8_sdwa v[50:51], v99 src0_sel:WORD_1
	v_mov_b32_e32 v60, v52
	v_and_b32_e32 v63, 0xffff0000, v77
	v_mov_b32_e32 v61, v50
	v_pk_mul_f32 v[60:61], v[60:61], v[178:179]
	s_nop 0
	v_add_f32_e32 v50, v61, v62
	v_add_f32_e32 v52, v60, v50
	v_mov_b32_e32 v50, v53
	v_pk_mul_f32 v[50:51], v[50:51], v[178:179]
	s_nop 0
	v_add_f32_e32 v51, v51, v63
	v_add_f32_e32 v50, v50, v51
	v_mul_f32_e32 v51, v50, v50
	v_fmac_f32_e32 v51, v52, v52
	v_add_f32_e32 v51, v57, v51
	v_cvt_pk_bf16_f32 v57, v52, v50
	s_nop 0
	v_lshlrev_b32_e32 v53, 16, v57
	v_sub_f32_e32 v52, v52, v53
	v_and_b32_e32 v53, 0xffff0000, v57
	v_sub_f32_e32 v50, v50, v53
	v_mul_f32_e32 v52, 0x43800000, v52
	v_mul_f32_e32 v50, 0x43800000, v50
	v_med3_f32 v52, v52, s68, v235
	v_med3_f32 v50, v50, s68, v235
	v_cvt_pk_fp8_f32 v59, v52, v50 op_sel:[0,0,1]
	ds_bpermute_b32 v50, v240, v51
	global_store_dwordx4 v[94:95], v[54:57], off sc1
	global_store_dwordx2 v[96:97], v[58:59], off
	s_waitcnt lgkmcnt(0)
	v_add_f32_e32 v50, v51, v50
	ds_bpermute_b32 v51, v239, v50
	s_and_saveexec_b64 s[2:3], s[38:39]
	s_cbranch_execz .LBB0_1435
	s_lshl_b32 s20, s8, 2
	s_waitcnt lgkmcnt(0)
	v_add_f32_e32 v52, v50, v51
	s_ashr_i32 s21, s20, 31
	v_lshl_add_u64 v[50:51], s[44:45], 0, v[168:169]
	v_lshl_add_u64 v[50:51], s[20:21], 2, v[50:51]
	s_lshl_b32 s18, s36, 2
	v_lshl_add_u64 v[50:51], v[50:51], 0, s[18:19]
	global_store_dword v[50:51], v52, off
;     __device__ __forceinline__ void core(const f32x4 (&acc)[2][2][4][2], const Unit& u, int wr, int wc, int fr, int fq, const float (&rsc)[2][4]) const {
;     ...
;                 for (int bj = 0; bj < 2; ++bj) { const size_t idx = (size_t)(row0 + ai * HALF + (mh + m) * 16) * D + col0 + bj * HALF;
;                     if (F32IN) { xa[m][bj] = *(const f32x4*)(Xin + idx); xb[m][bj] = *(const f32x4*)(Xin + idx + 4); }
;                     else { va[m][bj] = *(const u32x4*)(Hb + idx); vb[m][bj] = *(const u32x2*)(Hl + idx); } }
; #pragma unroll
;             for (int m = 0; m < MB; ++m) { const int row = row0 + ai * HALF + (mh + m) * 16; float sq = 0.f;
;                 const float rs1 = rsc[ai][mh + m];
; #pragma unroll
;                 for (int bj = 0; bj < 2; ++bj) { const size_t idx = (size_t)row * D + col0 + bj * HALF;
;                     unsigned hw[4]; int lw[2] = {0, 0};
; #pragma unroll
;                     for (int pq = 0; pq < 4; ++pq) {
;                         float h0, h1;
;                         if (F32IN) { h0 = (pq < 2) ? xa[m][bj][2 * pq] : xb[m][bj][2 * pq - 4]; h1 = (pq < 2) ? xa[m][bj][2 * pq + 1] : xb[m][bj][2 * pq - 3]; }
;                         else { const unsigned a = va[m][bj][pq]; const int bw = (int)vb[m][bj][pq >> 1]; const hf32x2 lp = (pq & 1) ? __builtin_amdgcn_cvt_pk_f32_fp8(bw, true) : __builtin_amdgcn_cvt_pk_f32_fp8(bw, false);
;                             h0 = __uint_as_float(a << 16) + lp.x * 0.00390625f; h1 = __uint_as_float(a & 0xffff0000u) + lp.y * 0.00390625f; }
;                         const float o0 = h0 + acc[ai][bj][mh + m][pq >> 1][(2 * pq) & 3] * rs1, o1 = h1 + acc[ai][bj][mh + m][pq >> 1][(2 * pq + 1) & 3] * rs1;
;                         sq += o0 * o0 + o1 * o1;
;                         const unsigned hi = cvt_pk_bf16(o0, o1);
;                         hw[pq] = hi;
;                         const float r0 = __builtin_amdgcn_fmed3f((o0 - __uint_as_float(hi << 16)) * 256.0f, -448.0f, 448.0f), r1 = __builtin_amdgcn_fmed3f((o1 - __uint_as_float(hi & 0xffff0000u)) * 256.0f, -448.0f, 448.0f);
;                         lw[pq >> 1] = (pq & 1) ? __builtin_amdgcn_cvt_pk_fp8_f32(r0, r1, lw[pq >> 1], true) : __builtin_amdgcn_cvt_pk_fp8_f32(r0, r1, lw[pq >> 1], false);
;                     }
.LBB0_1435:
	s_or_b64 exec, exec, s[2:3]
	v_add_f32_e32 v50, v245, v246
	v_fmamk_f32 v50, v50, 0x3a000000, v223
	s_waitcnt lgkmcnt(0)
	v_div_scale_f32 v51, s[2:3], v50, v50, 1.0
	v_rcp_f32_e32 v52, v51
	v_div_scale_f32 v53, vcc, 1.0, v50, 1.0
	s_waitcnt vmcnt(7)
	v_and_b32_e32 v56, 0xffff0000, v71
	v_fma_f32 v54, -v51, v52, 1.0
	v_fmac_f32_e32 v52, v54, v52
	v_mul_f32_e32 v54, v53, v52
	v_fma_f32 v55, -v51, v54, v53
	v_fmac_f32_e32 v54, v55, v52
	v_fma_f32 v51, -v51, v54, v53
	v_div_fmas_f32 v51, v51, v52, v54
	v_div_fixup_f32 v178, v51, v50, 1.0
	s_waitcnt vmcnt(6)
	v_cvt_pk_f32_fp8_e32 v[50:51], v92
	v_mov_b32_e32 v52, v46
	v_lshlrev_b32_e32 v54, 16, v70
	v_and_b32_e32 v55, 0xffff0000, v70
	v_mov_b32_e32 v53, v50
	v_pk_mul_f32 v[52:53], v[52:53], v[178:179]
	v_mov_b32_e32 v50, v47
	v_add_f32_e32 v46, v53, v54
	v_add_f32_e32 v52, v52, v46
	v_pk_mul_f32 v[46:47], v[50:51], v[178:179]
	v_mov_b32_e32 v54, v48
	v_add_f32_e32 v47, v47, v55
	v_add_f32_e32 v47, v46, v47
	v_cvt_pk_bf16_f32 v46, v52, v47
	v_mul_f32_e32 v51, v47, v47
	v_and_b32_e32 v50, 0xffff0000, v46
	v_sub_f32_e32 v47, v47, v50
	v_lshlrev_b32_e32 v50, 16, v46
	v_sub_f32_e32 v50, v52, v50
	v_mul_f32_e32 v47, 0x43800000, v47
	v_mul_f32_e32 v50, 0x43800000, v50
	v_fmac_f32_e32 v51, v52, v52
	v_med3_f32 v47, v47, s68, v235
	v_med3_f32 v52, v50, s68, v235
	v_mov_b32_e32 v50, v1
	v_cvt_pk_fp8_f32 v50, v52, v47
	v_cvt_pk_f32_fp8_sdwa v[52:53], v92 src0_sel:WORD_1
	v_lshlrev_b32_e32 v47, 16, v71
	v_mov_b32_e32 v55, v52
	v_pk_mul_f32 v[54:55], v[54:55], v[178:179]
	v_mov_b32_e32 v52, v49
	v_add_f32_e32 v47, v55, v47
	v_pk_mul_f32 v[48:49], v[52:53], v[178:179]
	v_add_f32_e32 v54, v54, v47
	v_add_f32_e32 v47, v49, v56
	v_add_f32_e32 v48, v48, v47
	v_mul_f32_e32 v47, v48, v48
	v_fmac_f32_e32 v47, v54, v54
	v_add_f32_e32 v51, v51, v47
	v_cvt_pk_bf16_f32 v47, v54, v48
	v_and_b32_e32 v55, 0xffff0000, v72
	v_lshlrev_b32_e32 v49, 16, v47
	v_and_b32_e32 v52, 0xffff0000, v47
	v_sub_f32_e32 v49, v54, v49
	v_sub_f32_e32 v48, v48, v52
	v_mul_f32_e32 v49, 0x43800000, v49
	v_mul_f32_e32 v48, 0x43800000, v48
	v_med3_f32 v49, v49, s68, v235
	v_med3_f32 v48, v48, s68, v235
	v_cvt_pk_fp8_f32 v50, v49, v48 op_sel:[0,0,1]
	v_cvt_pk_f32_fp8_e32 v[48:49], v93
	v_mov_b32_e32 v52, v42
	v_lshlrev_b32_e32 v54, 16, v72
	v_mov_b32_e32 v53, v48
	v_pk_mul_f32 v[52:53], v[52:53], v[178:179]
	v_mov_b32_e32 v48, v43
	v_add_f32_e32 v42, v53, v54
	v_add_f32_e32 v52, v52, v42
	v_pk_mul_f32 v[42:43], v[48:49], v[178:179]
	v_lshlrev_b32_e32 v49, 16, v73
	v_add_f32_e32 v43, v43, v55
	v_add_f32_e32 v42, v42, v43
	v_mul_f32_e32 v43, v42, v42
	v_fmac_f32_e32 v43, v52, v52
	v_add_f32_e32 v54, v51, v43
	v_cvt_pk_bf16_f32 v48, v52, v42
	v_mov_b32_e32 v51, v1
	v_and_b32_e32 v43, 0xffff0000, v48
	v_sub_f32_e32 v42, v42, v43
	v_lshlrev_b32_e32 v43, 16, v48
	v_sub_f32_e32 v43, v52, v43
	v_mul_f32_e32 v42, 0x43800000, v42
	v_mul_f32_e32 v43, 0x43800000, v43
	v_med3_f32 v42, v42, s68, v235
	v_med3_f32 v43, v43, s68, v235
	v_cvt_pk_fp8_f32 v51, v43, v42
	v_cvt_pk_f32_fp8_sdwa v[42:43], v93 src0_sel:WORD_1
	v_mov_b32_e32 v52, v44
	v_and_b32_e32 v55, 0xffff0000, v73
	v_mov_b32_e32 v53, v42
	v_pk_mul_f32 v[52:53], v[52:53], v[178:179]
	s_nop 0
	v_add_f32_e32 v42, v53, v49
	v_add_f32_e32 v44, v52, v42
	v_mov_b32_e32 v42, v45
	v_pk_mul_f32 v[42:43], v[42:43], v[178:179]
	s_nop 0
	v_add_f32_e32 v43, v43, v55
	v_add_f32_e32 v42, v42, v43
	v_cvt_pk_bf16_f32 v49, v44, v42
	v_mul_f32_e32 v43, v42, v42
	v_lshlrev_b32_e32 v45, 16, v49
	v_and_b32_e32 v52, 0xffff0000, v49
	v_sub_f32_e32 v45, v44, v45
	v_sub_f32_e32 v42, v42, v52
	v_mul_f32_e32 v45, 0x43800000, v45
	v_mul_f32_e32 v42, 0x43800000, v42
	v_med3_f32 v45, v45, s68, v235
	v_med3_f32 v42, v42, s68, v235
	v_fmac_f32_e32 v43, v44, v44
	v_cvt_pk_fp8_f32 v51, v45, v42 op_sel:[0,0,1]
	v_add_f32_e32 v52, v54, v43
	s_waitcnt vmcnt(4)
	v_cvt_pk_f32_fp8_e32 v[42:43], v86
	v_mov_b32_e32 v44, v38
	global_store_dwordx4 v[88:89], v[46:49], off sc1
	global_store_dwordx2 v[90:91], v[50:51], off
	v_mov_b32_e32 v45, v42
	v_lshlrev_b32_e32 v46, 16, v66
	v_pk_mul_f32 v[44:45], v[44:45], v[178:179]
	v_mov_b32_e32 v42, v39
	v_add_f32_e32 v38, v45, v46
	v_and_b32_e32 v47, 0xffff0000, v66
	v_add_f32_e32 v44, v44, v38
	v_pk_mul_f32 v[38:39], v[42:43], v[178:179]
	v_mov_b32_e32 v46, v40
	v_add_f32_e32 v39, v39, v47
	v_add_f32_e32 v39, v38, v39
	v_mul_f32_e32 v38, v39, v39
	v_fmac_f32_e32 v38, v44, v44
	v_add_f32_e32 v43, v52, v38
	v_cvt_pk_bf16_f32 v38, v44, v39
	v_and_b32_e32 v48, 0xffff0000, v67
	v_and_b32_e32 v42, 0xffff0000, v38
	v_sub_f32_e32 v39, v39, v42
	v_lshlrev_b32_e32 v42, 16, v38
	v_sub_f32_e32 v42, v44, v42
	v_mul_f32_e32 v39, 0x43800000, v39
	v_mul_f32_e32 v42, 0x43800000, v42
	v_med3_f32 v39, v39, s68, v235
	v_med3_f32 v44, v42, s68, v235
	v_mov_b32_e32 v42, v1
	v_cvt_pk_fp8_f32 v42, v44, v39
	v_cvt_pk_f32_fp8_sdwa v[44:45], v86 src0_sel:WORD_1
	v_lshlrev_b32_e32 v39, 16, v67
	v_mov_b32_e32 v47, v44
	v_pk_mul_f32 v[46:47], v[46:47], v[178:179]
	v_mov_b32_e32 v44, v41
	v_add_f32_e32 v39, v47, v39
	v_pk_mul_f32 v[40:41], v[44:45], v[178:179]
	v_add_f32_e32 v46, v46, v39
	v_add_f32_e32 v39, v41, v48
	v_add_f32_e32 v40, v40, v39
	v_mul_f32_e32 v39, v40, v40
	v_fmac_f32_e32 v39, v46, v46
	v_add_f32_e32 v43, v43, v39
	v_cvt_pk_bf16_f32 v39, v46, v40
	v_and_b32_e32 v47, 0xffff0000, v68
	v_lshlrev_b32_e32 v41, 16, v39
	v_and_b32_e32 v44, 0xffff0000, v39
	v_sub_f32_e32 v41, v46, v41
	v_sub_f32_e32 v40, v40, v44
	v_mul_f32_e32 v41, 0x43800000, v41
	v_mul_f32_e32 v40, 0x43800000, v40
	v_med3_f32 v41, v41, s68, v235
	v_med3_f32 v40, v40, s68, v235
	v_cvt_pk_fp8_f32 v42, v41, v40 op_sel:[0,0,1]
;     __device__ __forceinline__ void core(const f32x4 (&acc)[2][2][4][2], const Unit& u, int wr, int wc, int fr, int fq, const float (&rsc)[2][4]) const {
;     ...
;                 for (int bj = 0; bj < 2; ++bj) { const size_t idx = (size_t)(row0 + ai * HALF + (mh + m) * 16) * D + col0 + bj * HALF;
;                     if (F32IN) { xa[m][bj] = *(const f32x4*)(Xin + idx); xb[m][bj] = *(const f32x4*)(Xin + idx + 4); }
;                     else { va[m][bj] = *(const u32x4*)(Hb + idx); vb[m][bj] = *(const u32x2*)(Hl + idx); } }
; #pragma unroll
;             for (int m = 0; m < MB; ++m) { const int row = row0 + ai * HALF + (mh + m) * 16; float sq = 0.f;
;                 const float rs1 = rsc[ai][mh + m];
; #pragma unroll
;                 for (int bj = 0; bj < 2; ++bj) { const size_t idx = (size_t)row * D + col0 + bj * HALF;
;                     unsigned hw[4]; int lw[2] = {0, 0};
; #pragma unroll
;                     for (int pq = 0; pq < 4; ++pq) {
;                         float h0, h1;
;                         if (F32IN) { h0 = (pq < 2) ? xa[m][bj][2 * pq] : xb[m][bj][2 * pq - 4]; h1 = (pq < 2) ? xa[m][bj][2 * pq + 1] : xb[m][bj][2 * pq - 3]; }
;                         else { const unsigned a = va[m][bj][pq]; const int bw = (int)vb[m][bj][pq >> 1]; const hf32x2 lp = (pq & 1) ? __builtin_amdgcn_cvt_pk_f32_fp8(bw, true) : __builtin_amdgcn_cvt_pk_f32_fp8(bw, false);
;                             h0 = __uint_as_float(a << 16) + lp.x * 0.00390625f; h1 = __uint_as_float(a & 0xffff0000u) + lp.y * 0.00390625f; }
;                         const float o0 = h0 + acc[ai][bj][mh + m][pq >> 1][(2 * pq) & 3] * rs1, o1 = h1 + acc[ai][bj][mh + m][pq >> 1][(2 * pq + 1) & 3] * rs1;
;                         sq += o0 * o0 + o1 * o1;
;                         const unsigned hi = cvt_pk_bf16(o0, o1);
;                         hw[pq] = hi;
;                         const float r0 = __builtin_amdgcn_fmed3f((o0 - __uint_as_float(hi << 16)) * 256.0f, -448.0f, 448.0f), r1 = __builtin_amdgcn_fmed3f((o1 - __uint_as_float(hi & 0xffff0000u)) * 256.0f, -448.0f, 448.0f);
;                         lw[pq >> 1] = (pq & 1) ? __builtin_amdgcn_cvt_pk_fp8_f32(r0, r1, lw[pq >> 1], true) : __builtin_amdgcn_cvt_pk_fp8_f32(r0, r1, lw[pq >> 1], false);
;                     }
	v_cvt_pk_f32_fp8_e32 v[40:41], v87
	v_mov_b32_e32 v44, v34
	v_lshlrev_b32_e32 v46, 16, v68
	v_mov_b32_e32 v45, v40
	v_pk_mul_f32 v[44:45], v[44:45], v[178:179]
	v_mov_b32_e32 v40, v35
	v_add_f32_e32 v34, v45, v46
	v_add_f32_e32 v44, v44, v34
	v_pk_mul_f32 v[34:35], v[40:41], v[178:179]
	v_lshlrev_b32_e32 v46, 16, v69
	v_add_f32_e32 v35, v35, v47
	v_add_f32_e32 v34, v34, v35
	v_mul_f32_e32 v35, v34, v34
	v_fmac_f32_e32 v35, v44, v44
	v_add_f32_e32 v41, v43, v35
	v_cvt_pk_bf16_f32 v40, v44, v34
	v_mov_b32_e32 v43, v1
	v_and_b32_e32 v35, 0xffff0000, v40
	v_sub_f32_e32 v34, v34, v35
	v_lshlrev_b32_e32 v35, 16, v40
	v_sub_f32_e32 v35, v44, v35
	v_mul_f32_e32 v34, 0x43800000, v34
	v_mul_f32_e32 v35, 0x43800000, v35
	v_med3_f32 v34, v34, s68, v235
	v_med3_f32 v35, v35, s68, v235
	v_cvt_pk_fp8_f32 v43, v35, v34
	v_cvt_pk_f32_fp8_sdwa v[34:35], v87 src0_sel:WORD_1
	v_mov_b32_e32 v44, v36
	v_and_b32_e32 v47, 0xffff0000, v69
	v_mov_b32_e32 v45, v34
	v_pk_mul_f32 v[44:45], v[44:45], v[178:179]
	s_nop 0
	v_add_f32_e32 v34, v45, v46
	v_add_f32_e32 v36, v44, v34
	v_mov_b32_e32 v34, v37
	v_pk_mul_f32 v[34:35], v[34:35], v[178:179]
	s_nop 0
	v_add_f32_e32 v35, v35, v47
	v_add_f32_e32 v34, v34, v35
	v_mul_f32_e32 v35, v34, v34
	v_fmac_f32_e32 v35, v36, v36
	v_add_f32_e32 v35, v41, v35
	v_cvt_pk_bf16_f32 v41, v36, v34
	ds_bpermute_b32 v44, v240, v35
	v_lshlrev_b32_e32 v37, 16, v41
	v_sub_f32_e32 v36, v36, v37
	v_and_b32_e32 v37, 0xffff0000, v41
	v_sub_f32_e32 v34, v34, v37
	v_mul_f32_e32 v36, 0x43800000, v36
	v_mul_f32_e32 v34, 0x43800000, v34
	v_med3_f32 v36, v36, s68, v235
	v_med3_f32 v34, v34, s68, v235
	v_cvt_pk_fp8_f32 v43, v36, v34 op_sel:[0,0,1]
	s_waitcnt lgkmcnt(0)
	v_add_f32_e32 v34, v35, v44
	ds_bpermute_b32 v35, v239, v34
	global_store_dwordx4 v[82:83], v[38:41], off sc1
	global_store_dwordx2 v[84:85], v[42:43], off
	s_and_saveexec_b64 s[2:3], s[38:39]
	s_cbranch_execz .LBB0_1437
	s_lshl_b32 s20, s8, 2
	s_waitcnt lgkmcnt(0)
	v_add_f32_e32 v36, v34, v35
	s_ashr_i32 s21, s20, 31
	v_lshl_add_u64 v[34:35], s[44:45], 0, v[166:167]
	v_lshl_add_u64 v[34:35], s[20:21], 2, v[34:35]
	s_lshl_b32 s18, s36, 2
	v_lshl_add_u64 v[34:35], v[34:35], 0, s[18:19]
	global_store_dword v[34:35], v36, off
.LBB0_1437:
	s_or_b64 exec, exec, s[2:3]
	v_add_f32_e32 v34, v243, v244
	v_fmamk_f32 v34, v34, 0x3a000000, v223
	s_waitcnt lgkmcnt(0)
	v_div_scale_f32 v35, s[2:3], v34, v34, 1.0
	v_rcp_f32_e32 v36, v35
	v_mov_b32_e32 v76, v30
	v_fma_f32 v37, -v35, v36, 1.0
	v_fmac_f32_e32 v36, v37, v36
	v_div_scale_f32 v37, vcc, 1.0, v34, 1.0
	v_mul_f32_e32 v38, v37, v36
	v_fma_f32 v39, -v35, v38, v37
	v_fmac_f32_e32 v38, v39, v36
	v_fma_f32 v35, -v35, v38, v37
	v_div_fmas_f32 v35, v35, v36, v38
	v_div_fixup_f32 v178, v35, v34, 1.0
	v_lshlrev_b64 v[34:35], 11, v[164:165]
	v_lshl_add_u64 v[34:35], v[34:35], 0, v[170:171]
	v_lshl_add_u64 v[68:69], v[34:35], 1, s[34:35]
	v_lshl_add_u64 v[70:71], s[42:43], 0, v[34:35]
	global_load_dwordx4 v[46:49], v[68:69], off
	global_load_dwordx2 v[72:73], v[70:71], off
	v_or_b32_e32 v34, 0x80, v34
	v_lshl_add_u64 v[62:63], v[34:35], 1, s[34:35]
	v_lshl_add_u64 v[64:65], s[42:43], 0, v[34:35]
	global_load_dwordx4 v[42:45], v[62:63], off
	global_load_dwordx2 v[66:67], v[64:65], off
	v_lshlrev_b64 v[34:35], 11, v[162:163]
	v_lshl_add_u64 v[52:53], v[34:35], 0, v[170:171]
	v_lshl_add_u64 v[56:57], v[52:53], 1, s[34:35]
	v_lshl_add_u64 v[58:59], s[42:43], 0, v[52:53]
	v_or_b32_e32 v52, 0x80, v52
	v_lshl_add_u64 v[50:51], v[52:53], 1, s[34:35]
	v_lshl_add_u64 v[52:53], s[42:43], 0, v[52:53]
	global_load_dwordx4 v[38:41], v[56:57], off
	global_load_dwordx2 v[60:61], v[58:59], off
	global_load_dwordx4 v[34:37], v[50:51], off
	global_load_dwordx2 v[54:55], v[52:53], off
	s_waitcnt vmcnt(7)
	v_lshlrev_b32_e32 v78, 16, v46
	s_waitcnt vmcnt(6)
	v_cvt_pk_f32_fp8_e32 v[74:75], v72
	v_and_b32_e32 v46, 0xffff0000, v46
	v_mov_b32_e32 v77, v74
	v_pk_mul_f32 v[76:77], v[76:77], v[178:179]
	v_mov_b32_e32 v74, v31
	v_add_f32_e32 v30, v77, v78
	v_add_f32_e32 v76, v76, v30
	v_pk_mul_f32 v[30:31], v[74:75], v[178:179]
	s_nop 0
	v_add_f32_e32 v31, v31, v46
	v_add_f32_e32 v31, v30, v31
	v_cvt_pk_bf16_f32 v30, v76, v31
	v_mul_f32_e32 v78, v31, v31
	v_and_b32_e32 v46, 0xffff0000, v30
	v_sub_f32_e32 v31, v31, v46
	v_lshlrev_b32_e32 v46, 16, v30
	v_sub_f32_e32 v46, v76, v46
	v_mul_f32_e32 v31, 0x43800000, v31
	v_mul_f32_e32 v46, 0x43800000, v46
	v_med3_f32 v31, v31, s68, v235
	v_med3_f32 v74, v46, s68, v235
	v_mov_b32_e32 v46, v1
	v_cvt_pk_fp8_f32 v46, v74, v31
	v_cvt_pk_f32_fp8_sdwa v[74:75], v72 src0_sel:WORD_1
	v_fmac_f32_e32 v78, v76, v76
	v_mov_b32_e32 v76, v32
	v_lshlrev_b32_e32 v31, 16, v47
	v_mov_b32_e32 v77, v74
	v_pk_mul_f32 v[76:77], v[76:77], v[178:179]
	v_mov_b32_e32 v74, v33
	v_and_b32_e32 v47, 0xffff0000, v47
	v_add_f32_e32 v31, v77, v31
	v_pk_mul_f32 v[32:33], v[74:75], v[178:179]
	v_add_f32_e32 v72, v76, v31
	v_add_f32_e32 v31, v33, v47
	v_add_f32_e32 v32, v32, v31
	v_mul_f32_e32 v31, v32, v32
	v_fmac_f32_e32 v31, v72, v72
	v_add_f32_e32 v47, v78, v31
	v_cvt_pk_bf16_f32 v31, v72, v32
	v_mov_b32_e32 v74, v26
	v_lshlrev_b32_e32 v33, 16, v31
	v_sub_f32_e32 v33, v72, v33
	v_and_b32_e32 v72, 0xffff0000, v31
	v_sub_f32_e32 v32, v32, v72
	v_mul_f32_e32 v33, 0x43800000, v33
	v_mul_f32_e32 v32, 0x43800000, v32
	v_med3_f32 v33, v33, s68, v235
	v_med3_f32 v32, v32, s68, v235
	v_cvt_pk_fp8_f32 v46, v33, v32 op_sel:[0,0,1]
	v_cvt_pk_f32_fp8_e32 v[32:33], v73
	v_lshlrev_b32_e32 v72, 16, v48
	v_and_b32_e32 v48, 0xffff0000, v48
	v_mov_b32_e32 v75, v32
	v_pk_mul_f32 v[74:75], v[74:75], v[178:179]
	v_mov_b32_e32 v32, v27
	v_add_f32_e32 v26, v75, v72
	v_add_f32_e32 v72, v74, v26
;     __device__ __forceinline__ void core(const f32x4 (&acc)[2][2][4][2], const Unit& u, int wr, int wc, int fr, int fq, const float (&rsc)[2][4]) const {
;     ...
;                 for (int bj = 0; bj < 2; ++bj) { const size_t idx = (size_t)(row0 + ai * HALF + (mh + m) * 16) * D + col0 + bj * HALF;
;                     if (F32IN) { xa[m][bj] = *(const f32x4*)(Xin + idx); xb[m][bj] = *(const f32x4*)(Xin + idx + 4); }
;                     else { va[m][bj] = *(const u32x4*)(Hb + idx); vb[m][bj] = *(const u32x2*)(Hl + idx); } }
; #pragma unroll
;             for (int m = 0; m < MB; ++m) { const int row = row0 + ai * HALF + (mh + m) * 16; float sq = 0.f;
;                 const float rs1 = rsc[ai][mh + m];
; #pragma unroll
;                 for (int bj = 0; bj < 2; ++bj) { const size_t idx = (size_t)row * D + col0 + bj * HALF;
;                     unsigned hw[4]; int lw[2] = {0, 0};
; #pragma unroll
;                     for (int pq = 0; pq < 4; ++pq) {
;                         float h0, h1;
;                         if (F32IN) { h0 = (pq < 2) ? xa[m][bj][2 * pq] : xb[m][bj][2 * pq - 4]; h1 = (pq < 2) ? xa[m][bj][2 * pq + 1] : xb[m][bj][2 * pq - 3]; }
;                         else { const unsigned a = va[m][bj][pq]; const int bw = (int)vb[m][bj][pq >> 1]; const hf32x2 lp = (pq & 1) ? __builtin_amdgcn_cvt_pk_f32_fp8(bw, true) : __builtin_amdgcn_cvt_pk_f32_fp8(bw, false);
;                             h0 = __uint_as_float(a << 16) + lp.x * 0.00390625f; h1 = __uint_as_float(a & 0xffff0000u) + lp.y * 0.00390625f; }
;                         const float o0 = h0 + acc[ai][bj][mh + m][pq >> 1][(2 * pq) & 3] * rs1, o1 = h1 + acc[ai][bj][mh + m][pq >> 1][(2 * pq + 1) & 3] * rs1;
;                         sq += o0 * o0 + o1 * o1;
;                         const unsigned hi = cvt_pk_bf16(o0, o1);
;                         hw[pq] = hi;
;                         const float r0 = __builtin_amdgcn_fmed3f((o0 - __uint_as_float(hi << 16)) * 256.0f, -448.0f, 448.0f), r1 = __builtin_amdgcn_fmed3f((o1 - __uint_as_float(hi & 0xffff0000u)) * 256.0f, -448.0f, 448.0f);
;                         lw[pq >> 1] = (pq & 1) ? __builtin_amdgcn_cvt_pk_fp8_f32(r0, r1, lw[pq >> 1], true) : __builtin_amdgcn_cvt_pk_fp8_f32(r0, r1, lw[pq >> 1], false);
;                     }
	v_pk_mul_f32 v[26:27], v[32:33], v[178:179]
	s_nop 0
	v_add_f32_e32 v27, v27, v48
	v_add_f32_e32 v26, v26, v27
	v_mul_f32_e32 v27, v26, v26
	v_fmac_f32_e32 v27, v72, v72
	v_add_f32_e32 v33, v47, v27
	v_cvt_pk_bf16_f32 v32, v72, v26
	v_mov_b32_e32 v47, v1
	v_and_b32_e32 v27, 0xffff0000, v32
	v_sub_f32_e32 v26, v26, v27
	v_lshlrev_b32_e32 v27, 16, v32
	v_sub_f32_e32 v27, v72, v27
	v_mul_f32_e32 v26, 0x43800000, v26
	v_mul_f32_e32 v27, 0x43800000, v27
	v_med3_f32 v26, v26, s68, v235
	v_med3_f32 v27, v27, s68, v235
	v_cvt_pk_fp8_f32 v47, v27, v26
	v_cvt_pk_f32_fp8_sdwa v[26:27], v73 src0_sel:WORD_1
	v_lshlrev_b32_e32 v72, 16, v49
	v_and_b32_e32 v73, 0xffff0000, v49
	v_mov_b32_e32 v48, v28
	v_mov_b32_e32 v49, v26
	v_pk_mul_f32 v[48:49], v[48:49], v[178:179]
	s_nop 0
	v_add_f32_e32 v26, v49, v72
	v_add_f32_e32 v28, v48, v26
	v_mov_b32_e32 v26, v29
	v_pk_mul_f32 v[26:27], v[26:27], v[178:179]
	s_nop 0
	v_add_f32_e32 v27, v27, v73
	v_add_f32_e32 v26, v26, v27
	v_mul_f32_e32 v27, v26, v26
	v_fmac_f32_e32 v27, v28, v28
	v_add_f32_e32 v48, v33, v27
	v_cvt_pk_bf16_f32 v33, v28, v26
	s_nop 0
	v_lshlrev_b32_e32 v27, 16, v33
	v_sub_f32_e32 v27, v28, v27
	v_and_b32_e32 v28, 0xffff0000, v33
	v_sub_f32_e32 v26, v26, v28
	v_mul_f32_e32 v27, 0x43800000, v27
	v_mul_f32_e32 v26, 0x43800000, v26
	v_med3_f32 v27, v27, s68, v235
	v_med3_f32 v26, v26, s68, v235
	v_cvt_pk_fp8_f32 v47, v27, v26 op_sel:[0,0,1]
	s_waitcnt vmcnt(4)
	v_cvt_pk_f32_fp8_e32 v[26:27], v66
	v_mov_b32_e32 v28, v22
	global_store_dwordx4 v[68:69], v[30:33], off sc1
	global_store_dwordx2 v[70:71], v[46:47], off
	v_mov_b32_e32 v29, v26
	v_lshlrev_b32_e32 v30, 16, v42
	v_pk_mul_f32 v[28:29], v[28:29], v[178:179]
	v_mov_b32_e32 v26, v23
	v_add_f32_e32 v22, v29, v30
	v_and_b32_e32 v31, 0xffff0000, v42
	v_add_f32_e32 v28, v28, v22
	v_pk_mul_f32 v[22:23], v[26:27], v[178:179]
	v_mov_b32_e32 v30, v24
	v_add_f32_e32 v23, v23, v31
	v_add_f32_e32 v23, v22, v23
	v_mul_f32_e32 v22, v23, v23
	v_fmac_f32_e32 v22, v28, v28
	v_add_f32_e32 v27, v48, v22
	v_cvt_pk_bf16_f32 v22, v28, v23
	v_and_b32_e32 v32, 0xffff0000, v43
	v_and_b32_e32 v26, 0xffff0000, v22
	v_sub_f32_e32 v23, v23, v26
	v_lshlrev_b32_e32 v26, 16, v22
	v_sub_f32_e32 v26, v28, v26
	v_mul_f32_e32 v23, 0x43800000, v23
	v_mul_f32_e32 v26, 0x43800000, v26
	v_med3_f32 v23, v23, s68, v235
	v_med3_f32 v28, v26, s68, v235
	v_mov_b32_e32 v26, v1
	v_cvt_pk_fp8_f32 v26, v28, v23
	v_cvt_pk_f32_fp8_sdwa v[28:29], v66 src0_sel:WORD_1
	v_lshlrev_b32_e32 v23, 16, v43
	v_mov_b32_e32 v31, v28
	v_pk_mul_f32 v[30:31], v[30:31], v[178:179]
	v_mov_b32_e32 v28, v25
	v_add_f32_e32 v23, v31, v23
	v_pk_mul_f32 v[24:25], v[28:29], v[178:179]
	v_add_f32_e32 v30, v30, v23
	v_add_f32_e32 v23, v25, v32
	v_add_f32_e32 v24, v24, v23
	v_mul_f32_e32 v23, v24, v24
	v_fmac_f32_e32 v23, v30, v30
	v_add_f32_e32 v27, v27, v23
	v_cvt_pk_bf16_f32 v23, v30, v24
	v_and_b32_e32 v31, 0xffff0000, v44
	v_lshlrev_b32_e32 v25, 16, v23
	v_and_b32_e32 v28, 0xffff0000, v23
	v_sub_f32_e32 v25, v30, v25
	v_sub_f32_e32 v24, v24, v28
	v_mul_f32_e32 v25, 0x43800000, v25
	v_mul_f32_e32 v24, 0x43800000, v24
	v_med3_f32 v25, v25, s68, v235
	v_med3_f32 v24, v24, s68, v235
	v_cvt_pk_fp8_f32 v26, v25, v24 op_sel:[0,0,1]
	v_cvt_pk_f32_fp8_e32 v[24:25], v67
	v_mov_b32_e32 v28, v18
	v_lshlrev_b32_e32 v30, 16, v44
	v_mov_b32_e32 v29, v24
	v_pk_mul_f32 v[28:29], v[28:29], v[178:179]
	v_mov_b32_e32 v24, v19
	v_add_f32_e32 v18, v29, v30
	v_add_f32_e32 v28, v28, v18
	v_pk_mul_f32 v[18:19], v[24:25], v[178:179]
	v_lshlrev_b32_e32 v30, 16, v45
	v_add_f32_e32 v19, v19, v31
	v_add_f32_e32 v18, v18, v19
	v_mul_f32_e32 v19, v18, v18
	v_fmac_f32_e32 v19, v28, v28
	v_add_f32_e32 v25, v27, v19
	v_cvt_pk_bf16_f32 v24, v28, v18
	v_mov_b32_e32 v27, v1
	v_and_b32_e32 v19, 0xffff0000, v24
	v_sub_f32_e32 v18, v18, v19
	v_lshlrev_b32_e32 v19, 16, v24
	v_sub_f32_e32 v19, v28, v19
	v_mul_f32_e32 v18, 0x43800000, v18
	v_mul_f32_e32 v19, 0x43800000, v19
	v_med3_f32 v18, v18, s68, v235
	v_med3_f32 v19, v19, s68, v235
	v_cvt_pk_fp8_f32 v27, v19, v18
	v_cvt_pk_f32_fp8_sdwa v[18:19], v67 src0_sel:WORD_1
	v_mov_b32_e32 v28, v20
	v_and_b32_e32 v31, 0xffff0000, v45
	v_mov_b32_e32 v29, v18
	v_pk_mul_f32 v[28:29], v[28:29], v[178:179]
	s_nop 0
	v_add_f32_e32 v18, v29, v30
	v_add_f32_e32 v20, v28, v18
	v_mov_b32_e32 v18, v21
	v_pk_mul_f32 v[18:19], v[18:19], v[178:179]
	s_nop 0
	v_add_f32_e32 v19, v19, v31
	v_add_f32_e32 v18, v18, v19
	v_mul_f32_e32 v19, v18, v18
	v_fmac_f32_e32 v19, v20, v20
	v_add_f32_e32 v19, v25, v19
	v_cvt_pk_bf16_f32 v25, v20, v18
	s_nop 0
	v_lshlrev_b32_e32 v21, 16, v25
	v_sub_f32_e32 v20, v20, v21
	v_and_b32_e32 v21, 0xffff0000, v25
	v_sub_f32_e32 v18, v18, v21
	v_mul_f32_e32 v20, 0x43800000, v20
	v_mul_f32_e32 v18, 0x43800000, v18
	v_med3_f32 v20, v20, s68, v235
	v_med3_f32 v18, v18, s68, v235
	v_cvt_pk_fp8_f32 v27, v20, v18 op_sel:[0,0,1]
	ds_bpermute_b32 v18, v240, v19
	global_store_dwordx4 v[62:63], v[22:25], off sc1
	global_store_dwordx2 v[64:65], v[26:27], off
	s_waitcnt lgkmcnt(0)
	v_add_f32_e32 v18, v19, v18
	ds_bpermute_b32 v19, v239, v18
	s_and_saveexec_b64 s[2:3], s[38:39]
	s_cbranch_execz .LBB0_1439
	s_lshl_b32 s20, s8, 2
	s_waitcnt lgkmcnt(0)
	v_add_f32_e32 v20, v18, v19
	s_ashr_i32 s21, s20, 31
	v_lshl_add_u64 v[18:19], s[44:45], 0, v[160:161]
	v_lshl_add_u64 v[18:19], s[20:21], 2, v[18:19]
	s_lshl_b32 s18, s36, 2
	v_lshl_add_u64 v[18:19], v[18:19], 0, s[18:19]
	global_store_dword v[18:19], v20, off
;     __device__ __forceinline__ void core(const f32x4 (&acc)[2][2][4][2], const Unit& u, int wr, int wc, int fr, int fq, const float (&rsc)[2][4]) const {
;     ...
;                 for (int bj = 0; bj < 2; ++bj) { const size_t idx = (size_t)(row0 + ai * HALF + (mh + m) * 16) * D + col0 + bj * HALF;
;                     if (F32IN) { xa[m][bj] = *(const f32x4*)(Xin + idx); xb[m][bj] = *(const f32x4*)(Xin + idx + 4); }
;                     else { va[m][bj] = *(const u32x4*)(Hb + idx); vb[m][bj] = *(const u32x2*)(Hl + idx); } }
; #pragma unroll
;             for (int m = 0; m < MB; ++m) { const int row = row0 + ai * HALF + (mh + m) * 16; float sq = 0.f;
;                 const float rs1 = rsc[ai][mh + m];
; #pragma unroll
;                 for (int bj = 0; bj < 2; ++bj) { const size_t idx = (size_t)row * D + col0 + bj * HALF;
;                     unsigned hw[4]; int lw[2] = {0, 0};
; #pragma unroll
;                     for (int pq = 0; pq < 4; ++pq) {
;                         float h0, h1;
;                         if (F32IN) { h0 = (pq < 2) ? xa[m][bj][2 * pq] : xb[m][bj][2 * pq - 4]; h1 = (pq < 2) ? xa[m][bj][2 * pq + 1] : xb[m][bj][2 * pq - 3]; }
;                         else { const unsigned a = va[m][bj][pq]; const int bw = (int)vb[m][bj][pq >> 1]; const hf32x2 lp = (pq & 1) ? __builtin_amdgcn_cvt_pk_f32_fp8(bw, true) : __builtin_amdgcn_cvt_pk_f32_fp8(bw, false);
;                             h0 = __uint_as_float(a << 16) + lp.x * 0.00390625f; h1 = __uint_as_float(a & 0xffff0000u) + lp.y * 0.00390625f; }
;                         const float o0 = h0 + acc[ai][bj][mh + m][pq >> 1][(2 * pq) & 3] * rs1, o1 = h1 + acc[ai][bj][mh + m][pq >> 1][(2 * pq + 1) & 3] * rs1;
;                         sq += o0 * o0 + o1 * o1;
;                         const unsigned hi = cvt_pk_bf16(o0, o1);
;                         hw[pq] = hi;
;                         const float r0 = __builtin_amdgcn_fmed3f((o0 - __uint_as_float(hi << 16)) * 256.0f, -448.0f, 448.0f), r1 = __builtin_amdgcn_fmed3f((o1 - __uint_as_float(hi & 0xffff0000u)) * 256.0f, -448.0f, 448.0f);
;                         lw[pq >> 1] = (pq & 1) ? __builtin_amdgcn_cvt_pk_fp8_f32(r0, r1, lw[pq >> 1], true) : __builtin_amdgcn_cvt_pk_fp8_f32(r0, r1, lw[pq >> 1], false);
;                     }
.LBB0_1439:
	s_or_b64 exec, exec, s[2:3]
	v_add_f32_e32 v18, v241, v242
	v_fmamk_f32 v18, v18, 0x3a000000, v223
	s_waitcnt lgkmcnt(0)
	v_div_scale_f32 v19, s[2:3], v18, v18, 1.0
	v_rcp_f32_e32 v20, v19
	v_div_scale_f32 v21, vcc, 1.0, v18, 1.0
	s_waitcnt vmcnt(7)
	v_and_b32_e32 v24, 0xffff0000, v39
	v_fma_f32 v22, -v19, v20, 1.0
	v_fmac_f32_e32 v20, v22, v20
	v_mul_f32_e32 v22, v21, v20
	v_fma_f32 v23, -v19, v22, v21
	v_fmac_f32_e32 v22, v23, v20
	v_fma_f32 v19, -v19, v22, v21
	v_div_fmas_f32 v19, v19, v20, v22
	v_div_fixup_f32 v178, v19, v18, 1.0
	s_waitcnt vmcnt(6)
	v_cvt_pk_f32_fp8_e32 v[18:19], v60
	v_mov_b32_e32 v20, v14
	v_lshlrev_b32_e32 v22, 16, v38
	v_and_b32_e32 v23, 0xffff0000, v38
	v_mov_b32_e32 v21, v18
	v_pk_mul_f32 v[20:21], v[20:21], v[178:179]
	v_mov_b32_e32 v18, v15
	v_add_f32_e32 v14, v21, v22
	v_add_f32_e32 v20, v20, v14
	v_pk_mul_f32 v[14:15], v[18:19], v[178:179]
	v_mov_b32_e32 v22, v16
	v_add_f32_e32 v15, v15, v23
	v_add_f32_e32 v15, v14, v15
	v_cvt_pk_bf16_f32 v14, v20, v15
	v_mul_f32_e32 v19, v15, v15
	v_and_b32_e32 v18, 0xffff0000, v14
	v_sub_f32_e32 v15, v15, v18
	v_lshlrev_b32_e32 v18, 16, v14
	v_sub_f32_e32 v18, v20, v18
	v_mul_f32_e32 v15, 0x43800000, v15
	v_mul_f32_e32 v18, 0x43800000, v18
	v_fmac_f32_e32 v19, v20, v20
	v_med3_f32 v15, v15, s68, v235
	v_med3_f32 v20, v18, s68, v235
	v_mov_b32_e32 v18, v1
	v_cvt_pk_fp8_f32 v18, v20, v15
	v_cvt_pk_f32_fp8_sdwa v[20:21], v60 src0_sel:WORD_1
	v_lshlrev_b32_e32 v15, 16, v39
	v_mov_b32_e32 v23, v20
	v_pk_mul_f32 v[22:23], v[22:23], v[178:179]
	v_mov_b32_e32 v20, v17
	v_add_f32_e32 v15, v23, v15
	v_pk_mul_f32 v[16:17], v[20:21], v[178:179]
	v_add_f32_e32 v22, v22, v15
	v_add_f32_e32 v15, v17, v24
	v_add_f32_e32 v16, v16, v15
	v_mul_f32_e32 v15, v16, v16
	v_fmac_f32_e32 v15, v22, v22
	v_add_f32_e32 v19, v19, v15
	v_cvt_pk_bf16_f32 v15, v22, v16
	v_and_b32_e32 v23, 0xffff0000, v40
	v_lshlrev_b32_e32 v17, 16, v15
	v_and_b32_e32 v20, 0xffff0000, v15
	v_sub_f32_e32 v17, v22, v17
	v_sub_f32_e32 v16, v16, v20
	v_mul_f32_e32 v17, 0x43800000, v17
	v_mul_f32_e32 v16, 0x43800000, v16
	v_med3_f32 v17, v17, s68, v235
	v_med3_f32 v16, v16, s68, v235
	v_cvt_pk_fp8_f32 v18, v17, v16 op_sel:[0,0,1]
	v_cvt_pk_f32_fp8_e32 v[16:17], v61
	v_mov_b32_e32 v20, v10
	v_lshlrev_b32_e32 v22, 16, v40
	v_mov_b32_e32 v21, v16
	v_pk_mul_f32 v[20:21], v[20:21], v[178:179]
	v_mov_b32_e32 v16, v11
	v_add_f32_e32 v10, v21, v22
	v_add_f32_e32 v20, v20, v10
	v_pk_mul_f32 v[10:11], v[16:17], v[178:179]
	v_lshlrev_b32_e32 v17, 16, v41
	v_add_f32_e32 v11, v11, v23
	v_add_f32_e32 v10, v10, v11
	v_mul_f32_e32 v11, v10, v10
	v_fmac_f32_e32 v11, v20, v20
	v_add_f32_e32 v22, v19, v11
	v_cvt_pk_bf16_f32 v16, v20, v10
	v_mov_b32_e32 v19, v1
	v_and_b32_e32 v11, 0xffff0000, v16
	v_sub_f32_e32 v10, v10, v11
	v_lshlrev_b32_e32 v11, 16, v16
	v_sub_f32_e32 v11, v20, v11
	v_mul_f32_e32 v10, 0x43800000, v10
	v_mul_f32_e32 v11, 0x43800000, v11
	v_med3_f32 v10, v10, s68, v235
	v_med3_f32 v11, v11, s68, v235
	v_cvt_pk_fp8_f32 v19, v11, v10
	v_cvt_pk_f32_fp8_sdwa v[10:11], v61 src0_sel:WORD_1
	v_mov_b32_e32 v20, v12
	v_and_b32_e32 v23, 0xffff0000, v41
	v_mov_b32_e32 v21, v10
	v_pk_mul_f32 v[20:21], v[20:21], v[178:179]
	s_nop 0
	v_add_f32_e32 v10, v21, v17
	v_add_f32_e32 v12, v20, v10
	v_mov_b32_e32 v10, v13
	v_pk_mul_f32 v[10:11], v[10:11], v[178:179]
	s_nop 0
	v_add_f32_e32 v11, v11, v23
	v_add_f32_e32 v10, v10, v11
	v_cvt_pk_bf16_f32 v17, v12, v10
	v_mul_f32_e32 v11, v10, v10
	v_lshlrev_b32_e32 v13, 16, v17
	v_and_b32_e32 v20, 0xffff0000, v17
	v_sub_f32_e32 v13, v12, v13
	v_sub_f32_e32 v10, v10, v20
	v_mul_f32_e32 v13, 0x43800000, v13
	v_mul_f32_e32 v10, 0x43800000, v10
	v_med3_f32 v13, v13, s68, v235
	v_med3_f32 v10, v10, s68, v235
	v_fmac_f32_e32 v11, v12, v12
	v_cvt_pk_fp8_f32 v19, v13, v10 op_sel:[0,0,1]
	v_add_f32_e32 v20, v22, v11
	s_waitcnt vmcnt(4)
;     __device__ __forceinline__ void core(const f32x4 (&acc)[2][2][4][2], const Unit& u, int wr, int wc, int fr, int fq, const float (&rsc)[2][4]) const {
;     ...
;                 for (int bj = 0; bj < 2; ++bj) { const size_t idx = (size_t)(row0 + ai * HALF + (mh + m) * 16) * D + col0 + bj * HALF;
;                     if (F32IN) { xa[m][bj] = *(const f32x4*)(Xin + idx); xb[m][bj] = *(const f32x4*)(Xin + idx + 4); }
;                     else { va[m][bj] = *(const u32x4*)(Hb + idx); vb[m][bj] = *(const u32x2*)(Hl + idx); } }
; #pragma unroll
;             for (int m = 0; m < MB; ++m) { const int row = row0 + ai * HALF + (mh + m) * 16; float sq = 0.f;
;                 const float rs1 = rsc[ai][mh + m];
; #pragma unroll
;                 for (int bj = 0; bj < 2; ++bj) { const size_t idx = (size_t)row * D + col0 + bj * HALF;
;                     unsigned hw[4]; int lw[2] = {0, 0};
; #pragma unroll
;                     for (int pq = 0; pq < 4; ++pq) {
;                         float h0, h1;
;                         if (F32IN) { h0 = (pq < 2) ? xa[m][bj][2 * pq] : xb[m][bj][2 * pq - 4]; h1 = (pq < 2) ? xa[m][bj][2 * pq + 1] : xb[m][bj][2 * pq - 3]; }
;                         else { const unsigned a = va[m][bj][pq]; const int bw = (int)vb[m][bj][pq >> 1]; const hf32x2 lp = (pq & 1) ? __builtin_amdgcn_cvt_pk_f32_fp8(bw, true) : __builtin_amdgcn_cvt_pk_f32_fp8(bw, false);
;                             h0 = __uint_as_float(a << 16) + lp.x * 0.00390625f; h1 = __uint_as_float(a & 0xffff0000u) + lp.y * 0.00390625f; }
;                         const float o0 = h0 + acc[ai][bj][mh + m][pq >> 1][(2 * pq) & 3] * rs1, o1 = h1 + acc[ai][bj][mh + m][pq >> 1][(2 * pq + 1) & 3] * rs1;
;                         sq += o0 * o0 + o1 * o1;
;                         const unsigned hi = cvt_pk_bf16(o0, o1);
;                         hw[pq] = hi;
;                         const float r0 = __builtin_amdgcn_fmed3f((o0 - __uint_as_float(hi << 16)) * 256.0f, -448.0f, 448.0f), r1 = __builtin_amdgcn_fmed3f((o1 - __uint_as_float(hi & 0xffff0000u)) * 256.0f, -448.0f, 448.0f);
;                         lw[pq >> 1] = (pq & 1) ? __builtin_amdgcn_cvt_pk_fp8_f32(r0, r1, lw[pq >> 1], true) : __builtin_amdgcn_cvt_pk_fp8_f32(r0, r1, lw[pq >> 1], false);
;                     }
	v_cvt_pk_f32_fp8_e32 v[10:11], v54
	v_mov_b32_e32 v12, v6
	global_store_dwordx4 v[56:57], v[14:17], off sc1
	global_store_dwordx2 v[58:59], v[18:19], off
	v_mov_b32_e32 v13, v10
	v_lshlrev_b32_e32 v14, 16, v34
	v_pk_mul_f32 v[12:13], v[12:13], v[178:179]
	v_mov_b32_e32 v10, v7
	v_add_f32_e32 v6, v13, v14
	v_and_b32_e32 v15, 0xffff0000, v34
	v_add_f32_e32 v12, v12, v6
	v_pk_mul_f32 v[6:7], v[10:11], v[178:179]
	v_mov_b32_e32 v14, v8
	v_add_f32_e32 v7, v7, v15
	v_add_f32_e32 v7, v6, v7
	v_mul_f32_e32 v6, v7, v7
	v_fmac_f32_e32 v6, v12, v12
	v_add_f32_e32 v11, v20, v6
	v_cvt_pk_bf16_f32 v6, v12, v7
	v_and_b32_e32 v16, 0xffff0000, v35
	v_and_b32_e32 v10, 0xffff0000, v6
	v_sub_f32_e32 v7, v7, v10
	v_lshlrev_b32_e32 v10, 16, v6
	v_sub_f32_e32 v10, v12, v10
	v_mul_f32_e32 v7, 0x43800000, v7
	v_mul_f32_e32 v10, 0x43800000, v10
	v_med3_f32 v7, v7, s68, v235
	v_med3_f32 v12, v10, s68, v235
	v_mov_b32_e32 v10, v1
	v_cvt_pk_fp8_f32 v10, v12, v7
	v_cvt_pk_f32_fp8_sdwa v[12:13], v54 src0_sel:WORD_1
	v_lshlrev_b32_e32 v7, 16, v35
	v_mov_b32_e32 v15, v12
	v_pk_mul_f32 v[14:15], v[14:15], v[178:179]
	v_mov_b32_e32 v12, v9
	v_add_f32_e32 v7, v15, v7
	v_pk_mul_f32 v[8:9], v[12:13], v[178:179]
	v_add_f32_e32 v14, v14, v7
	v_add_f32_e32 v7, v9, v16
	v_add_f32_e32 v8, v8, v7
	v_mul_f32_e32 v7, v8, v8
	v_fmac_f32_e32 v7, v14, v14
	v_add_f32_e32 v11, v11, v7
	v_cvt_pk_bf16_f32 v7, v14, v8
	v_and_b32_e32 v15, 0xffff0000, v36
	v_lshlrev_b32_e32 v9, 16, v7
	v_and_b32_e32 v12, 0xffff0000, v7
	v_sub_f32_e32 v9, v14, v9
	v_sub_f32_e32 v8, v8, v12
	v_mul_f32_e32 v9, 0x43800000, v9
	v_mul_f32_e32 v8, 0x43800000, v8
	v_med3_f32 v9, v9, s68, v235
	v_med3_f32 v8, v8, s68, v235
	v_cvt_pk_fp8_f32 v10, v9, v8 op_sel:[0,0,1]
	v_cvt_pk_f32_fp8_e32 v[8:9], v55
	v_mov_b32_e32 v12, v2
	v_lshlrev_b32_e32 v14, 16, v36
	v_mov_b32_e32 v13, v8
	v_pk_mul_f32 v[12:13], v[12:13], v[178:179]
	v_mov_b32_e32 v8, v3
	v_add_f32_e32 v2, v13, v14
	v_add_f32_e32 v12, v12, v2
	v_pk_mul_f32 v[2:3], v[8:9], v[178:179]
	v_lshlrev_b32_e32 v14, 16, v37
	v_add_f32_e32 v3, v3, v15
	v_add_f32_e32 v2, v2, v3
	v_mul_f32_e32 v3, v2, v2
	v_fmac_f32_e32 v3, v12, v12
	v_add_f32_e32 v9, v11, v3
	v_cvt_pk_bf16_f32 v8, v12, v2
	v_mov_b32_e32 v11, v1
	v_and_b32_e32 v3, 0xffff0000, v8
	v_sub_f32_e32 v2, v2, v3
	v_lshlrev_b32_e32 v3, 16, v8
	v_sub_f32_e32 v3, v12, v3
	v_mul_f32_e32 v2, 0x43800000, v2
	v_mul_f32_e32 v3, 0x43800000, v3
	v_med3_f32 v2, v2, s68, v235
	v_med3_f32 v3, v3, s68, v235
	v_cvt_pk_fp8_f32 v11, v3, v2
	v_cvt_pk_f32_fp8_sdwa v[2:3], v55 src0_sel:WORD_1
	v_mov_b32_e32 v12, v4
	v_and_b32_e32 v15, 0xffff0000, v37
	v_mov_b32_e32 v13, v2
	v_pk_mul_f32 v[12:13], v[12:13], v[178:179]
	s_nop 0
	v_add_f32_e32 v2, v13, v14
	v_add_f32_e32 v4, v12, v2
	v_mov_b32_e32 v2, v5
	v_pk_mul_f32 v[2:3], v[2:3], v[178:179]
	s_nop 0
	v_add_f32_e32 v3, v3, v15
	v_add_f32_e32 v2, v2, v3
	v_mul_f32_e32 v3, v2, v2
	v_fmac_f32_e32 v3, v4, v4
	v_add_f32_e32 v3, v9, v3
	v_cvt_pk_bf16_f32 v9, v4, v2
	ds_bpermute_b32 v12, v240, v3
	v_lshlrev_b32_e32 v5, 16, v9
	v_sub_f32_e32 v4, v4, v5
	v_and_b32_e32 v5, 0xffff0000, v9
	v_sub_f32_e32 v2, v2, v5
	v_mul_f32_e32 v4, 0x43800000, v4
	v_mul_f32_e32 v2, 0x43800000, v2
	v_med3_f32 v4, v4, s68, v235
	v_med3_f32 v2, v2, s68, v235
	v_cvt_pk_fp8_f32 v11, v4, v2 op_sel:[0,0,1]
	s_waitcnt lgkmcnt(0)
	v_add_f32_e32 v2, v3, v12
	ds_bpermute_b32 v3, v239, v2
	global_store_dwordx4 v[50:51], v[6:9], off sc1
	global_store_dwordx2 v[52:53], v[10:11], off
	s_and_saveexec_b64 s[2:3], s[38:39]
	s_cbranch_execz .LBB0_1441
	s_lshl_b32 s20, s8, 2
	s_waitcnt lgkmcnt(0)
	v_add_f32_e32 v4, v2, v3
	s_ashr_i32 s21, s20, 31
	v_lshl_add_u64 v[2:3], s[44:45], 0, v[158:159]
	v_lshl_add_u64 v[2:3], s[20:21], 2, v[2:3]
	s_lshl_b32 s18, s36, 2
	v_lshl_add_u64 v[2:3], v[2:3], 0, s[18:19]
	global_store_dword v[2:3], v4, off
